# on top of trimmed K-loops: mid-segment setprio flips removed and first K-iteration peeled with C=0 so the 128 accumulator-zeroing moves per unit are gone
# speedup vs baseline: 1.0096x; 1.0010x over previous
; __device__ __forceinline__ const char* unitA(const Gemm& g, const Unit& u) { return (const char*)(g.A + (size_t)(u.z / g.zdiv) * g.sAhi + (size_t)(u.z % g.zdiv) * g.sAlo + (size_t)u.pm * BM * g.lda); }
; __device__ __forceinline__ const char* unitB(const Gemm& g, const Unit& u) { return (const char*)(g.Bt + (size_t)(u.z / g.zdiv) * g.sBhi + (size_t)(u.z % g.zdiv) * g.sBlo + (size_t)(u.pm / g.bdiv) * g.sBpm + (size_t)u.pn * BM * g.ldb); }
; #define PG8_STAGE(bufoff, gbase, voff) do { if constexpr (VAR != 1 && VAR != 3) { _Pragma("unroll") for (int _i = 0; _i < 2; ++_i) \
;         asm volatile("s_mov_b32 m0, %2\n\ts_nop 0\n\tglobal_load_lds_dwordx4 %0, %1" :: "v"((voff)[_i]), "s"((const char*)(gbase)), "s"(ldsbase + (unsigned)((bufoff) + _i * 8192)) : "memory", "m0"); } } while (0)
; #define PG8_LDA(dst, b, h) do { if constexpr (VAR < 2) _Pragma("unroll") for (int m = 0; m < 4; ++m) _Pragma("unroll") for (int k = 0; k < 2; ++k) dst[m][k] = *(const LAS bf16x8*)(lds + PG8_SA(b, h) + aoff + m * 2048 + k * 1024); } while (0)
; #define PG8_LDB(dst, b, h) do { if constexpr (VAR < 2) _Pragma("unroll") for (int n = 0; n < 2; ++n) _Pragma("unroll") for (int k = 0; k < 2; ++k) dst[n][k] = *(const LAS bf16x8*)(lds + PG8_SB(b, h) + boff + n * 2048 + k * 1024); } while (0)
; #define PG8_WAIT_V(n) asm volatile("s_waitcnt vmcnt(" #n ")" ::: "memory")
;     ...
;         const bool has_next = S.next(ui + 1, nxt);
;         const char* nA = has_next ? unitA(g, nxt) : cA; const char* nB = has_next ? unitB(g, nxt) : cB;
;         for (int t = 0; t < nt; t += 2) {
;             const bool last = (t == nt - 2);
;             const char* a1 = cA + (size_t)(t + 1) * kstep;
;             const char* a2 = last ? nA : cA + (size_t)(t + 2) * kstep; const char* b2 = last ? nB : cB + (size_t)(t + 2) * kstep;
;             const char* a3 = a2 + kstep; const char* b3 = b2 + kstep;
;             PG8_LDB(B0, 0, 0); PG8_LDB(B1, 0, 1); PG8_SCHED; PG8_LDA(At, 0, 0); PG8_STAGE(PG8_SA(1, 1), a1 + hstepA, voffA);
;             PG8_WAIT_V(8); PG8_WAIT_L(0); PG8_BAR; PG8_MMA(0, 0, At, B0); PG8_MMA(0, 1, At, B1); PG8_BAR; PG8_SCHED;
;             PG8_LDA(At, 0, 1); PG8_STAGE(PG8_SB(0, 0), b2, voffB); PG8_STAGE(PG8_SB(0, 1), b2 + hstepB, voffB); PG8_STAGE(PG8_SA(0, 0), a2, voffA);
;             PG8_WAIT_V(8); PG8_WAIT_L(0); PG8_BAR; PG8_MMA(1, 0, At, B0); PG8_MMA(1, 1, At, B1); PG8_BAR; PG8_SCHED;
.LBB0_345:
	s_ashr_i32 s65, s64, 31
	s_lshl_b64 s[6:7], s[64:65], 21
	s_add_u32 s70, s21, s6
	s_addc_u32 s71, s23, s7
	s_and_b64 s[6:7], s[2:3], exec
	s_cselect_b32 s14, s71, s93
	s_cselect_b32 s15, s70, s92
	s_ashr_i32 s69, s68, 31
	s_lshl_b64 s[6:7], s[68:69], 21
	s_add_u32 s88, s86, s6
	s_addc_u32 s89, s87, s7
	s_and_b64 s[6:7], s[2:3], exec
	s_cselect_b32 s63, s89, s91
	s_cselect_b32 s65, s88, s90
	s_add_u32 s66, s92, 0x100
	s_addc_u32 s67, s93, 0
	s_add_u32 s69, s90, 0x100
	s_addc_u32 vcc_lo, s91, 0
	s_add_u32 s90, s92, 0x100080
	s_addc_u32 s91, s93, 0
	s_mov_b32 vcc_hi, -2
	ds_read_b128 v[156:159], v151
	ds_read_b128 v[160:163], v151 offset:1024
	ds_read_b128 v[164:167], v151 offset:2048
	ds_read_b128 v[168:171], v151 offset:3072
	ds_read_b128 v[172:175], v152
	ds_read_b128 v[176:179], v152 offset:1024
	ds_read_b128 v[180:183], v152 offset:2048
	ds_read_b128 v[184:187], v152 offset:3072
	s_cmp_eq_u32 vcc_hi, 60
	s_cselect_b32 s96, s15, s66
	s_cselect_b32 s97, s14, s67
	s_cselect_b32 s94, s65, s69
	s_cselect_b32 s95, s63, vcc_lo
	s_add_u32 s92, s96, 0x80
	s_addc_u32 s93, s97, 0
	ds_read_b128 v[188:191], v153
	ds_read_b128 v[192:195], v153 offset:1024
	ds_read_b128 v[196:199], v153 offset:2048
	ds_read_b128 v[200:203], v153 offset:3072
	ds_read_b128 v[204:207], v153 offset:4096
	ds_read_b128 v[208:211], v153 offset:5120
	ds_read_b128 v[212:215], v153 offset:6144
	ds_read_b128 v[216:219], v153 offset:7168
	s_mov_b32 m0, s56
	s_nop 0
	global_load_lds_dwordx4 v1, s[90:91]
	s_mov_b32 m0, s57
	s_nop 0
	global_load_lds_dwordx4 v147, s[90:91]
	s_waitcnt vmcnt(8)
	s_waitcnt lgkmcnt(0)
	s_barrier
	s_setprio 1
	v_mfma_f32_16x16x32_bf16 v[126:129], v[156:159], v[188:191], 0
	v_mfma_f32_16x16x32_bf16 v[122:125], v[164:167], v[188:191], 0
	v_mfma_f32_16x16x32_bf16 v[118:121], v[156:159], v[196:199], 0
	v_mfma_f32_16x16x32_bf16 v[110:113], v[164:167], v[196:199], 0
	v_mfma_f32_16x16x32_bf16 v[102:105], v[156:159], v[204:207], 0
	v_mfma_f32_16x16x32_bf16 v[94:97], v[164:167], v[204:207], 0
	v_mfma_f32_16x16x32_bf16 v[86:89], v[156:159], v[212:215], 0
	v_mfma_f32_16x16x32_bf16 v[78:81], v[164:167], v[212:215], 0
	v_mfma_f32_16x16x32_bf16 v[126:129], v[160:163], v[192:195], v[126:129]
	v_mfma_f32_16x16x32_bf16 v[122:125], v[168:171], v[192:195], v[122:125]
	v_mfma_f32_16x16x32_bf16 v[118:121], v[160:163], v[200:203], v[118:121]
	v_mfma_f32_16x16x32_bf16 v[110:113], v[168:171], v[200:203], v[110:113]
	v_mfma_f32_16x16x32_bf16 v[102:105], v[160:163], v[208:211], v[102:105]
	v_mfma_f32_16x16x32_bf16 v[94:97], v[168:171], v[208:211], v[94:97]
	v_mfma_f32_16x16x32_bf16 v[86:89], v[160:163], v[216:219], v[86:89]
	v_mfma_f32_16x16x32_bf16 v[78:81], v[168:171], v[216:219], v[78:81]
	v_mfma_f32_16x16x32_bf16 v[114:117], v[172:175], v[188:191], 0
	v_mfma_f32_16x16x32_bf16 v[106:109], v[180:183], v[188:191], 0
	v_mfma_f32_16x16x32_bf16 v[98:101], v[172:175], v[196:199], 0
	v_mfma_f32_16x16x32_bf16 v[90:93], v[180:183], v[196:199], 0
	v_mfma_f32_16x16x32_bf16 v[82:85], v[172:175], v[204:207], 0
	v_mfma_f32_16x16x32_bf16 v[74:77], v[180:183], v[204:207], 0
	v_mfma_f32_16x16x32_bf16 v[70:73], v[172:175], v[212:215], 0
	v_mfma_f32_16x16x32_bf16 v[66:69], v[180:183], v[212:215], 0
	v_mfma_f32_16x16x32_bf16 v[114:117], v[176:179], v[192:195], v[114:117]
	v_mfma_f32_16x16x32_bf16 v[106:109], v[184:187], v[192:195], v[106:109]
	v_mfma_f32_16x16x32_bf16 v[98:101], v[176:179], v[200:203], v[98:101]
	v_mfma_f32_16x16x32_bf16 v[90:93], v[184:187], v[200:203], v[90:93]
	v_mfma_f32_16x16x32_bf16 v[82:85], v[176:179], v[208:211], v[82:85]
	v_mfma_f32_16x16x32_bf16 v[74:77], v[184:187], v[208:211], v[74:77]
	v_mfma_f32_16x16x32_bf16 v[70:73], v[176:179], v[216:219], v[70:73]
	v_mfma_f32_16x16x32_bf16 v[66:69], v[184:187], v[216:219], v[66:69]
	s_setprio 0
	s_barrier
	ds_read_b128 v[188:191], v153 offset:16384
	ds_read_b128 v[192:195], v153 offset:17408
	ds_read_b128 v[196:199], v153 offset:18432
	ds_read_b128 v[200:203], v153 offset:19456
	ds_read_b128 v[204:207], v153 offset:20480
	ds_read_b128 v[208:211], v153 offset:21504
	ds_read_b128 v[212:215], v153 offset:22528
	ds_read_b128 v[216:219], v153 offset:23552
	s_mov_b32 m0, s25
	s_nop 0
	global_load_lds_dwordx4 v146, s[94:95]
	s_add_u32 s6, s94, 0x100000
	s_mov_b32 m0, s26
	s_nop 0
	global_load_lds_dwordx4 v148, s[94:95]
	s_addc_u32 s7, s95, 0
	s_mov_b32 m0, s27
	s_nop 0
	global_load_lds_dwordx4 v146, s[6:7]
	s_mov_b32 m0, s28
	s_nop 0
	global_load_lds_dwordx4 v148, s[6:7]
	s_mov_b32 m0, s19
	s_nop 0
	global_load_lds_dwordx4 v1, s[96:97]
	s_mov_b32 m0, s29
	s_nop 0
	global_load_lds_dwordx4 v147, s[96:97]
	s_waitcnt vmcnt(8)
	s_waitcnt lgkmcnt(0)
	s_barrier
; #define PG8_STAGE(bufoff, gbase, voff) do { if constexpr (VAR != 1 && VAR != 3) { _Pragma("unroll") for (int _i = 0; _i < 2; ++_i) \
;         asm volatile("s_mov_b32 m0, %2\n\ts_nop 0\n\tglobal_load_lds_dwordx4 %0, %1" :: "v"((voff)[_i]), "s"((const char*)(gbase)), "s"(ldsbase + (unsigned)((bufoff) + _i * 8192)) : "memory", "m0"); } } while (0)
; #define PG8_LDA(dst, b, h) do { if constexpr (VAR < 2) _Pragma("unroll") for (int m = 0; m < 4; ++m) _Pragma("unroll") for (int k = 0; k < 2; ++k) dst[m][k] = *(const LAS bf16x8*)(lds + PG8_SA(b, h) + aoff + m * 2048 + k * 1024); } while (0)
; #define PG8_LDB(dst, b, h) do { if constexpr (VAR < 2) _Pragma("unroll") for (int n = 0; n < 2; ++n) _Pragma("unroll") for (int k = 0; k < 2; ++k) dst[n][k] = *(const LAS bf16x8*)(lds + PG8_SB(b, h) + boff + n * 2048 + k * 1024); } while (0)
; #define PG8_WAIT_V(n) asm volatile("s_waitcnt vmcnt(" #n ")" ::: "memory")
; #define PG8_WAIT_L(n) asm volatile("s_waitcnt lgkmcnt(" #n ")" ::: "memory")
; #define PG8_BAR do { if constexpr (VAR != 3) __builtin_amdgcn_s_barrier(); } while (0)
; #define PG8_SCHED __builtin_amdgcn_sched_barrier(0)
;     ...
;             PG8_WAIT_V(8); PG8_WAIT_L(0); PG8_BAR; PG8_MMA(1, 0, At, B0); PG8_MMA(1, 1, At, B1); PG8_BAR; PG8_SCHED;
;             PG8_LDB(B0, 1, 0); PG8_LDB(B1, 1, 1); PG8_SCHED; PG8_LDA(At, 1, 0); PG8_STAGE(PG8_SA(0, 1), a2 + hstepA, voffA);
;             PG8_WAIT_V(8); PG8_WAIT_L(0); PG8_BAR; PG8_MMA(0, 0, At, B0); PG8_MMA(0, 1, At, B1); PG8_BAR; PG8_SCHED;
	s_setprio 1
	v_mfma_f32_16x16x32_bf16 v[62:65], v[156:159], v[188:191], 0
	v_mfma_f32_16x16x32_bf16 v[58:61], v[164:167], v[188:191], 0
	v_mfma_f32_16x16x32_bf16 v[54:57], v[156:159], v[196:199], 0
	v_mfma_f32_16x16x32_bf16 v[46:49], v[164:167], v[196:199], 0
	v_mfma_f32_16x16x32_bf16 v[38:41], v[156:159], v[204:207], 0
	v_mfma_f32_16x16x32_bf16 v[30:33], v[164:167], v[204:207], 0
	v_mfma_f32_16x16x32_bf16 v[22:25], v[156:159], v[212:215], 0
	v_mfma_f32_16x16x32_bf16 v[14:17], v[164:167], v[212:215], 0
	v_mfma_f32_16x16x32_bf16 v[62:65], v[160:163], v[192:195], v[62:65]
	v_mfma_f32_16x16x32_bf16 v[58:61], v[168:171], v[192:195], v[58:61]
	v_mfma_f32_16x16x32_bf16 v[54:57], v[160:163], v[200:203], v[54:57]
	v_mfma_f32_16x16x32_bf16 v[46:49], v[168:171], v[200:203], v[46:49]
	v_mfma_f32_16x16x32_bf16 v[38:41], v[160:163], v[208:211], v[38:41]
	v_mfma_f32_16x16x32_bf16 v[30:33], v[168:171], v[208:211], v[30:33]
	v_mfma_f32_16x16x32_bf16 v[22:25], v[160:163], v[216:219], v[22:25]
	v_mfma_f32_16x16x32_bf16 v[14:17], v[168:171], v[216:219], v[14:17]
	v_mfma_f32_16x16x32_bf16 v[50:53], v[172:175], v[188:191], 0
	v_mfma_f32_16x16x32_bf16 v[42:45], v[180:183], v[188:191], 0
	v_mfma_f32_16x16x32_bf16 v[34:37], v[172:175], v[196:199], 0
	v_mfma_f32_16x16x32_bf16 v[26:29], v[180:183], v[196:199], 0
	v_mfma_f32_16x16x32_bf16 v[18:21], v[172:175], v[204:207], 0
	v_mfma_f32_16x16x32_bf16 v[10:13], v[180:183], v[204:207], 0
	v_mfma_f32_16x16x32_bf16 v[6:9], v[172:175], v[212:215], 0
	v_mfma_f32_16x16x32_bf16 v[2:5], v[180:183], v[212:215], 0
	v_mfma_f32_16x16x32_bf16 v[50:53], v[176:179], v[192:195], v[50:53]
	v_mfma_f32_16x16x32_bf16 v[42:45], v[184:187], v[192:195], v[42:45]
	v_mfma_f32_16x16x32_bf16 v[34:37], v[176:179], v[200:203], v[34:37]
	v_mfma_f32_16x16x32_bf16 v[26:29], v[184:187], v[200:203], v[26:29]
	v_mfma_f32_16x16x32_bf16 v[18:21], v[176:179], v[208:211], v[18:21]
	v_mfma_f32_16x16x32_bf16 v[10:13], v[184:187], v[208:211], v[10:13]
	v_mfma_f32_16x16x32_bf16 v[6:9], v[176:179], v[216:219], v[6:9]
	v_mfma_f32_16x16x32_bf16 v[2:5], v[184:187], v[216:219], v[2:5]
	s_setprio 0
	s_barrier
	ds_read_b128 v[156:159], v154
	ds_read_b128 v[160:163], v154 offset:1024
	ds_read_b128 v[164:167], v154 offset:2048
	ds_read_b128 v[168:171], v154 offset:3072
	ds_read_b128 v[172:175], v155
	ds_read_b128 v[176:179], v155 offset:1024
	ds_read_b128 v[180:183], v155 offset:2048
	ds_read_b128 v[184:187], v155 offset:3072
	ds_read_b128 v[188:191], v153 offset:32768
	ds_read_b128 v[192:195], v153 offset:33792
	ds_read_b128 v[196:199], v153 offset:34816
	ds_read_b128 v[200:203], v153 offset:35840
	ds_read_b128 v[204:207], v153 offset:36864
	ds_read_b128 v[208:211], v153 offset:37888
	ds_read_b128 v[212:215], v153 offset:38912
	ds_read_b128 v[216:219], v153 offset:39936
	s_add_u32 s6, s96, 0x100000
	s_addc_u32 s7, s97, 0
	s_mov_b32 m0, s30
	s_nop 0
	global_load_lds_dwordx4 v1, s[6:7]
	s_mov_b32 m0, s31
	s_nop 0
	global_load_lds_dwordx4 v147, s[6:7]
	s_waitcnt vmcnt(8)
	s_waitcnt lgkmcnt(0)
	s_barrier
	s_setprio 1
	v_mfma_f32_16x16x32_bf16 v[126:129], v[156:159], v[188:191], v[126:129]
	v_mfma_f32_16x16x32_bf16 v[122:125], v[164:167], v[188:191], v[122:125]
	v_mfma_f32_16x16x32_bf16 v[118:121], v[156:159], v[196:199], v[118:121]
	v_mfma_f32_16x16x32_bf16 v[110:113], v[164:167], v[196:199], v[110:113]
	v_mfma_f32_16x16x32_bf16 v[102:105], v[156:159], v[204:207], v[102:105]
	v_mfma_f32_16x16x32_bf16 v[94:97], v[164:167], v[204:207], v[94:97]
	v_mfma_f32_16x16x32_bf16 v[86:89], v[156:159], v[212:215], v[86:89]
	v_mfma_f32_16x16x32_bf16 v[78:81], v[164:167], v[212:215], v[78:81]
	v_mfma_f32_16x16x32_bf16 v[126:129], v[160:163], v[192:195], v[126:129]
	v_mfma_f32_16x16x32_bf16 v[122:125], v[168:171], v[192:195], v[122:125]
	v_mfma_f32_16x16x32_bf16 v[118:121], v[160:163], v[200:203], v[118:121]
	v_mfma_f32_16x16x32_bf16 v[110:113], v[168:171], v[200:203], v[110:113]
	v_mfma_f32_16x16x32_bf16 v[102:105], v[160:163], v[208:211], v[102:105]
	v_mfma_f32_16x16x32_bf16 v[94:97], v[168:171], v[208:211], v[94:97]
	v_mfma_f32_16x16x32_bf16 v[86:89], v[160:163], v[216:219], v[86:89]
	v_mfma_f32_16x16x32_bf16 v[78:81], v[168:171], v[216:219], v[78:81]
	v_mfma_f32_16x16x32_bf16 v[114:117], v[172:175], v[188:191], v[114:117]
	v_mfma_f32_16x16x32_bf16 v[106:109], v[180:183], v[188:191], v[106:109]
	v_mfma_f32_16x16x32_bf16 v[98:101], v[172:175], v[196:199], v[98:101]
	v_mfma_f32_16x16x32_bf16 v[90:93], v[180:183], v[196:199], v[90:93]
	v_mfma_f32_16x16x32_bf16 v[82:85], v[172:175], v[204:207], v[82:85]
	v_mfma_f32_16x16x32_bf16 v[74:77], v[180:183], v[204:207], v[74:77]
	v_mfma_f32_16x16x32_bf16 v[70:73], v[172:175], v[212:215], v[70:73]
	v_mfma_f32_16x16x32_bf16 v[66:69], v[180:183], v[212:215], v[66:69]
	v_mfma_f32_16x16x32_bf16 v[114:117], v[176:179], v[192:195], v[114:117]
	v_mfma_f32_16x16x32_bf16 v[106:109], v[184:187], v[192:195], v[106:109]
	v_mfma_f32_16x16x32_bf16 v[98:101], v[176:179], v[200:203], v[98:101]
	v_mfma_f32_16x16x32_bf16 v[90:93], v[184:187], v[200:203], v[90:93]
	v_mfma_f32_16x16x32_bf16 v[82:85], v[176:179], v[208:211], v[82:85]
	v_mfma_f32_16x16x32_bf16 v[74:77], v[184:187], v[208:211], v[74:77]
	v_mfma_f32_16x16x32_bf16 v[70:73], v[176:179], v[216:219], v[70:73]
	v_mfma_f32_16x16x32_bf16 v[66:69], v[184:187], v[216:219], v[66:69]
	s_setprio 0
	s_barrier
; #define PG8_STAGE(bufoff, gbase, voff) do { if constexpr (VAR != 1 && VAR != 3) { _Pragma("unroll") for (int _i = 0; _i < 2; ++_i) \
;         asm volatile("s_mov_b32 m0, %2\n\ts_nop 0\n\tglobal_load_lds_dwordx4 %0, %1" :: "v"((voff)[_i]), "s"((const char*)(gbase)), "s"(ldsbase + (unsigned)((bufoff) + _i * 8192)) : "memory", "m0"); } } while (0)
; #define PG8_LDA(dst, b, h) do { if constexpr (VAR < 2) _Pragma("unroll") for (int m = 0; m < 4; ++m) _Pragma("unroll") for (int k = 0; k < 2; ++k) dst[m][k] = *(const LAS bf16x8*)(lds + PG8_SA(b, h) + aoff + m * 2048 + k * 1024); } while (0)
; #define PG8_LDB(dst, b, h) do { if constexpr (VAR < 2) _Pragma("unroll") for (int n = 0; n < 2; ++n) _Pragma("unroll") for (int k = 0; k < 2; ++k) dst[n][k] = *(const LAS bf16x8*)(lds + PG8_SB(b, h) + boff + n * 2048 + k * 1024); } while (0)
; #define PG8_WAIT_V(n) asm volatile("s_waitcnt vmcnt(" #n ")" ::: "memory")
; #define PG8_WAIT_L(n) asm volatile("s_waitcnt lgkmcnt(" #n ")" ::: "memory")
;     ...
;         for (int t = 0; t < nt; t += 2) {
;             const bool last = (t == nt - 2);
;             const char* a1 = cA + (size_t)(t + 1) * kstep;
;             const char* a2 = last ? nA : cA + (size_t)(t + 2) * kstep; const char* b2 = last ? nB : cB + (size_t)(t + 2) * kstep;
;             const char* a3 = a2 + kstep; const char* b3 = b2 + kstep;
;             PG8_LDB(B0, 0, 0); PG8_LDB(B1, 0, 1); PG8_SCHED; PG8_LDA(At, 0, 0); PG8_STAGE(PG8_SA(1, 1), a1 + hstepA, voffA);
;             PG8_WAIT_V(8); PG8_WAIT_L(0); PG8_BAR; PG8_MMA(0, 0, At, B0); PG8_MMA(0, 1, At, B1); PG8_BAR; PG8_SCHED;
;             PG8_LDA(At, 0, 1); PG8_STAGE(PG8_SB(0, 0), b2, voffB); PG8_STAGE(PG8_SB(0, 1), b2 + hstepB, voffB); PG8_STAGE(PG8_SA(0, 0), a2, voffA);
;             PG8_WAIT_V(8); PG8_WAIT_L(0); PG8_BAR; PG8_MMA(1, 0, At, B0); PG8_MMA(1, 1, At, B1); PG8_BAR; PG8_SCHED;
;             PG8_LDB(B0, 1, 0); PG8_LDB(B1, 1, 1); PG8_SCHED; PG8_LDA(At, 1, 0); PG8_STAGE(PG8_SA(0, 1), a2 + hstepA, voffA);
;             PG8_WAIT_V(8); PG8_WAIT_L(0); PG8_BAR; PG8_MMA(0, 0, At, B0); PG8_MMA(0, 1, At, B1); PG8_BAR; PG8_SCHED;
;             PG8_LDA(At, 1, 1); PG8_STAGE(PG8_SB(1, 0), b3, voffB); PG8_STAGE(PG8_SB(1, 1), b3 + hstepB, voffB); PG8_STAGE(PG8_SA(1, 0), a3, voffA);
;             PG8_WAIT_V(8); PG8_WAIT_L(0); PG8_BAR; PG8_MMA(1, 0, At, B0); PG8_MMA(1, 1, At, B1); PG8_BAR; PG8_SCHED;
	ds_read_b128 v[188:191], v153 offset:49152
	ds_read_b128 v[192:195], v153 offset:50176
	ds_read_b128 v[196:199], v153 offset:51200
	ds_read_b128 v[200:203], v153 offset:52224
	ds_read_b128 v[204:207], v153 offset:53248
	ds_read_b128 v[208:211], v153 offset:54272
	ds_read_b128 v[212:215], v153 offset:55296
	ds_read_b128 v[216:219], v153 offset:56320
	s_add_u32 s6, s94, 0x80
	s_addc_u32 s7, s95, 0
	s_mov_b32 m0, s33
	s_nop 0
	global_load_lds_dwordx4 v146, s[6:7]
	s_mov_b32 m0, s35
	s_nop 0
	global_load_lds_dwordx4 v148, s[6:7]
	s_add_u32 s6, s94, 0x100080
	s_addc_u32 s7, s95, 0
	s_mov_b32 m0, s54
	s_nop 0
	global_load_lds_dwordx4 v146, s[6:7]
	s_mov_b32 m0, s55
	s_nop 0
	global_load_lds_dwordx4 v148, s[6:7]
	s_mov_b32 m0, s52
	s_nop 0
	global_load_lds_dwordx4 v1, s[92:93]
	s_mov_b32 m0, s53
	s_nop 0
	global_load_lds_dwordx4 v147, s[92:93]
	s_waitcnt vmcnt(8)
	s_waitcnt lgkmcnt(0)
	s_barrier
	s_setprio 1
	v_mfma_f32_16x16x32_bf16 v[62:65], v[156:159], v[188:191], v[62:65]
	v_mfma_f32_16x16x32_bf16 v[58:61], v[164:167], v[188:191], v[58:61]
	v_mfma_f32_16x16x32_bf16 v[54:57], v[156:159], v[196:199], v[54:57]
	v_mfma_f32_16x16x32_bf16 v[46:49], v[164:167], v[196:199], v[46:49]
	v_mfma_f32_16x16x32_bf16 v[38:41], v[156:159], v[204:207], v[38:41]
	v_mfma_f32_16x16x32_bf16 v[30:33], v[164:167], v[204:207], v[30:33]
	v_mfma_f32_16x16x32_bf16 v[22:25], v[156:159], v[212:215], v[22:25]
	v_mfma_f32_16x16x32_bf16 v[14:17], v[164:167], v[212:215], v[14:17]
	v_mfma_f32_16x16x32_bf16 v[62:65], v[160:163], v[192:195], v[62:65]
	v_mfma_f32_16x16x32_bf16 v[58:61], v[168:171], v[192:195], v[58:61]
	v_mfma_f32_16x16x32_bf16 v[54:57], v[160:163], v[200:203], v[54:57]
	v_mfma_f32_16x16x32_bf16 v[46:49], v[168:171], v[200:203], v[46:49]
	v_mfma_f32_16x16x32_bf16 v[38:41], v[160:163], v[208:211], v[38:41]
	v_mfma_f32_16x16x32_bf16 v[30:33], v[168:171], v[208:211], v[30:33]
	v_mfma_f32_16x16x32_bf16 v[22:25], v[160:163], v[216:219], v[22:25]
	v_mfma_f32_16x16x32_bf16 v[14:17], v[168:171], v[216:219], v[14:17]
	v_mfma_f32_16x16x32_bf16 v[50:53], v[172:175], v[188:191], v[50:53]
	v_mfma_f32_16x16x32_bf16 v[42:45], v[180:183], v[188:191], v[42:45]
	v_mfma_f32_16x16x32_bf16 v[34:37], v[172:175], v[196:199], v[34:37]
	v_mfma_f32_16x16x32_bf16 v[26:29], v[180:183], v[196:199], v[26:29]
	v_mfma_f32_16x16x32_bf16 v[18:21], v[172:175], v[204:207], v[18:21]
	v_mfma_f32_16x16x32_bf16 v[10:13], v[180:183], v[204:207], v[10:13]
	v_mfma_f32_16x16x32_bf16 v[6:9], v[172:175], v[212:215], v[6:9]
	v_mfma_f32_16x16x32_bf16 v[2:5], v[180:183], v[212:215], v[2:5]
	v_mfma_f32_16x16x32_bf16 v[50:53], v[176:179], v[192:195], v[50:53]
	v_mfma_f32_16x16x32_bf16 v[42:45], v[184:187], v[192:195], v[42:45]
	v_mfma_f32_16x16x32_bf16 v[34:37], v[176:179], v[200:203], v[34:37]
	v_mfma_f32_16x16x32_bf16 v[26:29], v[184:187], v[200:203], v[26:29]
	v_mfma_f32_16x16x32_bf16 v[18:21], v[176:179], v[208:211], v[18:21]
	v_mfma_f32_16x16x32_bf16 v[10:13], v[184:187], v[208:211], v[10:13]
	v_mfma_f32_16x16x32_bf16 v[6:9], v[176:179], v[216:219], v[6:9]
	v_mfma_f32_16x16x32_bf16 v[2:5], v[184:187], v[216:219], v[2:5]
	s_setprio 0
	s_barrier
	s_add_i32 vcc_hi, vcc_hi, 2
	s_add_u32 s66, s66, 0x100
	s_addc_u32 s67, s67, 0
	s_add_u32 s69, s69, 0x100
	s_addc_u32 vcc_lo, vcc_lo, 0
	s_add_u32 s90, s90, 0x100
	s_addc_u32 s91, s91, 0
	s_cmp_gt_u32 vcc_hi, 61
	s_cbranch_scc0 .LBB0_346
	s_branch .Lmy_kexit_0
.LBB0_346:
	ds_read_b128 v[156:159], v151
	ds_read_b128 v[160:163], v151 offset:1024
	ds_read_b128 v[164:167], v151 offset:2048
	ds_read_b128 v[168:171], v151 offset:3072
	ds_read_b128 v[172:175], v152
	ds_read_b128 v[176:179], v152 offset:1024
	ds_read_b128 v[180:183], v152 offset:2048
	ds_read_b128 v[184:187], v152 offset:3072
	s_cmp_eq_u32 vcc_hi, 60
	s_cselect_b32 s96, s15, s66
	s_cselect_b32 s97, s14, s67
	s_cselect_b32 s94, s65, s69
	s_cselect_b32 s95, s63, vcc_lo
	s_add_u32 s92, s96, 0x80
	s_addc_u32 s93, s97, 0
	ds_read_b128 v[188:191], v153
	ds_read_b128 v[192:195], v153 offset:1024
	ds_read_b128 v[196:199], v153 offset:2048
	ds_read_b128 v[200:203], v153 offset:3072
	ds_read_b128 v[204:207], v153 offset:4096
	ds_read_b128 v[208:211], v153 offset:5120
	ds_read_b128 v[212:215], v153 offset:6144
	ds_read_b128 v[216:219], v153 offset:7168
	s_mov_b32 m0, s56
	s_nop 0
	global_load_lds_dwordx4 v1, s[90:91]
	s_mov_b32 m0, s57
	s_nop 0
	global_load_lds_dwordx4 v147, s[90:91]
	s_waitcnt vmcnt(8)
	s_waitcnt lgkmcnt(0)
	s_barrier
	s_setprio 1
	v_mfma_f32_16x16x32_bf16 v[126:129], v[156:159], v[188:191], v[126:129]
	v_mfma_f32_16x16x32_bf16 v[122:125], v[164:167], v[188:191], v[122:125]
	v_mfma_f32_16x16x32_bf16 v[118:121], v[156:159], v[196:199], v[118:121]
	v_mfma_f32_16x16x32_bf16 v[110:113], v[164:167], v[196:199], v[110:113]
	v_mfma_f32_16x16x32_bf16 v[102:105], v[156:159], v[204:207], v[102:105]
	v_mfma_f32_16x16x32_bf16 v[94:97], v[164:167], v[204:207], v[94:97]
	v_mfma_f32_16x16x32_bf16 v[86:89], v[156:159], v[212:215], v[86:89]
	v_mfma_f32_16x16x32_bf16 v[78:81], v[164:167], v[212:215], v[78:81]
	v_mfma_f32_16x16x32_bf16 v[126:129], v[160:163], v[192:195], v[126:129]
	v_mfma_f32_16x16x32_bf16 v[122:125], v[168:171], v[192:195], v[122:125]
	v_mfma_f32_16x16x32_bf16 v[118:121], v[160:163], v[200:203], v[118:121]
	v_mfma_f32_16x16x32_bf16 v[110:113], v[168:171], v[200:203], v[110:113]
	v_mfma_f32_16x16x32_bf16 v[102:105], v[160:163], v[208:211], v[102:105]
	v_mfma_f32_16x16x32_bf16 v[94:97], v[168:171], v[208:211], v[94:97]
	v_mfma_f32_16x16x32_bf16 v[86:89], v[160:163], v[216:219], v[86:89]
	v_mfma_f32_16x16x32_bf16 v[78:81], v[168:171], v[216:219], v[78:81]
	v_mfma_f32_16x16x32_bf16 v[114:117], v[172:175], v[188:191], v[114:117]
	v_mfma_f32_16x16x32_bf16 v[106:109], v[180:183], v[188:191], v[106:109]
	v_mfma_f32_16x16x32_bf16 v[98:101], v[172:175], v[196:199], v[98:101]
	v_mfma_f32_16x16x32_bf16 v[90:93], v[180:183], v[196:199], v[90:93]
	v_mfma_f32_16x16x32_bf16 v[82:85], v[172:175], v[204:207], v[82:85]
	v_mfma_f32_16x16x32_bf16 v[74:77], v[180:183], v[204:207], v[74:77]
	v_mfma_f32_16x16x32_bf16 v[70:73], v[172:175], v[212:215], v[70:73]
	v_mfma_f32_16x16x32_bf16 v[66:69], v[180:183], v[212:215], v[66:69]
	v_mfma_f32_16x16x32_bf16 v[114:117], v[176:179], v[192:195], v[114:117]
	v_mfma_f32_16x16x32_bf16 v[106:109], v[184:187], v[192:195], v[106:109]
	v_mfma_f32_16x16x32_bf16 v[98:101], v[176:179], v[200:203], v[98:101]
	v_mfma_f32_16x16x32_bf16 v[90:93], v[184:187], v[200:203], v[90:93]
	v_mfma_f32_16x16x32_bf16 v[82:85], v[176:179], v[208:211], v[82:85]
	v_mfma_f32_16x16x32_bf16 v[74:77], v[184:187], v[208:211], v[74:77]
	v_mfma_f32_16x16x32_bf16 v[70:73], v[176:179], v[216:219], v[70:73]
	v_mfma_f32_16x16x32_bf16 v[66:69], v[184:187], v[216:219], v[66:69]
	s_setprio 0
	s_barrier
; #define PG8_STAGE(bufoff, gbase, voff) do { if constexpr (VAR != 1 && VAR != 3) { _Pragma("unroll") for (int _i = 0; _i < 2; ++_i) \
;         asm volatile("s_mov_b32 m0, %2\n\ts_nop 0\n\tglobal_load_lds_dwordx4 %0, %1" :: "v"((voff)[_i]), "s"((const char*)(gbase)), "s"(ldsbase + (unsigned)((bufoff) + _i * 8192)) : "memory", "m0"); } } while (0)
; #define PG8_LDA(dst, b, h) do { if constexpr (VAR < 2) _Pragma("unroll") for (int m = 0; m < 4; ++m) _Pragma("unroll") for (int k = 0; k < 2; ++k) dst[m][k] = *(const LAS bf16x8*)(lds + PG8_SA(b, h) + aoff + m * 2048 + k * 1024); } while (0)
; #define PG8_LDB(dst, b, h) do { if constexpr (VAR < 2) _Pragma("unroll") for (int n = 0; n < 2; ++n) _Pragma("unroll") for (int k = 0; k < 2; ++k) dst[n][k] = *(const LAS bf16x8*)(lds + PG8_SB(b, h) + boff + n * 2048 + k * 1024); } while (0)
; #define PG8_WAIT_V(n) asm volatile("s_waitcnt vmcnt(" #n ")" ::: "memory")
; #define PG8_WAIT_L(n) asm volatile("s_waitcnt lgkmcnt(" #n ")" ::: "memory")
; #define PG8_BAR do { if constexpr (VAR != 3) __builtin_amdgcn_s_barrier(); } while (0)
; #define PG8_SCHED __builtin_amdgcn_sched_barrier(0)
;     ...
;             PG8_LDA(At, 0, 1); PG8_STAGE(PG8_SB(0, 0), b2, voffB); PG8_STAGE(PG8_SB(0, 1), b2 + hstepB, voffB); PG8_STAGE(PG8_SA(0, 0), a2, voffA);
;             PG8_WAIT_V(8); PG8_WAIT_L(0); PG8_BAR; PG8_MMA(1, 0, At, B0); PG8_MMA(1, 1, At, B1); PG8_BAR; PG8_SCHED;
;             PG8_LDB(B0, 1, 0); PG8_LDB(B1, 1, 1); PG8_SCHED; PG8_LDA(At, 1, 0); PG8_STAGE(PG8_SA(0, 1), a2 + hstepA, voffA);
;             PG8_WAIT_V(8); PG8_WAIT_L(0); PG8_BAR; PG8_MMA(0, 0, At, B0); PG8_MMA(0, 1, At, B1); PG8_BAR; PG8_SCHED;
	ds_read_b128 v[188:191], v153 offset:16384
	ds_read_b128 v[192:195], v153 offset:17408
	ds_read_b128 v[196:199], v153 offset:18432
	ds_read_b128 v[200:203], v153 offset:19456
	ds_read_b128 v[204:207], v153 offset:20480
	ds_read_b128 v[208:211], v153 offset:21504
	ds_read_b128 v[212:215], v153 offset:22528
	ds_read_b128 v[216:219], v153 offset:23552
	s_mov_b32 m0, s25
	s_nop 0
	global_load_lds_dwordx4 v146, s[94:95]
	s_add_u32 s6, s94, 0x100000
	s_mov_b32 m0, s26
	s_nop 0
	global_load_lds_dwordx4 v148, s[94:95]
	s_addc_u32 s7, s95, 0
	s_mov_b32 m0, s27
	s_nop 0
	global_load_lds_dwordx4 v146, s[6:7]
	s_mov_b32 m0, s28
	s_nop 0
	global_load_lds_dwordx4 v148, s[6:7]
	s_mov_b32 m0, s19
	s_nop 0
	global_load_lds_dwordx4 v1, s[96:97]
	s_mov_b32 m0, s29
	s_nop 0
	global_load_lds_dwordx4 v147, s[96:97]
	s_waitcnt vmcnt(8)
	s_waitcnt lgkmcnt(0)
	s_barrier
	s_setprio 1
	v_mfma_f32_16x16x32_bf16 v[62:65], v[156:159], v[188:191], v[62:65]
	v_mfma_f32_16x16x32_bf16 v[58:61], v[164:167], v[188:191], v[58:61]
	v_mfma_f32_16x16x32_bf16 v[54:57], v[156:159], v[196:199], v[54:57]
	v_mfma_f32_16x16x32_bf16 v[46:49], v[164:167], v[196:199], v[46:49]
	v_mfma_f32_16x16x32_bf16 v[38:41], v[156:159], v[204:207], v[38:41]
	v_mfma_f32_16x16x32_bf16 v[30:33], v[164:167], v[204:207], v[30:33]
	v_mfma_f32_16x16x32_bf16 v[22:25], v[156:159], v[212:215], v[22:25]
	v_mfma_f32_16x16x32_bf16 v[14:17], v[164:167], v[212:215], v[14:17]
	v_mfma_f32_16x16x32_bf16 v[62:65], v[160:163], v[192:195], v[62:65]
	v_mfma_f32_16x16x32_bf16 v[58:61], v[168:171], v[192:195], v[58:61]
	v_mfma_f32_16x16x32_bf16 v[54:57], v[160:163], v[200:203], v[54:57]
	v_mfma_f32_16x16x32_bf16 v[46:49], v[168:171], v[200:203], v[46:49]
	v_mfma_f32_16x16x32_bf16 v[38:41], v[160:163], v[208:211], v[38:41]
	v_mfma_f32_16x16x32_bf16 v[30:33], v[168:171], v[208:211], v[30:33]
	v_mfma_f32_16x16x32_bf16 v[22:25], v[160:163], v[216:219], v[22:25]
	v_mfma_f32_16x16x32_bf16 v[14:17], v[168:171], v[216:219], v[14:17]
	v_mfma_f32_16x16x32_bf16 v[50:53], v[172:175], v[188:191], v[50:53]
	v_mfma_f32_16x16x32_bf16 v[42:45], v[180:183], v[188:191], v[42:45]
	v_mfma_f32_16x16x32_bf16 v[34:37], v[172:175], v[196:199], v[34:37]
	v_mfma_f32_16x16x32_bf16 v[26:29], v[180:183], v[196:199], v[26:29]
	v_mfma_f32_16x16x32_bf16 v[18:21], v[172:175], v[204:207], v[18:21]
	v_mfma_f32_16x16x32_bf16 v[10:13], v[180:183], v[204:207], v[10:13]
	v_mfma_f32_16x16x32_bf16 v[6:9], v[172:175], v[212:215], v[6:9]
	v_mfma_f32_16x16x32_bf16 v[2:5], v[180:183], v[212:215], v[2:5]
	v_mfma_f32_16x16x32_bf16 v[50:53], v[176:179], v[192:195], v[50:53]
	v_mfma_f32_16x16x32_bf16 v[42:45], v[184:187], v[192:195], v[42:45]
	v_mfma_f32_16x16x32_bf16 v[34:37], v[176:179], v[200:203], v[34:37]
	v_mfma_f32_16x16x32_bf16 v[26:29], v[184:187], v[200:203], v[26:29]
	v_mfma_f32_16x16x32_bf16 v[18:21], v[176:179], v[208:211], v[18:21]
	v_mfma_f32_16x16x32_bf16 v[10:13], v[184:187], v[208:211], v[10:13]
	v_mfma_f32_16x16x32_bf16 v[6:9], v[176:179], v[216:219], v[6:9]
	v_mfma_f32_16x16x32_bf16 v[2:5], v[184:187], v[216:219], v[2:5]
	s_setprio 0
	s_barrier
	ds_read_b128 v[156:159], v154
	ds_read_b128 v[160:163], v154 offset:1024
	ds_read_b128 v[164:167], v154 offset:2048
	ds_read_b128 v[168:171], v154 offset:3072
	ds_read_b128 v[172:175], v155
	ds_read_b128 v[176:179], v155 offset:1024
	ds_read_b128 v[180:183], v155 offset:2048
	ds_read_b128 v[184:187], v155 offset:3072
	ds_read_b128 v[188:191], v153 offset:32768
	ds_read_b128 v[192:195], v153 offset:33792
	ds_read_b128 v[196:199], v153 offset:34816
	ds_read_b128 v[200:203], v153 offset:35840
	ds_read_b128 v[204:207], v153 offset:36864
	ds_read_b128 v[208:211], v153 offset:37888
	ds_read_b128 v[212:215], v153 offset:38912
	ds_read_b128 v[216:219], v153 offset:39936
	s_add_u32 s6, s96, 0x100000
	s_addc_u32 s7, s97, 0
	s_mov_b32 m0, s30
	s_nop 0
	global_load_lds_dwordx4 v1, s[6:7]
	s_mov_b32 m0, s31
	s_nop 0
	global_load_lds_dwordx4 v147, s[6:7]
	s_waitcnt vmcnt(8)
	s_waitcnt lgkmcnt(0)
	s_barrier
; #define PG8_STAGE(bufoff, gbase, voff) do { if constexpr (VAR != 1 && VAR != 3) { _Pragma("unroll") for (int _i = 0; _i < 2; ++_i) \
;         asm volatile("s_mov_b32 m0, %2\n\ts_nop 0\n\tglobal_load_lds_dwordx4 %0, %1" :: "v"((voff)[_i]), "s"((const char*)(gbase)), "s"(ldsbase + (unsigned)((bufoff) + _i * 8192)) : "memory", "m0"); } } while (0)
; #define PG8_LDA(dst, b, h) do { if constexpr (VAR < 2) _Pragma("unroll") for (int m = 0; m < 4; ++m) _Pragma("unroll") for (int k = 0; k < 2; ++k) dst[m][k] = *(const LAS bf16x8*)(lds + PG8_SA(b, h) + aoff + m * 2048 + k * 1024); } while (0)
; #define PG8_WAIT_V(n) asm volatile("s_waitcnt vmcnt(" #n ")" ::: "memory")
; #define PG8_WAIT_L(n) asm volatile("s_waitcnt lgkmcnt(" #n ")" ::: "memory")
; #define PG8_BAR do { if constexpr (VAR != 3) __builtin_amdgcn_s_barrier(); } while (0)
; #define PG8_SCHED __builtin_amdgcn_sched_barrier(0)
;     ...
;             PG8_WAIT_V(8); PG8_WAIT_L(0); PG8_BAR; PG8_MMA(0, 0, At, B0); PG8_MMA(0, 1, At, B1); PG8_BAR; PG8_SCHED;
;             PG8_LDA(At, 1, 1); PG8_STAGE(PG8_SB(1, 0), b3, voffB); PG8_STAGE(PG8_SB(1, 1), b3 + hstepB, voffB); PG8_STAGE(PG8_SA(1, 0), a3, voffA);
;             PG8_WAIT_V(8); PG8_WAIT_L(0); PG8_BAR; PG8_MMA(1, 0, At, B0); PG8_MMA(1, 1, At, B1); PG8_BAR; PG8_SCHED;
;         }
;         if (wr == 0) PG8_BAR;
	s_setprio 1
	v_mfma_f32_16x16x32_bf16 v[126:129], v[156:159], v[188:191], v[126:129]
	v_mfma_f32_16x16x32_bf16 v[122:125], v[164:167], v[188:191], v[122:125]
	v_mfma_f32_16x16x32_bf16 v[118:121], v[156:159], v[196:199], v[118:121]
	v_mfma_f32_16x16x32_bf16 v[110:113], v[164:167], v[196:199], v[110:113]
	v_mfma_f32_16x16x32_bf16 v[102:105], v[156:159], v[204:207], v[102:105]
	v_mfma_f32_16x16x32_bf16 v[94:97], v[164:167], v[204:207], v[94:97]
	v_mfma_f32_16x16x32_bf16 v[86:89], v[156:159], v[212:215], v[86:89]
	v_mfma_f32_16x16x32_bf16 v[78:81], v[164:167], v[212:215], v[78:81]
	v_mfma_f32_16x16x32_bf16 v[126:129], v[160:163], v[192:195], v[126:129]
	v_mfma_f32_16x16x32_bf16 v[122:125], v[168:171], v[192:195], v[122:125]
	v_mfma_f32_16x16x32_bf16 v[118:121], v[160:163], v[200:203], v[118:121]
	v_mfma_f32_16x16x32_bf16 v[110:113], v[168:171], v[200:203], v[110:113]
	v_mfma_f32_16x16x32_bf16 v[102:105], v[160:163], v[208:211], v[102:105]
	v_mfma_f32_16x16x32_bf16 v[94:97], v[168:171], v[208:211], v[94:97]
	v_mfma_f32_16x16x32_bf16 v[86:89], v[160:163], v[216:219], v[86:89]
	v_mfma_f32_16x16x32_bf16 v[78:81], v[168:171], v[216:219], v[78:81]
	v_mfma_f32_16x16x32_bf16 v[114:117], v[172:175], v[188:191], v[114:117]
	v_mfma_f32_16x16x32_bf16 v[106:109], v[180:183], v[188:191], v[106:109]
	v_mfma_f32_16x16x32_bf16 v[98:101], v[172:175], v[196:199], v[98:101]
	v_mfma_f32_16x16x32_bf16 v[90:93], v[180:183], v[196:199], v[90:93]
	v_mfma_f32_16x16x32_bf16 v[82:85], v[172:175], v[204:207], v[82:85]
	v_mfma_f32_16x16x32_bf16 v[74:77], v[180:183], v[204:207], v[74:77]
	v_mfma_f32_16x16x32_bf16 v[70:73], v[172:175], v[212:215], v[70:73]
	v_mfma_f32_16x16x32_bf16 v[66:69], v[180:183], v[212:215], v[66:69]
	v_mfma_f32_16x16x32_bf16 v[114:117], v[176:179], v[192:195], v[114:117]
	v_mfma_f32_16x16x32_bf16 v[106:109], v[184:187], v[192:195], v[106:109]
	v_mfma_f32_16x16x32_bf16 v[98:101], v[176:179], v[200:203], v[98:101]
	v_mfma_f32_16x16x32_bf16 v[90:93], v[184:187], v[200:203], v[90:93]
	v_mfma_f32_16x16x32_bf16 v[82:85], v[176:179], v[208:211], v[82:85]
	v_mfma_f32_16x16x32_bf16 v[74:77], v[184:187], v[208:211], v[74:77]
	v_mfma_f32_16x16x32_bf16 v[70:73], v[176:179], v[216:219], v[70:73]
	v_mfma_f32_16x16x32_bf16 v[66:69], v[184:187], v[216:219], v[66:69]
	s_setprio 0
	s_barrier
	ds_read_b128 v[188:191], v153 offset:49152
	ds_read_b128 v[192:195], v153 offset:50176
	ds_read_b128 v[196:199], v153 offset:51200
	ds_read_b128 v[200:203], v153 offset:52224
	ds_read_b128 v[204:207], v153 offset:53248
	ds_read_b128 v[208:211], v153 offset:54272
	ds_read_b128 v[212:215], v153 offset:55296
	ds_read_b128 v[216:219], v153 offset:56320
	s_add_u32 s6, s94, 0x80
	s_addc_u32 s7, s95, 0
	s_mov_b32 m0, s33
	s_nop 0
	global_load_lds_dwordx4 v146, s[6:7]
	s_mov_b32 m0, s35
	s_nop 0
	global_load_lds_dwordx4 v148, s[6:7]
	s_add_u32 s6, s94, 0x100080
	s_addc_u32 s7, s95, 0
	s_mov_b32 m0, s54
	s_nop 0
	global_load_lds_dwordx4 v146, s[6:7]
	s_mov_b32 m0, s55
	s_nop 0
	global_load_lds_dwordx4 v148, s[6:7]
	s_mov_b32 m0, s52
	s_nop 0
	global_load_lds_dwordx4 v1, s[92:93]
	s_mov_b32 m0, s53
	s_nop 0
	global_load_lds_dwordx4 v147, s[92:93]
	s_waitcnt vmcnt(8)
	s_waitcnt lgkmcnt(0)
	s_barrier
	s_setprio 1
	v_mfma_f32_16x16x32_bf16 v[62:65], v[156:159], v[188:191], v[62:65]
	v_mfma_f32_16x16x32_bf16 v[58:61], v[164:167], v[188:191], v[58:61]
	v_mfma_f32_16x16x32_bf16 v[54:57], v[156:159], v[196:199], v[54:57]
	v_mfma_f32_16x16x32_bf16 v[46:49], v[164:167], v[196:199], v[46:49]
	v_mfma_f32_16x16x32_bf16 v[38:41], v[156:159], v[204:207], v[38:41]
	v_mfma_f32_16x16x32_bf16 v[30:33], v[164:167], v[204:207], v[30:33]
	v_mfma_f32_16x16x32_bf16 v[22:25], v[156:159], v[212:215], v[22:25]
	v_mfma_f32_16x16x32_bf16 v[14:17], v[164:167], v[212:215], v[14:17]
	v_mfma_f32_16x16x32_bf16 v[62:65], v[160:163], v[192:195], v[62:65]
	v_mfma_f32_16x16x32_bf16 v[58:61], v[168:171], v[192:195], v[58:61]
	v_mfma_f32_16x16x32_bf16 v[54:57], v[160:163], v[200:203], v[54:57]
	v_mfma_f32_16x16x32_bf16 v[46:49], v[168:171], v[200:203], v[46:49]
	v_mfma_f32_16x16x32_bf16 v[38:41], v[160:163], v[208:211], v[38:41]
	v_mfma_f32_16x16x32_bf16 v[30:33], v[168:171], v[208:211], v[30:33]
	v_mfma_f32_16x16x32_bf16 v[22:25], v[160:163], v[216:219], v[22:25]
	v_mfma_f32_16x16x32_bf16 v[14:17], v[168:171], v[216:219], v[14:17]
	v_mfma_f32_16x16x32_bf16 v[50:53], v[172:175], v[188:191], v[50:53]
	v_mfma_f32_16x16x32_bf16 v[42:45], v[180:183], v[188:191], v[42:45]
	v_mfma_f32_16x16x32_bf16 v[34:37], v[172:175], v[196:199], v[34:37]
	v_mfma_f32_16x16x32_bf16 v[26:29], v[180:183], v[196:199], v[26:29]
	v_mfma_f32_16x16x32_bf16 v[18:21], v[172:175], v[204:207], v[18:21]
	v_mfma_f32_16x16x32_bf16 v[10:13], v[180:183], v[204:207], v[10:13]
	v_mfma_f32_16x16x32_bf16 v[6:9], v[172:175], v[212:215], v[6:9]
	v_mfma_f32_16x16x32_bf16 v[2:5], v[180:183], v[212:215], v[2:5]
	v_mfma_f32_16x16x32_bf16 v[50:53], v[176:179], v[192:195], v[50:53]
	v_mfma_f32_16x16x32_bf16 v[42:45], v[184:187], v[192:195], v[42:45]
	v_mfma_f32_16x16x32_bf16 v[34:37], v[176:179], v[200:203], v[34:37]
	v_mfma_f32_16x16x32_bf16 v[26:29], v[184:187], v[200:203], v[26:29]
	v_mfma_f32_16x16x32_bf16 v[18:21], v[176:179], v[208:211], v[18:21]
	v_mfma_f32_16x16x32_bf16 v[10:13], v[184:187], v[208:211], v[10:13]
	v_mfma_f32_16x16x32_bf16 v[6:9], v[176:179], v[216:219], v[6:9]
	v_mfma_f32_16x16x32_bf16 v[2:5], v[184:187], v[216:219], v[2:5]
	s_setprio 0
	s_barrier
	s_add_i32 vcc_hi, vcc_hi, 2
	s_add_u32 s66, s66, 0x100
	s_addc_u32 s67, s67, 0
	s_add_u32 s69, s69, 0x100
	s_addc_u32 vcc_lo, vcc_lo, 0
	s_add_u32 s90, s90, 0x100
	s_addc_u32 s91, s91, 0
	s_cmp_gt_u32 vcc_hi, 61
	s_cbranch_scc0 .LBB0_346
.Lmy_kexit_0:
	s_and_b64 vcc, exec, s[4:5]
	s_cbranch_vccz .LBB0_349
	s_barrier

; __device__ __forceinline__ const char* unitA(const Gemm& g, const Unit& u) { return (const char*)(g.A + (size_t)(u.z / g.zdiv) * g.sAhi + (size_t)(u.z % g.zdiv) * g.sAlo + (size_t)u.pm * BM * g.lda); }
; __device__ __forceinline__ const char* unitB(const Gemm& g, const Unit& u) { return (const char*)(g.Bt + (size_t)(u.z / g.zdiv) * g.sBhi + (size_t)(u.z % g.zdiv) * g.sBlo + (size_t)(u.pm / g.bdiv) * g.sBpm + (size_t)u.pn * BM * g.ldb); }
; #define PG8_STAGE(bufoff, gbase, voff) do { if constexpr (VAR != 1 && VAR != 3) { _Pragma("unroll") for (int _i = 0; _i < 2; ++_i) \
;         asm volatile("s_mov_b32 m0, %2\n\ts_nop 0\n\tglobal_load_lds_dwordx4 %0, %1" :: "v"((voff)[_i]), "s"((const char*)(gbase)), "s"(ldsbase + (unsigned)((bufoff) + _i * 8192)) : "memory", "m0"); } } while (0)
; #define PG8_LDA(dst, b, h) do { if constexpr (VAR < 2) _Pragma("unroll") for (int m = 0; m < 4; ++m) _Pragma("unroll") for (int k = 0; k < 2; ++k) dst[m][k] = *(const LAS bf16x8*)(lds + PG8_SA(b, h) + aoff + m * 2048 + k * 1024); } while (0)
; #define PG8_LDB(dst, b, h) do { if constexpr (VAR < 2) _Pragma("unroll") for (int n = 0; n < 2; ++n) _Pragma("unroll") for (int k = 0; k < 2; ++k) dst[n][k] = *(const LAS bf16x8*)(lds + PG8_SB(b, h) + boff + n * 2048 + k * 1024); } while (0)
; #define PG8_WAIT_V(n) asm volatile("s_waitcnt vmcnt(" #n ")" ::: "memory")
; #define PG8_SCHED __builtin_amdgcn_sched_barrier(0)
;     ...
;         const char* nA = has_next ? unitA(g, nxt) : cA; const char* nB = has_next ? unitB(g, nxt) : cB;
;         for (int t = 0; t < nt; t += 2) {
;             const bool last = (t == nt - 2);
;             const char* a1 = cA + (size_t)(t + 1) * kstep;
;             const char* a2 = last ? nA : cA + (size_t)(t + 2) * kstep; const char* b2 = last ? nB : cB + (size_t)(t + 2) * kstep;
;             const char* a3 = a2 + kstep; const char* b3 = b2 + kstep;
;             PG8_LDB(B0, 0, 0); PG8_LDB(B1, 0, 1); PG8_SCHED; PG8_LDA(At, 0, 0); PG8_STAGE(PG8_SA(1, 1), a1 + hstepA, voffA);
;             PG8_WAIT_V(8); PG8_WAIT_L(0); PG8_BAR; PG8_MMA(0, 0, At, B0); PG8_MMA(0, 1, At, B1); PG8_BAR; PG8_SCHED;
;             PG8_LDA(At, 0, 1); PG8_STAGE(PG8_SB(0, 0), b2, voffB); PG8_STAGE(PG8_SB(0, 1), b2 + hstepB, voffB); PG8_STAGE(PG8_SA(0, 0), a2, voffA);
;             PG8_WAIT_V(8); PG8_WAIT_L(0); PG8_BAR; PG8_MMA(1, 0, At, B0); PG8_MMA(1, 1, At, B1); PG8_BAR; PG8_SCHED;
.LBB0_538:
	s_ashr_i32 s73, s72, 31
	s_lshl_b64 s[6:7], s[72:73], 20
	s_add_u32 s74, s27, s6
	s_addc_u32 s75, s28, s7
	s_and_b64 s[6:7], s[4:5], exec
	s_cselect_b32 s14, s75, s91
	s_cselect_b32 s15, s74, s90
	s_ashr_i32 s71, s70, 31
	s_lshl_b64 s[6:7], s[70:71], 20
	s_add_u32 s84, s0, s6
	s_addc_u32 s85, s1, s7
	s_and_b64 s[6:7], s[4:5], exec
	s_cselect_b32 s71, s85, s89
	s_cselect_b32 s73, s84, s88
	s_add_u32 vcc_lo, s90, 0x100
	s_addc_u32 vcc_hi, s91, 0
	s_add_u32 s54, s88, 0x100
	s_addc_u32 s55, s89, 0
	s_add_u32 s88, s90, 0x80080
	s_addc_u32 s89, s91, 0
	s_mov_b32 s6, -2
	s_waitcnt vmcnt(45)
	s_waitcnt vmcnt(41)
	s_waitcnt vmcnt(39)
	s_waitcnt vmcnt(38)
	s_waitcnt vmcnt(36)
	s_waitcnt vmcnt(35)
	s_waitcnt vmcnt(32)
	ds_read_b128 v[138:141], v159
	ds_read_b128 v[164:167], v159 offset:1024
	ds_read_b128 v[168:171], v159 offset:2048
	ds_read_b128 v[172:175], v159 offset:3072
	ds_read_b128 v[176:179], v160
	ds_read_b128 v[180:183], v160 offset:1024
	ds_read_b128 v[184:187], v160 offset:2048
	ds_read_b128 v[188:191], v160 offset:3072
	s_cmp_eq_u32 s6, 28
	s_cselect_b32 s94, s15, vcc_lo
	s_cselect_b32 s95, s14, vcc_hi
	s_cselect_b32 s92, s73, s54
	s_cselect_b32 s93, s71, s55
	s_add_u32 s90, s94, 0x80
	s_addc_u32 s91, s95, 0
	ds_read_b128 v[192:195], v161
	ds_read_b128 v[196:199], v161 offset:1024
	ds_read_b128 v[200:203], v161 offset:2048
	ds_read_b128 v[204:207], v161 offset:3072
	ds_read_b128 v[208:211], v161 offset:4096
	ds_read_b128 v[212:215], v161 offset:5120
	ds_read_b128 v[216:219], v161 offset:6144
	ds_read_b128 v[220:223], v161 offset:7168
	s_mov_b32 m0, s57
	s_nop 0
	global_load_lds_dwordx4 v151, s[88:89]
	s_mov_b32 m0, s24
	s_nop 0
	global_load_lds_dwordx4 v153, s[88:89]
	s_waitcnt vmcnt(8)
	s_waitcnt lgkmcnt(0)
	s_barrier
	s_setprio 1
	v_mfma_i32_16x16x64_i8 v[126:129], v[138:141], v[192:195], 0
	v_mfma_i32_16x16x64_i8 v[118:121], v[168:171], v[192:195], 0
	v_mfma_i32_16x16x64_i8 v[110:113], v[138:141], v[200:203], 0
	v_mfma_i32_16x16x64_i8 v[102:105], v[168:171], v[200:203], 0
	v_mfma_i32_16x16x64_i8 v[94:97], v[138:141], v[208:211], 0
	v_mfma_i32_16x16x64_i8 v[86:89], v[168:171], v[208:211], 0
	v_mfma_i32_16x16x64_i8 v[78:81], v[138:141], v[216:219], 0
	v_mfma_i32_16x16x64_i8 v[70:73], v[168:171], v[216:219], 0
	v_mfma_i32_16x16x64_i8 v[126:129], v[164:167], v[196:199], v[126:129]
	v_mfma_i32_16x16x64_i8 v[118:121], v[172:175], v[196:199], v[118:121]
	v_mfma_i32_16x16x64_i8 v[110:113], v[164:167], v[204:207], v[110:113]
	v_mfma_i32_16x16x64_i8 v[102:105], v[172:175], v[204:207], v[102:105]
	v_mfma_i32_16x16x64_i8 v[94:97], v[164:167], v[212:215], v[94:97]
	v_mfma_i32_16x16x64_i8 v[86:89], v[172:175], v[212:215], v[86:89]
	v_mfma_i32_16x16x64_i8 v[78:81], v[164:167], v[220:223], v[78:81]
	v_mfma_i32_16x16x64_i8 v[70:73], v[172:175], v[220:223], v[70:73]
	v_mfma_i32_16x16x64_i8 v[122:125], v[176:179], v[192:195], 0
	v_mfma_i32_16x16x64_i8 v[114:117], v[184:187], v[192:195], 0
	v_mfma_i32_16x16x64_i8 v[106:109], v[176:179], v[200:203], 0
	v_mfma_i32_16x16x64_i8 v[98:101], v[184:187], v[200:203], 0
	v_mfma_i32_16x16x64_i8 v[90:93], v[176:179], v[208:211], 0
	v_mfma_i32_16x16x64_i8 v[82:85], v[184:187], v[208:211], 0
	v_mfma_i32_16x16x64_i8 v[74:77], v[176:179], v[216:219], 0
	v_mfma_i32_16x16x64_i8 v[66:69], v[184:187], v[216:219], 0
	v_mfma_i32_16x16x64_i8 v[122:125], v[180:183], v[196:199], v[122:125]
	v_mfma_i32_16x16x64_i8 v[114:117], v[188:191], v[196:199], v[114:117]
	v_mfma_i32_16x16x64_i8 v[106:109], v[180:183], v[204:207], v[106:109]
	v_mfma_i32_16x16x64_i8 v[98:101], v[188:191], v[204:207], v[98:101]
	v_mfma_i32_16x16x64_i8 v[90:93], v[180:183], v[212:215], v[90:93]
	v_mfma_i32_16x16x64_i8 v[82:85], v[188:191], v[212:215], v[82:85]
	v_mfma_i32_16x16x64_i8 v[74:77], v[180:183], v[220:223], v[74:77]
	v_mfma_i32_16x16x64_i8 v[66:69], v[188:191], v[220:223], v[66:69]
	s_setprio 0
	s_barrier
	ds_read_b128 v[192:195], v161 offset:16384
	ds_read_b128 v[196:199], v161 offset:17408
	ds_read_b128 v[200:203], v161 offset:18432
	ds_read_b128 v[204:207], v161 offset:19456
	ds_read_b128 v[208:211], v161 offset:20480
	ds_read_b128 v[212:215], v161 offset:21504
	ds_read_b128 v[216:219], v161 offset:22528
	ds_read_b128 v[220:223], v161 offset:23552
	s_mov_b32 m0, s29
	s_nop 0
	global_load_lds_dwordx4 v152, s[92:93]
	s_add_u32 s10, s92, 0x80000
	s_mov_b32 m0, s30
	s_nop 0
	global_load_lds_dwordx4 v154, s[92:93]
	s_addc_u32 s11, s93, 0
	s_mov_b32 m0, s31
	s_nop 0
	global_load_lds_dwordx4 v152, s[10:11]
	s_mov_b32 m0, s33
	s_nop 0
	global_load_lds_dwordx4 v154, s[10:11]
	s_mov_b32 m0, s26
	s_nop 0
	global_load_lds_dwordx4 v151, s[94:95]
	s_mov_b32 m0, s35
	s_nop 0
	global_load_lds_dwordx4 v153, s[94:95]
	s_waitcnt vmcnt(8)
	s_waitcnt lgkmcnt(0)
	s_barrier
; #define PG8_STAGE(bufoff, gbase, voff) do { if constexpr (VAR != 1 && VAR != 3) { _Pragma("unroll") for (int _i = 0; _i < 2; ++_i) \
;         asm volatile("s_mov_b32 m0, %2\n\ts_nop 0\n\tglobal_load_lds_dwordx4 %0, %1" :: "v"((voff)[_i]), "s"((const char*)(gbase)), "s"(ldsbase + (unsigned)((bufoff) + _i * 8192)) : "memory", "m0"); } } while (0)
; #define PG8_LDA(dst, b, h) do { if constexpr (VAR < 2) _Pragma("unroll") for (int m = 0; m < 4; ++m) _Pragma("unroll") for (int k = 0; k < 2; ++k) dst[m][k] = *(const LAS bf16x8*)(lds + PG8_SA(b, h) + aoff + m * 2048 + k * 1024); } while (0)
; #define PG8_LDB(dst, b, h) do { if constexpr (VAR < 2) _Pragma("unroll") for (int n = 0; n < 2; ++n) _Pragma("unroll") for (int k = 0; k < 2; ++k) dst[n][k] = *(const LAS bf16x8*)(lds + PG8_SB(b, h) + boff + n * 2048 + k * 1024); } while (0)
; #define PG8_WAIT_V(n) asm volatile("s_waitcnt vmcnt(" #n ")" ::: "memory")
; #define PG8_WAIT_L(n) asm volatile("s_waitcnt lgkmcnt(" #n ")" ::: "memory")
; #define PG8_BAR do { if constexpr (VAR != 3) __builtin_amdgcn_s_barrier(); } while (0)
; #define PG8_SCHED __builtin_amdgcn_sched_barrier(0)
;     ...
;             PG8_WAIT_V(8); PG8_WAIT_L(0); PG8_BAR; PG8_MMA(1, 0, At, B0); PG8_MMA(1, 1, At, B1); PG8_BAR; PG8_SCHED;
;             PG8_LDB(B0, 1, 0); PG8_LDB(B1, 1, 1); PG8_SCHED; PG8_LDA(At, 1, 0); PG8_STAGE(PG8_SA(0, 1), a2 + hstepA, voffA);
;             PG8_WAIT_V(8); PG8_WAIT_L(0); PG8_BAR; PG8_MMA(0, 0, At, B0); PG8_MMA(0, 1, At, B1); PG8_BAR; PG8_SCHED;
	s_setprio 1
	v_mfma_i32_16x16x64_i8 v[62:65], v[138:141], v[192:195], 0
	v_mfma_i32_16x16x64_i8 v[54:57], v[168:171], v[192:195], 0
	v_mfma_i32_16x16x64_i8 v[46:49], v[138:141], v[200:203], 0
	v_mfma_i32_16x16x64_i8 v[38:41], v[168:171], v[200:203], 0
	v_mfma_i32_16x16x64_i8 v[30:33], v[138:141], v[208:211], 0
	v_mfma_i32_16x16x64_i8 v[22:25], v[168:171], v[208:211], 0
	v_mfma_i32_16x16x64_i8 v[14:17], v[138:141], v[216:219], 0
	v_mfma_i32_16x16x64_i8 v[6:9], v[168:171], v[216:219], 0
	v_mfma_i32_16x16x64_i8 v[62:65], v[164:167], v[196:199], v[62:65]
	v_mfma_i32_16x16x64_i8 v[54:57], v[172:175], v[196:199], v[54:57]
	v_mfma_i32_16x16x64_i8 v[46:49], v[164:167], v[204:207], v[46:49]
	v_mfma_i32_16x16x64_i8 v[38:41], v[172:175], v[204:207], v[38:41]
	v_mfma_i32_16x16x64_i8 v[30:33], v[164:167], v[212:215], v[30:33]
	v_mfma_i32_16x16x64_i8 v[22:25], v[172:175], v[212:215], v[22:25]
	v_mfma_i32_16x16x64_i8 v[14:17], v[164:167], v[220:223], v[14:17]
	v_mfma_i32_16x16x64_i8 v[6:9], v[172:175], v[220:223], v[6:9]
	v_mfma_i32_16x16x64_i8 v[58:61], v[176:179], v[192:195], 0
	v_mfma_i32_16x16x64_i8 v[50:53], v[184:187], v[192:195], 0
	v_mfma_i32_16x16x64_i8 v[42:45], v[176:179], v[200:203], 0
	v_mfma_i32_16x16x64_i8 v[34:37], v[184:187], v[200:203], 0
	v_mfma_i32_16x16x64_i8 v[26:29], v[176:179], v[208:211], 0
	v_mfma_i32_16x16x64_i8 v[18:21], v[184:187], v[208:211], 0
	v_mfma_i32_16x16x64_i8 v[10:13], v[176:179], v[216:219], 0
	v_mfma_i32_16x16x64_i8 v[2:5], v[184:187], v[216:219], 0
	v_mfma_i32_16x16x64_i8 v[58:61], v[180:183], v[196:199], v[58:61]
	v_mfma_i32_16x16x64_i8 v[50:53], v[188:191], v[196:199], v[50:53]
	v_mfma_i32_16x16x64_i8 v[42:45], v[180:183], v[204:207], v[42:45]
	v_mfma_i32_16x16x64_i8 v[34:37], v[188:191], v[204:207], v[34:37]
	v_mfma_i32_16x16x64_i8 v[26:29], v[180:183], v[212:215], v[26:29]
	v_mfma_i32_16x16x64_i8 v[18:21], v[188:191], v[212:215], v[18:21]
	v_mfma_i32_16x16x64_i8 v[10:13], v[180:183], v[220:223], v[10:13]
	v_mfma_i32_16x16x64_i8 v[2:5], v[188:191], v[220:223], v[2:5]
	s_setprio 0
	s_barrier
	ds_read_b128 v[138:141], v162
	ds_read_b128 v[164:167], v162 offset:1024
	ds_read_b128 v[168:171], v162 offset:2048
	ds_read_b128 v[172:175], v162 offset:3072
	ds_read_b128 v[176:179], v163
	ds_read_b128 v[180:183], v163 offset:1024
	ds_read_b128 v[184:187], v163 offset:2048
	ds_read_b128 v[188:191], v163 offset:3072
	ds_read_b128 v[192:195], v161 offset:32768
	ds_read_b128 v[196:199], v161 offset:33792
	ds_read_b128 v[200:203], v161 offset:34816
	ds_read_b128 v[204:207], v161 offset:35840
	ds_read_b128 v[208:211], v161 offset:36864
	ds_read_b128 v[212:215], v161 offset:37888
	ds_read_b128 v[216:219], v161 offset:38912
	ds_read_b128 v[220:223], v161 offset:39936
	s_add_u32 s10, s94, 0x80000
	s_addc_u32 s11, s95, 0
	s_mov_b32 m0, s62
	s_nop 0
	global_load_lds_dwordx4 v151, s[10:11]
	s_mov_b32 m0, s63
	s_nop 0
	global_load_lds_dwordx4 v153, s[10:11]
	s_waitcnt vmcnt(8)
	s_waitcnt lgkmcnt(0)
	s_barrier
	s_setprio 1
	v_mfma_i32_16x16x64_i8 v[126:129], v[138:141], v[192:195], v[126:129]
	v_mfma_i32_16x16x64_i8 v[118:121], v[168:171], v[192:195], v[118:121]
	v_mfma_i32_16x16x64_i8 v[110:113], v[138:141], v[200:203], v[110:113]
	v_mfma_i32_16x16x64_i8 v[102:105], v[168:171], v[200:203], v[102:105]
	v_mfma_i32_16x16x64_i8 v[94:97], v[138:141], v[208:211], v[94:97]
	v_mfma_i32_16x16x64_i8 v[86:89], v[168:171], v[208:211], v[86:89]
	v_mfma_i32_16x16x64_i8 v[78:81], v[138:141], v[216:219], v[78:81]
	v_mfma_i32_16x16x64_i8 v[70:73], v[168:171], v[216:219], v[70:73]
	v_mfma_i32_16x16x64_i8 v[126:129], v[164:167], v[196:199], v[126:129]
	v_mfma_i32_16x16x64_i8 v[118:121], v[172:175], v[196:199], v[118:121]
	v_mfma_i32_16x16x64_i8 v[110:113], v[164:167], v[204:207], v[110:113]
	v_mfma_i32_16x16x64_i8 v[102:105], v[172:175], v[204:207], v[102:105]
	v_mfma_i32_16x16x64_i8 v[94:97], v[164:167], v[212:215], v[94:97]
	v_mfma_i32_16x16x64_i8 v[86:89], v[172:175], v[212:215], v[86:89]
	v_mfma_i32_16x16x64_i8 v[78:81], v[164:167], v[220:223], v[78:81]
	v_mfma_i32_16x16x64_i8 v[70:73], v[172:175], v[220:223], v[70:73]
	v_mfma_i32_16x16x64_i8 v[122:125], v[176:179], v[192:195], v[122:125]
	v_mfma_i32_16x16x64_i8 v[114:117], v[184:187], v[192:195], v[114:117]
	v_mfma_i32_16x16x64_i8 v[106:109], v[176:179], v[200:203], v[106:109]
	v_mfma_i32_16x16x64_i8 v[98:101], v[184:187], v[200:203], v[98:101]
	v_mfma_i32_16x16x64_i8 v[90:93], v[176:179], v[208:211], v[90:93]
	v_mfma_i32_16x16x64_i8 v[82:85], v[184:187], v[208:211], v[82:85]
	v_mfma_i32_16x16x64_i8 v[74:77], v[176:179], v[216:219], v[74:77]
	v_mfma_i32_16x16x64_i8 v[66:69], v[184:187], v[216:219], v[66:69]
	v_mfma_i32_16x16x64_i8 v[122:125], v[180:183], v[196:199], v[122:125]
	v_mfma_i32_16x16x64_i8 v[114:117], v[188:191], v[196:199], v[114:117]
	v_mfma_i32_16x16x64_i8 v[106:109], v[180:183], v[204:207], v[106:109]
	v_mfma_i32_16x16x64_i8 v[98:101], v[188:191], v[204:207], v[98:101]
	v_mfma_i32_16x16x64_i8 v[90:93], v[180:183], v[212:215], v[90:93]
	v_mfma_i32_16x16x64_i8 v[82:85], v[188:191], v[212:215], v[82:85]
	v_mfma_i32_16x16x64_i8 v[74:77], v[180:183], v[220:223], v[74:77]
	v_mfma_i32_16x16x64_i8 v[66:69], v[188:191], v[220:223], v[66:69]
	s_setprio 0
	s_barrier
; #define PG8_STAGE(bufoff, gbase, voff) do { if constexpr (VAR != 1 && VAR != 3) { _Pragma("unroll") for (int _i = 0; _i < 2; ++_i) \
;         asm volatile("s_mov_b32 m0, %2\n\ts_nop 0\n\tglobal_load_lds_dwordx4 %0, %1" :: "v"((voff)[_i]), "s"((const char*)(gbase)), "s"(ldsbase + (unsigned)((bufoff) + _i * 8192)) : "memory", "m0"); } } while (0)
; #define PG8_LDA(dst, b, h) do { if constexpr (VAR < 2) _Pragma("unroll") for (int m = 0; m < 4; ++m) _Pragma("unroll") for (int k = 0; k < 2; ++k) dst[m][k] = *(const LAS bf16x8*)(lds + PG8_SA(b, h) + aoff + m * 2048 + k * 1024); } while (0)
; #define PG8_LDB(dst, b, h) do { if constexpr (VAR < 2) _Pragma("unroll") for (int n = 0; n < 2; ++n) _Pragma("unroll") for (int k = 0; k < 2; ++k) dst[n][k] = *(const LAS bf16x8*)(lds + PG8_SB(b, h) + boff + n * 2048 + k * 1024); } while (0)
; #define PG8_WAIT_V(n) asm volatile("s_waitcnt vmcnt(" #n ")" ::: "memory")
; #define PG8_WAIT_L(n) asm volatile("s_waitcnt lgkmcnt(" #n ")" ::: "memory")
;     ...
;         for (int t = 0; t < nt; t += 2) {
;             const bool last = (t == nt - 2);
;             const char* a1 = cA + (size_t)(t + 1) * kstep;
;             const char* a2 = last ? nA : cA + (size_t)(t + 2) * kstep; const char* b2 = last ? nB : cB + (size_t)(t + 2) * kstep;
;             const char* a3 = a2 + kstep; const char* b3 = b2 + kstep;
;             PG8_LDB(B0, 0, 0); PG8_LDB(B1, 0, 1); PG8_SCHED; PG8_LDA(At, 0, 0); PG8_STAGE(PG8_SA(1, 1), a1 + hstepA, voffA);
;             PG8_WAIT_V(8); PG8_WAIT_L(0); PG8_BAR; PG8_MMA(0, 0, At, B0); PG8_MMA(0, 1, At, B1); PG8_BAR; PG8_SCHED;
;             PG8_LDA(At, 0, 1); PG8_STAGE(PG8_SB(0, 0), b2, voffB); PG8_STAGE(PG8_SB(0, 1), b2 + hstepB, voffB); PG8_STAGE(PG8_SA(0, 0), a2, voffA);
;             PG8_WAIT_V(8); PG8_WAIT_L(0); PG8_BAR; PG8_MMA(1, 0, At, B0); PG8_MMA(1, 1, At, B1); PG8_BAR; PG8_SCHED;
;             PG8_LDB(B0, 1, 0); PG8_LDB(B1, 1, 1); PG8_SCHED; PG8_LDA(At, 1, 0); PG8_STAGE(PG8_SA(0, 1), a2 + hstepA, voffA);
;             PG8_WAIT_V(8); PG8_WAIT_L(0); PG8_BAR; PG8_MMA(0, 0, At, B0); PG8_MMA(0, 1, At, B1); PG8_BAR; PG8_SCHED;
;             PG8_LDA(At, 1, 1); PG8_STAGE(PG8_SB(1, 0), b3, voffB); PG8_STAGE(PG8_SB(1, 1), b3 + hstepB, voffB); PG8_STAGE(PG8_SA(1, 0), a3, voffA);
;             PG8_WAIT_V(8); PG8_WAIT_L(0); PG8_BAR; PG8_MMA(1, 0, At, B0); PG8_MMA(1, 1, At, B1); PG8_BAR; PG8_SCHED;
	ds_read_b128 v[192:195], v161 offset:49152
	ds_read_b128 v[196:199], v161 offset:50176
	ds_read_b128 v[200:203], v161 offset:51200
	ds_read_b128 v[204:207], v161 offset:52224
	ds_read_b128 v[208:211], v161 offset:53248
	ds_read_b128 v[212:215], v161 offset:54272
	ds_read_b128 v[216:219], v161 offset:55296
	ds_read_b128 v[220:223], v161 offset:56320
	s_add_u32 s10, s92, 0x80
	s_addc_u32 s11, s93, 0
	s_mov_b32 m0, s87
	s_nop 0
	global_load_lds_dwordx4 v152, s[10:11]
	s_mov_b32 m0, s96
	s_nop 0
	global_load_lds_dwordx4 v154, s[10:11]
	s_add_u32 s10, s92, 0x80080
	s_addc_u32 s11, s93, 0
	s_mov_b32 m0, s53
	s_nop 0
	global_load_lds_dwordx4 v152, s[10:11]
	s_mov_b32 m0, s56
	s_nop 0
	global_load_lds_dwordx4 v154, s[10:11]
	s_mov_b32 m0, s97
	s_nop 0
	global_load_lds_dwordx4 v151, s[90:91]
	s_mov_b32 m0, s52
	s_nop 0
	global_load_lds_dwordx4 v153, s[90:91]
	s_waitcnt vmcnt(8)
	s_waitcnt lgkmcnt(0)
	s_barrier
	s_setprio 1
	v_mfma_i32_16x16x64_i8 v[62:65], v[138:141], v[192:195], v[62:65]
	v_mfma_i32_16x16x64_i8 v[54:57], v[168:171], v[192:195], v[54:57]
	v_mfma_i32_16x16x64_i8 v[46:49], v[138:141], v[200:203], v[46:49]
	v_mfma_i32_16x16x64_i8 v[38:41], v[168:171], v[200:203], v[38:41]
	v_mfma_i32_16x16x64_i8 v[30:33], v[138:141], v[208:211], v[30:33]
	v_mfma_i32_16x16x64_i8 v[22:25], v[168:171], v[208:211], v[22:25]
	v_mfma_i32_16x16x64_i8 v[14:17], v[138:141], v[216:219], v[14:17]
	v_mfma_i32_16x16x64_i8 v[6:9], v[168:171], v[216:219], v[6:9]
	v_mfma_i32_16x16x64_i8 v[62:65], v[164:167], v[196:199], v[62:65]
	v_mfma_i32_16x16x64_i8 v[54:57], v[172:175], v[196:199], v[54:57]
	v_mfma_i32_16x16x64_i8 v[46:49], v[164:167], v[204:207], v[46:49]
	v_mfma_i32_16x16x64_i8 v[38:41], v[172:175], v[204:207], v[38:41]
	v_mfma_i32_16x16x64_i8 v[30:33], v[164:167], v[212:215], v[30:33]
	v_mfma_i32_16x16x64_i8 v[22:25], v[172:175], v[212:215], v[22:25]
	v_mfma_i32_16x16x64_i8 v[14:17], v[164:167], v[220:223], v[14:17]
	v_mfma_i32_16x16x64_i8 v[6:9], v[172:175], v[220:223], v[6:9]
	v_mfma_i32_16x16x64_i8 v[58:61], v[176:179], v[192:195], v[58:61]
	v_mfma_i32_16x16x64_i8 v[50:53], v[184:187], v[192:195], v[50:53]
	v_mfma_i32_16x16x64_i8 v[42:45], v[176:179], v[200:203], v[42:45]
	v_mfma_i32_16x16x64_i8 v[34:37], v[184:187], v[200:203], v[34:37]
	v_mfma_i32_16x16x64_i8 v[26:29], v[176:179], v[208:211], v[26:29]
	v_mfma_i32_16x16x64_i8 v[18:21], v[184:187], v[208:211], v[18:21]
	v_mfma_i32_16x16x64_i8 v[10:13], v[176:179], v[216:219], v[10:13]
	v_mfma_i32_16x16x64_i8 v[2:5], v[184:187], v[216:219], v[2:5]
	v_mfma_i32_16x16x64_i8 v[58:61], v[180:183], v[196:199], v[58:61]
	v_mfma_i32_16x16x64_i8 v[50:53], v[188:191], v[196:199], v[50:53]
	v_mfma_i32_16x16x64_i8 v[42:45], v[180:183], v[204:207], v[42:45]
	v_mfma_i32_16x16x64_i8 v[34:37], v[188:191], v[204:207], v[34:37]
	v_mfma_i32_16x16x64_i8 v[26:29], v[180:183], v[212:215], v[26:29]
	v_mfma_i32_16x16x64_i8 v[18:21], v[188:191], v[212:215], v[18:21]
	v_mfma_i32_16x16x64_i8 v[10:13], v[180:183], v[220:223], v[10:13]
	v_mfma_i32_16x16x64_i8 v[2:5], v[188:191], v[220:223], v[2:5]
	s_setprio 0
	s_barrier
	s_add_i32 s6, s6, 2
	s_add_u32 vcc_lo, vcc_lo, 0x100
	s_addc_u32 vcc_hi, vcc_hi, 0
	s_add_u32 s54, s54, 0x100
	s_addc_u32 s55, s55, 0
	s_add_u32 s88, s88, 0x100
	s_addc_u32 s89, s89, 0
	s_cmp_gt_u32 s6, 29
	s_cbranch_scc0 .LBB0_539
	s_branch .Lmy_kexit_1
.LBB0_539:
	ds_read_b128 v[138:141], v159
	ds_read_b128 v[164:167], v159 offset:1024
	ds_read_b128 v[168:171], v159 offset:2048
	ds_read_b128 v[172:175], v159 offset:3072
	ds_read_b128 v[176:179], v160
	ds_read_b128 v[180:183], v160 offset:1024
	ds_read_b128 v[184:187], v160 offset:2048
	ds_read_b128 v[188:191], v160 offset:3072
	s_cmp_eq_u32 s6, 28
	s_cselect_b32 s94, s15, vcc_lo
	s_cselect_b32 s95, s14, vcc_hi
	s_cselect_b32 s92, s73, s54
	s_cselect_b32 s93, s71, s55
	s_add_u32 s90, s94, 0x80
	s_addc_u32 s91, s95, 0
	ds_read_b128 v[192:195], v161
	ds_read_b128 v[196:199], v161 offset:1024
	ds_read_b128 v[200:203], v161 offset:2048
	ds_read_b128 v[204:207], v161 offset:3072
	ds_read_b128 v[208:211], v161 offset:4096
	ds_read_b128 v[212:215], v161 offset:5120
	ds_read_b128 v[216:219], v161 offset:6144
	ds_read_b128 v[220:223], v161 offset:7168
	s_mov_b32 m0, s57
	s_nop 0
	global_load_lds_dwordx4 v151, s[88:89]
	s_mov_b32 m0, s24
	s_nop 0
	global_load_lds_dwordx4 v153, s[88:89]
	s_waitcnt vmcnt(8)
	s_waitcnt lgkmcnt(0)
	s_barrier
	s_setprio 1
	v_mfma_i32_16x16x64_i8 v[126:129], v[138:141], v[192:195], v[126:129]
	v_mfma_i32_16x16x64_i8 v[118:121], v[168:171], v[192:195], v[118:121]
	v_mfma_i32_16x16x64_i8 v[110:113], v[138:141], v[200:203], v[110:113]
	v_mfma_i32_16x16x64_i8 v[102:105], v[168:171], v[200:203], v[102:105]
	v_mfma_i32_16x16x64_i8 v[94:97], v[138:141], v[208:211], v[94:97]
	v_mfma_i32_16x16x64_i8 v[86:89], v[168:171], v[208:211], v[86:89]
	v_mfma_i32_16x16x64_i8 v[78:81], v[138:141], v[216:219], v[78:81]
	v_mfma_i32_16x16x64_i8 v[70:73], v[168:171], v[216:219], v[70:73]
	v_mfma_i32_16x16x64_i8 v[126:129], v[164:167], v[196:199], v[126:129]
	v_mfma_i32_16x16x64_i8 v[118:121], v[172:175], v[196:199], v[118:121]
	v_mfma_i32_16x16x64_i8 v[110:113], v[164:167], v[204:207], v[110:113]
	v_mfma_i32_16x16x64_i8 v[102:105], v[172:175], v[204:207], v[102:105]
	v_mfma_i32_16x16x64_i8 v[94:97], v[164:167], v[212:215], v[94:97]
	v_mfma_i32_16x16x64_i8 v[86:89], v[172:175], v[212:215], v[86:89]
	v_mfma_i32_16x16x64_i8 v[78:81], v[164:167], v[220:223], v[78:81]
	v_mfma_i32_16x16x64_i8 v[70:73], v[172:175], v[220:223], v[70:73]
	v_mfma_i32_16x16x64_i8 v[122:125], v[176:179], v[192:195], v[122:125]
	v_mfma_i32_16x16x64_i8 v[114:117], v[184:187], v[192:195], v[114:117]
	v_mfma_i32_16x16x64_i8 v[106:109], v[176:179], v[200:203], v[106:109]
	v_mfma_i32_16x16x64_i8 v[98:101], v[184:187], v[200:203], v[98:101]
	v_mfma_i32_16x16x64_i8 v[90:93], v[176:179], v[208:211], v[90:93]
	v_mfma_i32_16x16x64_i8 v[82:85], v[184:187], v[208:211], v[82:85]
	v_mfma_i32_16x16x64_i8 v[74:77], v[176:179], v[216:219], v[74:77]
	v_mfma_i32_16x16x64_i8 v[66:69], v[184:187], v[216:219], v[66:69]
	v_mfma_i32_16x16x64_i8 v[122:125], v[180:183], v[196:199], v[122:125]
	v_mfma_i32_16x16x64_i8 v[114:117], v[188:191], v[196:199], v[114:117]
	v_mfma_i32_16x16x64_i8 v[106:109], v[180:183], v[204:207], v[106:109]
	v_mfma_i32_16x16x64_i8 v[98:101], v[188:191], v[204:207], v[98:101]
	v_mfma_i32_16x16x64_i8 v[90:93], v[180:183], v[212:215], v[90:93]
	v_mfma_i32_16x16x64_i8 v[82:85], v[188:191], v[212:215], v[82:85]
	v_mfma_i32_16x16x64_i8 v[74:77], v[180:183], v[220:223], v[74:77]
	v_mfma_i32_16x16x64_i8 v[66:69], v[188:191], v[220:223], v[66:69]
	s_setprio 0
	s_barrier
; #define PG8_STAGE(bufoff, gbase, voff) do { if constexpr (VAR != 1 && VAR != 3) { _Pragma("unroll") for (int _i = 0; _i < 2; ++_i) \
;         asm volatile("s_mov_b32 m0, %2\n\ts_nop 0\n\tglobal_load_lds_dwordx4 %0, %1" :: "v"((voff)[_i]), "s"((const char*)(gbase)), "s"(ldsbase + (unsigned)((bufoff) + _i * 8192)) : "memory", "m0"); } } while (0)
; #define PG8_LDA(dst, b, h) do { if constexpr (VAR < 2) _Pragma("unroll") for (int m = 0; m < 4; ++m) _Pragma("unroll") for (int k = 0; k < 2; ++k) dst[m][k] = *(const LAS bf16x8*)(lds + PG8_SA(b, h) + aoff + m * 2048 + k * 1024); } while (0)
; #define PG8_LDB(dst, b, h) do { if constexpr (VAR < 2) _Pragma("unroll") for (int n = 0; n < 2; ++n) _Pragma("unroll") for (int k = 0; k < 2; ++k) dst[n][k] = *(const LAS bf16x8*)(lds + PG8_SB(b, h) + boff + n * 2048 + k * 1024); } while (0)
; #define PG8_WAIT_V(n) asm volatile("s_waitcnt vmcnt(" #n ")" ::: "memory")
; #define PG8_WAIT_L(n) asm volatile("s_waitcnt lgkmcnt(" #n ")" ::: "memory")
; #define PG8_BAR do { if constexpr (VAR != 3) __builtin_amdgcn_s_barrier(); } while (0)
; #define PG8_SCHED __builtin_amdgcn_sched_barrier(0)
;     ...
;             PG8_LDA(At, 0, 1); PG8_STAGE(PG8_SB(0, 0), b2, voffB); PG8_STAGE(PG8_SB(0, 1), b2 + hstepB, voffB); PG8_STAGE(PG8_SA(0, 0), a2, voffA);
;             PG8_WAIT_V(8); PG8_WAIT_L(0); PG8_BAR; PG8_MMA(1, 0, At, B0); PG8_MMA(1, 1, At, B1); PG8_BAR; PG8_SCHED;
;             PG8_LDB(B0, 1, 0); PG8_LDB(B1, 1, 1); PG8_SCHED; PG8_LDA(At, 1, 0); PG8_STAGE(PG8_SA(0, 1), a2 + hstepA, voffA);
;             PG8_WAIT_V(8); PG8_WAIT_L(0); PG8_BAR; PG8_MMA(0, 0, At, B0); PG8_MMA(0, 1, At, B1); PG8_BAR; PG8_SCHED;
	ds_read_b128 v[192:195], v161 offset:16384
	ds_read_b128 v[196:199], v161 offset:17408
	ds_read_b128 v[200:203], v161 offset:18432
	ds_read_b128 v[204:207], v161 offset:19456
	ds_read_b128 v[208:211], v161 offset:20480
	ds_read_b128 v[212:215], v161 offset:21504
	ds_read_b128 v[216:219], v161 offset:22528
	ds_read_b128 v[220:223], v161 offset:23552
	s_mov_b32 m0, s29
	s_nop 0
	global_load_lds_dwordx4 v152, s[92:93]
	s_add_u32 s10, s92, 0x80000
	s_mov_b32 m0, s30
	s_nop 0
	global_load_lds_dwordx4 v154, s[92:93]
	s_addc_u32 s11, s93, 0
	s_mov_b32 m0, s31
	s_nop 0
	global_load_lds_dwordx4 v152, s[10:11]
	s_mov_b32 m0, s33
	s_nop 0
	global_load_lds_dwordx4 v154, s[10:11]
	s_mov_b32 m0, s26
	s_nop 0
	global_load_lds_dwordx4 v151, s[94:95]
	s_mov_b32 m0, s35
	s_nop 0
	global_load_lds_dwordx4 v153, s[94:95]
	s_waitcnt vmcnt(8)
	s_waitcnt lgkmcnt(0)
	s_barrier
	s_setprio 1
	v_mfma_i32_16x16x64_i8 v[62:65], v[138:141], v[192:195], v[62:65]
	v_mfma_i32_16x16x64_i8 v[54:57], v[168:171], v[192:195], v[54:57]
	v_mfma_i32_16x16x64_i8 v[46:49], v[138:141], v[200:203], v[46:49]
	v_mfma_i32_16x16x64_i8 v[38:41], v[168:171], v[200:203], v[38:41]
	v_mfma_i32_16x16x64_i8 v[30:33], v[138:141], v[208:211], v[30:33]
	v_mfma_i32_16x16x64_i8 v[22:25], v[168:171], v[208:211], v[22:25]
	v_mfma_i32_16x16x64_i8 v[14:17], v[138:141], v[216:219], v[14:17]
	v_mfma_i32_16x16x64_i8 v[6:9], v[168:171], v[216:219], v[6:9]
	v_mfma_i32_16x16x64_i8 v[62:65], v[164:167], v[196:199], v[62:65]
	v_mfma_i32_16x16x64_i8 v[54:57], v[172:175], v[196:199], v[54:57]
	v_mfma_i32_16x16x64_i8 v[46:49], v[164:167], v[204:207], v[46:49]
	v_mfma_i32_16x16x64_i8 v[38:41], v[172:175], v[204:207], v[38:41]
	v_mfma_i32_16x16x64_i8 v[30:33], v[164:167], v[212:215], v[30:33]
	v_mfma_i32_16x16x64_i8 v[22:25], v[172:175], v[212:215], v[22:25]
	v_mfma_i32_16x16x64_i8 v[14:17], v[164:167], v[220:223], v[14:17]
	v_mfma_i32_16x16x64_i8 v[6:9], v[172:175], v[220:223], v[6:9]
	v_mfma_i32_16x16x64_i8 v[58:61], v[176:179], v[192:195], v[58:61]
	v_mfma_i32_16x16x64_i8 v[50:53], v[184:187], v[192:195], v[50:53]
	v_mfma_i32_16x16x64_i8 v[42:45], v[176:179], v[200:203], v[42:45]
	v_mfma_i32_16x16x64_i8 v[34:37], v[184:187], v[200:203], v[34:37]
	v_mfma_i32_16x16x64_i8 v[26:29], v[176:179], v[208:211], v[26:29]
	v_mfma_i32_16x16x64_i8 v[18:21], v[184:187], v[208:211], v[18:21]
	v_mfma_i32_16x16x64_i8 v[10:13], v[176:179], v[216:219], v[10:13]
	v_mfma_i32_16x16x64_i8 v[2:5], v[184:187], v[216:219], v[2:5]
	v_mfma_i32_16x16x64_i8 v[58:61], v[180:183], v[196:199], v[58:61]
	v_mfma_i32_16x16x64_i8 v[50:53], v[188:191], v[196:199], v[50:53]
	v_mfma_i32_16x16x64_i8 v[42:45], v[180:183], v[204:207], v[42:45]
	v_mfma_i32_16x16x64_i8 v[34:37], v[188:191], v[204:207], v[34:37]
	v_mfma_i32_16x16x64_i8 v[26:29], v[180:183], v[212:215], v[26:29]
	v_mfma_i32_16x16x64_i8 v[18:21], v[188:191], v[212:215], v[18:21]
	v_mfma_i32_16x16x64_i8 v[10:13], v[180:183], v[220:223], v[10:13]
	v_mfma_i32_16x16x64_i8 v[2:5], v[188:191], v[220:223], v[2:5]
	s_setprio 0
	s_barrier
	ds_read_b128 v[138:141], v162
	ds_read_b128 v[164:167], v162 offset:1024
	ds_read_b128 v[168:171], v162 offset:2048
	ds_read_b128 v[172:175], v162 offset:3072
	ds_read_b128 v[176:179], v163
	ds_read_b128 v[180:183], v163 offset:1024
	ds_read_b128 v[184:187], v163 offset:2048
	ds_read_b128 v[188:191], v163 offset:3072
	ds_read_b128 v[192:195], v161 offset:32768
	ds_read_b128 v[196:199], v161 offset:33792
	ds_read_b128 v[200:203], v161 offset:34816
	ds_read_b128 v[204:207], v161 offset:35840
	ds_read_b128 v[208:211], v161 offset:36864
	ds_read_b128 v[212:215], v161 offset:37888
	ds_read_b128 v[216:219], v161 offset:38912
	ds_read_b128 v[220:223], v161 offset:39936
	s_add_u32 s10, s94, 0x80000
	s_addc_u32 s11, s95, 0
	s_mov_b32 m0, s62
	s_nop 0
	global_load_lds_dwordx4 v151, s[10:11]
	s_mov_b32 m0, s63
	s_nop 0
	global_load_lds_dwordx4 v153, s[10:11]
	s_waitcnt vmcnt(8)
	s_waitcnt lgkmcnt(0)
	s_barrier
; #define PG8_STAGE(bufoff, gbase, voff) do { if constexpr (VAR != 1 && VAR != 3) { _Pragma("unroll") for (int _i = 0; _i < 2; ++_i) \
;         asm volatile("s_mov_b32 m0, %2\n\ts_nop 0\n\tglobal_load_lds_dwordx4 %0, %1" :: "v"((voff)[_i]), "s"((const char*)(gbase)), "s"(ldsbase + (unsigned)((bufoff) + _i * 8192)) : "memory", "m0"); } } while (0)
; #define PG8_LDA(dst, b, h) do { if constexpr (VAR < 2) _Pragma("unroll") for (int m = 0; m < 4; ++m) _Pragma("unroll") for (int k = 0; k < 2; ++k) dst[m][k] = *(const LAS bf16x8*)(lds + PG8_SA(b, h) + aoff + m * 2048 + k * 1024); } while (0)
; #define PG8_WAIT_V(n) asm volatile("s_waitcnt vmcnt(" #n ")" ::: "memory")
; #define PG8_WAIT_L(n) asm volatile("s_waitcnt lgkmcnt(" #n ")" ::: "memory")
; #define PG8_BAR do { if constexpr (VAR != 3) __builtin_amdgcn_s_barrier(); } while (0)
; #define PG8_SCHED __builtin_amdgcn_sched_barrier(0)
;     ...
;             PG8_WAIT_V(8); PG8_WAIT_L(0); PG8_BAR; PG8_MMA(0, 0, At, B0); PG8_MMA(0, 1, At, B1); PG8_BAR; PG8_SCHED;
;             PG8_LDA(At, 1, 1); PG8_STAGE(PG8_SB(1, 0), b3, voffB); PG8_STAGE(PG8_SB(1, 1), b3 + hstepB, voffB); PG8_STAGE(PG8_SA(1, 0), a3, voffA);
;             PG8_WAIT_V(8); PG8_WAIT_L(0); PG8_BAR; PG8_MMA(1, 0, At, B0); PG8_MMA(1, 1, At, B1); PG8_BAR; PG8_SCHED;
;         }
;         if (wr == 0) PG8_BAR;
	s_setprio 1
	v_mfma_i32_16x16x64_i8 v[126:129], v[138:141], v[192:195], v[126:129]
	v_mfma_i32_16x16x64_i8 v[118:121], v[168:171], v[192:195], v[118:121]
	v_mfma_i32_16x16x64_i8 v[110:113], v[138:141], v[200:203], v[110:113]
	v_mfma_i32_16x16x64_i8 v[102:105], v[168:171], v[200:203], v[102:105]
	v_mfma_i32_16x16x64_i8 v[94:97], v[138:141], v[208:211], v[94:97]
	v_mfma_i32_16x16x64_i8 v[86:89], v[168:171], v[208:211], v[86:89]
	v_mfma_i32_16x16x64_i8 v[78:81], v[138:141], v[216:219], v[78:81]
	v_mfma_i32_16x16x64_i8 v[70:73], v[168:171], v[216:219], v[70:73]
	v_mfma_i32_16x16x64_i8 v[126:129], v[164:167], v[196:199], v[126:129]
	v_mfma_i32_16x16x64_i8 v[118:121], v[172:175], v[196:199], v[118:121]
	v_mfma_i32_16x16x64_i8 v[110:113], v[164:167], v[204:207], v[110:113]
	v_mfma_i32_16x16x64_i8 v[102:105], v[172:175], v[204:207], v[102:105]
	v_mfma_i32_16x16x64_i8 v[94:97], v[164:167], v[212:215], v[94:97]
	v_mfma_i32_16x16x64_i8 v[86:89], v[172:175], v[212:215], v[86:89]
	v_mfma_i32_16x16x64_i8 v[78:81], v[164:167], v[220:223], v[78:81]
	v_mfma_i32_16x16x64_i8 v[70:73], v[172:175], v[220:223], v[70:73]
	v_mfma_i32_16x16x64_i8 v[122:125], v[176:179], v[192:195], v[122:125]
	v_mfma_i32_16x16x64_i8 v[114:117], v[184:187], v[192:195], v[114:117]
	v_mfma_i32_16x16x64_i8 v[106:109], v[176:179], v[200:203], v[106:109]
	v_mfma_i32_16x16x64_i8 v[98:101], v[184:187], v[200:203], v[98:101]
	v_mfma_i32_16x16x64_i8 v[90:93], v[176:179], v[208:211], v[90:93]
	v_mfma_i32_16x16x64_i8 v[82:85], v[184:187], v[208:211], v[82:85]
	v_mfma_i32_16x16x64_i8 v[74:77], v[176:179], v[216:219], v[74:77]
	v_mfma_i32_16x16x64_i8 v[66:69], v[184:187], v[216:219], v[66:69]
	v_mfma_i32_16x16x64_i8 v[122:125], v[180:183], v[196:199], v[122:125]
	v_mfma_i32_16x16x64_i8 v[114:117], v[188:191], v[196:199], v[114:117]
	v_mfma_i32_16x16x64_i8 v[106:109], v[180:183], v[204:207], v[106:109]
	v_mfma_i32_16x16x64_i8 v[98:101], v[188:191], v[204:207], v[98:101]
	v_mfma_i32_16x16x64_i8 v[90:93], v[180:183], v[212:215], v[90:93]
	v_mfma_i32_16x16x64_i8 v[82:85], v[188:191], v[212:215], v[82:85]
	v_mfma_i32_16x16x64_i8 v[74:77], v[180:183], v[220:223], v[74:77]
	v_mfma_i32_16x16x64_i8 v[66:69], v[188:191], v[220:223], v[66:69]
	s_setprio 0
	s_barrier
	ds_read_b128 v[192:195], v161 offset:49152
	ds_read_b128 v[196:199], v161 offset:50176
	ds_read_b128 v[200:203], v161 offset:51200
	ds_read_b128 v[204:207], v161 offset:52224
	ds_read_b128 v[208:211], v161 offset:53248
	ds_read_b128 v[212:215], v161 offset:54272
	ds_read_b128 v[216:219], v161 offset:55296
	ds_read_b128 v[220:223], v161 offset:56320
	s_add_u32 s10, s92, 0x80
	s_addc_u32 s11, s93, 0
	s_mov_b32 m0, s87
	s_nop 0
	global_load_lds_dwordx4 v152, s[10:11]
	s_mov_b32 m0, s96
	s_nop 0
	global_load_lds_dwordx4 v154, s[10:11]
	s_add_u32 s10, s92, 0x80080
	s_addc_u32 s11, s93, 0
	s_mov_b32 m0, s53
	s_nop 0
	global_load_lds_dwordx4 v152, s[10:11]
	s_mov_b32 m0, s56
	s_nop 0
	global_load_lds_dwordx4 v154, s[10:11]
	s_mov_b32 m0, s97
	s_nop 0
	global_load_lds_dwordx4 v151, s[90:91]
	s_mov_b32 m0, s52
	s_nop 0
	global_load_lds_dwordx4 v153, s[90:91]
	s_waitcnt vmcnt(8)
	s_waitcnt lgkmcnt(0)
	s_barrier
	s_setprio 1
	v_mfma_i32_16x16x64_i8 v[62:65], v[138:141], v[192:195], v[62:65]
	v_mfma_i32_16x16x64_i8 v[54:57], v[168:171], v[192:195], v[54:57]
	v_mfma_i32_16x16x64_i8 v[46:49], v[138:141], v[200:203], v[46:49]
	v_mfma_i32_16x16x64_i8 v[38:41], v[168:171], v[200:203], v[38:41]
	v_mfma_i32_16x16x64_i8 v[30:33], v[138:141], v[208:211], v[30:33]
	v_mfma_i32_16x16x64_i8 v[22:25], v[168:171], v[208:211], v[22:25]
	v_mfma_i32_16x16x64_i8 v[14:17], v[138:141], v[216:219], v[14:17]
	v_mfma_i32_16x16x64_i8 v[6:9], v[168:171], v[216:219], v[6:9]
	v_mfma_i32_16x16x64_i8 v[62:65], v[164:167], v[196:199], v[62:65]
	v_mfma_i32_16x16x64_i8 v[54:57], v[172:175], v[196:199], v[54:57]
	v_mfma_i32_16x16x64_i8 v[46:49], v[164:167], v[204:207], v[46:49]
	v_mfma_i32_16x16x64_i8 v[38:41], v[172:175], v[204:207], v[38:41]
	v_mfma_i32_16x16x64_i8 v[30:33], v[164:167], v[212:215], v[30:33]
	v_mfma_i32_16x16x64_i8 v[22:25], v[172:175], v[212:215], v[22:25]
	v_mfma_i32_16x16x64_i8 v[14:17], v[164:167], v[220:223], v[14:17]
	v_mfma_i32_16x16x64_i8 v[6:9], v[172:175], v[220:223], v[6:9]
	v_mfma_i32_16x16x64_i8 v[58:61], v[176:179], v[192:195], v[58:61]
	v_mfma_i32_16x16x64_i8 v[50:53], v[184:187], v[192:195], v[50:53]
	v_mfma_i32_16x16x64_i8 v[42:45], v[176:179], v[200:203], v[42:45]
	v_mfma_i32_16x16x64_i8 v[34:37], v[184:187], v[200:203], v[34:37]
	v_mfma_i32_16x16x64_i8 v[26:29], v[176:179], v[208:211], v[26:29]
	v_mfma_i32_16x16x64_i8 v[18:21], v[184:187], v[208:211], v[18:21]
	v_mfma_i32_16x16x64_i8 v[10:13], v[176:179], v[216:219], v[10:13]
	v_mfma_i32_16x16x64_i8 v[2:5], v[184:187], v[216:219], v[2:5]
	v_mfma_i32_16x16x64_i8 v[58:61], v[180:183], v[196:199], v[58:61]
	v_mfma_i32_16x16x64_i8 v[50:53], v[188:191], v[196:199], v[50:53]
	v_mfma_i32_16x16x64_i8 v[42:45], v[180:183], v[204:207], v[42:45]
	v_mfma_i32_16x16x64_i8 v[34:37], v[188:191], v[204:207], v[34:37]
	v_mfma_i32_16x16x64_i8 v[26:29], v[180:183], v[212:215], v[26:29]
	v_mfma_i32_16x16x64_i8 v[18:21], v[188:191], v[212:215], v[18:21]
	v_mfma_i32_16x16x64_i8 v[10:13], v[180:183], v[220:223], v[10:13]
	v_mfma_i32_16x16x64_i8 v[2:5], v[188:191], v[220:223], v[2:5]
	s_setprio 0
	s_barrier
	s_add_i32 s6, s6, 2
	s_add_u32 vcc_lo, vcc_lo, 0x100
	s_addc_u32 vcc_hi, vcc_hi, 0
	s_add_u32 s54, s54, 0x100
	s_addc_u32 s55, s55, 0
	s_add_u32 s88, s88, 0x100
	s_addc_u32 s89, s89, 0
	s_cmp_gt_u32 s6, 29
	s_cbranch_scc0 .LBB0_539
.Lmy_kexit_1:
	s_and_b64 vcc, exec, s[66:67]
	s_cbranch_vccz .LBB0_542
	s_barrier

; __device__ __forceinline__ const char* unitA(const Gemm& g, const Unit& u) { return (const char*)(g.A + (size_t)(u.z / g.zdiv) * g.sAhi + (size_t)(u.z % g.zdiv) * g.sAlo + (size_t)u.pm * BM * g.lda); }
; __device__ __forceinline__ const char* unitB(const Gemm& g, const Unit& u) { return (const char*)(g.Bt + (size_t)(u.z / g.zdiv) * g.sBhi + (size_t)(u.z % g.zdiv) * g.sBlo + (size_t)(u.pm / g.bdiv) * g.sBpm + (size_t)u.pn * BM * g.ldb); }
; #define PG8_STAGE(bufoff, gbase, voff) do { if constexpr (VAR != 1 && VAR != 3) { _Pragma("unroll") for (int _i = 0; _i < 2; ++_i) \
;         asm volatile("s_mov_b32 m0, %2\n\ts_nop 0\n\tglobal_load_lds_dwordx4 %0, %1" :: "v"((voff)[_i]), "s"((const char*)(gbase)), "s"(ldsbase + (unsigned)((bufoff) + _i * 8192)) : "memory", "m0"); } } while (0)
; #define PG8_LDA(dst, b, h) do { if constexpr (VAR < 2) _Pragma("unroll") for (int m = 0; m < 4; ++m) _Pragma("unroll") for (int k = 0; k < 2; ++k) dst[m][k] = *(const LAS bf16x8*)(lds + PG8_SA(b, h) + aoff + m * 2048 + k * 1024); } while (0)
; #define PG8_LDB(dst, b, h) do { if constexpr (VAR < 2) _Pragma("unroll") for (int n = 0; n < 2; ++n) _Pragma("unroll") for (int k = 0; k < 2; ++k) dst[n][k] = *(const LAS bf16x8*)(lds + PG8_SB(b, h) + boff + n * 2048 + k * 1024); } while (0)
; #define PG8_WAIT_V(n) asm volatile("s_waitcnt vmcnt(" #n ")" ::: "memory")
; #define PG8_SCHED __builtin_amdgcn_sched_barrier(0)
;     ...
;         const char* nA = has_next ? unitA(g, nxt) : cA; const char* nB = has_next ? unitB(g, nxt) : cB;
;         for (int t = 0; t < nt; t += 2) {
;             const bool last = (t == nt - 2);
;             const char* a1 = cA + (size_t)(t + 1) * kstep;
;             const char* a2 = last ? nA : cA + (size_t)(t + 2) * kstep; const char* b2 = last ? nB : cB + (size_t)(t + 2) * kstep;
;             const char* a3 = a2 + kstep; const char* b3 = b2 + kstep;
;             PG8_LDB(B0, 0, 0); PG8_LDB(B1, 0, 1); PG8_SCHED; PG8_LDA(At, 0, 0); PG8_STAGE(PG8_SA(1, 1), a1 + hstepA, voffA);
;             PG8_WAIT_V(8); PG8_WAIT_L(0); PG8_BAR; PG8_MMA(0, 0, At, B0); PG8_MMA(0, 1, At, B1); PG8_BAR; PG8_SCHED;
;             PG8_LDA(At, 0, 1); PG8_STAGE(PG8_SB(0, 0), b2, voffB); PG8_STAGE(PG8_SB(0, 1), b2 + hstepB, voffB); PG8_STAGE(PG8_SA(0, 0), a2, voffA);
;             PG8_WAIT_V(8); PG8_WAIT_L(0); PG8_BAR; PG8_MMA(1, 0, At, B0); PG8_MMA(1, 1, At, B1); PG8_BAR; PG8_SCHED;
.LBB0_560:
	s_ashr_i32 s65, s64, 31
	s_lshl_b64 s[6:7], s[64:65], 21
	s_add_u32 s66, s12, s6
	s_addc_u32 s67, s13, s7
	s_and_b64 s[6:7], s[2:3], exec
	s_cselect_b32 s1, s67, s73
	s_cselect_b32 s14, s66, s72
	s_ashr_i32 s61, s60, 31
	s_lshl_b64 s[6:7], s[60:61], 21
	s_add_u32 s68, s26, s6
	s_addc_u32 s69, s27, s7
	s_and_b64 s[6:7], s[2:3], exec
	s_cselect_b32 s15, s69, s71
	s_cselect_b32 s61, s68, s70
	s_add_u32 s65, s72, 0x100
	s_addc_u32 s92, s73, 0
	s_add_u32 s93, s70, 0x100
	s_addc_u32 s94, s71, 0
	s_add_u32 s70, s72, 0x100080
	s_addc_u32 s71, s73, 0
	s_mov_b32 s6, -2
	ds_read_b128 v[136:139], v152
	ds_read_b128 v[140:143], v152 offset:1024
	ds_read_b128 v[158:161], v152 offset:2048
	ds_read_b128 v[162:165], v152 offset:3072
	ds_read_b128 v[166:169], v153
	ds_read_b128 v[170:173], v153 offset:1024
	ds_read_b128 v[174:177], v153 offset:2048
	ds_read_b128 v[178:181], v153 offset:3072
	s_cmp_eq_u32 s6, 60
	s_cselect_b32 s84, s14, s65
	s_cselect_b32 s85, s1, s92
	s_cselect_b32 s74, s61, s93
	s_cselect_b32 s75, s15, s94
	s_add_u32 s72, s84, 0x80
	s_addc_u32 s73, s85, 0
	ds_read_b128 v[182:185], v154
	ds_read_b128 v[186:189], v154 offset:1024
	ds_read_b128 v[190:193], v154 offset:2048
	ds_read_b128 v[194:197], v154 offset:3072
	ds_read_b128 v[198:201], v154 offset:4096
	ds_read_b128 v[202:205], v154 offset:5120
	ds_read_b128 v[206:209], v154 offset:6144
	ds_read_b128 v[210:213], v154 offset:7168
	s_mov_b32 m0, s86
	s_nop 0
	global_load_lds_dwordx4 v1, s[70:71]
	s_mov_b32 m0, s87
	s_nop 0
	global_load_lds_dwordx4 v147, s[70:71]
	s_waitcnt vmcnt(8)
	s_waitcnt lgkmcnt(0)
	s_barrier
	s_setprio 1
	v_mfma_f32_16x16x32_bf16 v[126:129], v[136:139], v[182:185], 0
	v_mfma_f32_16x16x32_bf16 v[118:121], v[158:161], v[182:185], 0
	v_mfma_f32_16x16x32_bf16 v[110:113], v[136:139], v[190:193], 0
	v_mfma_f32_16x16x32_bf16 v[102:105], v[158:161], v[190:193], 0
	v_mfma_f32_16x16x32_bf16 v[94:97], v[136:139], v[198:201], 0
	v_mfma_f32_16x16x32_bf16 v[86:89], v[158:161], v[198:201], 0
	v_mfma_f32_16x16x32_bf16 v[78:81], v[136:139], v[206:209], 0
	v_mfma_f32_16x16x32_bf16 v[70:73], v[158:161], v[206:209], 0
	v_mfma_f32_16x16x32_bf16 v[126:129], v[140:143], v[186:189], v[126:129]
	v_mfma_f32_16x16x32_bf16 v[118:121], v[162:165], v[186:189], v[118:121]
	v_mfma_f32_16x16x32_bf16 v[110:113], v[140:143], v[194:197], v[110:113]
	v_mfma_f32_16x16x32_bf16 v[102:105], v[162:165], v[194:197], v[102:105]
	v_mfma_f32_16x16x32_bf16 v[94:97], v[140:143], v[202:205], v[94:97]
	v_mfma_f32_16x16x32_bf16 v[86:89], v[162:165], v[202:205], v[86:89]
	v_mfma_f32_16x16x32_bf16 v[78:81], v[140:143], v[210:213], v[78:81]
	v_mfma_f32_16x16x32_bf16 v[70:73], v[162:165], v[210:213], v[70:73]
	v_mfma_f32_16x16x32_bf16 v[122:125], v[166:169], v[182:185], 0
	v_mfma_f32_16x16x32_bf16 v[114:117], v[174:177], v[182:185], 0
	v_mfma_f32_16x16x32_bf16 v[106:109], v[166:169], v[190:193], 0
	v_mfma_f32_16x16x32_bf16 v[98:101], v[174:177], v[190:193], 0
	v_mfma_f32_16x16x32_bf16 v[90:93], v[166:169], v[198:201], 0
	v_mfma_f32_16x16x32_bf16 v[82:85], v[174:177], v[198:201], 0
	v_mfma_f32_16x16x32_bf16 v[74:77], v[166:169], v[206:209], 0
	v_mfma_f32_16x16x32_bf16 v[66:69], v[174:177], v[206:209], 0
	v_mfma_f32_16x16x32_bf16 v[122:125], v[170:173], v[186:189], v[122:125]
	v_mfma_f32_16x16x32_bf16 v[114:117], v[178:181], v[186:189], v[114:117]
	v_mfma_f32_16x16x32_bf16 v[106:109], v[170:173], v[194:197], v[106:109]
	v_mfma_f32_16x16x32_bf16 v[98:101], v[178:181], v[194:197], v[98:101]
	v_mfma_f32_16x16x32_bf16 v[90:93], v[170:173], v[202:205], v[90:93]
	v_mfma_f32_16x16x32_bf16 v[82:85], v[178:181], v[202:205], v[82:85]
	v_mfma_f32_16x16x32_bf16 v[74:77], v[170:173], v[210:213], v[74:77]
	v_mfma_f32_16x16x32_bf16 v[66:69], v[178:181], v[210:213], v[66:69]
	s_setprio 0
	s_barrier
	ds_read_b128 v[182:185], v154 offset:16384
	ds_read_b128 v[186:189], v154 offset:17408
	ds_read_b128 v[190:193], v154 offset:18432
	ds_read_b128 v[194:197], v154 offset:19456
	ds_read_b128 v[198:201], v154 offset:20480
	ds_read_b128 v[202:205], v154 offset:21504
	ds_read_b128 v[206:209], v154 offset:22528
	ds_read_b128 v[210:213], v154 offset:23552
	s_mov_b32 m0, s21
	s_nop 0
	global_load_lds_dwordx4 v146, s[74:75]
	s_add_u32 s10, s74, 0x100000
	s_mov_b32 m0, s23
	s_nop 0
	global_load_lds_dwordx4 v148, s[74:75]
	s_addc_u32 s11, s75, 0
	s_mov_b32 m0, s29
	s_nop 0
	global_load_lds_dwordx4 v146, s[10:11]
	s_mov_b32 m0, s30
	s_nop 0
	global_load_lds_dwordx4 v148, s[10:11]
	s_mov_b32 m0, s25
	s_nop 0
	global_load_lds_dwordx4 v1, s[84:85]
	s_mov_b32 m0, s31
	s_nop 0
	global_load_lds_dwordx4 v147, s[84:85]
	s_waitcnt vmcnt(8)
	s_waitcnt lgkmcnt(0)
	s_barrier
; #define PG8_STAGE(bufoff, gbase, voff) do { if constexpr (VAR != 1 && VAR != 3) { _Pragma("unroll") for (int _i = 0; _i < 2; ++_i) \
;         asm volatile("s_mov_b32 m0, %2\n\ts_nop 0\n\tglobal_load_lds_dwordx4 %0, %1" :: "v"((voff)[_i]), "s"((const char*)(gbase)), "s"(ldsbase + (unsigned)((bufoff) + _i * 8192)) : "memory", "m0"); } } while (0)
; #define PG8_LDA(dst, b, h) do { if constexpr (VAR < 2) _Pragma("unroll") for (int m = 0; m < 4; ++m) _Pragma("unroll") for (int k = 0; k < 2; ++k) dst[m][k] = *(const LAS bf16x8*)(lds + PG8_SA(b, h) + aoff + m * 2048 + k * 1024); } while (0)
; #define PG8_LDB(dst, b, h) do { if constexpr (VAR < 2) _Pragma("unroll") for (int n = 0; n < 2; ++n) _Pragma("unroll") for (int k = 0; k < 2; ++k) dst[n][k] = *(const LAS bf16x8*)(lds + PG8_SB(b, h) + boff + n * 2048 + k * 1024); } while (0)
; #define PG8_WAIT_V(n) asm volatile("s_waitcnt vmcnt(" #n ")" ::: "memory")
; #define PG8_WAIT_L(n) asm volatile("s_waitcnt lgkmcnt(" #n ")" ::: "memory")
; #define PG8_BAR do { if constexpr (VAR != 3) __builtin_amdgcn_s_barrier(); } while (0)
; #define PG8_SCHED __builtin_amdgcn_sched_barrier(0)
;     ...
;             PG8_WAIT_V(8); PG8_WAIT_L(0); PG8_BAR; PG8_MMA(1, 0, At, B0); PG8_MMA(1, 1, At, B1); PG8_BAR; PG8_SCHED;
;             PG8_LDB(B0, 1, 0); PG8_LDB(B1, 1, 1); PG8_SCHED; PG8_LDA(At, 1, 0); PG8_STAGE(PG8_SA(0, 1), a2 + hstepA, voffA);
;             PG8_WAIT_V(8); PG8_WAIT_L(0); PG8_BAR; PG8_MMA(0, 0, At, B0); PG8_MMA(0, 1, At, B1); PG8_BAR; PG8_SCHED;
	s_setprio 1
	v_mfma_f32_16x16x32_bf16 v[62:65], v[136:139], v[182:185], 0
	v_mfma_f32_16x16x32_bf16 v[54:57], v[158:161], v[182:185], 0
	v_mfma_f32_16x16x32_bf16 v[46:49], v[136:139], v[190:193], 0
	v_mfma_f32_16x16x32_bf16 v[38:41], v[158:161], v[190:193], 0
	v_mfma_f32_16x16x32_bf16 v[30:33], v[136:139], v[198:201], 0
	v_mfma_f32_16x16x32_bf16 v[22:25], v[158:161], v[198:201], 0
	v_mfma_f32_16x16x32_bf16 v[14:17], v[136:139], v[206:209], 0
	v_mfma_f32_16x16x32_bf16 v[6:9], v[158:161], v[206:209], 0
	v_mfma_f32_16x16x32_bf16 v[62:65], v[140:143], v[186:189], v[62:65]
	v_mfma_f32_16x16x32_bf16 v[54:57], v[162:165], v[186:189], v[54:57]
	v_mfma_f32_16x16x32_bf16 v[46:49], v[140:143], v[194:197], v[46:49]
	v_mfma_f32_16x16x32_bf16 v[38:41], v[162:165], v[194:197], v[38:41]
	v_mfma_f32_16x16x32_bf16 v[30:33], v[140:143], v[202:205], v[30:33]
	v_mfma_f32_16x16x32_bf16 v[22:25], v[162:165], v[202:205], v[22:25]
	v_mfma_f32_16x16x32_bf16 v[14:17], v[140:143], v[210:213], v[14:17]
	v_mfma_f32_16x16x32_bf16 v[6:9], v[162:165], v[210:213], v[6:9]
	v_mfma_f32_16x16x32_bf16 v[58:61], v[166:169], v[182:185], 0
	v_mfma_f32_16x16x32_bf16 v[50:53], v[174:177], v[182:185], 0
	v_mfma_f32_16x16x32_bf16 v[42:45], v[166:169], v[190:193], 0
	v_mfma_f32_16x16x32_bf16 v[34:37], v[174:177], v[190:193], 0
	v_mfma_f32_16x16x32_bf16 v[26:29], v[166:169], v[198:201], 0
	v_mfma_f32_16x16x32_bf16 v[18:21], v[174:177], v[198:201], 0
	v_mfma_f32_16x16x32_bf16 v[10:13], v[166:169], v[206:209], 0
	v_mfma_f32_16x16x32_bf16 v[2:5], v[174:177], v[206:209], 0
	v_mfma_f32_16x16x32_bf16 v[58:61], v[170:173], v[186:189], v[58:61]
	v_mfma_f32_16x16x32_bf16 v[50:53], v[178:181], v[186:189], v[50:53]
	v_mfma_f32_16x16x32_bf16 v[42:45], v[170:173], v[194:197], v[42:45]
	v_mfma_f32_16x16x32_bf16 v[34:37], v[178:181], v[194:197], v[34:37]
	v_mfma_f32_16x16x32_bf16 v[26:29], v[170:173], v[202:205], v[26:29]
	v_mfma_f32_16x16x32_bf16 v[18:21], v[178:181], v[202:205], v[18:21]
	v_mfma_f32_16x16x32_bf16 v[10:13], v[170:173], v[210:213], v[10:13]
	v_mfma_f32_16x16x32_bf16 v[2:5], v[178:181], v[210:213], v[2:5]
	s_setprio 0
	s_barrier
	ds_read_b128 v[136:139], v155
	ds_read_b128 v[140:143], v155 offset:1024
	ds_read_b128 v[158:161], v155 offset:2048
	ds_read_b128 v[162:165], v155 offset:3072
	ds_read_b128 v[166:169], v156
	ds_read_b128 v[170:173], v156 offset:1024
	ds_read_b128 v[174:177], v156 offset:2048
	ds_read_b128 v[178:181], v156 offset:3072
	ds_read_b128 v[182:185], v154 offset:32768
	ds_read_b128 v[186:189], v154 offset:33792
	ds_read_b128 v[190:193], v154 offset:34816
	ds_read_b128 v[194:197], v154 offset:35840
	ds_read_b128 v[198:201], v154 offset:36864
	ds_read_b128 v[202:205], v154 offset:37888
	ds_read_b128 v[206:209], v154 offset:38912
	ds_read_b128 v[210:213], v154 offset:39936
	s_add_u32 s10, s84, 0x100000
	s_addc_u32 s11, s85, 0
	s_mov_b32 m0, s33
	s_nop 0
	global_load_lds_dwordx4 v1, s[10:11]
	s_mov_b32 m0, s35
	s_nop 0
	global_load_lds_dwordx4 v147, s[10:11]
	s_waitcnt vmcnt(8)
	s_waitcnt lgkmcnt(0)
	s_barrier
	s_setprio 1
	v_mfma_f32_16x16x32_bf16 v[126:129], v[136:139], v[182:185], v[126:129]
	v_mfma_f32_16x16x32_bf16 v[118:121], v[158:161], v[182:185], v[118:121]
	v_mfma_f32_16x16x32_bf16 v[110:113], v[136:139], v[190:193], v[110:113]
	v_mfma_f32_16x16x32_bf16 v[102:105], v[158:161], v[190:193], v[102:105]
	v_mfma_f32_16x16x32_bf16 v[94:97], v[136:139], v[198:201], v[94:97]
	v_mfma_f32_16x16x32_bf16 v[86:89], v[158:161], v[198:201], v[86:89]
	v_mfma_f32_16x16x32_bf16 v[78:81], v[136:139], v[206:209], v[78:81]
	v_mfma_f32_16x16x32_bf16 v[70:73], v[158:161], v[206:209], v[70:73]
	v_mfma_f32_16x16x32_bf16 v[126:129], v[140:143], v[186:189], v[126:129]
	v_mfma_f32_16x16x32_bf16 v[118:121], v[162:165], v[186:189], v[118:121]
	v_mfma_f32_16x16x32_bf16 v[110:113], v[140:143], v[194:197], v[110:113]
	v_mfma_f32_16x16x32_bf16 v[102:105], v[162:165], v[194:197], v[102:105]
	v_mfma_f32_16x16x32_bf16 v[94:97], v[140:143], v[202:205], v[94:97]
	v_mfma_f32_16x16x32_bf16 v[86:89], v[162:165], v[202:205], v[86:89]
	v_mfma_f32_16x16x32_bf16 v[78:81], v[140:143], v[210:213], v[78:81]
	v_mfma_f32_16x16x32_bf16 v[70:73], v[162:165], v[210:213], v[70:73]
	v_mfma_f32_16x16x32_bf16 v[122:125], v[166:169], v[182:185], v[122:125]
	v_mfma_f32_16x16x32_bf16 v[114:117], v[174:177], v[182:185], v[114:117]
	v_mfma_f32_16x16x32_bf16 v[106:109], v[166:169], v[190:193], v[106:109]
	v_mfma_f32_16x16x32_bf16 v[98:101], v[174:177], v[190:193], v[98:101]
	v_mfma_f32_16x16x32_bf16 v[90:93], v[166:169], v[198:201], v[90:93]
	v_mfma_f32_16x16x32_bf16 v[82:85], v[174:177], v[198:201], v[82:85]
	v_mfma_f32_16x16x32_bf16 v[74:77], v[166:169], v[206:209], v[74:77]
	v_mfma_f32_16x16x32_bf16 v[66:69], v[174:177], v[206:209], v[66:69]
	v_mfma_f32_16x16x32_bf16 v[122:125], v[170:173], v[186:189], v[122:125]
	v_mfma_f32_16x16x32_bf16 v[114:117], v[178:181], v[186:189], v[114:117]
	v_mfma_f32_16x16x32_bf16 v[106:109], v[170:173], v[194:197], v[106:109]
	v_mfma_f32_16x16x32_bf16 v[98:101], v[178:181], v[194:197], v[98:101]
	v_mfma_f32_16x16x32_bf16 v[90:93], v[170:173], v[202:205], v[90:93]
	v_mfma_f32_16x16x32_bf16 v[82:85], v[178:181], v[202:205], v[82:85]
	v_mfma_f32_16x16x32_bf16 v[74:77], v[170:173], v[210:213], v[74:77]
	v_mfma_f32_16x16x32_bf16 v[66:69], v[178:181], v[210:213], v[66:69]
	s_setprio 0
	s_barrier
; #define PG8_STAGE(bufoff, gbase, voff) do { if constexpr (VAR != 1 && VAR != 3) { _Pragma("unroll") for (int _i = 0; _i < 2; ++_i) \
;         asm volatile("s_mov_b32 m0, %2\n\ts_nop 0\n\tglobal_load_lds_dwordx4 %0, %1" :: "v"((voff)[_i]), "s"((const char*)(gbase)), "s"(ldsbase + (unsigned)((bufoff) + _i * 8192)) : "memory", "m0"); } } while (0)
; #define PG8_LDA(dst, b, h) do { if constexpr (VAR < 2) _Pragma("unroll") for (int m = 0; m < 4; ++m) _Pragma("unroll") for (int k = 0; k < 2; ++k) dst[m][k] = *(const LAS bf16x8*)(lds + PG8_SA(b, h) + aoff + m * 2048 + k * 1024); } while (0)
; #define PG8_LDB(dst, b, h) do { if constexpr (VAR < 2) _Pragma("unroll") for (int n = 0; n < 2; ++n) _Pragma("unroll") for (int k = 0; k < 2; ++k) dst[n][k] = *(const LAS bf16x8*)(lds + PG8_SB(b, h) + boff + n * 2048 + k * 1024); } while (0)
; #define PG8_WAIT_V(n) asm volatile("s_waitcnt vmcnt(" #n ")" ::: "memory")
; #define PG8_WAIT_L(n) asm volatile("s_waitcnt lgkmcnt(" #n ")" ::: "memory")
;     ...
;         for (int t = 0; t < nt; t += 2) {
;             const bool last = (t == nt - 2);
;             const char* a1 = cA + (size_t)(t + 1) * kstep;
;             const char* a2 = last ? nA : cA + (size_t)(t + 2) * kstep; const char* b2 = last ? nB : cB + (size_t)(t + 2) * kstep;
;             const char* a3 = a2 + kstep; const char* b3 = b2 + kstep;
;             PG8_LDB(B0, 0, 0); PG8_LDB(B1, 0, 1); PG8_SCHED; PG8_LDA(At, 0, 0); PG8_STAGE(PG8_SA(1, 1), a1 + hstepA, voffA);
;             PG8_WAIT_V(8); PG8_WAIT_L(0); PG8_BAR; PG8_MMA(0, 0, At, B0); PG8_MMA(0, 1, At, B1); PG8_BAR; PG8_SCHED;
;             PG8_LDA(At, 0, 1); PG8_STAGE(PG8_SB(0, 0), b2, voffB); PG8_STAGE(PG8_SB(0, 1), b2 + hstepB, voffB); PG8_STAGE(PG8_SA(0, 0), a2, voffA);
;             PG8_WAIT_V(8); PG8_WAIT_L(0); PG8_BAR; PG8_MMA(1, 0, At, B0); PG8_MMA(1, 1, At, B1); PG8_BAR; PG8_SCHED;
;             PG8_LDB(B0, 1, 0); PG8_LDB(B1, 1, 1); PG8_SCHED; PG8_LDA(At, 1, 0); PG8_STAGE(PG8_SA(0, 1), a2 + hstepA, voffA);
;             PG8_WAIT_V(8); PG8_WAIT_L(0); PG8_BAR; PG8_MMA(0, 0, At, B0); PG8_MMA(0, 1, At, B1); PG8_BAR; PG8_SCHED;
;             PG8_LDA(At, 1, 1); PG8_STAGE(PG8_SB(1, 0), b3, voffB); PG8_STAGE(PG8_SB(1, 1), b3 + hstepB, voffB); PG8_STAGE(PG8_SA(1, 0), a3, voffA);
;             PG8_WAIT_V(8); PG8_WAIT_L(0); PG8_BAR; PG8_MMA(1, 0, At, B0); PG8_MMA(1, 1, At, B1); PG8_BAR; PG8_SCHED;
	ds_read_b128 v[182:185], v154 offset:49152
	ds_read_b128 v[186:189], v154 offset:50176
	ds_read_b128 v[190:193], v154 offset:51200
	ds_read_b128 v[194:197], v154 offset:52224
	ds_read_b128 v[198:201], v154 offset:53248
	ds_read_b128 v[202:205], v154 offset:54272
	ds_read_b128 v[206:209], v154 offset:55296
	ds_read_b128 v[210:213], v154 offset:56320
	s_add_u32 s10, s74, 0x80
	s_addc_u32 s11, s75, 0
	s_mov_b32 m0, s52
	s_nop 0
	global_load_lds_dwordx4 v146, s[10:11]
	s_mov_b32 m0, s53
	s_nop 0
	global_load_lds_dwordx4 v148, s[10:11]
	s_add_u32 s10, s74, 0x100080
	s_addc_u32 s11, s75, 0
	s_mov_b32 m0, s62
	s_nop 0
	global_load_lds_dwordx4 v146, s[10:11]
	s_mov_b32 m0, s63
	s_nop 0
	global_load_lds_dwordx4 v148, s[10:11]
	s_mov_b32 m0, s56
	s_nop 0
	global_load_lds_dwordx4 v1, s[72:73]
	s_mov_b32 m0, s57
	s_nop 0
	global_load_lds_dwordx4 v147, s[72:73]
	s_waitcnt vmcnt(8)
	s_waitcnt lgkmcnt(0)
	s_barrier
	s_setprio 1
	v_mfma_f32_16x16x32_bf16 v[62:65], v[136:139], v[182:185], v[62:65]
	v_mfma_f32_16x16x32_bf16 v[54:57], v[158:161], v[182:185], v[54:57]
	v_mfma_f32_16x16x32_bf16 v[46:49], v[136:139], v[190:193], v[46:49]
	v_mfma_f32_16x16x32_bf16 v[38:41], v[158:161], v[190:193], v[38:41]
	v_mfma_f32_16x16x32_bf16 v[30:33], v[136:139], v[198:201], v[30:33]
	v_mfma_f32_16x16x32_bf16 v[22:25], v[158:161], v[198:201], v[22:25]
	v_mfma_f32_16x16x32_bf16 v[14:17], v[136:139], v[206:209], v[14:17]
	v_mfma_f32_16x16x32_bf16 v[6:9], v[158:161], v[206:209], v[6:9]
	v_mfma_f32_16x16x32_bf16 v[62:65], v[140:143], v[186:189], v[62:65]
	v_mfma_f32_16x16x32_bf16 v[54:57], v[162:165], v[186:189], v[54:57]
	v_mfma_f32_16x16x32_bf16 v[46:49], v[140:143], v[194:197], v[46:49]
	v_mfma_f32_16x16x32_bf16 v[38:41], v[162:165], v[194:197], v[38:41]
	v_mfma_f32_16x16x32_bf16 v[30:33], v[140:143], v[202:205], v[30:33]
	v_mfma_f32_16x16x32_bf16 v[22:25], v[162:165], v[202:205], v[22:25]
	v_mfma_f32_16x16x32_bf16 v[14:17], v[140:143], v[210:213], v[14:17]
	v_mfma_f32_16x16x32_bf16 v[6:9], v[162:165], v[210:213], v[6:9]
	v_mfma_f32_16x16x32_bf16 v[58:61], v[166:169], v[182:185], v[58:61]
	v_mfma_f32_16x16x32_bf16 v[50:53], v[174:177], v[182:185], v[50:53]
	v_mfma_f32_16x16x32_bf16 v[42:45], v[166:169], v[190:193], v[42:45]
	v_mfma_f32_16x16x32_bf16 v[34:37], v[174:177], v[190:193], v[34:37]
	v_mfma_f32_16x16x32_bf16 v[26:29], v[166:169], v[198:201], v[26:29]
	v_mfma_f32_16x16x32_bf16 v[18:21], v[174:177], v[198:201], v[18:21]
	v_mfma_f32_16x16x32_bf16 v[10:13], v[166:169], v[206:209], v[10:13]
	v_mfma_f32_16x16x32_bf16 v[2:5], v[174:177], v[206:209], v[2:5]
	v_mfma_f32_16x16x32_bf16 v[58:61], v[170:173], v[186:189], v[58:61]
	v_mfma_f32_16x16x32_bf16 v[50:53], v[178:181], v[186:189], v[50:53]
	v_mfma_f32_16x16x32_bf16 v[42:45], v[170:173], v[194:197], v[42:45]
	v_mfma_f32_16x16x32_bf16 v[34:37], v[178:181], v[194:197], v[34:37]
	v_mfma_f32_16x16x32_bf16 v[26:29], v[170:173], v[202:205], v[26:29]
	v_mfma_f32_16x16x32_bf16 v[18:21], v[178:181], v[202:205], v[18:21]
	v_mfma_f32_16x16x32_bf16 v[10:13], v[170:173], v[210:213], v[10:13]
	v_mfma_f32_16x16x32_bf16 v[2:5], v[178:181], v[210:213], v[2:5]
	s_setprio 0
	s_barrier
	s_add_i32 s6, s6, 2
	s_add_u32 s65, s65, 0x100
	s_addc_u32 s92, s92, 0
	s_add_u32 s93, s93, 0x100
	s_addc_u32 s94, s94, 0
	s_add_u32 s70, s70, 0x100
	s_addc_u32 s71, s71, 0
	s_cmp_gt_u32 s6, 61
	s_cbranch_scc0 .LBB0_561
	s_branch .Lmy_kexit_2
.LBB0_561:
	ds_read_b128 v[136:139], v152
	ds_read_b128 v[140:143], v152 offset:1024
	ds_read_b128 v[158:161], v152 offset:2048
	ds_read_b128 v[162:165], v152 offset:3072
	ds_read_b128 v[166:169], v153
	ds_read_b128 v[170:173], v153 offset:1024
	ds_read_b128 v[174:177], v153 offset:2048
	ds_read_b128 v[178:181], v153 offset:3072
	s_cmp_eq_u32 s6, 60
	s_cselect_b32 s84, s14, s65
	s_cselect_b32 s85, s1, s92
	s_cselect_b32 s74, s61, s93
	s_cselect_b32 s75, s15, s94
	s_add_u32 s72, s84, 0x80
	s_addc_u32 s73, s85, 0
	ds_read_b128 v[182:185], v154
	ds_read_b128 v[186:189], v154 offset:1024
	ds_read_b128 v[190:193], v154 offset:2048
	ds_read_b128 v[194:197], v154 offset:3072
	ds_read_b128 v[198:201], v154 offset:4096
	ds_read_b128 v[202:205], v154 offset:5120
	ds_read_b128 v[206:209], v154 offset:6144
	ds_read_b128 v[210:213], v154 offset:7168
	s_mov_b32 m0, s86
	s_nop 0
	global_load_lds_dwordx4 v1, s[70:71]
	s_mov_b32 m0, s87
	s_nop 0
	global_load_lds_dwordx4 v147, s[70:71]
	s_waitcnt vmcnt(8)
	s_waitcnt lgkmcnt(0)
	s_barrier
	s_setprio 1
	v_mfma_f32_16x16x32_bf16 v[126:129], v[136:139], v[182:185], v[126:129]
	v_mfma_f32_16x16x32_bf16 v[118:121], v[158:161], v[182:185], v[118:121]
	v_mfma_f32_16x16x32_bf16 v[110:113], v[136:139], v[190:193], v[110:113]
	v_mfma_f32_16x16x32_bf16 v[102:105], v[158:161], v[190:193], v[102:105]
	v_mfma_f32_16x16x32_bf16 v[94:97], v[136:139], v[198:201], v[94:97]
	v_mfma_f32_16x16x32_bf16 v[86:89], v[158:161], v[198:201], v[86:89]
	v_mfma_f32_16x16x32_bf16 v[78:81], v[136:139], v[206:209], v[78:81]
	v_mfma_f32_16x16x32_bf16 v[70:73], v[158:161], v[206:209], v[70:73]
	v_mfma_f32_16x16x32_bf16 v[126:129], v[140:143], v[186:189], v[126:129]
	v_mfma_f32_16x16x32_bf16 v[118:121], v[162:165], v[186:189], v[118:121]
	v_mfma_f32_16x16x32_bf16 v[110:113], v[140:143], v[194:197], v[110:113]
	v_mfma_f32_16x16x32_bf16 v[102:105], v[162:165], v[194:197], v[102:105]
	v_mfma_f32_16x16x32_bf16 v[94:97], v[140:143], v[202:205], v[94:97]
	v_mfma_f32_16x16x32_bf16 v[86:89], v[162:165], v[202:205], v[86:89]
	v_mfma_f32_16x16x32_bf16 v[78:81], v[140:143], v[210:213], v[78:81]
	v_mfma_f32_16x16x32_bf16 v[70:73], v[162:165], v[210:213], v[70:73]
	v_mfma_f32_16x16x32_bf16 v[122:125], v[166:169], v[182:185], v[122:125]
	v_mfma_f32_16x16x32_bf16 v[114:117], v[174:177], v[182:185], v[114:117]
	v_mfma_f32_16x16x32_bf16 v[106:109], v[166:169], v[190:193], v[106:109]
	v_mfma_f32_16x16x32_bf16 v[98:101], v[174:177], v[190:193], v[98:101]
	v_mfma_f32_16x16x32_bf16 v[90:93], v[166:169], v[198:201], v[90:93]
	v_mfma_f32_16x16x32_bf16 v[82:85], v[174:177], v[198:201], v[82:85]
	v_mfma_f32_16x16x32_bf16 v[74:77], v[166:169], v[206:209], v[74:77]
	v_mfma_f32_16x16x32_bf16 v[66:69], v[174:177], v[206:209], v[66:69]
	v_mfma_f32_16x16x32_bf16 v[122:125], v[170:173], v[186:189], v[122:125]
	v_mfma_f32_16x16x32_bf16 v[114:117], v[178:181], v[186:189], v[114:117]
	v_mfma_f32_16x16x32_bf16 v[106:109], v[170:173], v[194:197], v[106:109]
	v_mfma_f32_16x16x32_bf16 v[98:101], v[178:181], v[194:197], v[98:101]
	v_mfma_f32_16x16x32_bf16 v[90:93], v[170:173], v[202:205], v[90:93]
	v_mfma_f32_16x16x32_bf16 v[82:85], v[178:181], v[202:205], v[82:85]
	v_mfma_f32_16x16x32_bf16 v[74:77], v[170:173], v[210:213], v[74:77]
	v_mfma_f32_16x16x32_bf16 v[66:69], v[178:181], v[210:213], v[66:69]
	s_setprio 0
	s_barrier
; #define PG8_STAGE(bufoff, gbase, voff) do { if constexpr (VAR != 1 && VAR != 3) { _Pragma("unroll") for (int _i = 0; _i < 2; ++_i) \
;         asm volatile("s_mov_b32 m0, %2\n\ts_nop 0\n\tglobal_load_lds_dwordx4 %0, %1" :: "v"((voff)[_i]), "s"((const char*)(gbase)), "s"(ldsbase + (unsigned)((bufoff) + _i * 8192)) : "memory", "m0"); } } while (0)
; #define PG8_LDA(dst, b, h) do { if constexpr (VAR < 2) _Pragma("unroll") for (int m = 0; m < 4; ++m) _Pragma("unroll") for (int k = 0; k < 2; ++k) dst[m][k] = *(const LAS bf16x8*)(lds + PG8_SA(b, h) + aoff + m * 2048 + k * 1024); } while (0)
; #define PG8_LDB(dst, b, h) do { if constexpr (VAR < 2) _Pragma("unroll") for (int n = 0; n < 2; ++n) _Pragma("unroll") for (int k = 0; k < 2; ++k) dst[n][k] = *(const LAS bf16x8*)(lds + PG8_SB(b, h) + boff + n * 2048 + k * 1024); } while (0)
; #define PG8_WAIT_V(n) asm volatile("s_waitcnt vmcnt(" #n ")" ::: "memory")
; #define PG8_WAIT_L(n) asm volatile("s_waitcnt lgkmcnt(" #n ")" ::: "memory")
; #define PG8_BAR do { if constexpr (VAR != 3) __builtin_amdgcn_s_barrier(); } while (0)
; #define PG8_SCHED __builtin_amdgcn_sched_barrier(0)
;     ...
;             PG8_LDA(At, 0, 1); PG8_STAGE(PG8_SB(0, 0), b2, voffB); PG8_STAGE(PG8_SB(0, 1), b2 + hstepB, voffB); PG8_STAGE(PG8_SA(0, 0), a2, voffA);
;             PG8_WAIT_V(8); PG8_WAIT_L(0); PG8_BAR; PG8_MMA(1, 0, At, B0); PG8_MMA(1, 1, At, B1); PG8_BAR; PG8_SCHED;
;             PG8_LDB(B0, 1, 0); PG8_LDB(B1, 1, 1); PG8_SCHED; PG8_LDA(At, 1, 0); PG8_STAGE(PG8_SA(0, 1), a2 + hstepA, voffA);
;             PG8_WAIT_V(8); PG8_WAIT_L(0); PG8_BAR; PG8_MMA(0, 0, At, B0); PG8_MMA(0, 1, At, B1); PG8_BAR; PG8_SCHED;
	ds_read_b128 v[182:185], v154 offset:16384
	ds_read_b128 v[186:189], v154 offset:17408
	ds_read_b128 v[190:193], v154 offset:18432
	ds_read_b128 v[194:197], v154 offset:19456
	ds_read_b128 v[198:201], v154 offset:20480
	ds_read_b128 v[202:205], v154 offset:21504
	ds_read_b128 v[206:209], v154 offset:22528
	ds_read_b128 v[210:213], v154 offset:23552
	s_mov_b32 m0, s21
	s_nop 0
	global_load_lds_dwordx4 v146, s[74:75]
	s_add_u32 s10, s74, 0x100000
	s_mov_b32 m0, s23
	s_nop 0
	global_load_lds_dwordx4 v148, s[74:75]
	s_addc_u32 s11, s75, 0
	s_mov_b32 m0, s29
	s_nop 0
	global_load_lds_dwordx4 v146, s[10:11]
	s_mov_b32 m0, s30
	s_nop 0
	global_load_lds_dwordx4 v148, s[10:11]
	s_mov_b32 m0, s25
	s_nop 0
	global_load_lds_dwordx4 v1, s[84:85]
	s_mov_b32 m0, s31
	s_nop 0
	global_load_lds_dwordx4 v147, s[84:85]
	s_waitcnt vmcnt(8)
	s_waitcnt lgkmcnt(0)
	s_barrier
	s_setprio 1
	v_mfma_f32_16x16x32_bf16 v[62:65], v[136:139], v[182:185], v[62:65]
	v_mfma_f32_16x16x32_bf16 v[54:57], v[158:161], v[182:185], v[54:57]
	v_mfma_f32_16x16x32_bf16 v[46:49], v[136:139], v[190:193], v[46:49]
	v_mfma_f32_16x16x32_bf16 v[38:41], v[158:161], v[190:193], v[38:41]
	v_mfma_f32_16x16x32_bf16 v[30:33], v[136:139], v[198:201], v[30:33]
	v_mfma_f32_16x16x32_bf16 v[22:25], v[158:161], v[198:201], v[22:25]
	v_mfma_f32_16x16x32_bf16 v[14:17], v[136:139], v[206:209], v[14:17]
	v_mfma_f32_16x16x32_bf16 v[6:9], v[158:161], v[206:209], v[6:9]
	v_mfma_f32_16x16x32_bf16 v[62:65], v[140:143], v[186:189], v[62:65]
	v_mfma_f32_16x16x32_bf16 v[54:57], v[162:165], v[186:189], v[54:57]
	v_mfma_f32_16x16x32_bf16 v[46:49], v[140:143], v[194:197], v[46:49]
	v_mfma_f32_16x16x32_bf16 v[38:41], v[162:165], v[194:197], v[38:41]
	v_mfma_f32_16x16x32_bf16 v[30:33], v[140:143], v[202:205], v[30:33]
	v_mfma_f32_16x16x32_bf16 v[22:25], v[162:165], v[202:205], v[22:25]
	v_mfma_f32_16x16x32_bf16 v[14:17], v[140:143], v[210:213], v[14:17]
	v_mfma_f32_16x16x32_bf16 v[6:9], v[162:165], v[210:213], v[6:9]
	v_mfma_f32_16x16x32_bf16 v[58:61], v[166:169], v[182:185], v[58:61]
	v_mfma_f32_16x16x32_bf16 v[50:53], v[174:177], v[182:185], v[50:53]
	v_mfma_f32_16x16x32_bf16 v[42:45], v[166:169], v[190:193], v[42:45]
	v_mfma_f32_16x16x32_bf16 v[34:37], v[174:177], v[190:193], v[34:37]
	v_mfma_f32_16x16x32_bf16 v[26:29], v[166:169], v[198:201], v[26:29]
	v_mfma_f32_16x16x32_bf16 v[18:21], v[174:177], v[198:201], v[18:21]
	v_mfma_f32_16x16x32_bf16 v[10:13], v[166:169], v[206:209], v[10:13]
	v_mfma_f32_16x16x32_bf16 v[2:5], v[174:177], v[206:209], v[2:5]
	v_mfma_f32_16x16x32_bf16 v[58:61], v[170:173], v[186:189], v[58:61]
	v_mfma_f32_16x16x32_bf16 v[50:53], v[178:181], v[186:189], v[50:53]
	v_mfma_f32_16x16x32_bf16 v[42:45], v[170:173], v[194:197], v[42:45]
	v_mfma_f32_16x16x32_bf16 v[34:37], v[178:181], v[194:197], v[34:37]
	v_mfma_f32_16x16x32_bf16 v[26:29], v[170:173], v[202:205], v[26:29]
	v_mfma_f32_16x16x32_bf16 v[18:21], v[178:181], v[202:205], v[18:21]
	v_mfma_f32_16x16x32_bf16 v[10:13], v[170:173], v[210:213], v[10:13]
	v_mfma_f32_16x16x32_bf16 v[2:5], v[178:181], v[210:213], v[2:5]
	s_setprio 0
	s_barrier
	ds_read_b128 v[136:139], v155
	ds_read_b128 v[140:143], v155 offset:1024
	ds_read_b128 v[158:161], v155 offset:2048
	ds_read_b128 v[162:165], v155 offset:3072
	ds_read_b128 v[166:169], v156
	ds_read_b128 v[170:173], v156 offset:1024
	ds_read_b128 v[174:177], v156 offset:2048
	ds_read_b128 v[178:181], v156 offset:3072
	ds_read_b128 v[182:185], v154 offset:32768
	ds_read_b128 v[186:189], v154 offset:33792
	ds_read_b128 v[190:193], v154 offset:34816
	ds_read_b128 v[194:197], v154 offset:35840
	ds_read_b128 v[198:201], v154 offset:36864
	ds_read_b128 v[202:205], v154 offset:37888
	ds_read_b128 v[206:209], v154 offset:38912
	ds_read_b128 v[210:213], v154 offset:39936
	s_add_u32 s10, s84, 0x100000
	s_addc_u32 s11, s85, 0
	s_mov_b32 m0, s33
	s_nop 0
	global_load_lds_dwordx4 v1, s[10:11]
	s_mov_b32 m0, s35
	s_nop 0
	global_load_lds_dwordx4 v147, s[10:11]
	s_waitcnt vmcnt(8)
	s_waitcnt lgkmcnt(0)
	s_barrier
; #define PG8_STAGE(bufoff, gbase, voff) do { if constexpr (VAR != 1 && VAR != 3) { _Pragma("unroll") for (int _i = 0; _i < 2; ++_i) \
;         asm volatile("s_mov_b32 m0, %2\n\ts_nop 0\n\tglobal_load_lds_dwordx4 %0, %1" :: "v"((voff)[_i]), "s"((const char*)(gbase)), "s"(ldsbase + (unsigned)((bufoff) + _i * 8192)) : "memory", "m0"); } } while (0)
; #define PG8_LDA(dst, b, h) do { if constexpr (VAR < 2) _Pragma("unroll") for (int m = 0; m < 4; ++m) _Pragma("unroll") for (int k = 0; k < 2; ++k) dst[m][k] = *(const LAS bf16x8*)(lds + PG8_SA(b, h) + aoff + m * 2048 + k * 1024); } while (0)
; #define PG8_WAIT_V(n) asm volatile("s_waitcnt vmcnt(" #n ")" ::: "memory")
; #define PG8_WAIT_L(n) asm volatile("s_waitcnt lgkmcnt(" #n ")" ::: "memory")
; #define PG8_BAR do { if constexpr (VAR != 3) __builtin_amdgcn_s_barrier(); } while (0)
; #define PG8_SCHED __builtin_amdgcn_sched_barrier(0)
;     ...
;             PG8_WAIT_V(8); PG8_WAIT_L(0); PG8_BAR; PG8_MMA(0, 0, At, B0); PG8_MMA(0, 1, At, B1); PG8_BAR; PG8_SCHED;
;             PG8_LDA(At, 1, 1); PG8_STAGE(PG8_SB(1, 0), b3, voffB); PG8_STAGE(PG8_SB(1, 1), b3 + hstepB, voffB); PG8_STAGE(PG8_SA(1, 0), a3, voffA);
;             PG8_WAIT_V(8); PG8_WAIT_L(0); PG8_BAR; PG8_MMA(1, 0, At, B0); PG8_MMA(1, 1, At, B1); PG8_BAR; PG8_SCHED;
;         }
;         if (wr == 0) PG8_BAR;
	s_setprio 1
	v_mfma_f32_16x16x32_bf16 v[126:129], v[136:139], v[182:185], v[126:129]
	v_mfma_f32_16x16x32_bf16 v[118:121], v[158:161], v[182:185], v[118:121]
	v_mfma_f32_16x16x32_bf16 v[110:113], v[136:139], v[190:193], v[110:113]
	v_mfma_f32_16x16x32_bf16 v[102:105], v[158:161], v[190:193], v[102:105]
	v_mfma_f32_16x16x32_bf16 v[94:97], v[136:139], v[198:201], v[94:97]
	v_mfma_f32_16x16x32_bf16 v[86:89], v[158:161], v[198:201], v[86:89]
	v_mfma_f32_16x16x32_bf16 v[78:81], v[136:139], v[206:209], v[78:81]
	v_mfma_f32_16x16x32_bf16 v[70:73], v[158:161], v[206:209], v[70:73]
	v_mfma_f32_16x16x32_bf16 v[126:129], v[140:143], v[186:189], v[126:129]
	v_mfma_f32_16x16x32_bf16 v[118:121], v[162:165], v[186:189], v[118:121]
	v_mfma_f32_16x16x32_bf16 v[110:113], v[140:143], v[194:197], v[110:113]
	v_mfma_f32_16x16x32_bf16 v[102:105], v[162:165], v[194:197], v[102:105]
	v_mfma_f32_16x16x32_bf16 v[94:97], v[140:143], v[202:205], v[94:97]
	v_mfma_f32_16x16x32_bf16 v[86:89], v[162:165], v[202:205], v[86:89]
	v_mfma_f32_16x16x32_bf16 v[78:81], v[140:143], v[210:213], v[78:81]
	v_mfma_f32_16x16x32_bf16 v[70:73], v[162:165], v[210:213], v[70:73]
	v_mfma_f32_16x16x32_bf16 v[122:125], v[166:169], v[182:185], v[122:125]
	v_mfma_f32_16x16x32_bf16 v[114:117], v[174:177], v[182:185], v[114:117]
	v_mfma_f32_16x16x32_bf16 v[106:109], v[166:169], v[190:193], v[106:109]
	v_mfma_f32_16x16x32_bf16 v[98:101], v[174:177], v[190:193], v[98:101]
	v_mfma_f32_16x16x32_bf16 v[90:93], v[166:169], v[198:201], v[90:93]
	v_mfma_f32_16x16x32_bf16 v[82:85], v[174:177], v[198:201], v[82:85]
	v_mfma_f32_16x16x32_bf16 v[74:77], v[166:169], v[206:209], v[74:77]
	v_mfma_f32_16x16x32_bf16 v[66:69], v[174:177], v[206:209], v[66:69]
	v_mfma_f32_16x16x32_bf16 v[122:125], v[170:173], v[186:189], v[122:125]
	v_mfma_f32_16x16x32_bf16 v[114:117], v[178:181], v[186:189], v[114:117]
	v_mfma_f32_16x16x32_bf16 v[106:109], v[170:173], v[194:197], v[106:109]
	v_mfma_f32_16x16x32_bf16 v[98:101], v[178:181], v[194:197], v[98:101]
	v_mfma_f32_16x16x32_bf16 v[90:93], v[170:173], v[202:205], v[90:93]
	v_mfma_f32_16x16x32_bf16 v[82:85], v[178:181], v[202:205], v[82:85]
	v_mfma_f32_16x16x32_bf16 v[74:77], v[170:173], v[210:213], v[74:77]
	v_mfma_f32_16x16x32_bf16 v[66:69], v[178:181], v[210:213], v[66:69]
	s_setprio 0
	s_barrier
	ds_read_b128 v[182:185], v154 offset:49152
	ds_read_b128 v[186:189], v154 offset:50176
	ds_read_b128 v[190:193], v154 offset:51200
	ds_read_b128 v[194:197], v154 offset:52224
	ds_read_b128 v[198:201], v154 offset:53248
	ds_read_b128 v[202:205], v154 offset:54272
	ds_read_b128 v[206:209], v154 offset:55296
	ds_read_b128 v[210:213], v154 offset:56320
	s_add_u32 s10, s74, 0x80
	s_addc_u32 s11, s75, 0
	s_mov_b32 m0, s52
	s_nop 0
	global_load_lds_dwordx4 v146, s[10:11]
	s_mov_b32 m0, s53
	s_nop 0
	global_load_lds_dwordx4 v148, s[10:11]
	s_add_u32 s10, s74, 0x100080
	s_addc_u32 s11, s75, 0
	s_mov_b32 m0, s62
	s_nop 0
	global_load_lds_dwordx4 v146, s[10:11]
	s_mov_b32 m0, s63
	s_nop 0
	global_load_lds_dwordx4 v148, s[10:11]
	s_mov_b32 m0, s56
	s_nop 0
	global_load_lds_dwordx4 v1, s[72:73]
	s_mov_b32 m0, s57
	s_nop 0
	global_load_lds_dwordx4 v147, s[72:73]
	s_waitcnt vmcnt(8)
	s_waitcnt lgkmcnt(0)
	s_barrier
	s_setprio 1
	v_mfma_f32_16x16x32_bf16 v[62:65], v[136:139], v[182:185], v[62:65]
	v_mfma_f32_16x16x32_bf16 v[54:57], v[158:161], v[182:185], v[54:57]
	v_mfma_f32_16x16x32_bf16 v[46:49], v[136:139], v[190:193], v[46:49]
	v_mfma_f32_16x16x32_bf16 v[38:41], v[158:161], v[190:193], v[38:41]
	v_mfma_f32_16x16x32_bf16 v[30:33], v[136:139], v[198:201], v[30:33]
	v_mfma_f32_16x16x32_bf16 v[22:25], v[158:161], v[198:201], v[22:25]
	v_mfma_f32_16x16x32_bf16 v[14:17], v[136:139], v[206:209], v[14:17]
	v_mfma_f32_16x16x32_bf16 v[6:9], v[158:161], v[206:209], v[6:9]
	v_mfma_f32_16x16x32_bf16 v[62:65], v[140:143], v[186:189], v[62:65]
	v_mfma_f32_16x16x32_bf16 v[54:57], v[162:165], v[186:189], v[54:57]
	v_mfma_f32_16x16x32_bf16 v[46:49], v[140:143], v[194:197], v[46:49]
	v_mfma_f32_16x16x32_bf16 v[38:41], v[162:165], v[194:197], v[38:41]
	v_mfma_f32_16x16x32_bf16 v[30:33], v[140:143], v[202:205], v[30:33]
	v_mfma_f32_16x16x32_bf16 v[22:25], v[162:165], v[202:205], v[22:25]
	v_mfma_f32_16x16x32_bf16 v[14:17], v[140:143], v[210:213], v[14:17]
	v_mfma_f32_16x16x32_bf16 v[6:9], v[162:165], v[210:213], v[6:9]
	v_mfma_f32_16x16x32_bf16 v[58:61], v[166:169], v[182:185], v[58:61]
	v_mfma_f32_16x16x32_bf16 v[50:53], v[174:177], v[182:185], v[50:53]
	v_mfma_f32_16x16x32_bf16 v[42:45], v[166:169], v[190:193], v[42:45]
	v_mfma_f32_16x16x32_bf16 v[34:37], v[174:177], v[190:193], v[34:37]
	v_mfma_f32_16x16x32_bf16 v[26:29], v[166:169], v[198:201], v[26:29]
	v_mfma_f32_16x16x32_bf16 v[18:21], v[174:177], v[198:201], v[18:21]
	v_mfma_f32_16x16x32_bf16 v[10:13], v[166:169], v[206:209], v[10:13]
	v_mfma_f32_16x16x32_bf16 v[2:5], v[174:177], v[206:209], v[2:5]
	v_mfma_f32_16x16x32_bf16 v[58:61], v[170:173], v[186:189], v[58:61]
	v_mfma_f32_16x16x32_bf16 v[50:53], v[178:181], v[186:189], v[50:53]
	v_mfma_f32_16x16x32_bf16 v[42:45], v[170:173], v[194:197], v[42:45]
	v_mfma_f32_16x16x32_bf16 v[34:37], v[178:181], v[194:197], v[34:37]
	v_mfma_f32_16x16x32_bf16 v[26:29], v[170:173], v[202:205], v[26:29]
	v_mfma_f32_16x16x32_bf16 v[18:21], v[178:181], v[202:205], v[18:21]
	v_mfma_f32_16x16x32_bf16 v[10:13], v[170:173], v[210:213], v[10:13]
	v_mfma_f32_16x16x32_bf16 v[2:5], v[178:181], v[210:213], v[2:5]
	s_setprio 0
	s_barrier
	s_add_i32 s6, s6, 2
	s_add_u32 s65, s65, 0x100
	s_addc_u32 s92, s92, 0
	s_add_u32 s93, s93, 0x100
	s_addc_u32 s94, s94, 0
	s_add_u32 s70, s70, 0x100
	s_addc_u32 s71, s71, 0
	s_cmp_gt_u32 s6, 61
	s_cbranch_scc0 .LBB0_561
.Lmy_kexit_2:
	s_and_b64 vcc, exec, s[54:55]
	s_cbranch_vccz .LBB0_564
	s_barrier

; __device__ __forceinline__ const char* unitA(const Gemm& g, const Unit& u) { return (const char*)(g.A + (size_t)(u.z / g.zdiv) * g.sAhi + (size_t)(u.z % g.zdiv) * g.sAlo + (size_t)u.pm * BM * g.lda); }
; __device__ __forceinline__ const char* unitB(const Gemm& g, const Unit& u) { return (const char*)(g.Bt + (size_t)(u.z / g.zdiv) * g.sBhi + (size_t)(u.z % g.zdiv) * g.sBlo + (size_t)(u.pm / g.bdiv) * g.sBpm + (size_t)u.pn * BM * g.ldb); }
; #define PG8_STAGE(bufoff, gbase, voff) do { if constexpr (VAR != 1 && VAR != 3) { _Pragma("unroll") for (int _i = 0; _i < 2; ++_i) \
;         asm volatile("s_mov_b32 m0, %2\n\ts_nop 0\n\tglobal_load_lds_dwordx4 %0, %1" :: "v"((voff)[_i]), "s"((const char*)(gbase)), "s"(ldsbase + (unsigned)((bufoff) + _i * 8192)) : "memory", "m0"); } } while (0)
; #define PG8_LDA(dst, b, h) do { if constexpr (VAR < 2) _Pragma("unroll") for (int m = 0; m < 4; ++m) _Pragma("unroll") for (int k = 0; k < 2; ++k) dst[m][k] = *(const LAS bf16x8*)(lds + PG8_SA(b, h) + aoff + m * 2048 + k * 1024); } while (0)
; #define PG8_LDB(dst, b, h) do { if constexpr (VAR < 2) _Pragma("unroll") for (int n = 0; n < 2; ++n) _Pragma("unroll") for (int k = 0; k < 2; ++k) dst[n][k] = *(const LAS bf16x8*)(lds + PG8_SB(b, h) + boff + n * 2048 + k * 1024); } while (0)
; #define PG8_WAIT_V(n) asm volatile("s_waitcnt vmcnt(" #n ")" ::: "memory")
; #define PG8_SCHED __builtin_amdgcn_sched_barrier(0)
;     ...
;         const char* nA = has_next ? unitA(g, nxt) : cA; const char* nB = has_next ? unitB(g, nxt) : cB;
;         for (int t = 0; t < nt; t += 2) {
;             const bool last = (t == nt - 2);
;             const char* a1 = cA + (size_t)(t + 1) * kstep;
;             const char* a2 = last ? nA : cA + (size_t)(t + 2) * kstep; const char* b2 = last ? nB : cB + (size_t)(t + 2) * kstep;
;             const char* a3 = a2 + kstep; const char* b3 = b2 + kstep;
;             PG8_LDB(B0, 0, 0); PG8_LDB(B1, 0, 1); PG8_SCHED; PG8_LDA(At, 0, 0); PG8_STAGE(PG8_SA(1, 1), a1 + hstepA, voffA);
;             PG8_WAIT_V(8); PG8_WAIT_L(0); PG8_BAR; PG8_MMA(0, 0, At, B0); PG8_MMA(0, 1, At, B1); PG8_BAR; PG8_SCHED;
;             PG8_LDA(At, 0, 1); PG8_STAGE(PG8_SB(0, 0), b2, voffB); PG8_STAGE(PG8_SB(0, 1), b2 + hstepB, voffB); PG8_STAGE(PG8_SA(0, 0), a2, voffA);
;             PG8_WAIT_V(8); PG8_WAIT_L(0); PG8_BAR; PG8_MMA(1, 0, At, B0); PG8_MMA(1, 1, At, B1); PG8_BAR; PG8_SCHED;
.LBB0_672:
	s_add_u32 s75, s78, 0x100
	s_addc_u32 s92, s79, 0
	s_add_u32 s93, s4, 0x100
	s_addc_u32 s94, s5, 0
	s_add_u32 s4, s78, 0x200080
	s_addc_u32 s5, s79, 0
	s_mov_b32 s6, -2
	s_waitcnt vmcnt(34)
	s_waitcnt vmcnt(32)
	ds_read_b128 v[150:153], v183
	ds_read_b128 v[154:157], v183 offset:1024
	ds_read_b128 v[158:161], v183 offset:2048
	ds_read_b128 v[162:165], v183 offset:3072
	ds_read_b128 v[166:169], v184
	ds_read_b128 v[188:191], v184 offset:1024
	ds_read_b128 v[192:195], v184 offset:2048
	ds_read_b128 v[196:199], v184 offset:3072
	s_cmp_eq_u32 s6, 12
	s_cselect_b32 s82, s0, s75
	s_cselect_b32 s83, s1, s92
	s_cselect_b32 s80, s76, s93
	s_cselect_b32 s81, s77, s94
	s_add_u32 s78, s82, 0x80
	s_addc_u32 s79, s83, 0
	ds_read_b128 v[200:203], v185
	ds_read_b128 v[204:207], v185 offset:1024
	ds_read_b128 v[208:211], v185 offset:2048
	ds_read_b128 v[212:215], v185 offset:3072
	ds_read_b128 v[216:219], v185 offset:4096
	ds_read_b128 v[220:223], v185 offset:5120
	ds_read_b128 v[224:227], v185 offset:6144
	ds_read_b128 v[228:231], v185 offset:7168
	s_mov_b32 m0, s85
	s_nop 0
	global_load_lds_dwordx4 v178, s[4:5]
	s_mov_b32 m0, s86
	s_nop 0
	global_load_lds_dwordx4 v180, s[4:5]
	s_waitcnt vmcnt(8)
	s_waitcnt lgkmcnt(0)
	s_barrier
	s_setprio 1
	v_mfma_f32_16x16x32_bf16 v[126:129], v[150:153], v[200:203], 0
	v_mfma_f32_16x16x32_bf16 v[122:125], v[158:161], v[200:203], 0
	v_mfma_f32_16x16x32_bf16 v[114:117], v[150:153], v[208:211], 0
	v_mfma_f32_16x16x32_bf16 v[106:109], v[158:161], v[208:211], 0
	v_mfma_f32_16x16x32_bf16 v[98:101], v[150:153], v[216:219], 0
	v_mfma_f32_16x16x32_bf16 v[90:93], v[158:161], v[216:219], 0
	v_mfma_f32_16x16x32_bf16 v[82:85], v[150:153], v[224:227], 0
	v_mfma_f32_16x16x32_bf16 v[74:77], v[158:161], v[224:227], 0
	v_mfma_f32_16x16x32_bf16 v[126:129], v[154:157], v[204:207], v[126:129]
	v_mfma_f32_16x16x32_bf16 v[122:125], v[162:165], v[204:207], v[122:125]
	v_mfma_f32_16x16x32_bf16 v[114:117], v[154:157], v[212:215], v[114:117]
	v_mfma_f32_16x16x32_bf16 v[106:109], v[162:165], v[212:215], v[106:109]
	v_mfma_f32_16x16x32_bf16 v[98:101], v[154:157], v[220:223], v[98:101]
	v_mfma_f32_16x16x32_bf16 v[90:93], v[162:165], v[220:223], v[90:93]
	v_mfma_f32_16x16x32_bf16 v[82:85], v[154:157], v[228:231], v[82:85]
	v_mfma_f32_16x16x32_bf16 v[74:77], v[162:165], v[228:231], v[74:77]
	v_mfma_f32_16x16x32_bf16 v[118:121], v[166:169], v[200:203], 0
	v_mfma_f32_16x16x32_bf16 v[110:113], v[192:195], v[200:203], 0
	v_mfma_f32_16x16x32_bf16 v[102:105], v[166:169], v[208:211], 0
	v_mfma_f32_16x16x32_bf16 v[94:97], v[192:195], v[208:211], 0
	v_mfma_f32_16x16x32_bf16 v[86:89], v[166:169], v[216:219], 0
	v_mfma_f32_16x16x32_bf16 v[78:81], v[192:195], v[216:219], 0
	v_mfma_f32_16x16x32_bf16 v[70:73], v[166:169], v[224:227], 0
	v_mfma_f32_16x16x32_bf16 v[66:69], v[192:195], v[224:227], 0
	v_mfma_f32_16x16x32_bf16 v[118:121], v[188:191], v[204:207], v[118:121]
	v_mfma_f32_16x16x32_bf16 v[110:113], v[196:199], v[204:207], v[110:113]
	v_mfma_f32_16x16x32_bf16 v[102:105], v[188:191], v[212:215], v[102:105]
	v_mfma_f32_16x16x32_bf16 v[94:97], v[196:199], v[212:215], v[94:97]
	v_mfma_f32_16x16x32_bf16 v[86:89], v[188:191], v[220:223], v[86:89]
	v_mfma_f32_16x16x32_bf16 v[78:81], v[196:199], v[220:223], v[78:81]
	v_mfma_f32_16x16x32_bf16 v[70:73], v[188:191], v[228:231], v[70:73]
	v_mfma_f32_16x16x32_bf16 v[66:69], v[196:199], v[228:231], v[66:69]
	s_setprio 0
	s_barrier
	ds_read_b128 v[200:203], v185 offset:16384
	ds_read_b128 v[204:207], v185 offset:17408
	ds_read_b128 v[208:211], v185 offset:18432
	ds_read_b128 v[212:215], v185 offset:19456
	ds_read_b128 v[216:219], v185 offset:20480
	ds_read_b128 v[220:223], v185 offset:21504
	ds_read_b128 v[224:227], v185 offset:22528
	ds_read_b128 v[228:231], v185 offset:23552
	s_mov_b32 m0, s24
	s_nop 0
	global_load_lds_dwordx4 v179, s[80:81]
	s_add_u32 s96, s80, 0x100000
	s_mov_b32 m0, s25
	s_nop 0
	global_load_lds_dwordx4 v181, s[80:81]
	s_addc_u32 s97, s81, 0
	s_mov_b32 m0, s26
	s_nop 0
	global_load_lds_dwordx4 v179, s[96:97]
	s_mov_b32 m0, s27
	s_nop 0
	global_load_lds_dwordx4 v181, s[96:97]
	s_mov_b32 m0, s15
	s_nop 0
	global_load_lds_dwordx4 v178, s[82:83]
	s_mov_b32 m0, s28
	s_nop 0
	global_load_lds_dwordx4 v180, s[82:83]
	s_waitcnt vmcnt(8)
	s_waitcnt lgkmcnt(0)
	s_barrier
	s_setprio 1
	v_mfma_f32_16x16x32_bf16 v[62:65], v[150:153], v[200:203], 0
	v_mfma_f32_16x16x32_bf16 v[58:61], v[158:161], v[200:203], 0
	v_mfma_f32_16x16x32_bf16 v[50:53], v[150:153], v[208:211], 0
	v_mfma_f32_16x16x32_bf16 v[42:45], v[158:161], v[208:211], 0
	v_mfma_f32_16x16x32_bf16 v[34:37], v[150:153], v[216:219], 0
	v_mfma_f32_16x16x32_bf16 v[26:29], v[158:161], v[216:219], 0
	v_mfma_f32_16x16x32_bf16 v[18:21], v[150:153], v[224:227], 0
	v_mfma_f32_16x16x32_bf16 v[10:13], v[158:161], v[224:227], 0
	v_mfma_f32_16x16x32_bf16 v[62:65], v[154:157], v[204:207], v[62:65]
	v_mfma_f32_16x16x32_bf16 v[58:61], v[162:165], v[204:207], v[58:61]
	v_mfma_f32_16x16x32_bf16 v[50:53], v[154:157], v[212:215], v[50:53]
	v_mfma_f32_16x16x32_bf16 v[42:45], v[162:165], v[212:215], v[42:45]
	v_mfma_f32_16x16x32_bf16 v[34:37], v[154:157], v[220:223], v[34:37]
	v_mfma_f32_16x16x32_bf16 v[26:29], v[162:165], v[220:223], v[26:29]
	v_mfma_f32_16x16x32_bf16 v[18:21], v[154:157], v[228:231], v[18:21]
	v_mfma_f32_16x16x32_bf16 v[10:13], v[162:165], v[228:231], v[10:13]
	v_mfma_f32_16x16x32_bf16 v[54:57], v[166:169], v[200:203], 0
	v_mfma_f32_16x16x32_bf16 v[46:49], v[192:195], v[200:203], 0
	v_mfma_f32_16x16x32_bf16 v[38:41], v[166:169], v[208:211], 0
	v_mfma_f32_16x16x32_bf16 v[30:33], v[192:195], v[208:211], 0
	v_mfma_f32_16x16x32_bf16 v[22:25], v[166:169], v[216:219], 0
	v_mfma_f32_16x16x32_bf16 v[14:17], v[192:195], v[216:219], 0
	v_mfma_f32_16x16x32_bf16 v[6:9], v[166:169], v[224:227], 0
	v_mfma_f32_16x16x32_bf16 v[2:5], v[192:195], v[224:227], 0
	v_mfma_f32_16x16x32_bf16 v[54:57], v[188:191], v[204:207], v[54:57]
	v_mfma_f32_16x16x32_bf16 v[46:49], v[196:199], v[204:207], v[46:49]
	v_mfma_f32_16x16x32_bf16 v[38:41], v[188:191], v[212:215], v[38:41]
	v_mfma_f32_16x16x32_bf16 v[30:33], v[196:199], v[212:215], v[30:33]
	v_mfma_f32_16x16x32_bf16 v[22:25], v[188:191], v[220:223], v[22:25]
	v_mfma_f32_16x16x32_bf16 v[14:17], v[196:199], v[220:223], v[14:17]
	v_mfma_f32_16x16x32_bf16 v[6:9], v[188:191], v[228:231], v[6:9]
	v_mfma_f32_16x16x32_bf16 v[2:5], v[196:199], v[228:231], v[2:5]
	s_setprio 0
	s_barrier
; #define PG8_STAGE(bufoff, gbase, voff) do { if constexpr (VAR != 1 && VAR != 3) { _Pragma("unroll") for (int _i = 0; _i < 2; ++_i) \
;         asm volatile("s_mov_b32 m0, %2\n\ts_nop 0\n\tglobal_load_lds_dwordx4 %0, %1" :: "v"((voff)[_i]), "s"((const char*)(gbase)), "s"(ldsbase + (unsigned)((bufoff) + _i * 8192)) : "memory", "m0"); } } while (0)
; #define PG8_LDA(dst, b, h) do { if constexpr (VAR < 2) _Pragma("unroll") for (int m = 0; m < 4; ++m) _Pragma("unroll") for (int k = 0; k < 2; ++k) dst[m][k] = *(const LAS bf16x8*)(lds + PG8_SA(b, h) + aoff + m * 2048 + k * 1024); } while (0)
; #define PG8_LDB(dst, b, h) do { if constexpr (VAR < 2) _Pragma("unroll") for (int n = 0; n < 2; ++n) _Pragma("unroll") for (int k = 0; k < 2; ++k) dst[n][k] = *(const LAS bf16x8*)(lds + PG8_SB(b, h) + boff + n * 2048 + k * 1024); } while (0)
; #define PG8_WAIT_V(n) asm volatile("s_waitcnt vmcnt(" #n ")" ::: "memory")
; #define PG8_WAIT_L(n) asm volatile("s_waitcnt lgkmcnt(" #n ")" ::: "memory")
; #define PG8_BAR do { if constexpr (VAR != 3) __builtin_amdgcn_s_barrier(); } while (0)
; #define PG8_SCHED __builtin_amdgcn_sched_barrier(0)
;     ...
;             PG8_LDB(B0, 1, 0); PG8_LDB(B1, 1, 1); PG8_SCHED; PG8_LDA(At, 1, 0); PG8_STAGE(PG8_SA(0, 1), a2 + hstepA, voffA);
;             PG8_WAIT_V(8); PG8_WAIT_L(0); PG8_BAR; PG8_MMA(0, 0, At, B0); PG8_MMA(0, 1, At, B1); PG8_BAR; PG8_SCHED;
;             PG8_LDA(At, 1, 1); PG8_STAGE(PG8_SB(1, 0), b3, voffB); PG8_STAGE(PG8_SB(1, 1), b3 + hstepB, voffB); PG8_STAGE(PG8_SA(1, 0), a3, voffA);
;             PG8_WAIT_V(8); PG8_WAIT_L(0); PG8_BAR; PG8_MMA(1, 0, At, B0); PG8_MMA(1, 1, At, B1); PG8_BAR; PG8_SCHED;
	ds_read_b128 v[150:153], v186
	ds_read_b128 v[154:157], v186 offset:1024
	ds_read_b128 v[158:161], v186 offset:2048
	ds_read_b128 v[162:165], v186 offset:3072
	ds_read_b128 v[166:169], v187
	ds_read_b128 v[188:191], v187 offset:1024
	ds_read_b128 v[192:195], v187 offset:2048
	ds_read_b128 v[196:199], v187 offset:3072
	ds_read_b128 v[200:203], v185 offset:32768
	ds_read_b128 v[204:207], v185 offset:33792
	ds_read_b128 v[208:211], v185 offset:34816
	ds_read_b128 v[212:215], v185 offset:35840
	ds_read_b128 v[216:219], v185 offset:36864
	ds_read_b128 v[220:223], v185 offset:37888
	ds_read_b128 v[224:227], v185 offset:38912
	ds_read_b128 v[228:231], v185 offset:39936
	s_add_u32 s82, s82, 0x200000
	s_addc_u32 s83, s83, 0
	s_mov_b32 m0, s29
	s_nop 0
	global_load_lds_dwordx4 v178, s[82:83]
	s_mov_b32 m0, s30
	s_nop 0
	global_load_lds_dwordx4 v180, s[82:83]
	s_waitcnt vmcnt(8)
	s_waitcnt lgkmcnt(0)
	s_barrier
	s_setprio 1
	v_mfma_f32_16x16x32_bf16 v[126:129], v[150:153], v[200:203], v[126:129]
	v_mfma_f32_16x16x32_bf16 v[122:125], v[158:161], v[200:203], v[122:125]
	v_mfma_f32_16x16x32_bf16 v[114:117], v[150:153], v[208:211], v[114:117]
	v_mfma_f32_16x16x32_bf16 v[106:109], v[158:161], v[208:211], v[106:109]
	v_mfma_f32_16x16x32_bf16 v[98:101], v[150:153], v[216:219], v[98:101]
	v_mfma_f32_16x16x32_bf16 v[90:93], v[158:161], v[216:219], v[90:93]
	v_mfma_f32_16x16x32_bf16 v[82:85], v[150:153], v[224:227], v[82:85]
	v_mfma_f32_16x16x32_bf16 v[74:77], v[158:161], v[224:227], v[74:77]
	v_mfma_f32_16x16x32_bf16 v[126:129], v[154:157], v[204:207], v[126:129]
	v_mfma_f32_16x16x32_bf16 v[122:125], v[162:165], v[204:207], v[122:125]
	v_mfma_f32_16x16x32_bf16 v[114:117], v[154:157], v[212:215], v[114:117]
	v_mfma_f32_16x16x32_bf16 v[106:109], v[162:165], v[212:215], v[106:109]
	v_mfma_f32_16x16x32_bf16 v[98:101], v[154:157], v[220:223], v[98:101]
	v_mfma_f32_16x16x32_bf16 v[90:93], v[162:165], v[220:223], v[90:93]
	v_mfma_f32_16x16x32_bf16 v[82:85], v[154:157], v[228:231], v[82:85]
	v_mfma_f32_16x16x32_bf16 v[74:77], v[162:165], v[228:231], v[74:77]
	v_mfma_f32_16x16x32_bf16 v[118:121], v[166:169], v[200:203], v[118:121]
	v_mfma_f32_16x16x32_bf16 v[110:113], v[192:195], v[200:203], v[110:113]
	v_mfma_f32_16x16x32_bf16 v[102:105], v[166:169], v[208:211], v[102:105]
	v_mfma_f32_16x16x32_bf16 v[94:97], v[192:195], v[208:211], v[94:97]
	v_mfma_f32_16x16x32_bf16 v[86:89], v[166:169], v[216:219], v[86:89]
	v_mfma_f32_16x16x32_bf16 v[78:81], v[192:195], v[216:219], v[78:81]
	v_mfma_f32_16x16x32_bf16 v[70:73], v[166:169], v[224:227], v[70:73]
	v_mfma_f32_16x16x32_bf16 v[66:69], v[192:195], v[224:227], v[66:69]
	v_mfma_f32_16x16x32_bf16 v[118:121], v[188:191], v[204:207], v[118:121]
	v_mfma_f32_16x16x32_bf16 v[110:113], v[196:199], v[204:207], v[110:113]
	v_mfma_f32_16x16x32_bf16 v[102:105], v[188:191], v[212:215], v[102:105]
	v_mfma_f32_16x16x32_bf16 v[94:97], v[196:199], v[212:215], v[94:97]
	v_mfma_f32_16x16x32_bf16 v[86:89], v[188:191], v[220:223], v[86:89]
	v_mfma_f32_16x16x32_bf16 v[78:81], v[196:199], v[220:223], v[78:81]
	v_mfma_f32_16x16x32_bf16 v[70:73], v[188:191], v[228:231], v[70:73]
	v_mfma_f32_16x16x32_bf16 v[66:69], v[196:199], v[228:231], v[66:69]
	s_setprio 0
	s_barrier
	ds_read_b128 v[200:203], v185 offset:49152
	ds_read_b128 v[204:207], v185 offset:50176
	ds_read_b128 v[208:211], v185 offset:51200
	ds_read_b128 v[212:215], v185 offset:52224
	ds_read_b128 v[216:219], v185 offset:53248
	ds_read_b128 v[220:223], v185 offset:54272
	ds_read_b128 v[224:227], v185 offset:55296
	ds_read_b128 v[228:231], v185 offset:56320
	s_add_u32 s82, s80, 0x80
	s_addc_u32 s83, s81, 0
	s_mov_b32 m0, s31
	s_nop 0
	global_load_lds_dwordx4 v179, s[82:83]
	s_add_u32 s80, s80, 0x100080
	s_mov_b32 m0, s33
	s_nop 0
	global_load_lds_dwordx4 v181, s[82:83]
	s_addc_u32 s81, s81, 0
	s_mov_b32 m0, s73
	s_nop 0
	global_load_lds_dwordx4 v179, s[80:81]
	s_mov_b32 m0, s84
	s_nop 0
	global_load_lds_dwordx4 v181, s[80:81]
	s_mov_b32 m0, s56
	s_nop 0
	global_load_lds_dwordx4 v178, s[78:79]
	s_mov_b32 m0, s57
	s_nop 0
	global_load_lds_dwordx4 v180, s[78:79]
	s_waitcnt vmcnt(8)
	s_waitcnt lgkmcnt(0)
	s_barrier
	s_setprio 1
	v_mfma_f32_16x16x32_bf16 v[62:65], v[150:153], v[200:203], v[62:65]
	v_mfma_f32_16x16x32_bf16 v[58:61], v[158:161], v[200:203], v[58:61]
	v_mfma_f32_16x16x32_bf16 v[50:53], v[150:153], v[208:211], v[50:53]
	v_mfma_f32_16x16x32_bf16 v[42:45], v[158:161], v[208:211], v[42:45]
	v_mfma_f32_16x16x32_bf16 v[34:37], v[150:153], v[216:219], v[34:37]
	v_mfma_f32_16x16x32_bf16 v[26:29], v[158:161], v[216:219], v[26:29]
	v_mfma_f32_16x16x32_bf16 v[18:21], v[150:153], v[224:227], v[18:21]
	v_mfma_f32_16x16x32_bf16 v[10:13], v[158:161], v[224:227], v[10:13]
	v_mfma_f32_16x16x32_bf16 v[62:65], v[154:157], v[204:207], v[62:65]
	v_mfma_f32_16x16x32_bf16 v[58:61], v[162:165], v[204:207], v[58:61]
	v_mfma_f32_16x16x32_bf16 v[50:53], v[154:157], v[212:215], v[50:53]
	v_mfma_f32_16x16x32_bf16 v[42:45], v[162:165], v[212:215], v[42:45]
	v_mfma_f32_16x16x32_bf16 v[34:37], v[154:157], v[220:223], v[34:37]
	v_mfma_f32_16x16x32_bf16 v[26:29], v[162:165], v[220:223], v[26:29]
	v_mfma_f32_16x16x32_bf16 v[18:21], v[154:157], v[228:231], v[18:21]
	v_mfma_f32_16x16x32_bf16 v[10:13], v[162:165], v[228:231], v[10:13]
	v_mfma_f32_16x16x32_bf16 v[54:57], v[166:169], v[200:203], v[54:57]
	v_mfma_f32_16x16x32_bf16 v[46:49], v[192:195], v[200:203], v[46:49]
	v_mfma_f32_16x16x32_bf16 v[38:41], v[166:169], v[208:211], v[38:41]
	v_mfma_f32_16x16x32_bf16 v[30:33], v[192:195], v[208:211], v[30:33]
	v_mfma_f32_16x16x32_bf16 v[22:25], v[166:169], v[216:219], v[22:25]
	v_mfma_f32_16x16x32_bf16 v[14:17], v[192:195], v[216:219], v[14:17]
	v_mfma_f32_16x16x32_bf16 v[6:9], v[166:169], v[224:227], v[6:9]
	v_mfma_f32_16x16x32_bf16 v[2:5], v[192:195], v[224:227], v[2:5]
	v_mfma_f32_16x16x32_bf16 v[54:57], v[188:191], v[204:207], v[54:57]
	v_mfma_f32_16x16x32_bf16 v[46:49], v[196:199], v[204:207], v[46:49]
	v_mfma_f32_16x16x32_bf16 v[38:41], v[188:191], v[212:215], v[38:41]
	v_mfma_f32_16x16x32_bf16 v[30:33], v[196:199], v[212:215], v[30:33]
	v_mfma_f32_16x16x32_bf16 v[22:25], v[188:191], v[220:223], v[22:25]
	v_mfma_f32_16x16x32_bf16 v[14:17], v[196:199], v[220:223], v[14:17]
	v_mfma_f32_16x16x32_bf16 v[6:9], v[188:191], v[228:231], v[6:9]
	v_mfma_f32_16x16x32_bf16 v[2:5], v[196:199], v[228:231], v[2:5]
	s_setprio 0
	s_barrier
	s_add_i32 s6, s6, 2
	s_add_u32 s75, s75, 0x100
	s_addc_u32 s92, s92, 0
	s_add_u32 s93, s93, 0x100
	s_addc_u32 s94, s94, 0
	s_add_u32 s4, s4, 0x100
	s_addc_u32 s5, s5, 0
	s_cmp_gt_u32 s6, 13
	s_cbranch_scc0 .LBB0_673
	s_branch .Lmy_kexit_3
; #define PG8_STAGE(bufoff, gbase, voff) do { if constexpr (VAR != 1 && VAR != 3) { _Pragma("unroll") for (int _i = 0; _i < 2; ++_i) \
;         asm volatile("s_mov_b32 m0, %2\n\ts_nop 0\n\tglobal_load_lds_dwordx4 %0, %1" :: "v"((voff)[_i]), "s"((const char*)(gbase)), "s"(ldsbase + (unsigned)((bufoff) + _i * 8192)) : "memory", "m0"); } } while (0)
; #define PG8_LDA(dst, b, h) do { if constexpr (VAR < 2) _Pragma("unroll") for (int m = 0; m < 4; ++m) _Pragma("unroll") for (int k = 0; k < 2; ++k) dst[m][k] = *(const LAS bf16x8*)(lds + PG8_SA(b, h) + aoff + m * 2048 + k * 1024); } while (0)
; #define PG8_LDB(dst, b, h) do { if constexpr (VAR < 2) _Pragma("unroll") for (int n = 0; n < 2; ++n) _Pragma("unroll") for (int k = 0; k < 2; ++k) dst[n][k] = *(const LAS bf16x8*)(lds + PG8_SB(b, h) + boff + n * 2048 + k * 1024); } while (0)
; #define PG8_WAIT_V(n) asm volatile("s_waitcnt vmcnt(" #n ")" ::: "memory")
; #define PG8_WAIT_L(n) asm volatile("s_waitcnt lgkmcnt(" #n ")" ::: "memory")
; #define PG8_BAR do { if constexpr (VAR != 3) __builtin_amdgcn_s_barrier(); } while (0)
; #define PG8_SCHED __builtin_amdgcn_sched_barrier(0)
;     ...
;             PG8_LDB(B0, 0, 0); PG8_LDB(B1, 0, 1); PG8_SCHED; PG8_LDA(At, 0, 0); PG8_STAGE(PG8_SA(1, 1), a1 + hstepA, voffA);
;             PG8_WAIT_V(8); PG8_WAIT_L(0); PG8_BAR; PG8_MMA(0, 0, At, B0); PG8_MMA(0, 1, At, B1); PG8_BAR; PG8_SCHED;
;             PG8_LDA(At, 0, 1); PG8_STAGE(PG8_SB(0, 0), b2, voffB); PG8_STAGE(PG8_SB(0, 1), b2 + hstepB, voffB); PG8_STAGE(PG8_SA(0, 0), a2, voffA);
;             PG8_WAIT_V(8); PG8_WAIT_L(0); PG8_BAR; PG8_MMA(1, 0, At, B0); PG8_MMA(1, 1, At, B1); PG8_BAR; PG8_SCHED;
.LBB0_673:
	ds_read_b128 v[150:153], v183
	ds_read_b128 v[154:157], v183 offset:1024
	ds_read_b128 v[158:161], v183 offset:2048
	ds_read_b128 v[162:165], v183 offset:3072
	ds_read_b128 v[166:169], v184
	ds_read_b128 v[188:191], v184 offset:1024
	ds_read_b128 v[192:195], v184 offset:2048
	ds_read_b128 v[196:199], v184 offset:3072
	s_cmp_eq_u32 s6, 12
	s_cselect_b32 s82, s0, s75
	s_cselect_b32 s83, s1, s92
	s_cselect_b32 s80, s76, s93
	s_cselect_b32 s81, s77, s94
	s_add_u32 s78, s82, 0x80
	s_addc_u32 s79, s83, 0
	ds_read_b128 v[200:203], v185
	ds_read_b128 v[204:207], v185 offset:1024
	ds_read_b128 v[208:211], v185 offset:2048
	ds_read_b128 v[212:215], v185 offset:3072
	ds_read_b128 v[216:219], v185 offset:4096
	ds_read_b128 v[220:223], v185 offset:5120
	ds_read_b128 v[224:227], v185 offset:6144
	ds_read_b128 v[228:231], v185 offset:7168
	s_mov_b32 m0, s85
	s_nop 0
	global_load_lds_dwordx4 v178, s[4:5]
	s_mov_b32 m0, s86
	s_nop 0
	global_load_lds_dwordx4 v180, s[4:5]
	s_waitcnt vmcnt(8)
	s_waitcnt lgkmcnt(0)
	s_barrier
	s_setprio 1
	v_mfma_f32_16x16x32_bf16 v[126:129], v[150:153], v[200:203], v[126:129]
	v_mfma_f32_16x16x32_bf16 v[122:125], v[158:161], v[200:203], v[122:125]
	v_mfma_f32_16x16x32_bf16 v[114:117], v[150:153], v[208:211], v[114:117]
	v_mfma_f32_16x16x32_bf16 v[106:109], v[158:161], v[208:211], v[106:109]
	v_mfma_f32_16x16x32_bf16 v[98:101], v[150:153], v[216:219], v[98:101]
	v_mfma_f32_16x16x32_bf16 v[90:93], v[158:161], v[216:219], v[90:93]
	v_mfma_f32_16x16x32_bf16 v[82:85], v[150:153], v[224:227], v[82:85]
	v_mfma_f32_16x16x32_bf16 v[74:77], v[158:161], v[224:227], v[74:77]
	v_mfma_f32_16x16x32_bf16 v[126:129], v[154:157], v[204:207], v[126:129]
	v_mfma_f32_16x16x32_bf16 v[122:125], v[162:165], v[204:207], v[122:125]
	v_mfma_f32_16x16x32_bf16 v[114:117], v[154:157], v[212:215], v[114:117]
	v_mfma_f32_16x16x32_bf16 v[106:109], v[162:165], v[212:215], v[106:109]
	v_mfma_f32_16x16x32_bf16 v[98:101], v[154:157], v[220:223], v[98:101]
	v_mfma_f32_16x16x32_bf16 v[90:93], v[162:165], v[220:223], v[90:93]
	v_mfma_f32_16x16x32_bf16 v[82:85], v[154:157], v[228:231], v[82:85]
	v_mfma_f32_16x16x32_bf16 v[74:77], v[162:165], v[228:231], v[74:77]
	v_mfma_f32_16x16x32_bf16 v[118:121], v[166:169], v[200:203], v[118:121]
	v_mfma_f32_16x16x32_bf16 v[110:113], v[192:195], v[200:203], v[110:113]
	v_mfma_f32_16x16x32_bf16 v[102:105], v[166:169], v[208:211], v[102:105]
	v_mfma_f32_16x16x32_bf16 v[94:97], v[192:195], v[208:211], v[94:97]
	v_mfma_f32_16x16x32_bf16 v[86:89], v[166:169], v[216:219], v[86:89]
	v_mfma_f32_16x16x32_bf16 v[78:81], v[192:195], v[216:219], v[78:81]
	v_mfma_f32_16x16x32_bf16 v[70:73], v[166:169], v[224:227], v[70:73]
	v_mfma_f32_16x16x32_bf16 v[66:69], v[192:195], v[224:227], v[66:69]
	v_mfma_f32_16x16x32_bf16 v[118:121], v[188:191], v[204:207], v[118:121]
	v_mfma_f32_16x16x32_bf16 v[110:113], v[196:199], v[204:207], v[110:113]
	v_mfma_f32_16x16x32_bf16 v[102:105], v[188:191], v[212:215], v[102:105]
	v_mfma_f32_16x16x32_bf16 v[94:97], v[196:199], v[212:215], v[94:97]
	v_mfma_f32_16x16x32_bf16 v[86:89], v[188:191], v[220:223], v[86:89]
	v_mfma_f32_16x16x32_bf16 v[78:81], v[196:199], v[220:223], v[78:81]
	v_mfma_f32_16x16x32_bf16 v[70:73], v[188:191], v[228:231], v[70:73]
	v_mfma_f32_16x16x32_bf16 v[66:69], v[196:199], v[228:231], v[66:69]
	s_setprio 0
	s_barrier
	ds_read_b128 v[200:203], v185 offset:16384
	ds_read_b128 v[204:207], v185 offset:17408
	ds_read_b128 v[208:211], v185 offset:18432
	ds_read_b128 v[212:215], v185 offset:19456
	ds_read_b128 v[216:219], v185 offset:20480
	ds_read_b128 v[220:223], v185 offset:21504
	ds_read_b128 v[224:227], v185 offset:22528
	ds_read_b128 v[228:231], v185 offset:23552
	s_mov_b32 m0, s24
	s_nop 0
	global_load_lds_dwordx4 v179, s[80:81]
	s_add_u32 s96, s80, 0x100000
	s_mov_b32 m0, s25
	s_nop 0
	global_load_lds_dwordx4 v181, s[80:81]
	s_addc_u32 s97, s81, 0
	s_mov_b32 m0, s26
	s_nop 0
	global_load_lds_dwordx4 v179, s[96:97]
	s_mov_b32 m0, s27
	s_nop 0
	global_load_lds_dwordx4 v181, s[96:97]
	s_mov_b32 m0, s15
	s_nop 0
	global_load_lds_dwordx4 v178, s[82:83]
	s_mov_b32 m0, s28
	s_nop 0
	global_load_lds_dwordx4 v180, s[82:83]
	s_waitcnt vmcnt(8)
	s_waitcnt lgkmcnt(0)
	s_barrier
	s_setprio 1
	v_mfma_f32_16x16x32_bf16 v[62:65], v[150:153], v[200:203], v[62:65]
	v_mfma_f32_16x16x32_bf16 v[58:61], v[158:161], v[200:203], v[58:61]
	v_mfma_f32_16x16x32_bf16 v[50:53], v[150:153], v[208:211], v[50:53]
	v_mfma_f32_16x16x32_bf16 v[42:45], v[158:161], v[208:211], v[42:45]
	v_mfma_f32_16x16x32_bf16 v[34:37], v[150:153], v[216:219], v[34:37]
	v_mfma_f32_16x16x32_bf16 v[26:29], v[158:161], v[216:219], v[26:29]
	v_mfma_f32_16x16x32_bf16 v[18:21], v[150:153], v[224:227], v[18:21]
	v_mfma_f32_16x16x32_bf16 v[10:13], v[158:161], v[224:227], v[10:13]
	v_mfma_f32_16x16x32_bf16 v[62:65], v[154:157], v[204:207], v[62:65]
	v_mfma_f32_16x16x32_bf16 v[58:61], v[162:165], v[204:207], v[58:61]
	v_mfma_f32_16x16x32_bf16 v[50:53], v[154:157], v[212:215], v[50:53]
	v_mfma_f32_16x16x32_bf16 v[42:45], v[162:165], v[212:215], v[42:45]
	v_mfma_f32_16x16x32_bf16 v[34:37], v[154:157], v[220:223], v[34:37]
	v_mfma_f32_16x16x32_bf16 v[26:29], v[162:165], v[220:223], v[26:29]
	v_mfma_f32_16x16x32_bf16 v[18:21], v[154:157], v[228:231], v[18:21]
	v_mfma_f32_16x16x32_bf16 v[10:13], v[162:165], v[228:231], v[10:13]
	v_mfma_f32_16x16x32_bf16 v[54:57], v[166:169], v[200:203], v[54:57]
	v_mfma_f32_16x16x32_bf16 v[46:49], v[192:195], v[200:203], v[46:49]
	v_mfma_f32_16x16x32_bf16 v[38:41], v[166:169], v[208:211], v[38:41]
	v_mfma_f32_16x16x32_bf16 v[30:33], v[192:195], v[208:211], v[30:33]
	v_mfma_f32_16x16x32_bf16 v[22:25], v[166:169], v[216:219], v[22:25]
	v_mfma_f32_16x16x32_bf16 v[14:17], v[192:195], v[216:219], v[14:17]
	v_mfma_f32_16x16x32_bf16 v[6:9], v[166:169], v[224:227], v[6:9]
	v_mfma_f32_16x16x32_bf16 v[2:5], v[192:195], v[224:227], v[2:5]
	v_mfma_f32_16x16x32_bf16 v[54:57], v[188:191], v[204:207], v[54:57]
	v_mfma_f32_16x16x32_bf16 v[46:49], v[196:199], v[204:207], v[46:49]
	v_mfma_f32_16x16x32_bf16 v[38:41], v[188:191], v[212:215], v[38:41]
	v_mfma_f32_16x16x32_bf16 v[30:33], v[196:199], v[212:215], v[30:33]
	v_mfma_f32_16x16x32_bf16 v[22:25], v[188:191], v[220:223], v[22:25]
	v_mfma_f32_16x16x32_bf16 v[14:17], v[196:199], v[220:223], v[14:17]
	v_mfma_f32_16x16x32_bf16 v[6:9], v[188:191], v[228:231], v[6:9]
	v_mfma_f32_16x16x32_bf16 v[2:5], v[196:199], v[228:231], v[2:5]
	s_setprio 0
	s_barrier
; #define PG8_STAGE(bufoff, gbase, voff) do { if constexpr (VAR != 1 && VAR != 3) { _Pragma("unroll") for (int _i = 0; _i < 2; ++_i) \
;         asm volatile("s_mov_b32 m0, %2\n\ts_nop 0\n\tglobal_load_lds_dwordx4 %0, %1" :: "v"((voff)[_i]), "s"((const char*)(gbase)), "s"(ldsbase + (unsigned)((bufoff) + _i * 8192)) : "memory", "m0"); } } while (0)
; #define PG8_LDA(dst, b, h) do { if constexpr (VAR < 2) _Pragma("unroll") for (int m = 0; m < 4; ++m) _Pragma("unroll") for (int k = 0; k < 2; ++k) dst[m][k] = *(const LAS bf16x8*)(lds + PG8_SA(b, h) + aoff + m * 2048 + k * 1024); } while (0)
; #define PG8_LDB(dst, b, h) do { if constexpr (VAR < 2) _Pragma("unroll") for (int n = 0; n < 2; ++n) _Pragma("unroll") for (int k = 0; k < 2; ++k) dst[n][k] = *(const LAS bf16x8*)(lds + PG8_SB(b, h) + boff + n * 2048 + k * 1024); } while (0)
; #define PG8_WAIT_V(n) asm volatile("s_waitcnt vmcnt(" #n ")" ::: "memory")
; #define PG8_WAIT_L(n) asm volatile("s_waitcnt lgkmcnt(" #n ")" ::: "memory")
; #define PG8_BAR do { if constexpr (VAR != 3) __builtin_amdgcn_s_barrier(); } while (0)
; #define PG8_SCHED __builtin_amdgcn_sched_barrier(0)
;     ...
;             PG8_LDB(B0, 1, 0); PG8_LDB(B1, 1, 1); PG8_SCHED; PG8_LDA(At, 1, 0); PG8_STAGE(PG8_SA(0, 1), a2 + hstepA, voffA);
;             PG8_WAIT_V(8); PG8_WAIT_L(0); PG8_BAR; PG8_MMA(0, 0, At, B0); PG8_MMA(0, 1, At, B1); PG8_BAR; PG8_SCHED;
;             PG8_LDA(At, 1, 1); PG8_STAGE(PG8_SB(1, 0), b3, voffB); PG8_STAGE(PG8_SB(1, 1), b3 + hstepB, voffB); PG8_STAGE(PG8_SA(1, 0), a3, voffA);
;             PG8_WAIT_V(8); PG8_WAIT_L(0); PG8_BAR; PG8_MMA(1, 0, At, B0); PG8_MMA(1, 1, At, B1); PG8_BAR; PG8_SCHED;
;         }
;         if (wr == 0) PG8_BAR;
	ds_read_b128 v[150:153], v186
	ds_read_b128 v[154:157], v186 offset:1024
	ds_read_b128 v[158:161], v186 offset:2048
	ds_read_b128 v[162:165], v186 offset:3072
	ds_read_b128 v[166:169], v187
	ds_read_b128 v[188:191], v187 offset:1024
	ds_read_b128 v[192:195], v187 offset:2048
	ds_read_b128 v[196:199], v187 offset:3072
	ds_read_b128 v[200:203], v185 offset:32768
	ds_read_b128 v[204:207], v185 offset:33792
	ds_read_b128 v[208:211], v185 offset:34816
	ds_read_b128 v[212:215], v185 offset:35840
	ds_read_b128 v[216:219], v185 offset:36864
	ds_read_b128 v[220:223], v185 offset:37888
	ds_read_b128 v[224:227], v185 offset:38912
	ds_read_b128 v[228:231], v185 offset:39936
	s_add_u32 s82, s82, 0x200000
	s_addc_u32 s83, s83, 0
	s_mov_b32 m0, s29
	s_nop 0
	global_load_lds_dwordx4 v178, s[82:83]
	s_mov_b32 m0, s30
	s_nop 0
	global_load_lds_dwordx4 v180, s[82:83]
	s_waitcnt vmcnt(8)
	s_waitcnt lgkmcnt(0)
	s_barrier
	s_setprio 1
	v_mfma_f32_16x16x32_bf16 v[126:129], v[150:153], v[200:203], v[126:129]
	v_mfma_f32_16x16x32_bf16 v[122:125], v[158:161], v[200:203], v[122:125]
	v_mfma_f32_16x16x32_bf16 v[114:117], v[150:153], v[208:211], v[114:117]
	v_mfma_f32_16x16x32_bf16 v[106:109], v[158:161], v[208:211], v[106:109]
	v_mfma_f32_16x16x32_bf16 v[98:101], v[150:153], v[216:219], v[98:101]
	v_mfma_f32_16x16x32_bf16 v[90:93], v[158:161], v[216:219], v[90:93]
	v_mfma_f32_16x16x32_bf16 v[82:85], v[150:153], v[224:227], v[82:85]
	v_mfma_f32_16x16x32_bf16 v[74:77], v[158:161], v[224:227], v[74:77]
	v_mfma_f32_16x16x32_bf16 v[126:129], v[154:157], v[204:207], v[126:129]
	v_mfma_f32_16x16x32_bf16 v[122:125], v[162:165], v[204:207], v[122:125]
	v_mfma_f32_16x16x32_bf16 v[114:117], v[154:157], v[212:215], v[114:117]
	v_mfma_f32_16x16x32_bf16 v[106:109], v[162:165], v[212:215], v[106:109]
	v_mfma_f32_16x16x32_bf16 v[98:101], v[154:157], v[220:223], v[98:101]
	v_mfma_f32_16x16x32_bf16 v[90:93], v[162:165], v[220:223], v[90:93]
	v_mfma_f32_16x16x32_bf16 v[82:85], v[154:157], v[228:231], v[82:85]
	v_mfma_f32_16x16x32_bf16 v[74:77], v[162:165], v[228:231], v[74:77]
	v_mfma_f32_16x16x32_bf16 v[118:121], v[166:169], v[200:203], v[118:121]
	v_mfma_f32_16x16x32_bf16 v[110:113], v[192:195], v[200:203], v[110:113]
	v_mfma_f32_16x16x32_bf16 v[102:105], v[166:169], v[208:211], v[102:105]
	v_mfma_f32_16x16x32_bf16 v[94:97], v[192:195], v[208:211], v[94:97]
	v_mfma_f32_16x16x32_bf16 v[86:89], v[166:169], v[216:219], v[86:89]
	v_mfma_f32_16x16x32_bf16 v[78:81], v[192:195], v[216:219], v[78:81]
	v_mfma_f32_16x16x32_bf16 v[70:73], v[166:169], v[224:227], v[70:73]
	v_mfma_f32_16x16x32_bf16 v[66:69], v[192:195], v[224:227], v[66:69]
	v_mfma_f32_16x16x32_bf16 v[118:121], v[188:191], v[204:207], v[118:121]
	v_mfma_f32_16x16x32_bf16 v[110:113], v[196:199], v[204:207], v[110:113]
	v_mfma_f32_16x16x32_bf16 v[102:105], v[188:191], v[212:215], v[102:105]
	v_mfma_f32_16x16x32_bf16 v[94:97], v[196:199], v[212:215], v[94:97]
	v_mfma_f32_16x16x32_bf16 v[86:89], v[188:191], v[220:223], v[86:89]
	v_mfma_f32_16x16x32_bf16 v[78:81], v[196:199], v[220:223], v[78:81]
	v_mfma_f32_16x16x32_bf16 v[70:73], v[188:191], v[228:231], v[70:73]
	v_mfma_f32_16x16x32_bf16 v[66:69], v[196:199], v[228:231], v[66:69]
	s_setprio 0
	s_barrier
	ds_read_b128 v[200:203], v185 offset:49152
	ds_read_b128 v[204:207], v185 offset:50176
	ds_read_b128 v[208:211], v185 offset:51200
	ds_read_b128 v[212:215], v185 offset:52224
	ds_read_b128 v[216:219], v185 offset:53248
	ds_read_b128 v[220:223], v185 offset:54272
	ds_read_b128 v[224:227], v185 offset:55296
	ds_read_b128 v[228:231], v185 offset:56320
	s_add_u32 s82, s80, 0x80
	s_addc_u32 s83, s81, 0
	s_mov_b32 m0, s31
	s_nop 0
	global_load_lds_dwordx4 v179, s[82:83]
	s_add_u32 s80, s80, 0x100080
	s_mov_b32 m0, s33
	s_nop 0
	global_load_lds_dwordx4 v181, s[82:83]
	s_addc_u32 s81, s81, 0
	s_mov_b32 m0, s73
	s_nop 0
	global_load_lds_dwordx4 v179, s[80:81]
	s_mov_b32 m0, s84
	s_nop 0
	global_load_lds_dwordx4 v181, s[80:81]
	s_mov_b32 m0, s56
	s_nop 0
	global_load_lds_dwordx4 v178, s[78:79]
	s_mov_b32 m0, s57
	s_nop 0
	global_load_lds_dwordx4 v180, s[78:79]
	s_waitcnt vmcnt(8)
	s_waitcnt lgkmcnt(0)
	s_barrier
	s_setprio 1
	v_mfma_f32_16x16x32_bf16 v[62:65], v[150:153], v[200:203], v[62:65]
	v_mfma_f32_16x16x32_bf16 v[58:61], v[158:161], v[200:203], v[58:61]
	v_mfma_f32_16x16x32_bf16 v[50:53], v[150:153], v[208:211], v[50:53]
	v_mfma_f32_16x16x32_bf16 v[42:45], v[158:161], v[208:211], v[42:45]
	v_mfma_f32_16x16x32_bf16 v[34:37], v[150:153], v[216:219], v[34:37]
	v_mfma_f32_16x16x32_bf16 v[26:29], v[158:161], v[216:219], v[26:29]
	v_mfma_f32_16x16x32_bf16 v[18:21], v[150:153], v[224:227], v[18:21]
	v_mfma_f32_16x16x32_bf16 v[10:13], v[158:161], v[224:227], v[10:13]
	v_mfma_f32_16x16x32_bf16 v[62:65], v[154:157], v[204:207], v[62:65]
	v_mfma_f32_16x16x32_bf16 v[58:61], v[162:165], v[204:207], v[58:61]
	v_mfma_f32_16x16x32_bf16 v[50:53], v[154:157], v[212:215], v[50:53]
	v_mfma_f32_16x16x32_bf16 v[42:45], v[162:165], v[212:215], v[42:45]
	v_mfma_f32_16x16x32_bf16 v[34:37], v[154:157], v[220:223], v[34:37]
	v_mfma_f32_16x16x32_bf16 v[26:29], v[162:165], v[220:223], v[26:29]
	v_mfma_f32_16x16x32_bf16 v[18:21], v[154:157], v[228:231], v[18:21]
	v_mfma_f32_16x16x32_bf16 v[10:13], v[162:165], v[228:231], v[10:13]
	v_mfma_f32_16x16x32_bf16 v[54:57], v[166:169], v[200:203], v[54:57]
	v_mfma_f32_16x16x32_bf16 v[46:49], v[192:195], v[200:203], v[46:49]
	v_mfma_f32_16x16x32_bf16 v[38:41], v[166:169], v[208:211], v[38:41]
	v_mfma_f32_16x16x32_bf16 v[30:33], v[192:195], v[208:211], v[30:33]
	v_mfma_f32_16x16x32_bf16 v[22:25], v[166:169], v[216:219], v[22:25]
	v_mfma_f32_16x16x32_bf16 v[14:17], v[192:195], v[216:219], v[14:17]
	v_mfma_f32_16x16x32_bf16 v[6:9], v[166:169], v[224:227], v[6:9]
	v_mfma_f32_16x16x32_bf16 v[2:5], v[192:195], v[224:227], v[2:5]
	v_mfma_f32_16x16x32_bf16 v[54:57], v[188:191], v[204:207], v[54:57]
	v_mfma_f32_16x16x32_bf16 v[46:49], v[196:199], v[204:207], v[46:49]
	v_mfma_f32_16x16x32_bf16 v[38:41], v[188:191], v[212:215], v[38:41]
	v_mfma_f32_16x16x32_bf16 v[30:33], v[196:199], v[212:215], v[30:33]
	v_mfma_f32_16x16x32_bf16 v[22:25], v[188:191], v[220:223], v[22:25]
	v_mfma_f32_16x16x32_bf16 v[14:17], v[196:199], v[220:223], v[14:17]
	v_mfma_f32_16x16x32_bf16 v[6:9], v[188:191], v[228:231], v[6:9]
	v_mfma_f32_16x16x32_bf16 v[2:5], v[196:199], v[228:231], v[2:5]
	s_setprio 0
	s_barrier
	s_add_i32 s6, s6, 2
	s_add_u32 s75, s75, 0x100
	s_addc_u32 s92, s92, 0
	s_add_u32 s93, s93, 0x100
	s_addc_u32 s94, s94, 0
	s_add_u32 s4, s4, 0x100
	s_addc_u32 s5, s5, 0
	s_cmp_gt_u32 s6, 13
	s_cbranch_scc0 .LBB0_673
.Lmy_kexit_3:
	s_and_b64 vcc, exec, s[70:71]
	s_cbranch_vccz .LBB0_676
	s_barrier

; __device__ __forceinline__ const char* unitA(const Gemm& g, const Unit& u) { return (const char*)(g.A + (size_t)(u.z / g.zdiv) * g.sAhi + (size_t)(u.z % g.zdiv) * g.sAlo + (size_t)u.pm * BM * g.lda); }
; __device__ __forceinline__ const char* unitB(const Gemm& g, const Unit& u) { return (const char*)(g.Bt + (size_t)(u.z / g.zdiv) * g.sBhi + (size_t)(u.z % g.zdiv) * g.sBlo + (size_t)(u.pm / g.bdiv) * g.sBpm + (size_t)u.pn * BM * g.ldb); }
; #define PG8_STAGE(bufoff, gbase, voff) do { if constexpr (VAR != 1 && VAR != 3) { _Pragma("unroll") for (int _i = 0; _i < 2; ++_i) \
;         asm volatile("s_mov_b32 m0, %2\n\ts_nop 0\n\tglobal_load_lds_dwordx4 %0, %1" :: "v"((voff)[_i]), "s"((const char*)(gbase)), "s"(ldsbase + (unsigned)((bufoff) + _i * 8192)) : "memory", "m0"); } } while (0)
; #define PG8_LDA(dst, b, h) do { if constexpr (VAR < 2) _Pragma("unroll") for (int m = 0; m < 4; ++m) _Pragma("unroll") for (int k = 0; k < 2; ++k) dst[m][k] = *(const LAS bf16x8*)(lds + PG8_SA(b, h) + aoff + m * 2048 + k * 1024); } while (0)
; #define PG8_LDB(dst, b, h) do { if constexpr (VAR < 2) _Pragma("unroll") for (int n = 0; n < 2; ++n) _Pragma("unroll") for (int k = 0; k < 2; ++k) dst[n][k] = *(const LAS bf16x8*)(lds + PG8_SB(b, h) + boff + n * 2048 + k * 1024); } while (0)
; #define PG8_WAIT_V(n) asm volatile("s_waitcnt vmcnt(" #n ")" ::: "memory")
; #define PG8_SCHED __builtin_amdgcn_sched_barrier(0)
;     ...
;         const char* nA = has_next ? unitA(g, nxt) : cA; const char* nB = has_next ? unitB(g, nxt) : cB;
;         for (int t = 0; t < nt; t += 2) {
;             const bool last = (t == nt - 2);
;             const char* a1 = cA + (size_t)(t + 1) * kstep;
;             const char* a2 = last ? nA : cA + (size_t)(t + 2) * kstep; const char* b2 = last ? nB : cB + (size_t)(t + 2) * kstep;
;             const char* a3 = a2 + kstep; const char* b3 = b2 + kstep;
;             PG8_LDB(B0, 0, 0); PG8_LDB(B1, 0, 1); PG8_SCHED; PG8_LDA(At, 0, 0); PG8_STAGE(PG8_SA(1, 1), a1 + hstepA, voffA);
;             PG8_WAIT_V(8); PG8_WAIT_L(0); PG8_BAR; PG8_MMA(0, 0, At, B0); PG8_MMA(0, 1, At, B1); PG8_BAR; PG8_SCHED;
;             PG8_LDA(At, 0, 1); PG8_STAGE(PG8_SB(0, 0), b2, voffB); PG8_STAGE(PG8_SB(0, 1), b2 + hstepB, voffB); PG8_STAGE(PG8_SA(0, 0), a2, voffA);
;             PG8_WAIT_V(8); PG8_WAIT_L(0); PG8_BAR; PG8_MMA(1, 0, At, B0); PG8_MMA(1, 1, At, B1); PG8_BAR; PG8_SCHED;
.LBB0_700:
	s_add_u32 s57, s66, 0x100
	s_addc_u32 s81, s67, 0
	s_add_u32 s82, s64, 0x100
	s_addc_u32 s83, s65, 0
	s_add_u32 s64, s66, 0x100080
	s_addc_u32 s65, s67, 0
	s_mov_b32 s6, -2
	ds_read_b128 v[148:151], v1
	ds_read_b128 v[152:155], v1 offset:1024
	ds_read_b128 v[156:159], v1 offset:2048
	ds_read_b128 v[160:163], v1 offset:3072
	ds_read_b128 v[164:167], v143
	ds_read_b128 v[168:171], v143 offset:1024
	ds_read_b128 v[172:175], v143 offset:2048
	ds_read_b128 v[176:179], v143 offset:3072
	s_cmp_eq_u32 s6, 12
	s_cselect_b32 s70, s0, s57
	s_cselect_b32 s71, s1, s81
	s_cselect_b32 s68, s62, s82
	s_cselect_b32 s69, s63, s83
	s_add_u32 s66, s70, 0x80
	s_addc_u32 s67, s71, 0
	ds_read_b128 v[180:183], v144
	ds_read_b128 v[184:187], v144 offset:1024
	ds_read_b128 v[188:191], v144 offset:2048
	ds_read_b128 v[192:195], v144 offset:3072
	ds_read_b128 v[196:199], v144 offset:4096
	ds_read_b128 v[200:203], v144 offset:5120
	ds_read_b128 v[204:207], v144 offset:6144
	ds_read_b128 v[208:211], v144 offset:7168
	s_mov_b32 m0, s76
	s_nop 0
	global_load_lds_dwordx4 v138, s[64:65]
	s_mov_b32 m0, s77
	s_nop 0
	global_load_lds_dwordx4 v140, s[64:65]
	s_waitcnt vmcnt(8)
	s_waitcnt lgkmcnt(0)
	s_barrier
	s_setprio 1
	v_mfma_f32_16x16x32_bf16 v[126:129], v[148:151], v[180:183], 0
	v_mfma_f32_16x16x32_bf16 v[122:125], v[156:159], v[180:183], 0
	v_mfma_f32_16x16x32_bf16 v[118:121], v[148:151], v[188:191], 0
	v_mfma_f32_16x16x32_bf16 v[110:113], v[156:159], v[188:191], 0
	v_mfma_f32_16x16x32_bf16 v[102:105], v[148:151], v[196:199], 0
	v_mfma_f32_16x16x32_bf16 v[94:97], v[156:159], v[196:199], 0
	v_mfma_f32_16x16x32_bf16 v[86:89], v[148:151], v[204:207], 0
	v_mfma_f32_16x16x32_bf16 v[78:81], v[156:159], v[204:207], 0
	v_mfma_f32_16x16x32_bf16 v[126:129], v[152:155], v[184:187], v[126:129]
	v_mfma_f32_16x16x32_bf16 v[122:125], v[160:163], v[184:187], v[122:125]
	v_mfma_f32_16x16x32_bf16 v[118:121], v[152:155], v[192:195], v[118:121]
	v_mfma_f32_16x16x32_bf16 v[110:113], v[160:163], v[192:195], v[110:113]
	v_mfma_f32_16x16x32_bf16 v[102:105], v[152:155], v[200:203], v[102:105]
	v_mfma_f32_16x16x32_bf16 v[94:97], v[160:163], v[200:203], v[94:97]
	v_mfma_f32_16x16x32_bf16 v[86:89], v[152:155], v[208:211], v[86:89]
	v_mfma_f32_16x16x32_bf16 v[78:81], v[160:163], v[208:211], v[78:81]
	v_mfma_f32_16x16x32_bf16 v[114:117], v[164:167], v[180:183], 0
	v_mfma_f32_16x16x32_bf16 v[106:109], v[172:175], v[180:183], 0
	v_mfma_f32_16x16x32_bf16 v[98:101], v[164:167], v[188:191], 0
	v_mfma_f32_16x16x32_bf16 v[90:93], v[172:175], v[188:191], 0
	v_mfma_f32_16x16x32_bf16 v[82:85], v[164:167], v[196:199], 0
	v_mfma_f32_16x16x32_bf16 v[74:77], v[172:175], v[196:199], 0
	v_mfma_f32_16x16x32_bf16 v[70:73], v[164:167], v[204:207], 0
	v_mfma_f32_16x16x32_bf16 v[66:69], v[172:175], v[204:207], 0
	v_mfma_f32_16x16x32_bf16 v[114:117], v[168:171], v[184:187], v[114:117]
	v_mfma_f32_16x16x32_bf16 v[106:109], v[176:179], v[184:187], v[106:109]
	v_mfma_f32_16x16x32_bf16 v[98:101], v[168:171], v[192:195], v[98:101]
	v_mfma_f32_16x16x32_bf16 v[90:93], v[176:179], v[192:195], v[90:93]
	v_mfma_f32_16x16x32_bf16 v[82:85], v[168:171], v[200:203], v[82:85]
	v_mfma_f32_16x16x32_bf16 v[74:77], v[176:179], v[200:203], v[74:77]
	v_mfma_f32_16x16x32_bf16 v[70:73], v[168:171], v[208:211], v[70:73]
	v_mfma_f32_16x16x32_bf16 v[66:69], v[176:179], v[208:211], v[66:69]
	s_setprio 0
	s_barrier
	ds_read_b128 v[180:183], v144 offset:16384
	ds_read_b128 v[184:187], v144 offset:17408
	ds_read_b128 v[188:191], v144 offset:18432
	ds_read_b128 v[192:195], v144 offset:19456
	ds_read_b128 v[196:199], v144 offset:20480
	ds_read_b128 v[200:203], v144 offset:21504
	ds_read_b128 v[204:207], v144 offset:22528
	ds_read_b128 v[208:211], v144 offset:23552
	s_mov_b32 m0, s24
	s_nop 0
	global_load_lds_dwordx4 v139, s[68:69]
	s_add_u32 s84, s68, 0x200000
	s_mov_b32 m0, s25
	s_nop 0
	global_load_lds_dwordx4 v141, s[68:69]
	s_addc_u32 s85, s69, 0
	s_mov_b32 m0, s26
	s_nop 0
	global_load_lds_dwordx4 v139, s[84:85]
	s_mov_b32 m0, s27
	s_nop 0
	global_load_lds_dwordx4 v141, s[84:85]
	s_mov_b32 m0, s15
	s_nop 0
	global_load_lds_dwordx4 v138, s[70:71]
	s_mov_b32 m0, s28
	s_nop 0
	global_load_lds_dwordx4 v140, s[70:71]
	s_waitcnt vmcnt(8)
	s_waitcnt lgkmcnt(0)
	s_barrier
	s_setprio 1
	v_mfma_f32_16x16x32_bf16 v[62:65], v[148:151], v[180:183], 0
	v_mfma_f32_16x16x32_bf16 v[58:61], v[156:159], v[180:183], 0
	v_mfma_f32_16x16x32_bf16 v[54:57], v[148:151], v[188:191], 0
	v_mfma_f32_16x16x32_bf16 v[46:49], v[156:159], v[188:191], 0
	v_mfma_f32_16x16x32_bf16 v[38:41], v[148:151], v[196:199], 0
	v_mfma_f32_16x16x32_bf16 v[30:33], v[156:159], v[196:199], 0
	v_mfma_f32_16x16x32_bf16 v[22:25], v[148:151], v[204:207], 0
	v_mfma_f32_16x16x32_bf16 v[14:17], v[156:159], v[204:207], 0
	v_mfma_f32_16x16x32_bf16 v[62:65], v[152:155], v[184:187], v[62:65]
	v_mfma_f32_16x16x32_bf16 v[58:61], v[160:163], v[184:187], v[58:61]
	v_mfma_f32_16x16x32_bf16 v[54:57], v[152:155], v[192:195], v[54:57]
	v_mfma_f32_16x16x32_bf16 v[46:49], v[160:163], v[192:195], v[46:49]
	v_mfma_f32_16x16x32_bf16 v[38:41], v[152:155], v[200:203], v[38:41]
	v_mfma_f32_16x16x32_bf16 v[30:33], v[160:163], v[200:203], v[30:33]
	v_mfma_f32_16x16x32_bf16 v[22:25], v[152:155], v[208:211], v[22:25]
	v_mfma_f32_16x16x32_bf16 v[14:17], v[160:163], v[208:211], v[14:17]
	v_mfma_f32_16x16x32_bf16 v[50:53], v[164:167], v[180:183], 0
	v_mfma_f32_16x16x32_bf16 v[42:45], v[172:175], v[180:183], 0
	v_mfma_f32_16x16x32_bf16 v[34:37], v[164:167], v[188:191], 0
	v_mfma_f32_16x16x32_bf16 v[26:29], v[172:175], v[188:191], 0
	v_mfma_f32_16x16x32_bf16 v[18:21], v[164:167], v[196:199], 0
	v_mfma_f32_16x16x32_bf16 v[10:13], v[172:175], v[196:199], 0
	v_mfma_f32_16x16x32_bf16 v[6:9], v[164:167], v[204:207], 0
	v_mfma_f32_16x16x32_bf16 v[2:5], v[172:175], v[204:207], 0
	v_mfma_f32_16x16x32_bf16 v[50:53], v[168:171], v[184:187], v[50:53]
	v_mfma_f32_16x16x32_bf16 v[42:45], v[176:179], v[184:187], v[42:45]
	v_mfma_f32_16x16x32_bf16 v[34:37], v[168:171], v[192:195], v[34:37]
	v_mfma_f32_16x16x32_bf16 v[26:29], v[176:179], v[192:195], v[26:29]
	v_mfma_f32_16x16x32_bf16 v[18:21], v[168:171], v[200:203], v[18:21]
	v_mfma_f32_16x16x32_bf16 v[10:13], v[176:179], v[200:203], v[10:13]
	v_mfma_f32_16x16x32_bf16 v[6:9], v[168:171], v[208:211], v[6:9]
	v_mfma_f32_16x16x32_bf16 v[2:5], v[176:179], v[208:211], v[2:5]
	s_setprio 0
	s_barrier
; #define PG8_STAGE(bufoff, gbase, voff) do { if constexpr (VAR != 1 && VAR != 3) { _Pragma("unroll") for (int _i = 0; _i < 2; ++_i) \
;         asm volatile("s_mov_b32 m0, %2\n\ts_nop 0\n\tglobal_load_lds_dwordx4 %0, %1" :: "v"((voff)[_i]), "s"((const char*)(gbase)), "s"(ldsbase + (unsigned)((bufoff) + _i * 8192)) : "memory", "m0"); } } while (0)
; #define PG8_LDA(dst, b, h) do { if constexpr (VAR < 2) _Pragma("unroll") for (int m = 0; m < 4; ++m) _Pragma("unroll") for (int k = 0; k < 2; ++k) dst[m][k] = *(const LAS bf16x8*)(lds + PG8_SA(b, h) + aoff + m * 2048 + k * 1024); } while (0)
; #define PG8_LDB(dst, b, h) do { if constexpr (VAR < 2) _Pragma("unroll") for (int n = 0; n < 2; ++n) _Pragma("unroll") for (int k = 0; k < 2; ++k) dst[n][k] = *(const LAS bf16x8*)(lds + PG8_SB(b, h) + boff + n * 2048 + k * 1024); } while (0)
; #define PG8_WAIT_V(n) asm volatile("s_waitcnt vmcnt(" #n ")" ::: "memory")
; #define PG8_WAIT_L(n) asm volatile("s_waitcnt lgkmcnt(" #n ")" ::: "memory")
; #define PG8_BAR do { if constexpr (VAR != 3) __builtin_amdgcn_s_barrier(); } while (0)
; #define PG8_SCHED __builtin_amdgcn_sched_barrier(0)
;     ...
;             PG8_LDB(B0, 1, 0); PG8_LDB(B1, 1, 1); PG8_SCHED; PG8_LDA(At, 1, 0); PG8_STAGE(PG8_SA(0, 1), a2 + hstepA, voffA);
;             PG8_WAIT_V(8); PG8_WAIT_L(0); PG8_BAR; PG8_MMA(0, 0, At, B0); PG8_MMA(0, 1, At, B1); PG8_BAR; PG8_SCHED;
;             PG8_LDA(At, 1, 1); PG8_STAGE(PG8_SB(1, 0), b3, voffB); PG8_STAGE(PG8_SB(1, 1), b3 + hstepB, voffB); PG8_STAGE(PG8_SA(1, 0), a3, voffA);
;             PG8_WAIT_V(8); PG8_WAIT_L(0); PG8_BAR; PG8_MMA(1, 0, At, B0); PG8_MMA(1, 1, At, B1); PG8_BAR; PG8_SCHED;
	ds_read_b128 v[148:151], v145
	ds_read_b128 v[152:155], v145 offset:1024
	ds_read_b128 v[156:159], v145 offset:2048
	ds_read_b128 v[160:163], v145 offset:3072
	ds_read_b128 v[164:167], v146
	ds_read_b128 v[168:171], v146 offset:1024
	ds_read_b128 v[172:175], v146 offset:2048
	ds_read_b128 v[176:179], v146 offset:3072
	ds_read_b128 v[180:183], v144 offset:32768
	ds_read_b128 v[184:187], v144 offset:33792
	ds_read_b128 v[188:191], v144 offset:34816
	ds_read_b128 v[192:195], v144 offset:35840
	ds_read_b128 v[196:199], v144 offset:36864
	ds_read_b128 v[200:203], v144 offset:37888
	ds_read_b128 v[204:207], v144 offset:38912
	ds_read_b128 v[208:211], v144 offset:39936
	s_add_u32 s70, s70, 0x100000
	s_addc_u32 s71, s71, 0
	s_mov_b32 m0, s29
	s_nop 0
	global_load_lds_dwordx4 v138, s[70:71]
	s_mov_b32 m0, s30
	s_nop 0
	global_load_lds_dwordx4 v140, s[70:71]
	s_waitcnt vmcnt(8)
	s_waitcnt lgkmcnt(0)
	s_barrier
	s_setprio 1
	v_mfma_f32_16x16x32_bf16 v[126:129], v[148:151], v[180:183], v[126:129]
	v_mfma_f32_16x16x32_bf16 v[122:125], v[156:159], v[180:183], v[122:125]
	v_mfma_f32_16x16x32_bf16 v[118:121], v[148:151], v[188:191], v[118:121]
	v_mfma_f32_16x16x32_bf16 v[110:113], v[156:159], v[188:191], v[110:113]
	v_mfma_f32_16x16x32_bf16 v[102:105], v[148:151], v[196:199], v[102:105]
	v_mfma_f32_16x16x32_bf16 v[94:97], v[156:159], v[196:199], v[94:97]
	v_mfma_f32_16x16x32_bf16 v[86:89], v[148:151], v[204:207], v[86:89]
	v_mfma_f32_16x16x32_bf16 v[78:81], v[156:159], v[204:207], v[78:81]
	v_mfma_f32_16x16x32_bf16 v[126:129], v[152:155], v[184:187], v[126:129]
	v_mfma_f32_16x16x32_bf16 v[122:125], v[160:163], v[184:187], v[122:125]
	v_mfma_f32_16x16x32_bf16 v[118:121], v[152:155], v[192:195], v[118:121]
	v_mfma_f32_16x16x32_bf16 v[110:113], v[160:163], v[192:195], v[110:113]
	v_mfma_f32_16x16x32_bf16 v[102:105], v[152:155], v[200:203], v[102:105]
	v_mfma_f32_16x16x32_bf16 v[94:97], v[160:163], v[200:203], v[94:97]
	v_mfma_f32_16x16x32_bf16 v[86:89], v[152:155], v[208:211], v[86:89]
	v_mfma_f32_16x16x32_bf16 v[78:81], v[160:163], v[208:211], v[78:81]
	v_mfma_f32_16x16x32_bf16 v[114:117], v[164:167], v[180:183], v[114:117]
	v_mfma_f32_16x16x32_bf16 v[106:109], v[172:175], v[180:183], v[106:109]
	v_mfma_f32_16x16x32_bf16 v[98:101], v[164:167], v[188:191], v[98:101]
	v_mfma_f32_16x16x32_bf16 v[90:93], v[172:175], v[188:191], v[90:93]
	v_mfma_f32_16x16x32_bf16 v[82:85], v[164:167], v[196:199], v[82:85]
	v_mfma_f32_16x16x32_bf16 v[74:77], v[172:175], v[196:199], v[74:77]
	v_mfma_f32_16x16x32_bf16 v[70:73], v[164:167], v[204:207], v[70:73]
	v_mfma_f32_16x16x32_bf16 v[66:69], v[172:175], v[204:207], v[66:69]
	v_mfma_f32_16x16x32_bf16 v[114:117], v[168:171], v[184:187], v[114:117]
	v_mfma_f32_16x16x32_bf16 v[106:109], v[176:179], v[184:187], v[106:109]
	v_mfma_f32_16x16x32_bf16 v[98:101], v[168:171], v[192:195], v[98:101]
	v_mfma_f32_16x16x32_bf16 v[90:93], v[176:179], v[192:195], v[90:93]
	v_mfma_f32_16x16x32_bf16 v[82:85], v[168:171], v[200:203], v[82:85]
	v_mfma_f32_16x16x32_bf16 v[74:77], v[176:179], v[200:203], v[74:77]
	v_mfma_f32_16x16x32_bf16 v[70:73], v[168:171], v[208:211], v[70:73]
	v_mfma_f32_16x16x32_bf16 v[66:69], v[176:179], v[208:211], v[66:69]
	s_setprio 0
	s_barrier
	ds_read_b128 v[180:183], v144 offset:49152
	ds_read_b128 v[184:187], v144 offset:50176
	ds_read_b128 v[188:191], v144 offset:51200
	ds_read_b128 v[192:195], v144 offset:52224
	ds_read_b128 v[196:199], v144 offset:53248
	ds_read_b128 v[200:203], v144 offset:54272
	ds_read_b128 v[204:207], v144 offset:55296
	ds_read_b128 v[208:211], v144 offset:56320
	s_add_u32 s70, s68, 0x80
	s_addc_u32 s71, s69, 0
	s_mov_b32 m0, s31
	s_nop 0
	global_load_lds_dwordx4 v139, s[70:71]
	s_add_u32 s68, s68, 0x200080
	s_mov_b32 m0, s33
	s_nop 0
	global_load_lds_dwordx4 v141, s[70:71]
	s_addc_u32 s69, s69, 0
	s_mov_b32 m0, s74
	s_nop 0
	global_load_lds_dwordx4 v139, s[68:69]
	s_mov_b32 m0, s75
	s_nop 0
	global_load_lds_dwordx4 v141, s[68:69]
	s_mov_b32 m0, s72
	s_nop 0
	global_load_lds_dwordx4 v138, s[66:67]
	s_mov_b32 m0, s73
	s_nop 0
	global_load_lds_dwordx4 v140, s[66:67]
	s_waitcnt vmcnt(8)
	s_waitcnt lgkmcnt(0)
	s_barrier
	s_setprio 1
	v_mfma_f32_16x16x32_bf16 v[62:65], v[148:151], v[180:183], v[62:65]
	v_mfma_f32_16x16x32_bf16 v[58:61], v[156:159], v[180:183], v[58:61]
	v_mfma_f32_16x16x32_bf16 v[54:57], v[148:151], v[188:191], v[54:57]
	v_mfma_f32_16x16x32_bf16 v[46:49], v[156:159], v[188:191], v[46:49]
	v_mfma_f32_16x16x32_bf16 v[38:41], v[148:151], v[196:199], v[38:41]
	v_mfma_f32_16x16x32_bf16 v[30:33], v[156:159], v[196:199], v[30:33]
	v_mfma_f32_16x16x32_bf16 v[22:25], v[148:151], v[204:207], v[22:25]
	v_mfma_f32_16x16x32_bf16 v[14:17], v[156:159], v[204:207], v[14:17]
	v_mfma_f32_16x16x32_bf16 v[62:65], v[152:155], v[184:187], v[62:65]
	v_mfma_f32_16x16x32_bf16 v[58:61], v[160:163], v[184:187], v[58:61]
	v_mfma_f32_16x16x32_bf16 v[54:57], v[152:155], v[192:195], v[54:57]
	v_mfma_f32_16x16x32_bf16 v[46:49], v[160:163], v[192:195], v[46:49]
	v_mfma_f32_16x16x32_bf16 v[38:41], v[152:155], v[200:203], v[38:41]
	v_mfma_f32_16x16x32_bf16 v[30:33], v[160:163], v[200:203], v[30:33]
	v_mfma_f32_16x16x32_bf16 v[22:25], v[152:155], v[208:211], v[22:25]
	v_mfma_f32_16x16x32_bf16 v[14:17], v[160:163], v[208:211], v[14:17]
	v_mfma_f32_16x16x32_bf16 v[50:53], v[164:167], v[180:183], v[50:53]
	v_mfma_f32_16x16x32_bf16 v[42:45], v[172:175], v[180:183], v[42:45]
	v_mfma_f32_16x16x32_bf16 v[34:37], v[164:167], v[188:191], v[34:37]
	v_mfma_f32_16x16x32_bf16 v[26:29], v[172:175], v[188:191], v[26:29]
	v_mfma_f32_16x16x32_bf16 v[18:21], v[164:167], v[196:199], v[18:21]
	v_mfma_f32_16x16x32_bf16 v[10:13], v[172:175], v[196:199], v[10:13]
	v_mfma_f32_16x16x32_bf16 v[6:9], v[164:167], v[204:207], v[6:9]
	v_mfma_f32_16x16x32_bf16 v[2:5], v[172:175], v[204:207], v[2:5]
	v_mfma_f32_16x16x32_bf16 v[50:53], v[168:171], v[184:187], v[50:53]
	v_mfma_f32_16x16x32_bf16 v[42:45], v[176:179], v[184:187], v[42:45]
	v_mfma_f32_16x16x32_bf16 v[34:37], v[168:171], v[192:195], v[34:37]
	v_mfma_f32_16x16x32_bf16 v[26:29], v[176:179], v[192:195], v[26:29]
	v_mfma_f32_16x16x32_bf16 v[18:21], v[168:171], v[200:203], v[18:21]
	v_mfma_f32_16x16x32_bf16 v[10:13], v[176:179], v[200:203], v[10:13]
	v_mfma_f32_16x16x32_bf16 v[6:9], v[168:171], v[208:211], v[6:9]
	v_mfma_f32_16x16x32_bf16 v[2:5], v[176:179], v[208:211], v[2:5]
	s_setprio 0
	s_barrier
	s_add_i32 s6, s6, 2
	s_add_u32 s57, s57, 0x100
	s_addc_u32 s81, s81, 0
	s_add_u32 s82, s82, 0x100
	s_addc_u32 s83, s83, 0
	s_add_u32 s64, s64, 0x100
	s_addc_u32 s65, s65, 0
	s_cmp_gt_u32 s6, 13
	s_cbranch_scc0 .LBB0_701
	s_branch .Lmy_kexit_4
; #define PG8_STAGE(bufoff, gbase, voff) do { if constexpr (VAR != 1 && VAR != 3) { _Pragma("unroll") for (int _i = 0; _i < 2; ++_i) \
;         asm volatile("s_mov_b32 m0, %2\n\ts_nop 0\n\tglobal_load_lds_dwordx4 %0, %1" :: "v"((voff)[_i]), "s"((const char*)(gbase)), "s"(ldsbase + (unsigned)((bufoff) + _i * 8192)) : "memory", "m0"); } } while (0)
; #define PG8_LDA(dst, b, h) do { if constexpr (VAR < 2) _Pragma("unroll") for (int m = 0; m < 4; ++m) _Pragma("unroll") for (int k = 0; k < 2; ++k) dst[m][k] = *(const LAS bf16x8*)(lds + PG8_SA(b, h) + aoff + m * 2048 + k * 1024); } while (0)
; #define PG8_LDB(dst, b, h) do { if constexpr (VAR < 2) _Pragma("unroll") for (int n = 0; n < 2; ++n) _Pragma("unroll") for (int k = 0; k < 2; ++k) dst[n][k] = *(const LAS bf16x8*)(lds + PG8_SB(b, h) + boff + n * 2048 + k * 1024); } while (0)
; #define PG8_WAIT_V(n) asm volatile("s_waitcnt vmcnt(" #n ")" ::: "memory")
; #define PG8_WAIT_L(n) asm volatile("s_waitcnt lgkmcnt(" #n ")" ::: "memory")
; #define PG8_BAR do { if constexpr (VAR != 3) __builtin_amdgcn_s_barrier(); } while (0)
; #define PG8_SCHED __builtin_amdgcn_sched_barrier(0)
;     ...
;             const bool last = (t == nt - 2);
;             const char* a1 = cA + (size_t)(t + 1) * kstep;
;             const char* a2 = last ? nA : cA + (size_t)(t + 2) * kstep; const char* b2 = last ? nB : cB + (size_t)(t + 2) * kstep;
;             const char* a3 = a2 + kstep; const char* b3 = b2 + kstep;
;             PG8_LDB(B0, 0, 0); PG8_LDB(B1, 0, 1); PG8_SCHED; PG8_LDA(At, 0, 0); PG8_STAGE(PG8_SA(1, 1), a1 + hstepA, voffA);
;             PG8_WAIT_V(8); PG8_WAIT_L(0); PG8_BAR; PG8_MMA(0, 0, At, B0); PG8_MMA(0, 1, At, B1); PG8_BAR; PG8_SCHED;
;             PG8_LDA(At, 0, 1); PG8_STAGE(PG8_SB(0, 0), b2, voffB); PG8_STAGE(PG8_SB(0, 1), b2 + hstepB, voffB); PG8_STAGE(PG8_SA(0, 0), a2, voffA);
;             PG8_WAIT_V(8); PG8_WAIT_L(0); PG8_BAR; PG8_MMA(1, 0, At, B0); PG8_MMA(1, 1, At, B1); PG8_BAR; PG8_SCHED;
.LBB0_701:
	ds_read_b128 v[148:151], v1
	ds_read_b128 v[152:155], v1 offset:1024
	ds_read_b128 v[156:159], v1 offset:2048
	ds_read_b128 v[160:163], v1 offset:3072
	ds_read_b128 v[164:167], v143
	ds_read_b128 v[168:171], v143 offset:1024
	ds_read_b128 v[172:175], v143 offset:2048
	ds_read_b128 v[176:179], v143 offset:3072
	s_cmp_eq_u32 s6, 12
	s_cselect_b32 s70, s0, s57
	s_cselect_b32 s71, s1, s81
	s_cselect_b32 s68, s62, s82
	s_cselect_b32 s69, s63, s83
	s_add_u32 s66, s70, 0x80
	s_addc_u32 s67, s71, 0
	ds_read_b128 v[180:183], v144
	ds_read_b128 v[184:187], v144 offset:1024
	ds_read_b128 v[188:191], v144 offset:2048
	ds_read_b128 v[192:195], v144 offset:3072
	ds_read_b128 v[196:199], v144 offset:4096
	ds_read_b128 v[200:203], v144 offset:5120
	ds_read_b128 v[204:207], v144 offset:6144
	ds_read_b128 v[208:211], v144 offset:7168
	s_mov_b32 m0, s76
	s_nop 0
	global_load_lds_dwordx4 v138, s[64:65]
	s_mov_b32 m0, s77
	s_nop 0
	global_load_lds_dwordx4 v140, s[64:65]
	s_waitcnt vmcnt(8)
	s_waitcnt lgkmcnt(0)
	s_barrier
	s_setprio 1
	v_mfma_f32_16x16x32_bf16 v[126:129], v[148:151], v[180:183], v[126:129]
	v_mfma_f32_16x16x32_bf16 v[122:125], v[156:159], v[180:183], v[122:125]
	v_mfma_f32_16x16x32_bf16 v[118:121], v[148:151], v[188:191], v[118:121]
	v_mfma_f32_16x16x32_bf16 v[110:113], v[156:159], v[188:191], v[110:113]
	v_mfma_f32_16x16x32_bf16 v[102:105], v[148:151], v[196:199], v[102:105]
	v_mfma_f32_16x16x32_bf16 v[94:97], v[156:159], v[196:199], v[94:97]
	v_mfma_f32_16x16x32_bf16 v[86:89], v[148:151], v[204:207], v[86:89]
	v_mfma_f32_16x16x32_bf16 v[78:81], v[156:159], v[204:207], v[78:81]
	v_mfma_f32_16x16x32_bf16 v[126:129], v[152:155], v[184:187], v[126:129]
	v_mfma_f32_16x16x32_bf16 v[122:125], v[160:163], v[184:187], v[122:125]
	v_mfma_f32_16x16x32_bf16 v[118:121], v[152:155], v[192:195], v[118:121]
	v_mfma_f32_16x16x32_bf16 v[110:113], v[160:163], v[192:195], v[110:113]
	v_mfma_f32_16x16x32_bf16 v[102:105], v[152:155], v[200:203], v[102:105]
	v_mfma_f32_16x16x32_bf16 v[94:97], v[160:163], v[200:203], v[94:97]
	v_mfma_f32_16x16x32_bf16 v[86:89], v[152:155], v[208:211], v[86:89]
	v_mfma_f32_16x16x32_bf16 v[78:81], v[160:163], v[208:211], v[78:81]
	v_mfma_f32_16x16x32_bf16 v[114:117], v[164:167], v[180:183], v[114:117]
	v_mfma_f32_16x16x32_bf16 v[106:109], v[172:175], v[180:183], v[106:109]
	v_mfma_f32_16x16x32_bf16 v[98:101], v[164:167], v[188:191], v[98:101]
	v_mfma_f32_16x16x32_bf16 v[90:93], v[172:175], v[188:191], v[90:93]
	v_mfma_f32_16x16x32_bf16 v[82:85], v[164:167], v[196:199], v[82:85]
	v_mfma_f32_16x16x32_bf16 v[74:77], v[172:175], v[196:199], v[74:77]
	v_mfma_f32_16x16x32_bf16 v[70:73], v[164:167], v[204:207], v[70:73]
	v_mfma_f32_16x16x32_bf16 v[66:69], v[172:175], v[204:207], v[66:69]
	v_mfma_f32_16x16x32_bf16 v[114:117], v[168:171], v[184:187], v[114:117]
	v_mfma_f32_16x16x32_bf16 v[106:109], v[176:179], v[184:187], v[106:109]
	v_mfma_f32_16x16x32_bf16 v[98:101], v[168:171], v[192:195], v[98:101]
	v_mfma_f32_16x16x32_bf16 v[90:93], v[176:179], v[192:195], v[90:93]
	v_mfma_f32_16x16x32_bf16 v[82:85], v[168:171], v[200:203], v[82:85]
	v_mfma_f32_16x16x32_bf16 v[74:77], v[176:179], v[200:203], v[74:77]
	v_mfma_f32_16x16x32_bf16 v[70:73], v[168:171], v[208:211], v[70:73]
	v_mfma_f32_16x16x32_bf16 v[66:69], v[176:179], v[208:211], v[66:69]
	s_setprio 0
	s_barrier
	ds_read_b128 v[180:183], v144 offset:16384
	ds_read_b128 v[184:187], v144 offset:17408
	ds_read_b128 v[188:191], v144 offset:18432
	ds_read_b128 v[192:195], v144 offset:19456
	ds_read_b128 v[196:199], v144 offset:20480
	ds_read_b128 v[200:203], v144 offset:21504
	ds_read_b128 v[204:207], v144 offset:22528
	ds_read_b128 v[208:211], v144 offset:23552
	s_mov_b32 m0, s24
	s_nop 0
	global_load_lds_dwordx4 v139, s[68:69]
	s_add_u32 s84, s68, 0x200000
	s_mov_b32 m0, s25
	s_nop 0
	global_load_lds_dwordx4 v141, s[68:69]
	s_addc_u32 s85, s69, 0
	s_mov_b32 m0, s26
	s_nop 0
	global_load_lds_dwordx4 v139, s[84:85]
	s_mov_b32 m0, s27
	s_nop 0
	global_load_lds_dwordx4 v141, s[84:85]
	s_mov_b32 m0, s15
	s_nop 0
	global_load_lds_dwordx4 v138, s[70:71]
	s_mov_b32 m0, s28
	s_nop 0
	global_load_lds_dwordx4 v140, s[70:71]
	s_waitcnt vmcnt(8)
	s_waitcnt lgkmcnt(0)
	s_barrier
	s_setprio 1
	v_mfma_f32_16x16x32_bf16 v[62:65], v[148:151], v[180:183], v[62:65]
	v_mfma_f32_16x16x32_bf16 v[58:61], v[156:159], v[180:183], v[58:61]
	v_mfma_f32_16x16x32_bf16 v[54:57], v[148:151], v[188:191], v[54:57]
	v_mfma_f32_16x16x32_bf16 v[46:49], v[156:159], v[188:191], v[46:49]
	v_mfma_f32_16x16x32_bf16 v[38:41], v[148:151], v[196:199], v[38:41]
	v_mfma_f32_16x16x32_bf16 v[30:33], v[156:159], v[196:199], v[30:33]
	v_mfma_f32_16x16x32_bf16 v[22:25], v[148:151], v[204:207], v[22:25]
	v_mfma_f32_16x16x32_bf16 v[14:17], v[156:159], v[204:207], v[14:17]
	v_mfma_f32_16x16x32_bf16 v[62:65], v[152:155], v[184:187], v[62:65]
	v_mfma_f32_16x16x32_bf16 v[58:61], v[160:163], v[184:187], v[58:61]
	v_mfma_f32_16x16x32_bf16 v[54:57], v[152:155], v[192:195], v[54:57]
	v_mfma_f32_16x16x32_bf16 v[46:49], v[160:163], v[192:195], v[46:49]
	v_mfma_f32_16x16x32_bf16 v[38:41], v[152:155], v[200:203], v[38:41]
	v_mfma_f32_16x16x32_bf16 v[30:33], v[160:163], v[200:203], v[30:33]
	v_mfma_f32_16x16x32_bf16 v[22:25], v[152:155], v[208:211], v[22:25]
	v_mfma_f32_16x16x32_bf16 v[14:17], v[160:163], v[208:211], v[14:17]
	v_mfma_f32_16x16x32_bf16 v[50:53], v[164:167], v[180:183], v[50:53]
	v_mfma_f32_16x16x32_bf16 v[42:45], v[172:175], v[180:183], v[42:45]
	v_mfma_f32_16x16x32_bf16 v[34:37], v[164:167], v[188:191], v[34:37]
	v_mfma_f32_16x16x32_bf16 v[26:29], v[172:175], v[188:191], v[26:29]
	v_mfma_f32_16x16x32_bf16 v[18:21], v[164:167], v[196:199], v[18:21]
	v_mfma_f32_16x16x32_bf16 v[10:13], v[172:175], v[196:199], v[10:13]
	v_mfma_f32_16x16x32_bf16 v[6:9], v[164:167], v[204:207], v[6:9]
	v_mfma_f32_16x16x32_bf16 v[2:5], v[172:175], v[204:207], v[2:5]
	v_mfma_f32_16x16x32_bf16 v[50:53], v[168:171], v[184:187], v[50:53]
	v_mfma_f32_16x16x32_bf16 v[42:45], v[176:179], v[184:187], v[42:45]
	v_mfma_f32_16x16x32_bf16 v[34:37], v[168:171], v[192:195], v[34:37]
	v_mfma_f32_16x16x32_bf16 v[26:29], v[176:179], v[192:195], v[26:29]
	v_mfma_f32_16x16x32_bf16 v[18:21], v[168:171], v[200:203], v[18:21]
	v_mfma_f32_16x16x32_bf16 v[10:13], v[176:179], v[200:203], v[10:13]
	v_mfma_f32_16x16x32_bf16 v[6:9], v[168:171], v[208:211], v[6:9]
	v_mfma_f32_16x16x32_bf16 v[2:5], v[176:179], v[208:211], v[2:5]
	s_setprio 0
	s_barrier
; #define PG8_STAGE(bufoff, gbase, voff) do { if constexpr (VAR != 1 && VAR != 3) { _Pragma("unroll") for (int _i = 0; _i < 2; ++_i) \
;         asm volatile("s_mov_b32 m0, %2\n\ts_nop 0\n\tglobal_load_lds_dwordx4 %0, %1" :: "v"((voff)[_i]), "s"((const char*)(gbase)), "s"(ldsbase + (unsigned)((bufoff) + _i * 8192)) : "memory", "m0"); } } while (0)
; #define PG8_LDA(dst, b, h) do { if constexpr (VAR < 2) _Pragma("unroll") for (int m = 0; m < 4; ++m) _Pragma("unroll") for (int k = 0; k < 2; ++k) dst[m][k] = *(const LAS bf16x8*)(lds + PG8_SA(b, h) + aoff + m * 2048 + k * 1024); } while (0)
; #define PG8_LDB(dst, b, h) do { if constexpr (VAR < 2) _Pragma("unroll") for (int n = 0; n < 2; ++n) _Pragma("unroll") for (int k = 0; k < 2; ++k) dst[n][k] = *(const LAS bf16x8*)(lds + PG8_SB(b, h) + boff + n * 2048 + k * 1024); } while (0)
; #define PG8_WAIT_V(n) asm volatile("s_waitcnt vmcnt(" #n ")" ::: "memory")
; #define PG8_WAIT_L(n) asm volatile("s_waitcnt lgkmcnt(" #n ")" ::: "memory")
; #define PG8_BAR do { if constexpr (VAR != 3) __builtin_amdgcn_s_barrier(); } while (0)
; #define PG8_SCHED __builtin_amdgcn_sched_barrier(0)
;     ...
;             PG8_LDB(B0, 1, 0); PG8_LDB(B1, 1, 1); PG8_SCHED; PG8_LDA(At, 1, 0); PG8_STAGE(PG8_SA(0, 1), a2 + hstepA, voffA);
;             PG8_WAIT_V(8); PG8_WAIT_L(0); PG8_BAR; PG8_MMA(0, 0, At, B0); PG8_MMA(0, 1, At, B1); PG8_BAR; PG8_SCHED;
;             PG8_LDA(At, 1, 1); PG8_STAGE(PG8_SB(1, 0), b3, voffB); PG8_STAGE(PG8_SB(1, 1), b3 + hstepB, voffB); PG8_STAGE(PG8_SA(1, 0), a3, voffA);
;             PG8_WAIT_V(8); PG8_WAIT_L(0); PG8_BAR; PG8_MMA(1, 0, At, B0); PG8_MMA(1, 1, At, B1); PG8_BAR; PG8_SCHED;
;         }
;         if (wr == 0) PG8_BAR;
	ds_read_b128 v[148:151], v145
	ds_read_b128 v[152:155], v145 offset:1024
	ds_read_b128 v[156:159], v145 offset:2048
	ds_read_b128 v[160:163], v145 offset:3072
	ds_read_b128 v[164:167], v146
	ds_read_b128 v[168:171], v146 offset:1024
	ds_read_b128 v[172:175], v146 offset:2048
	ds_read_b128 v[176:179], v146 offset:3072
	ds_read_b128 v[180:183], v144 offset:32768
	ds_read_b128 v[184:187], v144 offset:33792
	ds_read_b128 v[188:191], v144 offset:34816
	ds_read_b128 v[192:195], v144 offset:35840
	ds_read_b128 v[196:199], v144 offset:36864
	ds_read_b128 v[200:203], v144 offset:37888
	ds_read_b128 v[204:207], v144 offset:38912
	ds_read_b128 v[208:211], v144 offset:39936
	s_add_u32 s70, s70, 0x100000
	s_addc_u32 s71, s71, 0
	s_mov_b32 m0, s29
	s_nop 0
	global_load_lds_dwordx4 v138, s[70:71]
	s_mov_b32 m0, s30
	s_nop 0
	global_load_lds_dwordx4 v140, s[70:71]
	s_waitcnt vmcnt(8)
	s_waitcnt lgkmcnt(0)
	s_barrier
	s_setprio 1
	v_mfma_f32_16x16x32_bf16 v[126:129], v[148:151], v[180:183], v[126:129]
	v_mfma_f32_16x16x32_bf16 v[122:125], v[156:159], v[180:183], v[122:125]
	v_mfma_f32_16x16x32_bf16 v[118:121], v[148:151], v[188:191], v[118:121]
	v_mfma_f32_16x16x32_bf16 v[110:113], v[156:159], v[188:191], v[110:113]
	v_mfma_f32_16x16x32_bf16 v[102:105], v[148:151], v[196:199], v[102:105]
	v_mfma_f32_16x16x32_bf16 v[94:97], v[156:159], v[196:199], v[94:97]
	v_mfma_f32_16x16x32_bf16 v[86:89], v[148:151], v[204:207], v[86:89]
	v_mfma_f32_16x16x32_bf16 v[78:81], v[156:159], v[204:207], v[78:81]
	v_mfma_f32_16x16x32_bf16 v[126:129], v[152:155], v[184:187], v[126:129]
	v_mfma_f32_16x16x32_bf16 v[122:125], v[160:163], v[184:187], v[122:125]
	v_mfma_f32_16x16x32_bf16 v[118:121], v[152:155], v[192:195], v[118:121]
	v_mfma_f32_16x16x32_bf16 v[110:113], v[160:163], v[192:195], v[110:113]
	v_mfma_f32_16x16x32_bf16 v[102:105], v[152:155], v[200:203], v[102:105]
	v_mfma_f32_16x16x32_bf16 v[94:97], v[160:163], v[200:203], v[94:97]
	v_mfma_f32_16x16x32_bf16 v[86:89], v[152:155], v[208:211], v[86:89]
	v_mfma_f32_16x16x32_bf16 v[78:81], v[160:163], v[208:211], v[78:81]
	v_mfma_f32_16x16x32_bf16 v[114:117], v[164:167], v[180:183], v[114:117]
	v_mfma_f32_16x16x32_bf16 v[106:109], v[172:175], v[180:183], v[106:109]
	v_mfma_f32_16x16x32_bf16 v[98:101], v[164:167], v[188:191], v[98:101]
	v_mfma_f32_16x16x32_bf16 v[90:93], v[172:175], v[188:191], v[90:93]
	v_mfma_f32_16x16x32_bf16 v[82:85], v[164:167], v[196:199], v[82:85]
	v_mfma_f32_16x16x32_bf16 v[74:77], v[172:175], v[196:199], v[74:77]
	v_mfma_f32_16x16x32_bf16 v[70:73], v[164:167], v[204:207], v[70:73]
	v_mfma_f32_16x16x32_bf16 v[66:69], v[172:175], v[204:207], v[66:69]
	v_mfma_f32_16x16x32_bf16 v[114:117], v[168:171], v[184:187], v[114:117]
	v_mfma_f32_16x16x32_bf16 v[106:109], v[176:179], v[184:187], v[106:109]
	v_mfma_f32_16x16x32_bf16 v[98:101], v[168:171], v[192:195], v[98:101]
	v_mfma_f32_16x16x32_bf16 v[90:93], v[176:179], v[192:195], v[90:93]
	v_mfma_f32_16x16x32_bf16 v[82:85], v[168:171], v[200:203], v[82:85]
	v_mfma_f32_16x16x32_bf16 v[74:77], v[176:179], v[200:203], v[74:77]
	v_mfma_f32_16x16x32_bf16 v[70:73], v[168:171], v[208:211], v[70:73]
	v_mfma_f32_16x16x32_bf16 v[66:69], v[176:179], v[208:211], v[66:69]
	s_setprio 0
	s_barrier
	ds_read_b128 v[180:183], v144 offset:49152
	ds_read_b128 v[184:187], v144 offset:50176
	ds_read_b128 v[188:191], v144 offset:51200
	ds_read_b128 v[192:195], v144 offset:52224
	ds_read_b128 v[196:199], v144 offset:53248
	ds_read_b128 v[200:203], v144 offset:54272
	ds_read_b128 v[204:207], v144 offset:55296
	ds_read_b128 v[208:211], v144 offset:56320
	s_add_u32 s70, s68, 0x80
	s_addc_u32 s71, s69, 0
	s_mov_b32 m0, s31
	s_nop 0
	global_load_lds_dwordx4 v139, s[70:71]
	s_add_u32 s68, s68, 0x200080
	s_mov_b32 m0, s33
	s_nop 0
	global_load_lds_dwordx4 v141, s[70:71]
	s_addc_u32 s69, s69, 0
	s_mov_b32 m0, s74
	s_nop 0
	global_load_lds_dwordx4 v139, s[68:69]
	s_mov_b32 m0, s75
	s_nop 0
	global_load_lds_dwordx4 v141, s[68:69]
	s_mov_b32 m0, s72
	s_nop 0
	global_load_lds_dwordx4 v138, s[66:67]
	s_mov_b32 m0, s73
	s_nop 0
	global_load_lds_dwordx4 v140, s[66:67]
	s_waitcnt vmcnt(8)
	s_waitcnt lgkmcnt(0)
	s_barrier
	s_setprio 1
	v_mfma_f32_16x16x32_bf16 v[62:65], v[148:151], v[180:183], v[62:65]
	v_mfma_f32_16x16x32_bf16 v[58:61], v[156:159], v[180:183], v[58:61]
	v_mfma_f32_16x16x32_bf16 v[54:57], v[148:151], v[188:191], v[54:57]
	v_mfma_f32_16x16x32_bf16 v[46:49], v[156:159], v[188:191], v[46:49]
	v_mfma_f32_16x16x32_bf16 v[38:41], v[148:151], v[196:199], v[38:41]
	v_mfma_f32_16x16x32_bf16 v[30:33], v[156:159], v[196:199], v[30:33]
	v_mfma_f32_16x16x32_bf16 v[22:25], v[148:151], v[204:207], v[22:25]
	v_mfma_f32_16x16x32_bf16 v[14:17], v[156:159], v[204:207], v[14:17]
	v_mfma_f32_16x16x32_bf16 v[62:65], v[152:155], v[184:187], v[62:65]
	v_mfma_f32_16x16x32_bf16 v[58:61], v[160:163], v[184:187], v[58:61]
	v_mfma_f32_16x16x32_bf16 v[54:57], v[152:155], v[192:195], v[54:57]
	v_mfma_f32_16x16x32_bf16 v[46:49], v[160:163], v[192:195], v[46:49]
	v_mfma_f32_16x16x32_bf16 v[38:41], v[152:155], v[200:203], v[38:41]
	v_mfma_f32_16x16x32_bf16 v[30:33], v[160:163], v[200:203], v[30:33]
	v_mfma_f32_16x16x32_bf16 v[22:25], v[152:155], v[208:211], v[22:25]
	v_mfma_f32_16x16x32_bf16 v[14:17], v[160:163], v[208:211], v[14:17]
	v_mfma_f32_16x16x32_bf16 v[50:53], v[164:167], v[180:183], v[50:53]
	v_mfma_f32_16x16x32_bf16 v[42:45], v[172:175], v[180:183], v[42:45]
	v_mfma_f32_16x16x32_bf16 v[34:37], v[164:167], v[188:191], v[34:37]
	v_mfma_f32_16x16x32_bf16 v[26:29], v[172:175], v[188:191], v[26:29]
	v_mfma_f32_16x16x32_bf16 v[18:21], v[164:167], v[196:199], v[18:21]
	v_mfma_f32_16x16x32_bf16 v[10:13], v[172:175], v[196:199], v[10:13]
	v_mfma_f32_16x16x32_bf16 v[6:9], v[164:167], v[204:207], v[6:9]
	v_mfma_f32_16x16x32_bf16 v[2:5], v[172:175], v[204:207], v[2:5]
	v_mfma_f32_16x16x32_bf16 v[50:53], v[168:171], v[184:187], v[50:53]
	v_mfma_f32_16x16x32_bf16 v[42:45], v[176:179], v[184:187], v[42:45]
	v_mfma_f32_16x16x32_bf16 v[34:37], v[168:171], v[192:195], v[34:37]
	v_mfma_f32_16x16x32_bf16 v[26:29], v[176:179], v[192:195], v[26:29]
	v_mfma_f32_16x16x32_bf16 v[18:21], v[168:171], v[200:203], v[18:21]
	v_mfma_f32_16x16x32_bf16 v[10:13], v[176:179], v[200:203], v[10:13]
	v_mfma_f32_16x16x32_bf16 v[6:9], v[168:171], v[208:211], v[6:9]
	v_mfma_f32_16x16x32_bf16 v[2:5], v[176:179], v[208:211], v[2:5]
	s_setprio 0
	s_barrier
	s_add_i32 s6, s6, 2
	s_add_u32 s57, s57, 0x100
	s_addc_u32 s81, s81, 0
	s_add_u32 s82, s82, 0x100
	s_addc_u32 s83, s83, 0
	s_add_u32 s64, s64, 0x100
	s_addc_u32 s65, s65, 0
	s_cmp_gt_u32 s6, 13
	s_cbranch_scc0 .LBB0_701
.Lmy_kexit_4:
	s_and_b64 vcc, exec, s[8:9]
	s_cbranch_vccz .LBB0_704
	s_barrier

; __device__ __forceinline__ const char* unitA(const Gemm& g, const Unit& u) { return (const char*)(g.A + (size_t)(u.z / g.zdiv) * g.sAhi + (size_t)(u.z % g.zdiv) * g.sAlo + (size_t)u.pm * BM * g.lda); }
; __device__ __forceinline__ const char* unitB(const Gemm& g, const Unit& u) { return (const char*)(g.Bt + (size_t)(u.z / g.zdiv) * g.sBhi + (size_t)(u.z % g.zdiv) * g.sBlo + (size_t)(u.pm / g.bdiv) * g.sBpm + (size_t)u.pn * BM * g.ldb); }
; #define PG8_STAGE(bufoff, gbase, voff) do { if constexpr (VAR != 1 && VAR != 3) { _Pragma("unroll") for (int _i = 0; _i < 2; ++_i) \
;         asm volatile("s_mov_b32 m0, %2\n\ts_nop 0\n\tglobal_load_lds_dwordx4 %0, %1" :: "v"((voff)[_i]), "s"((const char*)(gbase)), "s"(ldsbase + (unsigned)((bufoff) + _i * 8192)) : "memory", "m0"); } } while (0)
; #define PG8_LDA(dst, b, h) do { if constexpr (VAR < 2) _Pragma("unroll") for (int m = 0; m < 4; ++m) _Pragma("unroll") for (int k = 0; k < 2; ++k) dst[m][k] = *(const LAS bf16x8*)(lds + PG8_SA(b, h) + aoff + m * 2048 + k * 1024); } while (0)
; #define PG8_LDB(dst, b, h) do { if constexpr (VAR < 2) _Pragma("unroll") for (int n = 0; n < 2; ++n) _Pragma("unroll") for (int k = 0; k < 2; ++k) dst[n][k] = *(const LAS bf16x8*)(lds + PG8_SB(b, h) + boff + n * 2048 + k * 1024); } while (0)
; #define PG8_WAIT_V(n) asm volatile("s_waitcnt vmcnt(" #n ")" ::: "memory")
;     ...
;         const bool has_next = S.next(ui + 1, nxt);
;         const char* nA = has_next ? unitA(g, nxt) : cA; const char* nB = has_next ? unitB(g, nxt) : cB;
;         for (int t = 0; t < nt; t += 2) {
;             const bool last = (t == nt - 2);
;             const char* a1 = cA + (size_t)(t + 1) * kstep;
;             const char* a2 = last ? nA : cA + (size_t)(t + 2) * kstep; const char* b2 = last ? nB : cB + (size_t)(t + 2) * kstep;
;             const char* a3 = a2 + kstep; const char* b3 = b2 + kstep;
;             PG8_LDB(B0, 0, 0); PG8_LDB(B1, 0, 1); PG8_SCHED; PG8_LDA(At, 0, 0); PG8_STAGE(PG8_SA(1, 1), a1 + hstepA, voffA);
;             PG8_WAIT_V(8); PG8_WAIT_L(0); PG8_BAR; PG8_MMA(0, 0, At, B0); PG8_MMA(0, 1, At, B1); PG8_BAR; PG8_SCHED;
;             PG8_LDA(At, 0, 1); PG8_STAGE(PG8_SB(0, 0), b2, voffB); PG8_STAGE(PG8_SB(0, 1), b2 + hstepB, voffB); PG8_STAGE(PG8_SA(0, 0), a2, voffA);
;             PG8_WAIT_V(8); PG8_WAIT_L(0); PG8_BAR; PG8_MMA(1, 0, At, B0); PG8_MMA(1, 1, At, B1); PG8_BAR; PG8_SCHED;
.LBB0_788:
	s_ashr_i32 s73, s72, 31
	s_lshl_b64 s[14:15], s[72:73], 21
	s_add_u32 s74, s60, s14
	s_addc_u32 s75, s61, s15
	s_and_b64 s[14:15], s[10:11], exec
	s_cselect_b32 s14, s75, s83
	s_cselect_b32 s15, s74, s82
	s_ashr_i32 s71, s70, 31
	s_lshl_b64 s[26:27], s[70:71], 21
	s_add_u32 s76, s58, s26
	s_addc_u32 s77, s59, s27
	s_and_b64 s[26:27], s[10:11], exec
	s_cselect_b32 s25, s77, s81
	s_cselect_b32 s26, s76, s80
	s_add_u32 s27, s82, 0x100
	s_addc_u32 s71, s83, 0
	s_add_u32 s73, s80, 0x100
	s_addc_u32 vcc_lo, s81, 0
	s_add_u32 s80, s82, 0x100080
	s_addc_u32 s81, s83, 0
	s_mov_b32 vcc_hi, -2
	s_waitcnt vmcnt(41)
	s_waitcnt vmcnt(40)
	s_waitcnt vmcnt(38)
	s_waitcnt vmcnt(35)
	s_waitcnt vmcnt(34)
	s_waitcnt vmcnt(32)
	ds_read_b128 v[98:101], v191
	ds_read_b128 v[110:113], v191 offset:1024
	ds_read_b128 v[122:125], v191 offset:2048
	ds_read_b128 v[134:137], v191 offset:3072
	ds_read_b128 v[138:141], v192
	ds_read_b128 v[150:153], v192 offset:1024
	ds_read_b128 v[154:157], v192 offset:2048
	ds_read_b128 v[162:165], v192 offset:3072
	s_cmp_eq_u32 vcc_hi, 60
	s_cselect_b32 s86, s15, s27
	s_cselect_b32 s87, s14, s71
	s_cselect_b32 s84, s26, s73
	s_cselect_b32 s85, s25, vcc_lo
	s_add_u32 s82, s86, 0x80
	s_addc_u32 s83, s87, 0
	ds_read_b128 v[166:169], v193
	ds_read_b128 v[170:173], v193 offset:1024
	ds_read_b128 v[174:177], v193 offset:2048
	ds_read_b128 v[178:181], v193 offset:3072
	ds_read_b128 v[198:201], v193 offset:4096
	ds_read_b128 v[202:205], v193 offset:5120
	ds_read_b128 v[206:209], v193 offset:6144
	ds_read_b128 v[210:213], v193 offset:7168
	s_mov_b32 m0, s31
	s_nop 0
	global_load_lds_dwordx4 v184, s[80:81]
	s_mov_b32 m0, s19
	s_nop 0
	global_load_lds_dwordx4 v186, s[80:81]
	s_waitcnt vmcnt(8)
	s_waitcnt lgkmcnt(0)
	s_barrier
	s_setprio 1
	v_mfma_f32_16x16x32_bf16 v[146:149], v[98:101], v[166:169], 0
	v_mfma_f32_16x16x32_bf16 v[142:145], v[122:125], v[166:169], 0
	v_mfma_f32_16x16x32_bf16 v[118:121], v[98:101], v[174:177], 0
	v_mfma_f32_16x16x32_bf16 v[114:117], v[122:125], v[174:177], 0
	v_mfma_f32_16x16x32_bf16 v[94:97], v[98:101], v[198:201], 0
	v_mfma_f32_16x16x32_bf16 v[90:93], v[122:125], v[198:201], 0
	v_mfma_f32_16x16x32_bf16 v[78:81], v[98:101], v[206:209], 0
	v_mfma_f32_16x16x32_bf16 v[74:77], v[122:125], v[206:209], 0
	v_mfma_f32_16x16x32_bf16 v[146:149], v[110:113], v[170:173], v[146:149]
	v_mfma_f32_16x16x32_bf16 v[142:145], v[134:137], v[170:173], v[142:145]
	v_mfma_f32_16x16x32_bf16 v[118:121], v[110:113], v[178:181], v[118:121]
	v_mfma_f32_16x16x32_bf16 v[114:117], v[134:137], v[178:181], v[114:117]
	v_mfma_f32_16x16x32_bf16 v[94:97], v[110:113], v[202:205], v[94:97]
	v_mfma_f32_16x16x32_bf16 v[90:93], v[134:137], v[202:205], v[90:93]
	v_mfma_f32_16x16x32_bf16 v[78:81], v[110:113], v[210:213], v[78:81]
	v_mfma_f32_16x16x32_bf16 v[74:77], v[134:137], v[210:213], v[74:77]
	v_mfma_f32_16x16x32_bf16 v[130:133], v[138:141], v[166:169], 0
	v_mfma_f32_16x16x32_bf16 v[126:129], v[154:157], v[166:169], 0
	v_mfma_f32_16x16x32_bf16 v[106:109], v[138:141], v[174:177], 0
	v_mfma_f32_16x16x32_bf16 v[102:105], v[154:157], v[174:177], 0
	v_mfma_f32_16x16x32_bf16 v[86:89], v[138:141], v[198:201], 0
	v_mfma_f32_16x16x32_bf16 v[82:85], v[154:157], v[198:201], 0
	v_mfma_f32_16x16x32_bf16 v[70:73], v[138:141], v[206:209], 0
	v_mfma_f32_16x16x32_bf16 v[66:69], v[154:157], v[206:209], 0
	v_mfma_f32_16x16x32_bf16 v[130:133], v[150:153], v[170:173], v[130:133]
	v_mfma_f32_16x16x32_bf16 v[126:129], v[162:165], v[170:173], v[126:129]
	v_mfma_f32_16x16x32_bf16 v[106:109], v[150:153], v[178:181], v[106:109]
	v_mfma_f32_16x16x32_bf16 v[102:105], v[162:165], v[178:181], v[102:105]
	v_mfma_f32_16x16x32_bf16 v[86:89], v[150:153], v[202:205], v[86:89]
	v_mfma_f32_16x16x32_bf16 v[82:85], v[162:165], v[202:205], v[82:85]
	v_mfma_f32_16x16x32_bf16 v[70:73], v[150:153], v[210:213], v[70:73]
	v_mfma_f32_16x16x32_bf16 v[66:69], v[162:165], v[210:213], v[66:69]
	s_setprio 0
	s_barrier
	ds_read_b128 v[166:169], v193 offset:16384
	ds_read_b128 v[170:173], v193 offset:17408
	ds_read_b128 v[174:177], v193 offset:18432
	ds_read_b128 v[178:181], v193 offset:19456
	ds_read_b128 v[198:201], v193 offset:20480
	ds_read_b128 v[202:205], v193 offset:21504
	ds_read_b128 v[206:209], v193 offset:22528
	ds_read_b128 v[210:213], v193 offset:23552
	s_mov_b32 m0, s91
	s_nop 0
	global_load_lds_dwordx4 v185, s[84:85]
	s_add_u32 s88, s84, 0x100000
	s_mov_b32 m0, s92
	s_nop 0
	global_load_lds_dwordx4 v187, s[84:85]
	s_addc_u32 s89, s85, 0
	s_mov_b32 m0, s93
	s_nop 0
	global_load_lds_dwordx4 v185, s[88:89]
	s_mov_b32 m0, s94
	s_nop 0
	global_load_lds_dwordx4 v187, s[88:89]
	s_mov_b32 m0, s35
	s_nop 0
	global_load_lds_dwordx4 v184, s[86:87]
	s_mov_b32 m0, s79
	s_nop 0
	global_load_lds_dwordx4 v186, s[86:87]
	s_waitcnt vmcnt(8)
	s_waitcnt lgkmcnt(0)
	s_barrier
; #define PG8_STAGE(bufoff, gbase, voff) do { if constexpr (VAR != 1 && VAR != 3) { _Pragma("unroll") for (int _i = 0; _i < 2; ++_i) \
;         asm volatile("s_mov_b32 m0, %2\n\ts_nop 0\n\tglobal_load_lds_dwordx4 %0, %1" :: "v"((voff)[_i]), "s"((const char*)(gbase)), "s"(ldsbase + (unsigned)((bufoff) + _i * 8192)) : "memory", "m0"); } } while (0)
; #define PG8_LDA(dst, b, h) do { if constexpr (VAR < 2) _Pragma("unroll") for (int m = 0; m < 4; ++m) _Pragma("unroll") for (int k = 0; k < 2; ++k) dst[m][k] = *(const LAS bf16x8*)(lds + PG8_SA(b, h) + aoff + m * 2048 + k * 1024); } while (0)
; #define PG8_LDB(dst, b, h) do { if constexpr (VAR < 2) _Pragma("unroll") for (int n = 0; n < 2; ++n) _Pragma("unroll") for (int k = 0; k < 2; ++k) dst[n][k] = *(const LAS bf16x8*)(lds + PG8_SB(b, h) + boff + n * 2048 + k * 1024); } while (0)
; #define PG8_WAIT_V(n) asm volatile("s_waitcnt vmcnt(" #n ")" ::: "memory")
; #define PG8_WAIT_L(n) asm volatile("s_waitcnt lgkmcnt(" #n ")" ::: "memory")
; #define PG8_BAR do { if constexpr (VAR != 3) __builtin_amdgcn_s_barrier(); } while (0)
; #define PG8_SCHED __builtin_amdgcn_sched_barrier(0)
;     ...
;             PG8_WAIT_V(8); PG8_WAIT_L(0); PG8_BAR; PG8_MMA(1, 0, At, B0); PG8_MMA(1, 1, At, B1); PG8_BAR; PG8_SCHED;
;             PG8_LDB(B0, 1, 0); PG8_LDB(B1, 1, 1); PG8_SCHED; PG8_LDA(At, 1, 0); PG8_STAGE(PG8_SA(0, 1), a2 + hstepA, voffA);
;             PG8_WAIT_V(8); PG8_WAIT_L(0); PG8_BAR; PG8_MMA(0, 0, At, B0); PG8_MMA(0, 1, At, B1); PG8_BAR; PG8_SCHED;
	s_setprio 1
	v_mfma_f32_16x16x32_bf16 v[62:65], v[98:101], v[166:169], 0
	v_mfma_f32_16x16x32_bf16 v[58:61], v[122:125], v[166:169], 0
	v_mfma_f32_16x16x32_bf16 v[46:49], v[98:101], v[174:177], 0
	v_mfma_f32_16x16x32_bf16 v[42:45], v[122:125], v[174:177], 0
	v_mfma_f32_16x16x32_bf16 v[30:33], v[98:101], v[198:201], 0
	v_mfma_f32_16x16x32_bf16 v[26:29], v[122:125], v[198:201], 0
	v_mfma_f32_16x16x32_bf16 v[14:17], v[98:101], v[206:209], 0
	v_mfma_f32_16x16x32_bf16 v[10:13], v[122:125], v[206:209], 0
	v_mfma_f32_16x16x32_bf16 v[62:65], v[110:113], v[170:173], v[62:65]
	v_mfma_f32_16x16x32_bf16 v[58:61], v[134:137], v[170:173], v[58:61]
	v_mfma_f32_16x16x32_bf16 v[46:49], v[110:113], v[178:181], v[46:49]
	v_mfma_f32_16x16x32_bf16 v[42:45], v[134:137], v[178:181], v[42:45]
	v_mfma_f32_16x16x32_bf16 v[30:33], v[110:113], v[202:205], v[30:33]
	v_mfma_f32_16x16x32_bf16 v[26:29], v[134:137], v[202:205], v[26:29]
	v_mfma_f32_16x16x32_bf16 v[14:17], v[110:113], v[210:213], v[14:17]
	v_mfma_f32_16x16x32_bf16 v[10:13], v[134:137], v[210:213], v[10:13]
	v_mfma_f32_16x16x32_bf16 v[54:57], v[138:141], v[166:169], 0
	v_mfma_f32_16x16x32_bf16 v[50:53], v[154:157], v[166:169], 0
	v_mfma_f32_16x16x32_bf16 v[38:41], v[138:141], v[174:177], 0
	v_mfma_f32_16x16x32_bf16 v[34:37], v[154:157], v[174:177], 0
	v_mfma_f32_16x16x32_bf16 v[22:25], v[138:141], v[198:201], 0
	v_mfma_f32_16x16x32_bf16 v[18:21], v[154:157], v[198:201], 0
	v_mfma_f32_16x16x32_bf16 v[6:9], v[138:141], v[206:209], 0
	v_mfma_f32_16x16x32_bf16 v[2:5], v[154:157], v[206:209], 0
	v_mfma_f32_16x16x32_bf16 v[54:57], v[150:153], v[170:173], v[54:57]
	v_mfma_f32_16x16x32_bf16 v[50:53], v[162:165], v[170:173], v[50:53]
	v_mfma_f32_16x16x32_bf16 v[38:41], v[150:153], v[178:181], v[38:41]
	v_mfma_f32_16x16x32_bf16 v[34:37], v[162:165], v[178:181], v[34:37]
	v_mfma_f32_16x16x32_bf16 v[22:25], v[150:153], v[202:205], v[22:25]
	v_mfma_f32_16x16x32_bf16 v[18:21], v[162:165], v[202:205], v[18:21]
	v_mfma_f32_16x16x32_bf16 v[6:9], v[150:153], v[210:213], v[6:9]
	v_mfma_f32_16x16x32_bf16 v[2:5], v[162:165], v[210:213], v[2:5]
	s_setprio 0
	s_barrier
	ds_read_b128 v[98:101], v194
	ds_read_b128 v[110:113], v194 offset:1024
	ds_read_b128 v[122:125], v194 offset:2048
	ds_read_b128 v[134:137], v194 offset:3072
	ds_read_b128 v[138:141], v195
	ds_read_b128 v[150:153], v195 offset:1024
	ds_read_b128 v[154:157], v195 offset:2048
	ds_read_b128 v[162:165], v195 offset:3072
	ds_read_b128 v[166:169], v193 offset:32768
	ds_read_b128 v[170:173], v193 offset:33792
	ds_read_b128 v[174:177], v193 offset:34816
	ds_read_b128 v[178:181], v193 offset:35840
	ds_read_b128 v[198:201], v193 offset:36864
	ds_read_b128 v[202:205], v193 offset:37888
	ds_read_b128 v[206:209], v193 offset:38912
	ds_read_b128 v[210:213], v193 offset:39936
	s_add_u32 s86, s86, 0x100000
	s_addc_u32 s87, s87, 0
	s_mov_b32 m0, s95
	s_nop 0
	global_load_lds_dwordx4 v184, s[86:87]
	s_mov_b32 m0, s96
	s_nop 0
	global_load_lds_dwordx4 v186, s[86:87]
	s_waitcnt vmcnt(8)
	s_waitcnt lgkmcnt(0)
	s_barrier
	s_setprio 1
	v_mfma_f32_16x16x32_bf16 v[146:149], v[98:101], v[166:169], v[146:149]
	v_mfma_f32_16x16x32_bf16 v[142:145], v[122:125], v[166:169], v[142:145]
	v_mfma_f32_16x16x32_bf16 v[118:121], v[98:101], v[174:177], v[118:121]
	v_mfma_f32_16x16x32_bf16 v[114:117], v[122:125], v[174:177], v[114:117]
	v_mfma_f32_16x16x32_bf16 v[94:97], v[98:101], v[198:201], v[94:97]
	v_mfma_f32_16x16x32_bf16 v[90:93], v[122:125], v[198:201], v[90:93]
	v_mfma_f32_16x16x32_bf16 v[78:81], v[98:101], v[206:209], v[78:81]
	v_mfma_f32_16x16x32_bf16 v[74:77], v[122:125], v[206:209], v[74:77]
	v_mfma_f32_16x16x32_bf16 v[146:149], v[110:113], v[170:173], v[146:149]
	v_mfma_f32_16x16x32_bf16 v[142:145], v[134:137], v[170:173], v[142:145]
	v_mfma_f32_16x16x32_bf16 v[118:121], v[110:113], v[178:181], v[118:121]
	v_mfma_f32_16x16x32_bf16 v[114:117], v[134:137], v[178:181], v[114:117]
	v_mfma_f32_16x16x32_bf16 v[94:97], v[110:113], v[202:205], v[94:97]
	v_mfma_f32_16x16x32_bf16 v[90:93], v[134:137], v[202:205], v[90:93]
	v_mfma_f32_16x16x32_bf16 v[78:81], v[110:113], v[210:213], v[78:81]
	v_mfma_f32_16x16x32_bf16 v[74:77], v[134:137], v[210:213], v[74:77]
	v_mfma_f32_16x16x32_bf16 v[130:133], v[138:141], v[166:169], v[130:133]
	v_mfma_f32_16x16x32_bf16 v[126:129], v[154:157], v[166:169], v[126:129]
	v_mfma_f32_16x16x32_bf16 v[106:109], v[138:141], v[174:177], v[106:109]
	v_mfma_f32_16x16x32_bf16 v[102:105], v[154:157], v[174:177], v[102:105]
	v_mfma_f32_16x16x32_bf16 v[86:89], v[138:141], v[198:201], v[86:89]
	v_mfma_f32_16x16x32_bf16 v[82:85], v[154:157], v[198:201], v[82:85]
	v_mfma_f32_16x16x32_bf16 v[70:73], v[138:141], v[206:209], v[70:73]
	v_mfma_f32_16x16x32_bf16 v[66:69], v[154:157], v[206:209], v[66:69]
	v_mfma_f32_16x16x32_bf16 v[130:133], v[150:153], v[170:173], v[130:133]
	v_mfma_f32_16x16x32_bf16 v[126:129], v[162:165], v[170:173], v[126:129]
	v_mfma_f32_16x16x32_bf16 v[106:109], v[150:153], v[178:181], v[106:109]
	v_mfma_f32_16x16x32_bf16 v[102:105], v[162:165], v[178:181], v[102:105]
	v_mfma_f32_16x16x32_bf16 v[86:89], v[150:153], v[202:205], v[86:89]
	v_mfma_f32_16x16x32_bf16 v[82:85], v[162:165], v[202:205], v[82:85]
	v_mfma_f32_16x16x32_bf16 v[70:73], v[150:153], v[210:213], v[70:73]
	v_mfma_f32_16x16x32_bf16 v[66:69], v[162:165], v[210:213], v[66:69]
	s_setprio 0
	s_barrier
; #define PG8_STAGE(bufoff, gbase, voff) do { if constexpr (VAR != 1 && VAR != 3) { _Pragma("unroll") for (int _i = 0; _i < 2; ++_i) \
;         asm volatile("s_mov_b32 m0, %2\n\ts_nop 0\n\tglobal_load_lds_dwordx4 %0, %1" :: "v"((voff)[_i]), "s"((const char*)(gbase)), "s"(ldsbase + (unsigned)((bufoff) + _i * 8192)) : "memory", "m0"); } } while (0)
; #define PG8_LDA(dst, b, h) do { if constexpr (VAR < 2) _Pragma("unroll") for (int m = 0; m < 4; ++m) _Pragma("unroll") for (int k = 0; k < 2; ++k) dst[m][k] = *(const LAS bf16x8*)(lds + PG8_SA(b, h) + aoff + m * 2048 + k * 1024); } while (0)
; #define PG8_LDB(dst, b, h) do { if constexpr (VAR < 2) _Pragma("unroll") for (int n = 0; n < 2; ++n) _Pragma("unroll") for (int k = 0; k < 2; ++k) dst[n][k] = *(const LAS bf16x8*)(lds + PG8_SB(b, h) + boff + n * 2048 + k * 1024); } while (0)
; #define PG8_WAIT_V(n) asm volatile("s_waitcnt vmcnt(" #n ")" ::: "memory")
; #define PG8_WAIT_L(n) asm volatile("s_waitcnt lgkmcnt(" #n ")" ::: "memory")
; #define PG8_BAR do { if constexpr (VAR != 3) __builtin_amdgcn_s_barrier(); } while (0)
; #define PG8_SCHED __builtin_amdgcn_sched_barrier(0)
;     ...
;             const bool last = (t == nt - 2);
;             const char* a1 = cA + (size_t)(t + 1) * kstep;
;             const char* a2 = last ? nA : cA + (size_t)(t + 2) * kstep; const char* b2 = last ? nB : cB + (size_t)(t + 2) * kstep;
;             const char* a3 = a2 + kstep; const char* b3 = b2 + kstep;
;             PG8_LDB(B0, 0, 0); PG8_LDB(B1, 0, 1); PG8_SCHED; PG8_LDA(At, 0, 0); PG8_STAGE(PG8_SA(1, 1), a1 + hstepA, voffA);
;             PG8_WAIT_V(8); PG8_WAIT_L(0); PG8_BAR; PG8_MMA(0, 0, At, B0); PG8_MMA(0, 1, At, B1); PG8_BAR; PG8_SCHED;
;     ...
;             PG8_LDA(At, 1, 1); PG8_STAGE(PG8_SB(1, 0), b3, voffB); PG8_STAGE(PG8_SB(1, 1), b3 + hstepB, voffB); PG8_STAGE(PG8_SA(1, 0), a3, voffA);
;             PG8_WAIT_V(8); PG8_WAIT_L(0); PG8_BAR; PG8_MMA(1, 0, At, B0); PG8_MMA(1, 1, At, B1); PG8_BAR; PG8_SCHED;
;         }
	ds_read_b128 v[166:169], v193 offset:49152
	ds_read_b128 v[170:173], v193 offset:50176
	ds_read_b128 v[174:177], v193 offset:51200
	ds_read_b128 v[178:181], v193 offset:52224
	ds_read_b128 v[198:201], v193 offset:53248
	ds_read_b128 v[202:205], v193 offset:54272
	ds_read_b128 v[206:209], v193 offset:55296
	ds_read_b128 v[210:213], v193 offset:56320
	s_add_u32 s86, s84, 0x80
	s_addc_u32 s87, s85, 0
	s_mov_b32 m0, s64
	s_nop 0
	global_load_lds_dwordx4 v185, s[86:87]
	s_add_u32 s84, s84, 0x100080
	s_mov_b32 m0, s65
	s_nop 0
	global_load_lds_dwordx4 v187, s[86:87]
	s_addc_u32 s85, s85, 0
	s_mov_b32 m0, s33
	s_nop 0
	global_load_lds_dwordx4 v185, s[84:85]
	s_mov_b32 m0, s30
	s_nop 0
	global_load_lds_dwordx4 v187, s[84:85]
	s_mov_b32 m0, s17
	s_nop 0
	global_load_lds_dwordx4 v184, s[82:83]
	s_mov_b32 m0, s28
	s_nop 0
	global_load_lds_dwordx4 v186, s[82:83]
	s_waitcnt vmcnt(8)
	s_waitcnt lgkmcnt(0)
	s_barrier
	s_setprio 1
	v_mfma_f32_16x16x32_bf16 v[62:65], v[98:101], v[166:169], v[62:65]
	v_mfma_f32_16x16x32_bf16 v[58:61], v[122:125], v[166:169], v[58:61]
	v_mfma_f32_16x16x32_bf16 v[46:49], v[98:101], v[174:177], v[46:49]
	v_mfma_f32_16x16x32_bf16 v[42:45], v[122:125], v[174:177], v[42:45]
	v_mfma_f32_16x16x32_bf16 v[30:33], v[98:101], v[198:201], v[30:33]
	v_mfma_f32_16x16x32_bf16 v[26:29], v[122:125], v[198:201], v[26:29]
	v_mfma_f32_16x16x32_bf16 v[14:17], v[98:101], v[206:209], v[14:17]
	v_mfma_f32_16x16x32_bf16 v[10:13], v[122:125], v[206:209], v[10:13]
	v_mfma_f32_16x16x32_bf16 v[62:65], v[110:113], v[170:173], v[62:65]
	v_mfma_f32_16x16x32_bf16 v[58:61], v[134:137], v[170:173], v[58:61]
	v_mfma_f32_16x16x32_bf16 v[46:49], v[110:113], v[178:181], v[46:49]
	v_mfma_f32_16x16x32_bf16 v[42:45], v[134:137], v[178:181], v[42:45]
	v_mfma_f32_16x16x32_bf16 v[30:33], v[110:113], v[202:205], v[30:33]
	v_mfma_f32_16x16x32_bf16 v[26:29], v[134:137], v[202:205], v[26:29]
	v_mfma_f32_16x16x32_bf16 v[14:17], v[110:113], v[210:213], v[14:17]
	v_mfma_f32_16x16x32_bf16 v[10:13], v[134:137], v[210:213], v[10:13]
	v_mfma_f32_16x16x32_bf16 v[54:57], v[138:141], v[166:169], v[54:57]
	v_mfma_f32_16x16x32_bf16 v[50:53], v[154:157], v[166:169], v[50:53]
	v_mfma_f32_16x16x32_bf16 v[38:41], v[138:141], v[174:177], v[38:41]
	v_mfma_f32_16x16x32_bf16 v[34:37], v[154:157], v[174:177], v[34:37]
	v_mfma_f32_16x16x32_bf16 v[22:25], v[138:141], v[198:201], v[22:25]
	v_mfma_f32_16x16x32_bf16 v[18:21], v[154:157], v[198:201], v[18:21]
	v_mfma_f32_16x16x32_bf16 v[6:9], v[138:141], v[206:209], v[6:9]
	v_mfma_f32_16x16x32_bf16 v[2:5], v[154:157], v[206:209], v[2:5]
	v_mfma_f32_16x16x32_bf16 v[54:57], v[150:153], v[170:173], v[54:57]
	v_mfma_f32_16x16x32_bf16 v[50:53], v[162:165], v[170:173], v[50:53]
	v_mfma_f32_16x16x32_bf16 v[38:41], v[150:153], v[178:181], v[38:41]
	v_mfma_f32_16x16x32_bf16 v[34:37], v[162:165], v[178:181], v[34:37]
	v_mfma_f32_16x16x32_bf16 v[22:25], v[150:153], v[202:205], v[22:25]
	v_mfma_f32_16x16x32_bf16 v[18:21], v[162:165], v[202:205], v[18:21]
	v_mfma_f32_16x16x32_bf16 v[6:9], v[150:153], v[210:213], v[6:9]
	v_mfma_f32_16x16x32_bf16 v[2:5], v[162:165], v[210:213], v[2:5]
	s_setprio 0
	s_barrier
	s_add_i32 vcc_hi, vcc_hi, 2
	s_add_u32 s27, s27, 0x100
	s_addc_u32 s71, s71, 0
	s_add_u32 s73, s73, 0x100
	s_addc_u32 vcc_lo, vcc_lo, 0
	s_add_u32 s80, s80, 0x100
	s_addc_u32 s81, s81, 0
	s_cmp_gt_u32 vcc_hi, 61
	s_cbranch_scc0 .LBB0_789
	s_branch .Lmy_kexit_5
.LBB0_789:
	ds_read_b128 v[98:101], v191
	ds_read_b128 v[110:113], v191 offset:1024
	ds_read_b128 v[122:125], v191 offset:2048
	ds_read_b128 v[134:137], v191 offset:3072
	ds_read_b128 v[138:141], v192
	ds_read_b128 v[150:153], v192 offset:1024
	ds_read_b128 v[154:157], v192 offset:2048
	ds_read_b128 v[162:165], v192 offset:3072
	s_cmp_eq_u32 vcc_hi, 60
	s_cselect_b32 s86, s15, s27
	s_cselect_b32 s87, s14, s71
	s_cselect_b32 s84, s26, s73
	s_cselect_b32 s85, s25, vcc_lo
	s_add_u32 s82, s86, 0x80
	s_addc_u32 s83, s87, 0
	ds_read_b128 v[166:169], v193
	ds_read_b128 v[170:173], v193 offset:1024
	ds_read_b128 v[174:177], v193 offset:2048
	ds_read_b128 v[178:181], v193 offset:3072
	ds_read_b128 v[198:201], v193 offset:4096
	ds_read_b128 v[202:205], v193 offset:5120
	ds_read_b128 v[206:209], v193 offset:6144
	ds_read_b128 v[210:213], v193 offset:7168
	s_mov_b32 m0, s31
	s_nop 0
	global_load_lds_dwordx4 v184, s[80:81]
	s_mov_b32 m0, s19
	s_nop 0
	global_load_lds_dwordx4 v186, s[80:81]
	s_waitcnt vmcnt(8)
	s_waitcnt lgkmcnt(0)
	s_barrier
	s_setprio 1
	v_mfma_f32_16x16x32_bf16 v[146:149], v[98:101], v[166:169], v[146:149]
	v_mfma_f32_16x16x32_bf16 v[142:145], v[122:125], v[166:169], v[142:145]
	v_mfma_f32_16x16x32_bf16 v[118:121], v[98:101], v[174:177], v[118:121]
	v_mfma_f32_16x16x32_bf16 v[114:117], v[122:125], v[174:177], v[114:117]
	v_mfma_f32_16x16x32_bf16 v[94:97], v[98:101], v[198:201], v[94:97]
	v_mfma_f32_16x16x32_bf16 v[90:93], v[122:125], v[198:201], v[90:93]
	v_mfma_f32_16x16x32_bf16 v[78:81], v[98:101], v[206:209], v[78:81]
	v_mfma_f32_16x16x32_bf16 v[74:77], v[122:125], v[206:209], v[74:77]
	v_mfma_f32_16x16x32_bf16 v[146:149], v[110:113], v[170:173], v[146:149]
	v_mfma_f32_16x16x32_bf16 v[142:145], v[134:137], v[170:173], v[142:145]
	v_mfma_f32_16x16x32_bf16 v[118:121], v[110:113], v[178:181], v[118:121]
	v_mfma_f32_16x16x32_bf16 v[114:117], v[134:137], v[178:181], v[114:117]
	v_mfma_f32_16x16x32_bf16 v[94:97], v[110:113], v[202:205], v[94:97]
	v_mfma_f32_16x16x32_bf16 v[90:93], v[134:137], v[202:205], v[90:93]
	v_mfma_f32_16x16x32_bf16 v[78:81], v[110:113], v[210:213], v[78:81]
	v_mfma_f32_16x16x32_bf16 v[74:77], v[134:137], v[210:213], v[74:77]
	v_mfma_f32_16x16x32_bf16 v[130:133], v[138:141], v[166:169], v[130:133]
	v_mfma_f32_16x16x32_bf16 v[126:129], v[154:157], v[166:169], v[126:129]
	v_mfma_f32_16x16x32_bf16 v[106:109], v[138:141], v[174:177], v[106:109]
	v_mfma_f32_16x16x32_bf16 v[102:105], v[154:157], v[174:177], v[102:105]
	v_mfma_f32_16x16x32_bf16 v[86:89], v[138:141], v[198:201], v[86:89]
	v_mfma_f32_16x16x32_bf16 v[82:85], v[154:157], v[198:201], v[82:85]
	v_mfma_f32_16x16x32_bf16 v[70:73], v[138:141], v[206:209], v[70:73]
	v_mfma_f32_16x16x32_bf16 v[66:69], v[154:157], v[206:209], v[66:69]
	v_mfma_f32_16x16x32_bf16 v[130:133], v[150:153], v[170:173], v[130:133]
	v_mfma_f32_16x16x32_bf16 v[126:129], v[162:165], v[170:173], v[126:129]
	v_mfma_f32_16x16x32_bf16 v[106:109], v[150:153], v[178:181], v[106:109]
	v_mfma_f32_16x16x32_bf16 v[102:105], v[162:165], v[178:181], v[102:105]
	v_mfma_f32_16x16x32_bf16 v[86:89], v[150:153], v[202:205], v[86:89]
	v_mfma_f32_16x16x32_bf16 v[82:85], v[162:165], v[202:205], v[82:85]
	v_mfma_f32_16x16x32_bf16 v[70:73], v[150:153], v[210:213], v[70:73]
	v_mfma_f32_16x16x32_bf16 v[66:69], v[162:165], v[210:213], v[66:69]
	s_setprio 0
	s_barrier
; #define PG8_STAGE(bufoff, gbase, voff) do { if constexpr (VAR != 1 && VAR != 3) { _Pragma("unroll") for (int _i = 0; _i < 2; ++_i) \
;         asm volatile("s_mov_b32 m0, %2\n\ts_nop 0\n\tglobal_load_lds_dwordx4 %0, %1" :: "v"((voff)[_i]), "s"((const char*)(gbase)), "s"(ldsbase + (unsigned)((bufoff) + _i * 8192)) : "memory", "m0"); } } while (0)
; #define PG8_LDA(dst, b, h) do { if constexpr (VAR < 2) _Pragma("unroll") for (int m = 0; m < 4; ++m) _Pragma("unroll") for (int k = 0; k < 2; ++k) dst[m][k] = *(const LAS bf16x8*)(lds + PG8_SA(b, h) + aoff + m * 2048 + k * 1024); } while (0)
; #define PG8_LDB(dst, b, h) do { if constexpr (VAR < 2) _Pragma("unroll") for (int n = 0; n < 2; ++n) _Pragma("unroll") for (int k = 0; k < 2; ++k) dst[n][k] = *(const LAS bf16x8*)(lds + PG8_SB(b, h) + boff + n * 2048 + k * 1024); } while (0)
; #define PG8_WAIT_V(n) asm volatile("s_waitcnt vmcnt(" #n ")" ::: "memory")
; #define PG8_WAIT_L(n) asm volatile("s_waitcnt lgkmcnt(" #n ")" ::: "memory")
; #define PG8_BAR do { if constexpr (VAR != 3) __builtin_amdgcn_s_barrier(); } while (0)
; #define PG8_SCHED __builtin_amdgcn_sched_barrier(0)
;     ...
;             PG8_LDA(At, 0, 1); PG8_STAGE(PG8_SB(0, 0), b2, voffB); PG8_STAGE(PG8_SB(0, 1), b2 + hstepB, voffB); PG8_STAGE(PG8_SA(0, 0), a2, voffA);
;             PG8_WAIT_V(8); PG8_WAIT_L(0); PG8_BAR; PG8_MMA(1, 0, At, B0); PG8_MMA(1, 1, At, B1); PG8_BAR; PG8_SCHED;
;             PG8_LDB(B0, 1, 0); PG8_LDB(B1, 1, 1); PG8_SCHED; PG8_LDA(At, 1, 0); PG8_STAGE(PG8_SA(0, 1), a2 + hstepA, voffA);
;             PG8_WAIT_V(8); PG8_WAIT_L(0); PG8_BAR; PG8_MMA(0, 0, At, B0); PG8_MMA(0, 1, At, B1); PG8_BAR; PG8_SCHED;
	ds_read_b128 v[166:169], v193 offset:16384
	ds_read_b128 v[170:173], v193 offset:17408
	ds_read_b128 v[174:177], v193 offset:18432
	ds_read_b128 v[178:181], v193 offset:19456
	ds_read_b128 v[198:201], v193 offset:20480
	ds_read_b128 v[202:205], v193 offset:21504
	ds_read_b128 v[206:209], v193 offset:22528
	ds_read_b128 v[210:213], v193 offset:23552
	s_mov_b32 m0, s91
	s_nop 0
	global_load_lds_dwordx4 v185, s[84:85]
	s_add_u32 s88, s84, 0x100000
	s_mov_b32 m0, s92
	s_nop 0
	global_load_lds_dwordx4 v187, s[84:85]
	s_addc_u32 s89, s85, 0
	s_mov_b32 m0, s93
	s_nop 0
	global_load_lds_dwordx4 v185, s[88:89]
	s_mov_b32 m0, s94
	s_nop 0
	global_load_lds_dwordx4 v187, s[88:89]
	s_mov_b32 m0, s35
	s_nop 0
	global_load_lds_dwordx4 v184, s[86:87]
	s_mov_b32 m0, s79
	s_nop 0
	global_load_lds_dwordx4 v186, s[86:87]
	s_waitcnt vmcnt(8)
	s_waitcnt lgkmcnt(0)
	s_barrier
	s_setprio 1
	v_mfma_f32_16x16x32_bf16 v[62:65], v[98:101], v[166:169], v[62:65]
	v_mfma_f32_16x16x32_bf16 v[58:61], v[122:125], v[166:169], v[58:61]
	v_mfma_f32_16x16x32_bf16 v[46:49], v[98:101], v[174:177], v[46:49]
	v_mfma_f32_16x16x32_bf16 v[42:45], v[122:125], v[174:177], v[42:45]
	v_mfma_f32_16x16x32_bf16 v[30:33], v[98:101], v[198:201], v[30:33]
	v_mfma_f32_16x16x32_bf16 v[26:29], v[122:125], v[198:201], v[26:29]
	v_mfma_f32_16x16x32_bf16 v[14:17], v[98:101], v[206:209], v[14:17]
	v_mfma_f32_16x16x32_bf16 v[10:13], v[122:125], v[206:209], v[10:13]
	v_mfma_f32_16x16x32_bf16 v[62:65], v[110:113], v[170:173], v[62:65]
	v_mfma_f32_16x16x32_bf16 v[58:61], v[134:137], v[170:173], v[58:61]
	v_mfma_f32_16x16x32_bf16 v[46:49], v[110:113], v[178:181], v[46:49]
	v_mfma_f32_16x16x32_bf16 v[42:45], v[134:137], v[178:181], v[42:45]
	v_mfma_f32_16x16x32_bf16 v[30:33], v[110:113], v[202:205], v[30:33]
	v_mfma_f32_16x16x32_bf16 v[26:29], v[134:137], v[202:205], v[26:29]
	v_mfma_f32_16x16x32_bf16 v[14:17], v[110:113], v[210:213], v[14:17]
	v_mfma_f32_16x16x32_bf16 v[10:13], v[134:137], v[210:213], v[10:13]
	v_mfma_f32_16x16x32_bf16 v[54:57], v[138:141], v[166:169], v[54:57]
	v_mfma_f32_16x16x32_bf16 v[50:53], v[154:157], v[166:169], v[50:53]
	v_mfma_f32_16x16x32_bf16 v[38:41], v[138:141], v[174:177], v[38:41]
	v_mfma_f32_16x16x32_bf16 v[34:37], v[154:157], v[174:177], v[34:37]
	v_mfma_f32_16x16x32_bf16 v[22:25], v[138:141], v[198:201], v[22:25]
	v_mfma_f32_16x16x32_bf16 v[18:21], v[154:157], v[198:201], v[18:21]
	v_mfma_f32_16x16x32_bf16 v[6:9], v[138:141], v[206:209], v[6:9]
	v_mfma_f32_16x16x32_bf16 v[2:5], v[154:157], v[206:209], v[2:5]
	v_mfma_f32_16x16x32_bf16 v[54:57], v[150:153], v[170:173], v[54:57]
	v_mfma_f32_16x16x32_bf16 v[50:53], v[162:165], v[170:173], v[50:53]
	v_mfma_f32_16x16x32_bf16 v[38:41], v[150:153], v[178:181], v[38:41]
	v_mfma_f32_16x16x32_bf16 v[34:37], v[162:165], v[178:181], v[34:37]
	v_mfma_f32_16x16x32_bf16 v[22:25], v[150:153], v[202:205], v[22:25]
	v_mfma_f32_16x16x32_bf16 v[18:21], v[162:165], v[202:205], v[18:21]
	v_mfma_f32_16x16x32_bf16 v[6:9], v[150:153], v[210:213], v[6:9]
	v_mfma_f32_16x16x32_bf16 v[2:5], v[162:165], v[210:213], v[2:5]
	s_setprio 0
	s_barrier
	ds_read_b128 v[98:101], v194
	ds_read_b128 v[110:113], v194 offset:1024
	ds_read_b128 v[122:125], v194 offset:2048
	ds_read_b128 v[134:137], v194 offset:3072
	ds_read_b128 v[138:141], v195
	ds_read_b128 v[150:153], v195 offset:1024
	ds_read_b128 v[154:157], v195 offset:2048
	ds_read_b128 v[162:165], v195 offset:3072
	ds_read_b128 v[166:169], v193 offset:32768
	ds_read_b128 v[170:173], v193 offset:33792
	ds_read_b128 v[174:177], v193 offset:34816
	ds_read_b128 v[178:181], v193 offset:35840
	ds_read_b128 v[198:201], v193 offset:36864
	ds_read_b128 v[202:205], v193 offset:37888
	ds_read_b128 v[206:209], v193 offset:38912
	ds_read_b128 v[210:213], v193 offset:39936
	s_add_u32 s86, s86, 0x100000
	s_addc_u32 s87, s87, 0
	s_mov_b32 m0, s95
	s_nop 0
	global_load_lds_dwordx4 v184, s[86:87]
	s_mov_b32 m0, s96
	s_nop 0
	global_load_lds_dwordx4 v186, s[86:87]
	s_waitcnt vmcnt(8)
	s_waitcnt lgkmcnt(0)
	s_barrier
; #define PG8_STAGE(bufoff, gbase, voff) do { if constexpr (VAR != 1 && VAR != 3) { _Pragma("unroll") for (int _i = 0; _i < 2; ++_i) \
;         asm volatile("s_mov_b32 m0, %2\n\ts_nop 0\n\tglobal_load_lds_dwordx4 %0, %1" :: "v"((voff)[_i]), "s"((const char*)(gbase)), "s"(ldsbase + (unsigned)((bufoff) + _i * 8192)) : "memory", "m0"); } } while (0)
; #define PG8_LDA(dst, b, h) do { if constexpr (VAR < 2) _Pragma("unroll") for (int m = 0; m < 4; ++m) _Pragma("unroll") for (int k = 0; k < 2; ++k) dst[m][k] = *(const LAS bf16x8*)(lds + PG8_SA(b, h) + aoff + m * 2048 + k * 1024); } while (0)
; #define PG8_WAIT_V(n) asm volatile("s_waitcnt vmcnt(" #n ")" ::: "memory")
; #define PG8_WAIT_L(n) asm volatile("s_waitcnt lgkmcnt(" #n ")" ::: "memory")
; #define PG8_BAR do { if constexpr (VAR != 3) __builtin_amdgcn_s_barrier(); } while (0)
; #define PG8_SCHED __builtin_amdgcn_sched_barrier(0)
;     ...
;             PG8_WAIT_V(8); PG8_WAIT_L(0); PG8_BAR; PG8_MMA(0, 0, At, B0); PG8_MMA(0, 1, At, B1); PG8_BAR; PG8_SCHED;
;             PG8_LDA(At, 1, 1); PG8_STAGE(PG8_SB(1, 0), b3, voffB); PG8_STAGE(PG8_SB(1, 1), b3 + hstepB, voffB); PG8_STAGE(PG8_SA(1, 0), a3, voffA);
;             PG8_WAIT_V(8); PG8_WAIT_L(0); PG8_BAR; PG8_MMA(1, 0, At, B0); PG8_MMA(1, 1, At, B1); PG8_BAR; PG8_SCHED;
;         }
;         if (wr == 0) PG8_BAR;
	s_setprio 1
	v_mfma_f32_16x16x32_bf16 v[146:149], v[98:101], v[166:169], v[146:149]
	v_mfma_f32_16x16x32_bf16 v[142:145], v[122:125], v[166:169], v[142:145]
	v_mfma_f32_16x16x32_bf16 v[118:121], v[98:101], v[174:177], v[118:121]
	v_mfma_f32_16x16x32_bf16 v[114:117], v[122:125], v[174:177], v[114:117]
	v_mfma_f32_16x16x32_bf16 v[94:97], v[98:101], v[198:201], v[94:97]
	v_mfma_f32_16x16x32_bf16 v[90:93], v[122:125], v[198:201], v[90:93]
	v_mfma_f32_16x16x32_bf16 v[78:81], v[98:101], v[206:209], v[78:81]
	v_mfma_f32_16x16x32_bf16 v[74:77], v[122:125], v[206:209], v[74:77]
	v_mfma_f32_16x16x32_bf16 v[146:149], v[110:113], v[170:173], v[146:149]
	v_mfma_f32_16x16x32_bf16 v[142:145], v[134:137], v[170:173], v[142:145]
	v_mfma_f32_16x16x32_bf16 v[118:121], v[110:113], v[178:181], v[118:121]
	v_mfma_f32_16x16x32_bf16 v[114:117], v[134:137], v[178:181], v[114:117]
	v_mfma_f32_16x16x32_bf16 v[94:97], v[110:113], v[202:205], v[94:97]
	v_mfma_f32_16x16x32_bf16 v[90:93], v[134:137], v[202:205], v[90:93]
	v_mfma_f32_16x16x32_bf16 v[78:81], v[110:113], v[210:213], v[78:81]
	v_mfma_f32_16x16x32_bf16 v[74:77], v[134:137], v[210:213], v[74:77]
	v_mfma_f32_16x16x32_bf16 v[130:133], v[138:141], v[166:169], v[130:133]
	v_mfma_f32_16x16x32_bf16 v[126:129], v[154:157], v[166:169], v[126:129]
	v_mfma_f32_16x16x32_bf16 v[106:109], v[138:141], v[174:177], v[106:109]
	v_mfma_f32_16x16x32_bf16 v[102:105], v[154:157], v[174:177], v[102:105]
	v_mfma_f32_16x16x32_bf16 v[86:89], v[138:141], v[198:201], v[86:89]
	v_mfma_f32_16x16x32_bf16 v[82:85], v[154:157], v[198:201], v[82:85]
	v_mfma_f32_16x16x32_bf16 v[70:73], v[138:141], v[206:209], v[70:73]
	v_mfma_f32_16x16x32_bf16 v[66:69], v[154:157], v[206:209], v[66:69]
	v_mfma_f32_16x16x32_bf16 v[130:133], v[150:153], v[170:173], v[130:133]
	v_mfma_f32_16x16x32_bf16 v[126:129], v[162:165], v[170:173], v[126:129]
	v_mfma_f32_16x16x32_bf16 v[106:109], v[150:153], v[178:181], v[106:109]
	v_mfma_f32_16x16x32_bf16 v[102:105], v[162:165], v[178:181], v[102:105]
	v_mfma_f32_16x16x32_bf16 v[86:89], v[150:153], v[202:205], v[86:89]
	v_mfma_f32_16x16x32_bf16 v[82:85], v[162:165], v[202:205], v[82:85]
	v_mfma_f32_16x16x32_bf16 v[70:73], v[150:153], v[210:213], v[70:73]
	v_mfma_f32_16x16x32_bf16 v[66:69], v[162:165], v[210:213], v[66:69]
	s_setprio 0
	s_barrier
	ds_read_b128 v[166:169], v193 offset:49152
	ds_read_b128 v[170:173], v193 offset:50176
	ds_read_b128 v[174:177], v193 offset:51200
	ds_read_b128 v[178:181], v193 offset:52224
	ds_read_b128 v[198:201], v193 offset:53248
	ds_read_b128 v[202:205], v193 offset:54272
	ds_read_b128 v[206:209], v193 offset:55296
	ds_read_b128 v[210:213], v193 offset:56320
	s_add_u32 s86, s84, 0x80
	s_addc_u32 s87, s85, 0
	s_mov_b32 m0, s64
	s_nop 0
	global_load_lds_dwordx4 v185, s[86:87]
	s_add_u32 s84, s84, 0x100080
	s_mov_b32 m0, s65
	s_nop 0
	global_load_lds_dwordx4 v187, s[86:87]
	s_addc_u32 s85, s85, 0
	s_mov_b32 m0, s33
	s_nop 0
	global_load_lds_dwordx4 v185, s[84:85]
	s_mov_b32 m0, s30
	s_nop 0
	global_load_lds_dwordx4 v187, s[84:85]
	s_mov_b32 m0, s17
	s_nop 0
	global_load_lds_dwordx4 v184, s[82:83]
	s_mov_b32 m0, s28
	s_nop 0
	global_load_lds_dwordx4 v186, s[82:83]
	s_waitcnt vmcnt(8)
	s_waitcnt lgkmcnt(0)
	s_barrier
	s_setprio 1
	v_mfma_f32_16x16x32_bf16 v[62:65], v[98:101], v[166:169], v[62:65]
	v_mfma_f32_16x16x32_bf16 v[58:61], v[122:125], v[166:169], v[58:61]
	v_mfma_f32_16x16x32_bf16 v[46:49], v[98:101], v[174:177], v[46:49]
	v_mfma_f32_16x16x32_bf16 v[42:45], v[122:125], v[174:177], v[42:45]
	v_mfma_f32_16x16x32_bf16 v[30:33], v[98:101], v[198:201], v[30:33]
	v_mfma_f32_16x16x32_bf16 v[26:29], v[122:125], v[198:201], v[26:29]
	v_mfma_f32_16x16x32_bf16 v[14:17], v[98:101], v[206:209], v[14:17]
	v_mfma_f32_16x16x32_bf16 v[10:13], v[122:125], v[206:209], v[10:13]
	v_mfma_f32_16x16x32_bf16 v[62:65], v[110:113], v[170:173], v[62:65]
	v_mfma_f32_16x16x32_bf16 v[58:61], v[134:137], v[170:173], v[58:61]
	v_mfma_f32_16x16x32_bf16 v[46:49], v[110:113], v[178:181], v[46:49]
	v_mfma_f32_16x16x32_bf16 v[42:45], v[134:137], v[178:181], v[42:45]
	v_mfma_f32_16x16x32_bf16 v[30:33], v[110:113], v[202:205], v[30:33]
	v_mfma_f32_16x16x32_bf16 v[26:29], v[134:137], v[202:205], v[26:29]
	v_mfma_f32_16x16x32_bf16 v[14:17], v[110:113], v[210:213], v[14:17]
	v_mfma_f32_16x16x32_bf16 v[10:13], v[134:137], v[210:213], v[10:13]
	v_mfma_f32_16x16x32_bf16 v[54:57], v[138:141], v[166:169], v[54:57]
	v_mfma_f32_16x16x32_bf16 v[50:53], v[154:157], v[166:169], v[50:53]
	v_mfma_f32_16x16x32_bf16 v[38:41], v[138:141], v[174:177], v[38:41]
	v_mfma_f32_16x16x32_bf16 v[34:37], v[154:157], v[174:177], v[34:37]
	v_mfma_f32_16x16x32_bf16 v[22:25], v[138:141], v[198:201], v[22:25]
	v_mfma_f32_16x16x32_bf16 v[18:21], v[154:157], v[198:201], v[18:21]
	v_mfma_f32_16x16x32_bf16 v[6:9], v[138:141], v[206:209], v[6:9]
	v_mfma_f32_16x16x32_bf16 v[2:5], v[154:157], v[206:209], v[2:5]
	v_mfma_f32_16x16x32_bf16 v[54:57], v[150:153], v[170:173], v[54:57]
	v_mfma_f32_16x16x32_bf16 v[50:53], v[162:165], v[170:173], v[50:53]
	v_mfma_f32_16x16x32_bf16 v[38:41], v[150:153], v[178:181], v[38:41]
	v_mfma_f32_16x16x32_bf16 v[34:37], v[162:165], v[178:181], v[34:37]
	v_mfma_f32_16x16x32_bf16 v[22:25], v[150:153], v[202:205], v[22:25]
	v_mfma_f32_16x16x32_bf16 v[18:21], v[162:165], v[202:205], v[18:21]
	v_mfma_f32_16x16x32_bf16 v[6:9], v[150:153], v[210:213], v[6:9]
	v_mfma_f32_16x16x32_bf16 v[2:5], v[162:165], v[210:213], v[2:5]
	s_setprio 0
	s_barrier
	s_add_i32 vcc_hi, vcc_hi, 2
	s_add_u32 s27, s27, 0x100
	s_addc_u32 s71, s71, 0
	s_add_u32 s73, s73, 0x100
	s_addc_u32 vcc_lo, vcc_lo, 0
	s_add_u32 s80, s80, 0x100
	s_addc_u32 s81, s81, 0
	s_cmp_gt_u32 vcc_hi, 61
	s_cbranch_scc0 .LBB0_789
.Lmy_kexit_5:
	s_and_b64 vcc, exec, s[68:69]
	s_cbranch_vccz .LBB0_792
	s_barrier

; __device__ __forceinline__ const char* unitA(const Gemm& g, const Unit& u) { return (const char*)(g.A + (size_t)(u.z / g.zdiv) * g.sAhi + (size_t)(u.z % g.zdiv) * g.sAlo + (size_t)u.pm * BM * g.lda); }
; __device__ __forceinline__ const char* unitB(const Gemm& g, const Unit& u) { return (const char*)(g.Bt + (size_t)(u.z / g.zdiv) * g.sBhi + (size_t)(u.z % g.zdiv) * g.sBlo + (size_t)(u.pm / g.bdiv) * g.sBpm + (size_t)u.pn * BM * g.ldb); }
; #define PG8_STAGE(bufoff, gbase, voff) do { if constexpr (VAR != 1 && VAR != 3) { _Pragma("unroll") for (int _i = 0; _i < 2; ++_i) \
;         asm volatile("s_mov_b32 m0, %2\n\ts_nop 0\n\tglobal_load_lds_dwordx4 %0, %1" :: "v"((voff)[_i]), "s"((const char*)(gbase)), "s"(ldsbase + (unsigned)((bufoff) + _i * 8192)) : "memory", "m0"); } } while (0)
; #define PG8_LDA(dst, b, h) do { if constexpr (VAR < 2) _Pragma("unroll") for (int m = 0; m < 4; ++m) _Pragma("unroll") for (int k = 0; k < 2; ++k) dst[m][k] = *(const LAS bf16x8*)(lds + PG8_SA(b, h) + aoff + m * 2048 + k * 1024); } while (0)
; #define PG8_LDB(dst, b, h) do { if constexpr (VAR < 2) _Pragma("unroll") for (int n = 0; n < 2; ++n) _Pragma("unroll") for (int k = 0; k < 2; ++k) dst[n][k] = *(const LAS bf16x8*)(lds + PG8_SB(b, h) + boff + n * 2048 + k * 1024); } while (0)
; #define PG8_WAIT_V(n) asm volatile("s_waitcnt vmcnt(" #n ")" ::: "memory")
;     ...
;         const bool has_next = S.next(ui + 1, nxt);
;         const char* nA = has_next ? unitA(g, nxt) : cA; const char* nB = has_next ? unitB(g, nxt) : cB;
;         for (int t = 0; t < nt; t += 2) {
;             const bool last = (t == nt - 2);
;             const char* a1 = cA + (size_t)(t + 1) * kstep;
;             const char* a2 = last ? nA : cA + (size_t)(t + 2) * kstep; const char* b2 = last ? nB : cB + (size_t)(t + 2) * kstep;
;             const char* a3 = a2 + kstep; const char* b3 = b2 + kstep;
;             PG8_LDB(B0, 0, 0); PG8_LDB(B1, 0, 1); PG8_SCHED; PG8_LDA(At, 0, 0); PG8_STAGE(PG8_SA(1, 1), a1 + hstepA, voffA);
;             PG8_WAIT_V(8); PG8_WAIT_L(0); PG8_BAR; PG8_MMA(0, 0, At, B0); PG8_MMA(0, 1, At, B1); PG8_BAR; PG8_SCHED;
;             PG8_LDA(At, 0, 1); PG8_STAGE(PG8_SB(0, 0), b2, voffB); PG8_STAGE(PG8_SB(0, 1), b2 + hstepB, voffB); PG8_STAGE(PG8_SA(0, 0), a2, voffA);
;             PG8_WAIT_V(8); PG8_WAIT_L(0); PG8_BAR; PG8_MMA(1, 0, At, B0); PG8_MMA(1, 1, At, B1); PG8_BAR; PG8_SCHED;
.LBB0_891:
	s_ashr_i32 s59, s58, 31
	s_lshl_b64 s[24:25], s[58:59], 21
	s_add_u32 s64, s52, s24
	s_addc_u32 s65, s53, s25
	s_and_b64 s[6:7], s[6:7], exec
	s_cselect_b32 s1, s65, s71
	s_cselect_b32 s24, s64, s70
	s_add_u32 s25, s70, 0x100
	s_addc_u32 s39, s71, 0
	s_add_u32 s59, s68, 0x100
	s_addc_u32 s84, s69, 0
	s_add_u32 s6, s70, 0x100080
	s_addc_u32 s7, s71, 0
	s_mov_b32 s85, -2
	s_waitcnt vmcnt(41)
	s_waitcnt vmcnt(40)
	s_waitcnt vmcnt(38)
	s_waitcnt vmcnt(35)
	s_waitcnt vmcnt(34)
	s_waitcnt vmcnt(32)
	ds_read_b128 v[134:137], v201
	ds_read_b128 v[138:141], v201 offset:1024
	ds_read_b128 v[142:145], v201 offset:2048
	ds_read_b128 v[146:149], v201 offset:3072
	ds_read_b128 v[150:153], v202
	ds_read_b128 v[154:157], v202 offset:1024
	ds_read_b128 v[158:161], v202 offset:2048
	ds_read_b128 v[162:165], v202 offset:3072
	s_cmp_eq_u32 s85, 60
	s_cselect_b32 s72, s24, s25
	s_cselect_b32 s73, s1, s39
	s_cselect_b32 s70, s60, s59
	s_cselect_b32 s71, s61, s84
	s_add_u32 s68, s72, 0x80
	s_addc_u32 s69, s73, 0
	ds_read_b128 v[166:169], v203
	ds_read_b128 v[210:213], v203 offset:1024
	ds_read_b128 v[214:217], v203 offset:2048
	ds_read_b128 v[218:221], v203 offset:3072
	ds_read_b128 v[222:225], v203 offset:4096
	ds_read_b128 v[226:229], v203 offset:5120
	ds_read_b128 v[230:233], v203 offset:6144
	ds_read_b128 v[234:237], v203 offset:7168
	s_mov_b32 m0, s77
	s_nop 0
	global_load_lds_dwordx4 v1, s[6:7]
	s_mov_b32 m0, s79
	s_nop 0
	global_load_lds_dwordx4 v173, s[6:7]
	s_waitcnt vmcnt(8)
	s_waitcnt lgkmcnt(0)
	s_barrier
	s_setprio 1
	v_mfma_f32_16x16x32_bf16 v[126:129], v[134:137], v[166:169], 0
	v_mfma_f32_16x16x32_bf16 v[122:125], v[142:145], v[166:169], 0
	v_mfma_f32_16x16x32_bf16 v[110:113], v[134:137], v[214:217], 0
	v_mfma_f32_16x16x32_bf16 v[106:109], v[142:145], v[214:217], 0
	v_mfma_f32_16x16x32_bf16 v[94:97], v[134:137], v[222:225], 0
	v_mfma_f32_16x16x32_bf16 v[90:93], v[142:145], v[222:225], 0
	v_mfma_f32_16x16x32_bf16 v[78:81], v[134:137], v[230:233], 0
	v_mfma_f32_16x16x32_bf16 v[74:77], v[142:145], v[230:233], 0
	v_mfma_f32_16x16x32_bf16 v[126:129], v[138:141], v[210:213], v[126:129]
	v_mfma_f32_16x16x32_bf16 v[122:125], v[146:149], v[210:213], v[122:125]
	v_mfma_f32_16x16x32_bf16 v[110:113], v[138:141], v[218:221], v[110:113]
	v_mfma_f32_16x16x32_bf16 v[106:109], v[146:149], v[218:221], v[106:109]
	v_mfma_f32_16x16x32_bf16 v[94:97], v[138:141], v[226:229], v[94:97]
	v_mfma_f32_16x16x32_bf16 v[90:93], v[146:149], v[226:229], v[90:93]
	v_mfma_f32_16x16x32_bf16 v[78:81], v[138:141], v[234:237], v[78:81]
	v_mfma_f32_16x16x32_bf16 v[74:77], v[146:149], v[234:237], v[74:77]
	v_mfma_f32_16x16x32_bf16 v[118:121], v[150:153], v[166:169], 0
	v_mfma_f32_16x16x32_bf16 v[114:117], v[158:161], v[166:169], 0
	v_mfma_f32_16x16x32_bf16 v[102:105], v[150:153], v[214:217], 0
	v_mfma_f32_16x16x32_bf16 v[98:101], v[158:161], v[214:217], 0
	v_mfma_f32_16x16x32_bf16 v[86:89], v[150:153], v[222:225], 0
	v_mfma_f32_16x16x32_bf16 v[82:85], v[158:161], v[222:225], 0
	v_mfma_f32_16x16x32_bf16 v[70:73], v[150:153], v[230:233], 0
	v_mfma_f32_16x16x32_bf16 v[66:69], v[158:161], v[230:233], 0
	v_mfma_f32_16x16x32_bf16 v[118:121], v[154:157], v[210:213], v[118:121]
	v_mfma_f32_16x16x32_bf16 v[114:117], v[162:165], v[210:213], v[114:117]
	v_mfma_f32_16x16x32_bf16 v[102:105], v[154:157], v[218:221], v[102:105]
	v_mfma_f32_16x16x32_bf16 v[98:101], v[162:165], v[218:221], v[98:101]
	v_mfma_f32_16x16x32_bf16 v[86:89], v[154:157], v[226:229], v[86:89]
	v_mfma_f32_16x16x32_bf16 v[82:85], v[162:165], v[226:229], v[82:85]
	v_mfma_f32_16x16x32_bf16 v[70:73], v[154:157], v[234:237], v[70:73]
	v_mfma_f32_16x16x32_bf16 v[66:69], v[162:165], v[234:237], v[66:69]
	s_setprio 0
	s_barrier
	ds_read_b128 v[166:169], v203 offset:16384
	ds_read_b128 v[210:213], v203 offset:17408
	ds_read_b128 v[214:217], v203 offset:18432
	ds_read_b128 v[218:221], v203 offset:19456
	ds_read_b128 v[222:225], v203 offset:20480
	ds_read_b128 v[226:229], v203 offset:21504
	ds_read_b128 v[230:233], v203 offset:22528
	ds_read_b128 v[234:237], v203 offset:23552
	s_mov_b32 m0, s17
	s_nop 0
	global_load_lds_dwordx4 v172, s[70:71]
	s_add_u32 s86, s70, 0x100000
	s_mov_b32 m0, s19
	s_nop 0
	global_load_lds_dwordx4 v174, s[70:71]
	s_addc_u32 s87, s71, 0
	s_mov_b32 m0, s23
	s_nop 0
	global_load_lds_dwordx4 v172, s[86:87]
	s_mov_b32 m0, s26
	s_nop 0
	global_load_lds_dwordx4 v174, s[86:87]
	s_mov_b32 m0, s15
	s_nop 0
	global_load_lds_dwordx4 v1, s[72:73]
	s_mov_b32 m0, s27
	s_nop 0
	global_load_lds_dwordx4 v173, s[72:73]
	s_waitcnt vmcnt(8)
	s_waitcnt lgkmcnt(0)
	s_barrier
	s_setprio 1
	v_mfma_f32_16x16x32_bf16 v[62:65], v[134:137], v[166:169], 0
	v_mfma_f32_16x16x32_bf16 v[58:61], v[142:145], v[166:169], 0
	v_mfma_f32_16x16x32_bf16 v[46:49], v[134:137], v[214:217], 0
	v_mfma_f32_16x16x32_bf16 v[42:45], v[142:145], v[214:217], 0
	v_mfma_f32_16x16x32_bf16 v[30:33], v[134:137], v[222:225], 0
	v_mfma_f32_16x16x32_bf16 v[26:29], v[142:145], v[222:225], 0
	v_mfma_f32_16x16x32_bf16 v[14:17], v[134:137], v[230:233], 0
	v_mfma_f32_16x16x32_bf16 v[10:13], v[142:145], v[230:233], 0
	v_mfma_f32_16x16x32_bf16 v[62:65], v[138:141], v[210:213], v[62:65]
	v_mfma_f32_16x16x32_bf16 v[58:61], v[146:149], v[210:213], v[58:61]
	v_mfma_f32_16x16x32_bf16 v[46:49], v[138:141], v[218:221], v[46:49]
	v_mfma_f32_16x16x32_bf16 v[42:45], v[146:149], v[218:221], v[42:45]
	v_mfma_f32_16x16x32_bf16 v[30:33], v[138:141], v[226:229], v[30:33]
	v_mfma_f32_16x16x32_bf16 v[26:29], v[146:149], v[226:229], v[26:29]
	v_mfma_f32_16x16x32_bf16 v[14:17], v[138:141], v[234:237], v[14:17]
	v_mfma_f32_16x16x32_bf16 v[10:13], v[146:149], v[234:237], v[10:13]
	v_mfma_f32_16x16x32_bf16 v[54:57], v[150:153], v[166:169], 0
	v_mfma_f32_16x16x32_bf16 v[50:53], v[158:161], v[166:169], 0
	v_mfma_f32_16x16x32_bf16 v[38:41], v[150:153], v[214:217], 0
	v_mfma_f32_16x16x32_bf16 v[34:37], v[158:161], v[214:217], 0
	v_mfma_f32_16x16x32_bf16 v[22:25], v[150:153], v[222:225], 0
	v_mfma_f32_16x16x32_bf16 v[18:21], v[158:161], v[222:225], 0
	v_mfma_f32_16x16x32_bf16 v[6:9], v[150:153], v[230:233], 0
	v_mfma_f32_16x16x32_bf16 v[2:5], v[158:161], v[230:233], 0
	v_mfma_f32_16x16x32_bf16 v[54:57], v[154:157], v[210:213], v[54:57]
	v_mfma_f32_16x16x32_bf16 v[50:53], v[162:165], v[210:213], v[50:53]
	v_mfma_f32_16x16x32_bf16 v[38:41], v[154:157], v[218:221], v[38:41]
	v_mfma_f32_16x16x32_bf16 v[34:37], v[162:165], v[218:221], v[34:37]
	v_mfma_f32_16x16x32_bf16 v[22:25], v[154:157], v[226:229], v[22:25]
	v_mfma_f32_16x16x32_bf16 v[18:21], v[162:165], v[226:229], v[18:21]
	v_mfma_f32_16x16x32_bf16 v[6:9], v[154:157], v[234:237], v[6:9]
	v_mfma_f32_16x16x32_bf16 v[2:5], v[162:165], v[234:237], v[2:5]
	s_setprio 0
	s_barrier
; #define PG8_STAGE(bufoff, gbase, voff) do { if constexpr (VAR != 1 && VAR != 3) { _Pragma("unroll") for (int _i = 0; _i < 2; ++_i) \
;         asm volatile("s_mov_b32 m0, %2\n\ts_nop 0\n\tglobal_load_lds_dwordx4 %0, %1" :: "v"((voff)[_i]), "s"((const char*)(gbase)), "s"(ldsbase + (unsigned)((bufoff) + _i * 8192)) : "memory", "m0"); } } while (0)
; #define PG8_LDA(dst, b, h) do { if constexpr (VAR < 2) _Pragma("unroll") for (int m = 0; m < 4; ++m) _Pragma("unroll") for (int k = 0; k < 2; ++k) dst[m][k] = *(const LAS bf16x8*)(lds + PG8_SA(b, h) + aoff + m * 2048 + k * 1024); } while (0)
; #define PG8_LDB(dst, b, h) do { if constexpr (VAR < 2) _Pragma("unroll") for (int n = 0; n < 2; ++n) _Pragma("unroll") for (int k = 0; k < 2; ++k) dst[n][k] = *(const LAS bf16x8*)(lds + PG8_SB(b, h) + boff + n * 2048 + k * 1024); } while (0)
; #define PG8_WAIT_V(n) asm volatile("s_waitcnt vmcnt(" #n ")" ::: "memory")
; #define PG8_WAIT_L(n) asm volatile("s_waitcnt lgkmcnt(" #n ")" ::: "memory")
; #define PG8_BAR do { if constexpr (VAR != 3) __builtin_amdgcn_s_barrier(); } while (0)
; #define PG8_SCHED __builtin_amdgcn_sched_barrier(0)
;     ...
;             PG8_LDB(B0, 1, 0); PG8_LDB(B1, 1, 1); PG8_SCHED; PG8_LDA(At, 1, 0); PG8_STAGE(PG8_SA(0, 1), a2 + hstepA, voffA);
;             PG8_WAIT_V(8); PG8_WAIT_L(0); PG8_BAR; PG8_MMA(0, 0, At, B0); PG8_MMA(0, 1, At, B1); PG8_BAR; PG8_SCHED;
;             PG8_LDA(At, 1, 1); PG8_STAGE(PG8_SB(1, 0), b3, voffB); PG8_STAGE(PG8_SB(1, 1), b3 + hstepB, voffB); PG8_STAGE(PG8_SA(1, 0), a3, voffA);
;             PG8_WAIT_V(8); PG8_WAIT_L(0); PG8_BAR; PG8_MMA(1, 0, At, B0); PG8_MMA(1, 1, At, B1); PG8_BAR; PG8_SCHED;
;         }
	ds_read_b128 v[134:137], v204
	ds_read_b128 v[138:141], v204 offset:1024
	ds_read_b128 v[142:145], v204 offset:2048
	ds_read_b128 v[146:149], v204 offset:3072
	ds_read_b128 v[150:153], v205
	ds_read_b128 v[154:157], v205 offset:1024
	ds_read_b128 v[158:161], v205 offset:2048
	ds_read_b128 v[162:165], v205 offset:3072
	ds_read_b128 v[166:169], v203 offset:32768
	ds_read_b128 v[210:213], v203 offset:33792
	ds_read_b128 v[214:217], v203 offset:34816
	ds_read_b128 v[218:221], v203 offset:35840
	ds_read_b128 v[222:225], v203 offset:36864
	ds_read_b128 v[226:229], v203 offset:37888
	ds_read_b128 v[230:233], v203 offset:38912
	ds_read_b128 v[234:237], v203 offset:39936
	s_add_u32 s72, s72, 0x100000
	s_addc_u32 s73, s73, 0
	s_mov_b32 m0, s28
	s_nop 0
	global_load_lds_dwordx4 v1, s[72:73]
	s_mov_b32 m0, s29
	s_nop 0
	global_load_lds_dwordx4 v173, s[72:73]
	s_waitcnt vmcnt(8)
	s_waitcnt lgkmcnt(0)
	s_barrier
	s_setprio 1
	v_mfma_f32_16x16x32_bf16 v[126:129], v[134:137], v[166:169], v[126:129]
	v_mfma_f32_16x16x32_bf16 v[122:125], v[142:145], v[166:169], v[122:125]
	v_mfma_f32_16x16x32_bf16 v[110:113], v[134:137], v[214:217], v[110:113]
	v_mfma_f32_16x16x32_bf16 v[106:109], v[142:145], v[214:217], v[106:109]
	v_mfma_f32_16x16x32_bf16 v[94:97], v[134:137], v[222:225], v[94:97]
	v_mfma_f32_16x16x32_bf16 v[90:93], v[142:145], v[222:225], v[90:93]
	v_mfma_f32_16x16x32_bf16 v[78:81], v[134:137], v[230:233], v[78:81]
	v_mfma_f32_16x16x32_bf16 v[74:77], v[142:145], v[230:233], v[74:77]
	v_mfma_f32_16x16x32_bf16 v[126:129], v[138:141], v[210:213], v[126:129]
	v_mfma_f32_16x16x32_bf16 v[122:125], v[146:149], v[210:213], v[122:125]
	v_mfma_f32_16x16x32_bf16 v[110:113], v[138:141], v[218:221], v[110:113]
	v_mfma_f32_16x16x32_bf16 v[106:109], v[146:149], v[218:221], v[106:109]
	v_mfma_f32_16x16x32_bf16 v[94:97], v[138:141], v[226:229], v[94:97]
	v_mfma_f32_16x16x32_bf16 v[90:93], v[146:149], v[226:229], v[90:93]
	v_mfma_f32_16x16x32_bf16 v[78:81], v[138:141], v[234:237], v[78:81]
	v_mfma_f32_16x16x32_bf16 v[74:77], v[146:149], v[234:237], v[74:77]
	v_mfma_f32_16x16x32_bf16 v[118:121], v[150:153], v[166:169], v[118:121]
	v_mfma_f32_16x16x32_bf16 v[114:117], v[158:161], v[166:169], v[114:117]
	v_mfma_f32_16x16x32_bf16 v[102:105], v[150:153], v[214:217], v[102:105]
	v_mfma_f32_16x16x32_bf16 v[98:101], v[158:161], v[214:217], v[98:101]
	v_mfma_f32_16x16x32_bf16 v[86:89], v[150:153], v[222:225], v[86:89]
	v_mfma_f32_16x16x32_bf16 v[82:85], v[158:161], v[222:225], v[82:85]
	v_mfma_f32_16x16x32_bf16 v[70:73], v[150:153], v[230:233], v[70:73]
	v_mfma_f32_16x16x32_bf16 v[66:69], v[158:161], v[230:233], v[66:69]
	v_mfma_f32_16x16x32_bf16 v[118:121], v[154:157], v[210:213], v[118:121]
	v_mfma_f32_16x16x32_bf16 v[114:117], v[162:165], v[210:213], v[114:117]
	v_mfma_f32_16x16x32_bf16 v[102:105], v[154:157], v[218:221], v[102:105]
	v_mfma_f32_16x16x32_bf16 v[98:101], v[162:165], v[218:221], v[98:101]
	v_mfma_f32_16x16x32_bf16 v[86:89], v[154:157], v[226:229], v[86:89]
	v_mfma_f32_16x16x32_bf16 v[82:85], v[162:165], v[226:229], v[82:85]
	v_mfma_f32_16x16x32_bf16 v[70:73], v[154:157], v[234:237], v[70:73]
	v_mfma_f32_16x16x32_bf16 v[66:69], v[162:165], v[234:237], v[66:69]
	s_setprio 0
	s_barrier
	ds_read_b128 v[166:169], v203 offset:49152
	ds_read_b128 v[210:213], v203 offset:50176
	ds_read_b128 v[214:217], v203 offset:51200
	ds_read_b128 v[218:221], v203 offset:52224
	ds_read_b128 v[222:225], v203 offset:53248
	ds_read_b128 v[226:229], v203 offset:54272
	ds_read_b128 v[230:233], v203 offset:55296
	ds_read_b128 v[234:237], v203 offset:56320
	s_add_u32 s72, s70, 0x80
	s_addc_u32 s73, s71, 0
	s_mov_b32 m0, s33
	s_nop 0
	global_load_lds_dwordx4 v172, s[72:73]
	s_add_u32 s70, s70, 0x100080
	s_mov_b32 m0, s35
	s_nop 0
	global_load_lds_dwordx4 v174, s[72:73]
	s_addc_u32 s71, s71, 0
	s_mov_b32 m0, s75
	s_nop 0
	global_load_lds_dwordx4 v172, s[70:71]
	s_mov_b32 m0, s76
	s_nop 0
	global_load_lds_dwordx4 v174, s[70:71]
	s_mov_b32 m0, s67
	s_nop 0
	global_load_lds_dwordx4 v1, s[68:69]
	s_mov_b32 m0, s74
	s_nop 0
	global_load_lds_dwordx4 v173, s[68:69]
	s_waitcnt vmcnt(8)
	s_waitcnt lgkmcnt(0)
	s_barrier
	s_setprio 1
	v_mfma_f32_16x16x32_bf16 v[62:65], v[134:137], v[166:169], v[62:65]
	v_mfma_f32_16x16x32_bf16 v[58:61], v[142:145], v[166:169], v[58:61]
	v_mfma_f32_16x16x32_bf16 v[46:49], v[134:137], v[214:217], v[46:49]
	v_mfma_f32_16x16x32_bf16 v[42:45], v[142:145], v[214:217], v[42:45]
	v_mfma_f32_16x16x32_bf16 v[30:33], v[134:137], v[222:225], v[30:33]
	v_mfma_f32_16x16x32_bf16 v[26:29], v[142:145], v[222:225], v[26:29]
	v_mfma_f32_16x16x32_bf16 v[14:17], v[134:137], v[230:233], v[14:17]
	v_mfma_f32_16x16x32_bf16 v[10:13], v[142:145], v[230:233], v[10:13]
	v_mfma_f32_16x16x32_bf16 v[62:65], v[138:141], v[210:213], v[62:65]
	v_mfma_f32_16x16x32_bf16 v[58:61], v[146:149], v[210:213], v[58:61]
	v_mfma_f32_16x16x32_bf16 v[46:49], v[138:141], v[218:221], v[46:49]
	v_mfma_f32_16x16x32_bf16 v[42:45], v[146:149], v[218:221], v[42:45]
	v_mfma_f32_16x16x32_bf16 v[30:33], v[138:141], v[226:229], v[30:33]
	v_mfma_f32_16x16x32_bf16 v[26:29], v[146:149], v[226:229], v[26:29]
	v_mfma_f32_16x16x32_bf16 v[14:17], v[138:141], v[234:237], v[14:17]
	v_mfma_f32_16x16x32_bf16 v[10:13], v[146:149], v[234:237], v[10:13]
	v_mfma_f32_16x16x32_bf16 v[54:57], v[150:153], v[166:169], v[54:57]
	v_mfma_f32_16x16x32_bf16 v[50:53], v[158:161], v[166:169], v[50:53]
	v_mfma_f32_16x16x32_bf16 v[38:41], v[150:153], v[214:217], v[38:41]
	v_mfma_f32_16x16x32_bf16 v[34:37], v[158:161], v[214:217], v[34:37]
	v_mfma_f32_16x16x32_bf16 v[22:25], v[150:153], v[222:225], v[22:25]
	v_mfma_f32_16x16x32_bf16 v[18:21], v[158:161], v[222:225], v[18:21]
	v_mfma_f32_16x16x32_bf16 v[6:9], v[150:153], v[230:233], v[6:9]
	v_mfma_f32_16x16x32_bf16 v[2:5], v[158:161], v[230:233], v[2:5]
	v_mfma_f32_16x16x32_bf16 v[54:57], v[154:157], v[210:213], v[54:57]
	v_mfma_f32_16x16x32_bf16 v[50:53], v[162:165], v[210:213], v[50:53]
	v_mfma_f32_16x16x32_bf16 v[38:41], v[154:157], v[218:221], v[38:41]
	v_mfma_f32_16x16x32_bf16 v[34:37], v[162:165], v[218:221], v[34:37]
	v_mfma_f32_16x16x32_bf16 v[22:25], v[154:157], v[226:229], v[22:25]
	v_mfma_f32_16x16x32_bf16 v[18:21], v[162:165], v[226:229], v[18:21]
	v_mfma_f32_16x16x32_bf16 v[6:9], v[154:157], v[234:237], v[6:9]
	v_mfma_f32_16x16x32_bf16 v[2:5], v[162:165], v[234:237], v[2:5]
	s_setprio 0
	s_barrier
	s_add_i32 s85, s85, 2
	s_add_u32 s25, s25, 0x100
	s_addc_u32 s39, s39, 0
	s_add_u32 s59, s59, 0x100
	s_addc_u32 s84, s84, 0
	s_add_u32 s6, s6, 0x100
	s_addc_u32 s7, s7, 0
	s_cmp_gt_u32 s85, 61
	s_cbranch_scc0 .LBB0_892
	s_branch .Lmy_kexit_6
; #define PG8_STAGE(bufoff, gbase, voff) do { if constexpr (VAR != 1 && VAR != 3) { _Pragma("unroll") for (int _i = 0; _i < 2; ++_i) \
;         asm volatile("s_mov_b32 m0, %2\n\ts_nop 0\n\tglobal_load_lds_dwordx4 %0, %1" :: "v"((voff)[_i]), "s"((const char*)(gbase)), "s"(ldsbase + (unsigned)((bufoff) + _i * 8192)) : "memory", "m0"); } } while (0)
; #define PG8_LDA(dst, b, h) do { if constexpr (VAR < 2) _Pragma("unroll") for (int m = 0; m < 4; ++m) _Pragma("unroll") for (int k = 0; k < 2; ++k) dst[m][k] = *(const LAS bf16x8*)(lds + PG8_SA(b, h) + aoff + m * 2048 + k * 1024); } while (0)
; #define PG8_LDB(dst, b, h) do { if constexpr (VAR < 2) _Pragma("unroll") for (int n = 0; n < 2; ++n) _Pragma("unroll") for (int k = 0; k < 2; ++k) dst[n][k] = *(const LAS bf16x8*)(lds + PG8_SB(b, h) + boff + n * 2048 + k * 1024); } while (0)
; #define PG8_WAIT_V(n) asm volatile("s_waitcnt vmcnt(" #n ")" ::: "memory")
; #define PG8_WAIT_L(n) asm volatile("s_waitcnt lgkmcnt(" #n ")" ::: "memory")
; #define PG8_BAR do { if constexpr (VAR != 3) __builtin_amdgcn_s_barrier(); } while (0)
; #define PG8_SCHED __builtin_amdgcn_sched_barrier(0)
;     ...
;             const bool last = (t == nt - 2);
;             const char* a1 = cA + (size_t)(t + 1) * kstep;
;             const char* a2 = last ? nA : cA + (size_t)(t + 2) * kstep; const char* b2 = last ? nB : cB + (size_t)(t + 2) * kstep;
;             const char* a3 = a2 + kstep; const char* b3 = b2 + kstep;
;             PG8_LDB(B0, 0, 0); PG8_LDB(B1, 0, 1); PG8_SCHED; PG8_LDA(At, 0, 0); PG8_STAGE(PG8_SA(1, 1), a1 + hstepA, voffA);
;             PG8_WAIT_V(8); PG8_WAIT_L(0); PG8_BAR; PG8_MMA(0, 0, At, B0); PG8_MMA(0, 1, At, B1); PG8_BAR; PG8_SCHED;
;             PG8_LDA(At, 0, 1); PG8_STAGE(PG8_SB(0, 0), b2, voffB); PG8_STAGE(PG8_SB(0, 1), b2 + hstepB, voffB); PG8_STAGE(PG8_SA(0, 0), a2, voffA);
;             PG8_WAIT_V(8); PG8_WAIT_L(0); PG8_BAR; PG8_MMA(1, 0, At, B0); PG8_MMA(1, 1, At, B1); PG8_BAR; PG8_SCHED;
.LBB0_892:
	ds_read_b128 v[134:137], v201
	ds_read_b128 v[138:141], v201 offset:1024
	ds_read_b128 v[142:145], v201 offset:2048
	ds_read_b128 v[146:149], v201 offset:3072
	ds_read_b128 v[150:153], v202
	ds_read_b128 v[154:157], v202 offset:1024
	ds_read_b128 v[158:161], v202 offset:2048
	ds_read_b128 v[162:165], v202 offset:3072
	s_cmp_eq_u32 s85, 60
	s_cselect_b32 s72, s24, s25
	s_cselect_b32 s73, s1, s39
	s_cselect_b32 s70, s60, s59
	s_cselect_b32 s71, s61, s84
	s_add_u32 s68, s72, 0x80
	s_addc_u32 s69, s73, 0
	ds_read_b128 v[166:169], v203
	ds_read_b128 v[210:213], v203 offset:1024
	ds_read_b128 v[214:217], v203 offset:2048
	ds_read_b128 v[218:221], v203 offset:3072
	ds_read_b128 v[222:225], v203 offset:4096
	ds_read_b128 v[226:229], v203 offset:5120
	ds_read_b128 v[230:233], v203 offset:6144
	ds_read_b128 v[234:237], v203 offset:7168
	s_mov_b32 m0, s77
	s_nop 0
	global_load_lds_dwordx4 v1, s[6:7]
	s_mov_b32 m0, s79
	s_nop 0
	global_load_lds_dwordx4 v173, s[6:7]
	s_waitcnt vmcnt(8)
	s_waitcnt lgkmcnt(0)
	s_barrier
	s_setprio 1
	v_mfma_f32_16x16x32_bf16 v[126:129], v[134:137], v[166:169], v[126:129]
	v_mfma_f32_16x16x32_bf16 v[122:125], v[142:145], v[166:169], v[122:125]
	v_mfma_f32_16x16x32_bf16 v[110:113], v[134:137], v[214:217], v[110:113]
	v_mfma_f32_16x16x32_bf16 v[106:109], v[142:145], v[214:217], v[106:109]
	v_mfma_f32_16x16x32_bf16 v[94:97], v[134:137], v[222:225], v[94:97]
	v_mfma_f32_16x16x32_bf16 v[90:93], v[142:145], v[222:225], v[90:93]
	v_mfma_f32_16x16x32_bf16 v[78:81], v[134:137], v[230:233], v[78:81]
	v_mfma_f32_16x16x32_bf16 v[74:77], v[142:145], v[230:233], v[74:77]
	v_mfma_f32_16x16x32_bf16 v[126:129], v[138:141], v[210:213], v[126:129]
	v_mfma_f32_16x16x32_bf16 v[122:125], v[146:149], v[210:213], v[122:125]
	v_mfma_f32_16x16x32_bf16 v[110:113], v[138:141], v[218:221], v[110:113]
	v_mfma_f32_16x16x32_bf16 v[106:109], v[146:149], v[218:221], v[106:109]
	v_mfma_f32_16x16x32_bf16 v[94:97], v[138:141], v[226:229], v[94:97]
	v_mfma_f32_16x16x32_bf16 v[90:93], v[146:149], v[226:229], v[90:93]
	v_mfma_f32_16x16x32_bf16 v[78:81], v[138:141], v[234:237], v[78:81]
	v_mfma_f32_16x16x32_bf16 v[74:77], v[146:149], v[234:237], v[74:77]
	v_mfma_f32_16x16x32_bf16 v[118:121], v[150:153], v[166:169], v[118:121]
	v_mfma_f32_16x16x32_bf16 v[114:117], v[158:161], v[166:169], v[114:117]
	v_mfma_f32_16x16x32_bf16 v[102:105], v[150:153], v[214:217], v[102:105]
	v_mfma_f32_16x16x32_bf16 v[98:101], v[158:161], v[214:217], v[98:101]
	v_mfma_f32_16x16x32_bf16 v[86:89], v[150:153], v[222:225], v[86:89]
	v_mfma_f32_16x16x32_bf16 v[82:85], v[158:161], v[222:225], v[82:85]
	v_mfma_f32_16x16x32_bf16 v[70:73], v[150:153], v[230:233], v[70:73]
	v_mfma_f32_16x16x32_bf16 v[66:69], v[158:161], v[230:233], v[66:69]
	v_mfma_f32_16x16x32_bf16 v[118:121], v[154:157], v[210:213], v[118:121]
	v_mfma_f32_16x16x32_bf16 v[114:117], v[162:165], v[210:213], v[114:117]
	v_mfma_f32_16x16x32_bf16 v[102:105], v[154:157], v[218:221], v[102:105]
	v_mfma_f32_16x16x32_bf16 v[98:101], v[162:165], v[218:221], v[98:101]
	v_mfma_f32_16x16x32_bf16 v[86:89], v[154:157], v[226:229], v[86:89]
	v_mfma_f32_16x16x32_bf16 v[82:85], v[162:165], v[226:229], v[82:85]
	v_mfma_f32_16x16x32_bf16 v[70:73], v[154:157], v[234:237], v[70:73]
	v_mfma_f32_16x16x32_bf16 v[66:69], v[162:165], v[234:237], v[66:69]
	s_setprio 0
	s_barrier
	ds_read_b128 v[166:169], v203 offset:16384
	ds_read_b128 v[210:213], v203 offset:17408
	ds_read_b128 v[214:217], v203 offset:18432
	ds_read_b128 v[218:221], v203 offset:19456
	ds_read_b128 v[222:225], v203 offset:20480
	ds_read_b128 v[226:229], v203 offset:21504
	ds_read_b128 v[230:233], v203 offset:22528
	ds_read_b128 v[234:237], v203 offset:23552
	s_mov_b32 m0, s17
	s_nop 0
	global_load_lds_dwordx4 v172, s[70:71]
	s_add_u32 s86, s70, 0x100000
	s_mov_b32 m0, s19
	s_nop 0
	global_load_lds_dwordx4 v174, s[70:71]
	s_addc_u32 s87, s71, 0
	s_mov_b32 m0, s23
	s_nop 0
	global_load_lds_dwordx4 v172, s[86:87]
	s_mov_b32 m0, s26
	s_nop 0
	global_load_lds_dwordx4 v174, s[86:87]
	s_mov_b32 m0, s15
	s_nop 0
	global_load_lds_dwordx4 v1, s[72:73]
	s_mov_b32 m0, s27
	s_nop 0
	global_load_lds_dwordx4 v173, s[72:73]
	s_waitcnt vmcnt(8)
	s_waitcnt lgkmcnt(0)
	s_barrier
	s_setprio 1
	v_mfma_f32_16x16x32_bf16 v[62:65], v[134:137], v[166:169], v[62:65]
	v_mfma_f32_16x16x32_bf16 v[58:61], v[142:145], v[166:169], v[58:61]
	v_mfma_f32_16x16x32_bf16 v[46:49], v[134:137], v[214:217], v[46:49]
	v_mfma_f32_16x16x32_bf16 v[42:45], v[142:145], v[214:217], v[42:45]
	v_mfma_f32_16x16x32_bf16 v[30:33], v[134:137], v[222:225], v[30:33]
	v_mfma_f32_16x16x32_bf16 v[26:29], v[142:145], v[222:225], v[26:29]
	v_mfma_f32_16x16x32_bf16 v[14:17], v[134:137], v[230:233], v[14:17]
	v_mfma_f32_16x16x32_bf16 v[10:13], v[142:145], v[230:233], v[10:13]
	v_mfma_f32_16x16x32_bf16 v[62:65], v[138:141], v[210:213], v[62:65]
	v_mfma_f32_16x16x32_bf16 v[58:61], v[146:149], v[210:213], v[58:61]
	v_mfma_f32_16x16x32_bf16 v[46:49], v[138:141], v[218:221], v[46:49]
	v_mfma_f32_16x16x32_bf16 v[42:45], v[146:149], v[218:221], v[42:45]
	v_mfma_f32_16x16x32_bf16 v[30:33], v[138:141], v[226:229], v[30:33]
	v_mfma_f32_16x16x32_bf16 v[26:29], v[146:149], v[226:229], v[26:29]
	v_mfma_f32_16x16x32_bf16 v[14:17], v[138:141], v[234:237], v[14:17]
	v_mfma_f32_16x16x32_bf16 v[10:13], v[146:149], v[234:237], v[10:13]
	v_mfma_f32_16x16x32_bf16 v[54:57], v[150:153], v[166:169], v[54:57]
	v_mfma_f32_16x16x32_bf16 v[50:53], v[158:161], v[166:169], v[50:53]
	v_mfma_f32_16x16x32_bf16 v[38:41], v[150:153], v[214:217], v[38:41]
	v_mfma_f32_16x16x32_bf16 v[34:37], v[158:161], v[214:217], v[34:37]
	v_mfma_f32_16x16x32_bf16 v[22:25], v[150:153], v[222:225], v[22:25]
	v_mfma_f32_16x16x32_bf16 v[18:21], v[158:161], v[222:225], v[18:21]
	v_mfma_f32_16x16x32_bf16 v[6:9], v[150:153], v[230:233], v[6:9]
	v_mfma_f32_16x16x32_bf16 v[2:5], v[158:161], v[230:233], v[2:5]
	v_mfma_f32_16x16x32_bf16 v[54:57], v[154:157], v[210:213], v[54:57]
	v_mfma_f32_16x16x32_bf16 v[50:53], v[162:165], v[210:213], v[50:53]
	v_mfma_f32_16x16x32_bf16 v[38:41], v[154:157], v[218:221], v[38:41]
	v_mfma_f32_16x16x32_bf16 v[34:37], v[162:165], v[218:221], v[34:37]
	v_mfma_f32_16x16x32_bf16 v[22:25], v[154:157], v[226:229], v[22:25]
	v_mfma_f32_16x16x32_bf16 v[18:21], v[162:165], v[226:229], v[18:21]
	v_mfma_f32_16x16x32_bf16 v[6:9], v[154:157], v[234:237], v[6:9]
	v_mfma_f32_16x16x32_bf16 v[2:5], v[162:165], v[234:237], v[2:5]
	s_setprio 0
	s_barrier
; #define PG8_STAGE(bufoff, gbase, voff) do { if constexpr (VAR != 1 && VAR != 3) { _Pragma("unroll") for (int _i = 0; _i < 2; ++_i) \
;         asm volatile("s_mov_b32 m0, %2\n\ts_nop 0\n\tglobal_load_lds_dwordx4 %0, %1" :: "v"((voff)[_i]), "s"((const char*)(gbase)), "s"(ldsbase + (unsigned)((bufoff) + _i * 8192)) : "memory", "m0"); } } while (0)
; #define PG8_LDA(dst, b, h) do { if constexpr (VAR < 2) _Pragma("unroll") for (int m = 0; m < 4; ++m) _Pragma("unroll") for (int k = 0; k < 2; ++k) dst[m][k] = *(const LAS bf16x8*)(lds + PG8_SA(b, h) + aoff + m * 2048 + k * 1024); } while (0)
; #define PG8_LDB(dst, b, h) do { if constexpr (VAR < 2) _Pragma("unroll") for (int n = 0; n < 2; ++n) _Pragma("unroll") for (int k = 0; k < 2; ++k) dst[n][k] = *(const LAS bf16x8*)(lds + PG8_SB(b, h) + boff + n * 2048 + k * 1024); } while (0)
; #define PG8_WAIT_V(n) asm volatile("s_waitcnt vmcnt(" #n ")" ::: "memory")
; #define PG8_WAIT_L(n) asm volatile("s_waitcnt lgkmcnt(" #n ")" ::: "memory")
; #define PG8_BAR do { if constexpr (VAR != 3) __builtin_amdgcn_s_barrier(); } while (0)
; #define PG8_SCHED __builtin_amdgcn_sched_barrier(0)
;     ...
;             PG8_LDB(B0, 1, 0); PG8_LDB(B1, 1, 1); PG8_SCHED; PG8_LDA(At, 1, 0); PG8_STAGE(PG8_SA(0, 1), a2 + hstepA, voffA);
;             PG8_WAIT_V(8); PG8_WAIT_L(0); PG8_BAR; PG8_MMA(0, 0, At, B0); PG8_MMA(0, 1, At, B1); PG8_BAR; PG8_SCHED;
;             PG8_LDA(At, 1, 1); PG8_STAGE(PG8_SB(1, 0), b3, voffB); PG8_STAGE(PG8_SB(1, 1), b3 + hstepB, voffB); PG8_STAGE(PG8_SA(1, 0), a3, voffA);
;             PG8_WAIT_V(8); PG8_WAIT_L(0); PG8_BAR; PG8_MMA(1, 0, At, B0); PG8_MMA(1, 1, At, B1); PG8_BAR; PG8_SCHED;
;         }
;         if (wr == 0) PG8_BAR;
	ds_read_b128 v[134:137], v204
	ds_read_b128 v[138:141], v204 offset:1024
	ds_read_b128 v[142:145], v204 offset:2048
	ds_read_b128 v[146:149], v204 offset:3072
	ds_read_b128 v[150:153], v205
	ds_read_b128 v[154:157], v205 offset:1024
	ds_read_b128 v[158:161], v205 offset:2048
	ds_read_b128 v[162:165], v205 offset:3072
	ds_read_b128 v[166:169], v203 offset:32768
	ds_read_b128 v[210:213], v203 offset:33792
	ds_read_b128 v[214:217], v203 offset:34816
	ds_read_b128 v[218:221], v203 offset:35840
	ds_read_b128 v[222:225], v203 offset:36864
	ds_read_b128 v[226:229], v203 offset:37888
	ds_read_b128 v[230:233], v203 offset:38912
	ds_read_b128 v[234:237], v203 offset:39936
	s_add_u32 s72, s72, 0x100000
	s_addc_u32 s73, s73, 0
	s_mov_b32 m0, s28
	s_nop 0
	global_load_lds_dwordx4 v1, s[72:73]
	s_mov_b32 m0, s29
	s_nop 0
	global_load_lds_dwordx4 v173, s[72:73]
	s_waitcnt vmcnt(8)
	s_waitcnt lgkmcnt(0)
	s_barrier
	s_setprio 1
	v_mfma_f32_16x16x32_bf16 v[126:129], v[134:137], v[166:169], v[126:129]
	v_mfma_f32_16x16x32_bf16 v[122:125], v[142:145], v[166:169], v[122:125]
	v_mfma_f32_16x16x32_bf16 v[110:113], v[134:137], v[214:217], v[110:113]
	v_mfma_f32_16x16x32_bf16 v[106:109], v[142:145], v[214:217], v[106:109]
	v_mfma_f32_16x16x32_bf16 v[94:97], v[134:137], v[222:225], v[94:97]
	v_mfma_f32_16x16x32_bf16 v[90:93], v[142:145], v[222:225], v[90:93]
	v_mfma_f32_16x16x32_bf16 v[78:81], v[134:137], v[230:233], v[78:81]
	v_mfma_f32_16x16x32_bf16 v[74:77], v[142:145], v[230:233], v[74:77]
	v_mfma_f32_16x16x32_bf16 v[126:129], v[138:141], v[210:213], v[126:129]
	v_mfma_f32_16x16x32_bf16 v[122:125], v[146:149], v[210:213], v[122:125]
	v_mfma_f32_16x16x32_bf16 v[110:113], v[138:141], v[218:221], v[110:113]
	v_mfma_f32_16x16x32_bf16 v[106:109], v[146:149], v[218:221], v[106:109]
	v_mfma_f32_16x16x32_bf16 v[94:97], v[138:141], v[226:229], v[94:97]
	v_mfma_f32_16x16x32_bf16 v[90:93], v[146:149], v[226:229], v[90:93]
	v_mfma_f32_16x16x32_bf16 v[78:81], v[138:141], v[234:237], v[78:81]
	v_mfma_f32_16x16x32_bf16 v[74:77], v[146:149], v[234:237], v[74:77]
	v_mfma_f32_16x16x32_bf16 v[118:121], v[150:153], v[166:169], v[118:121]
	v_mfma_f32_16x16x32_bf16 v[114:117], v[158:161], v[166:169], v[114:117]
	v_mfma_f32_16x16x32_bf16 v[102:105], v[150:153], v[214:217], v[102:105]
	v_mfma_f32_16x16x32_bf16 v[98:101], v[158:161], v[214:217], v[98:101]
	v_mfma_f32_16x16x32_bf16 v[86:89], v[150:153], v[222:225], v[86:89]
	v_mfma_f32_16x16x32_bf16 v[82:85], v[158:161], v[222:225], v[82:85]
	v_mfma_f32_16x16x32_bf16 v[70:73], v[150:153], v[230:233], v[70:73]
	v_mfma_f32_16x16x32_bf16 v[66:69], v[158:161], v[230:233], v[66:69]
	v_mfma_f32_16x16x32_bf16 v[118:121], v[154:157], v[210:213], v[118:121]
	v_mfma_f32_16x16x32_bf16 v[114:117], v[162:165], v[210:213], v[114:117]
	v_mfma_f32_16x16x32_bf16 v[102:105], v[154:157], v[218:221], v[102:105]
	v_mfma_f32_16x16x32_bf16 v[98:101], v[162:165], v[218:221], v[98:101]
	v_mfma_f32_16x16x32_bf16 v[86:89], v[154:157], v[226:229], v[86:89]
	v_mfma_f32_16x16x32_bf16 v[82:85], v[162:165], v[226:229], v[82:85]
	v_mfma_f32_16x16x32_bf16 v[70:73], v[154:157], v[234:237], v[70:73]
	v_mfma_f32_16x16x32_bf16 v[66:69], v[162:165], v[234:237], v[66:69]
	s_setprio 0
	s_barrier
	ds_read_b128 v[166:169], v203 offset:49152
	ds_read_b128 v[210:213], v203 offset:50176
	ds_read_b128 v[214:217], v203 offset:51200
	ds_read_b128 v[218:221], v203 offset:52224
	ds_read_b128 v[222:225], v203 offset:53248
	ds_read_b128 v[226:229], v203 offset:54272
	ds_read_b128 v[230:233], v203 offset:55296
	ds_read_b128 v[234:237], v203 offset:56320
	s_add_u32 s72, s70, 0x80
	s_addc_u32 s73, s71, 0
	s_mov_b32 m0, s33
	s_nop 0
	global_load_lds_dwordx4 v172, s[72:73]
	s_add_u32 s70, s70, 0x100080
	s_mov_b32 m0, s35
	s_nop 0
	global_load_lds_dwordx4 v174, s[72:73]
	s_addc_u32 s71, s71, 0
	s_mov_b32 m0, s75
	s_nop 0
	global_load_lds_dwordx4 v172, s[70:71]
	s_mov_b32 m0, s76
	s_nop 0
	global_load_lds_dwordx4 v174, s[70:71]
	s_mov_b32 m0, s67
	s_nop 0
	global_load_lds_dwordx4 v1, s[68:69]
	s_mov_b32 m0, s74
	s_nop 0
	global_load_lds_dwordx4 v173, s[68:69]
	s_waitcnt vmcnt(8)
	s_waitcnt lgkmcnt(0)
	s_barrier
	s_setprio 1
	v_mfma_f32_16x16x32_bf16 v[62:65], v[134:137], v[166:169], v[62:65]
	v_mfma_f32_16x16x32_bf16 v[58:61], v[142:145], v[166:169], v[58:61]
	v_mfma_f32_16x16x32_bf16 v[46:49], v[134:137], v[214:217], v[46:49]
	v_mfma_f32_16x16x32_bf16 v[42:45], v[142:145], v[214:217], v[42:45]
	v_mfma_f32_16x16x32_bf16 v[30:33], v[134:137], v[222:225], v[30:33]
	v_mfma_f32_16x16x32_bf16 v[26:29], v[142:145], v[222:225], v[26:29]
	v_mfma_f32_16x16x32_bf16 v[14:17], v[134:137], v[230:233], v[14:17]
	v_mfma_f32_16x16x32_bf16 v[10:13], v[142:145], v[230:233], v[10:13]
	v_mfma_f32_16x16x32_bf16 v[62:65], v[138:141], v[210:213], v[62:65]
	v_mfma_f32_16x16x32_bf16 v[58:61], v[146:149], v[210:213], v[58:61]
	v_mfma_f32_16x16x32_bf16 v[46:49], v[138:141], v[218:221], v[46:49]
	v_mfma_f32_16x16x32_bf16 v[42:45], v[146:149], v[218:221], v[42:45]
	v_mfma_f32_16x16x32_bf16 v[30:33], v[138:141], v[226:229], v[30:33]
	v_mfma_f32_16x16x32_bf16 v[26:29], v[146:149], v[226:229], v[26:29]
	v_mfma_f32_16x16x32_bf16 v[14:17], v[138:141], v[234:237], v[14:17]
	v_mfma_f32_16x16x32_bf16 v[10:13], v[146:149], v[234:237], v[10:13]
	v_mfma_f32_16x16x32_bf16 v[54:57], v[150:153], v[166:169], v[54:57]
	v_mfma_f32_16x16x32_bf16 v[50:53], v[158:161], v[166:169], v[50:53]
	v_mfma_f32_16x16x32_bf16 v[38:41], v[150:153], v[214:217], v[38:41]
	v_mfma_f32_16x16x32_bf16 v[34:37], v[158:161], v[214:217], v[34:37]
	v_mfma_f32_16x16x32_bf16 v[22:25], v[150:153], v[222:225], v[22:25]
	v_mfma_f32_16x16x32_bf16 v[18:21], v[158:161], v[222:225], v[18:21]
	v_mfma_f32_16x16x32_bf16 v[6:9], v[150:153], v[230:233], v[6:9]
	v_mfma_f32_16x16x32_bf16 v[2:5], v[158:161], v[230:233], v[2:5]
	v_mfma_f32_16x16x32_bf16 v[54:57], v[154:157], v[210:213], v[54:57]
	v_mfma_f32_16x16x32_bf16 v[50:53], v[162:165], v[210:213], v[50:53]
	v_mfma_f32_16x16x32_bf16 v[38:41], v[154:157], v[218:221], v[38:41]
	v_mfma_f32_16x16x32_bf16 v[34:37], v[162:165], v[218:221], v[34:37]
	v_mfma_f32_16x16x32_bf16 v[22:25], v[154:157], v[226:229], v[22:25]
	v_mfma_f32_16x16x32_bf16 v[18:21], v[162:165], v[226:229], v[18:21]
	v_mfma_f32_16x16x32_bf16 v[6:9], v[154:157], v[234:237], v[6:9]
	v_mfma_f32_16x16x32_bf16 v[2:5], v[162:165], v[234:237], v[2:5]
	s_setprio 0
	s_barrier
	s_add_i32 s85, s85, 2
	s_add_u32 s25, s25, 0x100
	s_addc_u32 s39, s39, 0
	s_add_u32 s59, s59, 0x100
	s_addc_u32 s84, s84, 0
	s_add_u32 s6, s6, 0x100
	s_addc_u32 s7, s7, 0
	s_cmp_gt_u32 s85, 61
	s_cbranch_scc0 .LBB0_892
.Lmy_kexit_6:
	s_and_b64 vcc, exec, s[10:11]
	s_cbranch_vccz .LBB0_895
	s_barrier

; __device__ __forceinline__ const char* unitA(const Gemm& g, const Unit& u) { return (const char*)(g.A + (size_t)(u.z / g.zdiv) * g.sAhi + (size_t)(u.z % g.zdiv) * g.sAlo + (size_t)u.pm * BM * g.lda); }
; __device__ __forceinline__ const char* unitB(const Gemm& g, const Unit& u) { return (const char*)(g.Bt + (size_t)(u.z / g.zdiv) * g.sBhi + (size_t)(u.z % g.zdiv) * g.sBlo + (size_t)(u.pm / g.bdiv) * g.sBpm + (size_t)u.pn * BM * g.ldb); }
; #define PG8_STAGE(bufoff, gbase, voff) do { if constexpr (VAR != 1 && VAR != 3) { _Pragma("unroll") for (int _i = 0; _i < 2; ++_i) \
;         asm volatile("s_mov_b32 m0, %2\n\ts_nop 0\n\tglobal_load_lds_dwordx4 %0, %1" :: "v"((voff)[_i]), "s"((const char*)(gbase)), "s"(ldsbase + (unsigned)((bufoff) + _i * 8192)) : "memory", "m0"); } } while (0)
; #define PG8_LDA(dst, b, h) do { if constexpr (VAR < 2) _Pragma("unroll") for (int m = 0; m < 4; ++m) _Pragma("unroll") for (int k = 0; k < 2; ++k) dst[m][k] = *(const LAS bf16x8*)(lds + PG8_SA(b, h) + aoff + m * 2048 + k * 1024); } while (0)
; #define PG8_LDB(dst, b, h) do { if constexpr (VAR < 2) _Pragma("unroll") for (int n = 0; n < 2; ++n) _Pragma("unroll") for (int k = 0; k < 2; ++k) dst[n][k] = *(const LAS bf16x8*)(lds + PG8_SB(b, h) + boff + n * 2048 + k * 1024); } while (0)
; #define PG8_WAIT_V(n) asm volatile("s_waitcnt vmcnt(" #n ")" ::: "memory")
;     ...
;         const bool has_next = S.next(ui + 1, nxt);
;         const char* nA = has_next ? unitA(g, nxt) : cA; const char* nB = has_next ? unitB(g, nxt) : cB;
;         for (int t = 0; t < nt; t += 2) {
;             const bool last = (t == nt - 2);
;             const char* a1 = cA + (size_t)(t + 1) * kstep;
;             const char* a2 = last ? nA : cA + (size_t)(t + 2) * kstep; const char* b2 = last ? nB : cB + (size_t)(t + 2) * kstep;
;             const char* a3 = a2 + kstep; const char* b3 = b2 + kstep;
;             PG8_LDB(B0, 0, 0); PG8_LDB(B1, 0, 1); PG8_SCHED; PG8_LDA(At, 0, 0); PG8_STAGE(PG8_SA(1, 1), a1 + hstepA, voffA);
;             PG8_WAIT_V(8); PG8_WAIT_L(0); PG8_BAR; PG8_MMA(0, 0, At, B0); PG8_MMA(0, 1, At, B1); PG8_BAR; PG8_SCHED;
;             PG8_LDA(At, 0, 1); PG8_STAGE(PG8_SB(0, 0), b2, voffB); PG8_STAGE(PG8_SB(0, 1), b2 + hstepB, voffB); PG8_STAGE(PG8_SA(0, 0), a2, voffA);
;             PG8_WAIT_V(8); PG8_WAIT_L(0); PG8_BAR; PG8_MMA(1, 0, At, B0); PG8_MMA(1, 1, At, B1); PG8_BAR; PG8_SCHED;
.LBB0_1001:
	s_ashr_i32 s65, s64, 31
	s_lshl_b64 s[24:25], s[64:65], 19
	s_add_u32 s68, s40, s24
	s_addc_u32 s69, s41, s25
	s_and_b64 s[12:13], s[12:13], exec
	s_cselect_b32 s24, s69, s77
	s_cselect_b32 s25, s68, s76
	s_add_u32 s63, s76, 0x100
	s_addc_u32 s65, s77, 0
	s_add_u32 s84, s74, 0x100
	s_addc_u32 s85, s75, 0
	s_add_u32 s12, s76, 0x40080
	s_addc_u32 s13, s77, 0
	s_mov_b32 s86, -2
	s_waitcnt vmcnt(41)
	s_waitcnt vmcnt(40)
	s_waitcnt vmcnt(38)
	s_waitcnt vmcnt(35)
	s_waitcnt vmcnt(34)
	s_waitcnt vmcnt(32)
	ds_read_b128 v[130:133], v183
	ds_read_b128 v[134:137], v183 offset:1024
	ds_read_b128 v[138:141], v183 offset:2048
	ds_read_b128 v[142:145], v183 offset:3072
	ds_read_b128 v[146:149], v184
	ds_read_b128 v[150:153], v184 offset:1024
	ds_read_b128 v[154:157], v184 offset:2048
	ds_read_b128 v[162:165], v184 offset:3072
	s_cmp_eq_u32 s86, 12
	s_cselect_b32 s78, s25, s63
	s_cselect_b32 s79, s24, s65
	s_cselect_b32 s76, s66, s84
	s_cselect_b32 s77, s67, s85
	s_add_u32 s74, s78, 0x80
	s_addc_u32 s75, s79, 0
	ds_read_b128 v[166:169], v185
	ds_read_b128 v[170:173], v185 offset:1024
	ds_read_b128 v[190:193], v185 offset:2048
	ds_read_b128 v[194:197], v185 offset:3072
	ds_read_b128 v[198:201], v185 offset:4096
	ds_read_b128 v[202:205], v185 offset:5120
	ds_read_b128 v[206:209], v185 offset:6144
	ds_read_b128 v[210:213], v185 offset:7168
	s_mov_b32 m0, s82
	s_nop 0
	global_load_lds_dwordx4 v176, s[12:13]
	s_mov_b32 m0, s83
	s_nop 0
	global_load_lds_dwordx4 v178, s[12:13]
	s_waitcnt vmcnt(8)
	s_waitcnt lgkmcnt(0)
	s_barrier
	s_setprio 1
	v_mfma_f32_16x16x32_bf16 v[126:129], v[130:133], v[166:169], 0
	v_mfma_f32_16x16x32_bf16 v[122:125], v[138:141], v[166:169], 0
	v_mfma_f32_16x16x32_bf16 v[110:113], v[130:133], v[190:193], 0
	v_mfma_f32_16x16x32_bf16 v[106:109], v[138:141], v[190:193], 0
	v_mfma_f32_16x16x32_bf16 v[94:97], v[130:133], v[198:201], 0
	v_mfma_f32_16x16x32_bf16 v[90:93], v[138:141], v[198:201], 0
	v_mfma_f32_16x16x32_bf16 v[78:81], v[130:133], v[206:209], 0
	v_mfma_f32_16x16x32_bf16 v[74:77], v[138:141], v[206:209], 0
	v_mfma_f32_16x16x32_bf16 v[126:129], v[134:137], v[170:173], v[126:129]
	v_mfma_f32_16x16x32_bf16 v[122:125], v[142:145], v[170:173], v[122:125]
	v_mfma_f32_16x16x32_bf16 v[110:113], v[134:137], v[194:197], v[110:113]
	v_mfma_f32_16x16x32_bf16 v[106:109], v[142:145], v[194:197], v[106:109]
	v_mfma_f32_16x16x32_bf16 v[94:97], v[134:137], v[202:205], v[94:97]
	v_mfma_f32_16x16x32_bf16 v[90:93], v[142:145], v[202:205], v[90:93]
	v_mfma_f32_16x16x32_bf16 v[78:81], v[134:137], v[210:213], v[78:81]
	v_mfma_f32_16x16x32_bf16 v[74:77], v[142:145], v[210:213], v[74:77]
	v_mfma_f32_16x16x32_bf16 v[118:121], v[146:149], v[166:169], 0
	v_mfma_f32_16x16x32_bf16 v[114:117], v[154:157], v[166:169], 0
	v_mfma_f32_16x16x32_bf16 v[102:105], v[146:149], v[190:193], 0
	v_mfma_f32_16x16x32_bf16 v[98:101], v[154:157], v[190:193], 0
	v_mfma_f32_16x16x32_bf16 v[86:89], v[146:149], v[198:201], 0
	v_mfma_f32_16x16x32_bf16 v[82:85], v[154:157], v[198:201], 0
	v_mfma_f32_16x16x32_bf16 v[70:73], v[146:149], v[206:209], 0
	v_mfma_f32_16x16x32_bf16 v[66:69], v[154:157], v[206:209], 0
	v_mfma_f32_16x16x32_bf16 v[118:121], v[150:153], v[170:173], v[118:121]
	v_mfma_f32_16x16x32_bf16 v[114:117], v[162:165], v[170:173], v[114:117]
	v_mfma_f32_16x16x32_bf16 v[102:105], v[150:153], v[194:197], v[102:105]
	v_mfma_f32_16x16x32_bf16 v[98:101], v[162:165], v[194:197], v[98:101]
	v_mfma_f32_16x16x32_bf16 v[86:89], v[150:153], v[202:205], v[86:89]
	v_mfma_f32_16x16x32_bf16 v[82:85], v[162:165], v[202:205], v[82:85]
	v_mfma_f32_16x16x32_bf16 v[70:73], v[150:153], v[210:213], v[70:73]
	v_mfma_f32_16x16x32_bf16 v[66:69], v[162:165], v[210:213], v[66:69]
	s_setprio 0
	s_barrier
	ds_read_b128 v[166:169], v185 offset:16384
	ds_read_b128 v[170:173], v185 offset:17408
	ds_read_b128 v[190:193], v185 offset:18432
	ds_read_b128 v[194:197], v185 offset:19456
	ds_read_b128 v[198:201], v185 offset:20480
	ds_read_b128 v[202:205], v185 offset:21504
	ds_read_b128 v[206:209], v185 offset:22528
	ds_read_b128 v[210:213], v185 offset:23552
	s_mov_b32 m0, s17
	s_nop 0
	global_load_lds_dwordx4 v177, s[76:77]
	s_add_u32 s88, s76, 0x40000
	s_mov_b32 m0, s19
	s_nop 0
	global_load_lds_dwordx4 v179, s[76:77]
	s_addc_u32 s89, s77, 0
	s_mov_b32 m0, s23
	s_nop 0
	global_load_lds_dwordx4 v177, s[88:89]
	s_mov_b32 m0, s26
	s_nop 0
	global_load_lds_dwordx4 v179, s[88:89]
	s_mov_b32 m0, s15
	s_nop 0
	global_load_lds_dwordx4 v176, s[78:79]
	s_mov_b32 m0, s27
	s_nop 0
	global_load_lds_dwordx4 v178, s[78:79]
	s_waitcnt vmcnt(8)
	s_waitcnt lgkmcnt(0)
	s_barrier
; #define PG8_STAGE(bufoff, gbase, voff) do { if constexpr (VAR != 1 && VAR != 3) { _Pragma("unroll") for (int _i = 0; _i < 2; ++_i) \
;         asm volatile("s_mov_b32 m0, %2\n\ts_nop 0\n\tglobal_load_lds_dwordx4 %0, %1" :: "v"((voff)[_i]), "s"((const char*)(gbase)), "s"(ldsbase + (unsigned)((bufoff) + _i * 8192)) : "memory", "m0"); } } while (0)
; #define PG8_LDA(dst, b, h) do { if constexpr (VAR < 2) _Pragma("unroll") for (int m = 0; m < 4; ++m) _Pragma("unroll") for (int k = 0; k < 2; ++k) dst[m][k] = *(const LAS bf16x8*)(lds + PG8_SA(b, h) + aoff + m * 2048 + k * 1024); } while (0)
; #define PG8_LDB(dst, b, h) do { if constexpr (VAR < 2) _Pragma("unroll") for (int n = 0; n < 2; ++n) _Pragma("unroll") for (int k = 0; k < 2; ++k) dst[n][k] = *(const LAS bf16x8*)(lds + PG8_SB(b, h) + boff + n * 2048 + k * 1024); } while (0)
; #define PG8_WAIT_V(n) asm volatile("s_waitcnt vmcnt(" #n ")" ::: "memory")
; #define PG8_WAIT_L(n) asm volatile("s_waitcnt lgkmcnt(" #n ")" ::: "memory")
; #define PG8_BAR do { if constexpr (VAR != 3) __builtin_amdgcn_s_barrier(); } while (0)
; #define PG8_SCHED __builtin_amdgcn_sched_barrier(0)
;     ...
;             PG8_WAIT_V(8); PG8_WAIT_L(0); PG8_BAR; PG8_MMA(1, 0, At, B0); PG8_MMA(1, 1, At, B1); PG8_BAR; PG8_SCHED;
;             PG8_LDB(B0, 1, 0); PG8_LDB(B1, 1, 1); PG8_SCHED; PG8_LDA(At, 1, 0); PG8_STAGE(PG8_SA(0, 1), a2 + hstepA, voffA);
;             PG8_WAIT_V(8); PG8_WAIT_L(0); PG8_BAR; PG8_MMA(0, 0, At, B0); PG8_MMA(0, 1, At, B1); PG8_BAR; PG8_SCHED;
	s_setprio 1
	v_mfma_f32_16x16x32_bf16 v[62:65], v[130:133], v[166:169], 0
	v_mfma_f32_16x16x32_bf16 v[58:61], v[138:141], v[166:169], 0
	v_mfma_f32_16x16x32_bf16 v[46:49], v[130:133], v[190:193], 0
	v_mfma_f32_16x16x32_bf16 v[42:45], v[138:141], v[190:193], 0
	v_mfma_f32_16x16x32_bf16 v[30:33], v[130:133], v[198:201], 0
	v_mfma_f32_16x16x32_bf16 v[26:29], v[138:141], v[198:201], 0
	v_mfma_f32_16x16x32_bf16 v[14:17], v[130:133], v[206:209], 0
	v_mfma_f32_16x16x32_bf16 v[10:13], v[138:141], v[206:209], 0
	v_mfma_f32_16x16x32_bf16 v[62:65], v[134:137], v[170:173], v[62:65]
	v_mfma_f32_16x16x32_bf16 v[58:61], v[142:145], v[170:173], v[58:61]
	v_mfma_f32_16x16x32_bf16 v[46:49], v[134:137], v[194:197], v[46:49]
	v_mfma_f32_16x16x32_bf16 v[42:45], v[142:145], v[194:197], v[42:45]
	v_mfma_f32_16x16x32_bf16 v[30:33], v[134:137], v[202:205], v[30:33]
	v_mfma_f32_16x16x32_bf16 v[26:29], v[142:145], v[202:205], v[26:29]
	v_mfma_f32_16x16x32_bf16 v[14:17], v[134:137], v[210:213], v[14:17]
	v_mfma_f32_16x16x32_bf16 v[10:13], v[142:145], v[210:213], v[10:13]
	v_mfma_f32_16x16x32_bf16 v[54:57], v[146:149], v[166:169], 0
	v_mfma_f32_16x16x32_bf16 v[50:53], v[154:157], v[166:169], 0
	v_mfma_f32_16x16x32_bf16 v[38:41], v[146:149], v[190:193], 0
	v_mfma_f32_16x16x32_bf16 v[34:37], v[154:157], v[190:193], 0
	v_mfma_f32_16x16x32_bf16 v[22:25], v[146:149], v[198:201], 0
	v_mfma_f32_16x16x32_bf16 v[18:21], v[154:157], v[198:201], 0
	v_mfma_f32_16x16x32_bf16 v[6:9], v[146:149], v[206:209], 0
	v_mfma_f32_16x16x32_bf16 v[2:5], v[154:157], v[206:209], 0
	v_mfma_f32_16x16x32_bf16 v[54:57], v[150:153], v[170:173], v[54:57]
	v_mfma_f32_16x16x32_bf16 v[50:53], v[162:165], v[170:173], v[50:53]
	v_mfma_f32_16x16x32_bf16 v[38:41], v[150:153], v[194:197], v[38:41]
	v_mfma_f32_16x16x32_bf16 v[34:37], v[162:165], v[194:197], v[34:37]
	v_mfma_f32_16x16x32_bf16 v[22:25], v[150:153], v[202:205], v[22:25]
	v_mfma_f32_16x16x32_bf16 v[18:21], v[162:165], v[202:205], v[18:21]
	v_mfma_f32_16x16x32_bf16 v[6:9], v[150:153], v[210:213], v[6:9]
	v_mfma_f32_16x16x32_bf16 v[2:5], v[162:165], v[210:213], v[2:5]
	s_setprio 0
	s_barrier
	ds_read_b128 v[130:133], v186
	ds_read_b128 v[134:137], v186 offset:1024
	ds_read_b128 v[138:141], v186 offset:2048
	ds_read_b128 v[142:145], v186 offset:3072
	ds_read_b128 v[146:149], v187
	ds_read_b128 v[150:153], v187 offset:1024
	ds_read_b128 v[154:157], v187 offset:2048
	ds_read_b128 v[162:165], v187 offset:3072
	ds_read_b128 v[166:169], v185 offset:32768
	ds_read_b128 v[170:173], v185 offset:33792
	ds_read_b128 v[190:193], v185 offset:34816
	ds_read_b128 v[194:197], v185 offset:35840
	ds_read_b128 v[198:201], v185 offset:36864
	ds_read_b128 v[202:205], v185 offset:37888
	ds_read_b128 v[206:209], v185 offset:38912
	ds_read_b128 v[210:213], v185 offset:39936
	s_add_u32 s78, s78, 0x40000
	s_addc_u32 s79, s79, 0
	s_mov_b32 m0, s28
	s_nop 0
	global_load_lds_dwordx4 v176, s[78:79]
	s_mov_b32 m0, s29
	s_nop 0
	global_load_lds_dwordx4 v178, s[78:79]
	s_waitcnt vmcnt(8)
	s_waitcnt lgkmcnt(0)
	s_barrier
	s_setprio 1
	v_mfma_f32_16x16x32_bf16 v[126:129], v[130:133], v[166:169], v[126:129]
	v_mfma_f32_16x16x32_bf16 v[122:125], v[138:141], v[166:169], v[122:125]
	v_mfma_f32_16x16x32_bf16 v[110:113], v[130:133], v[190:193], v[110:113]
	v_mfma_f32_16x16x32_bf16 v[106:109], v[138:141], v[190:193], v[106:109]
	v_mfma_f32_16x16x32_bf16 v[94:97], v[130:133], v[198:201], v[94:97]
	v_mfma_f32_16x16x32_bf16 v[90:93], v[138:141], v[198:201], v[90:93]
	v_mfma_f32_16x16x32_bf16 v[78:81], v[130:133], v[206:209], v[78:81]
	v_mfma_f32_16x16x32_bf16 v[74:77], v[138:141], v[206:209], v[74:77]
	v_mfma_f32_16x16x32_bf16 v[126:129], v[134:137], v[170:173], v[126:129]
	v_mfma_f32_16x16x32_bf16 v[122:125], v[142:145], v[170:173], v[122:125]
	v_mfma_f32_16x16x32_bf16 v[110:113], v[134:137], v[194:197], v[110:113]
	v_mfma_f32_16x16x32_bf16 v[106:109], v[142:145], v[194:197], v[106:109]
	v_mfma_f32_16x16x32_bf16 v[94:97], v[134:137], v[202:205], v[94:97]
	v_mfma_f32_16x16x32_bf16 v[90:93], v[142:145], v[202:205], v[90:93]
	v_mfma_f32_16x16x32_bf16 v[78:81], v[134:137], v[210:213], v[78:81]
	v_mfma_f32_16x16x32_bf16 v[74:77], v[142:145], v[210:213], v[74:77]
	v_mfma_f32_16x16x32_bf16 v[118:121], v[146:149], v[166:169], v[118:121]
	v_mfma_f32_16x16x32_bf16 v[114:117], v[154:157], v[166:169], v[114:117]
	v_mfma_f32_16x16x32_bf16 v[102:105], v[146:149], v[190:193], v[102:105]
	v_mfma_f32_16x16x32_bf16 v[98:101], v[154:157], v[190:193], v[98:101]
	v_mfma_f32_16x16x32_bf16 v[86:89], v[146:149], v[198:201], v[86:89]
	v_mfma_f32_16x16x32_bf16 v[82:85], v[154:157], v[198:201], v[82:85]
	v_mfma_f32_16x16x32_bf16 v[70:73], v[146:149], v[206:209], v[70:73]
	v_mfma_f32_16x16x32_bf16 v[66:69], v[154:157], v[206:209], v[66:69]
	v_mfma_f32_16x16x32_bf16 v[118:121], v[150:153], v[170:173], v[118:121]
	v_mfma_f32_16x16x32_bf16 v[114:117], v[162:165], v[170:173], v[114:117]
	v_mfma_f32_16x16x32_bf16 v[102:105], v[150:153], v[194:197], v[102:105]
	v_mfma_f32_16x16x32_bf16 v[98:101], v[162:165], v[194:197], v[98:101]
	v_mfma_f32_16x16x32_bf16 v[86:89], v[150:153], v[202:205], v[86:89]
	v_mfma_f32_16x16x32_bf16 v[82:85], v[162:165], v[202:205], v[82:85]
	v_mfma_f32_16x16x32_bf16 v[70:73], v[150:153], v[210:213], v[70:73]
	v_mfma_f32_16x16x32_bf16 v[66:69], v[162:165], v[210:213], v[66:69]
	s_setprio 0
	s_barrier
; #define PG8_STAGE(bufoff, gbase, voff) do { if constexpr (VAR != 1 && VAR != 3) { _Pragma("unroll") for (int _i = 0; _i < 2; ++_i) \
;         asm volatile("s_mov_b32 m0, %2\n\ts_nop 0\n\tglobal_load_lds_dwordx4 %0, %1" :: "v"((voff)[_i]), "s"((const char*)(gbase)), "s"(ldsbase + (unsigned)((bufoff) + _i * 8192)) : "memory", "m0"); } } while (0)
; #define PG8_LDA(dst, b, h) do { if constexpr (VAR < 2) _Pragma("unroll") for (int m = 0; m < 4; ++m) _Pragma("unroll") for (int k = 0; k < 2; ++k) dst[m][k] = *(const LAS bf16x8*)(lds + PG8_SA(b, h) + aoff + m * 2048 + k * 1024); } while (0)
; #define PG8_LDB(dst, b, h) do { if constexpr (VAR < 2) _Pragma("unroll") for (int n = 0; n < 2; ++n) _Pragma("unroll") for (int k = 0; k < 2; ++k) dst[n][k] = *(const LAS bf16x8*)(lds + PG8_SB(b, h) + boff + n * 2048 + k * 1024); } while (0)
; #define PG8_WAIT_V(n) asm volatile("s_waitcnt vmcnt(" #n ")" ::: "memory")
; #define PG8_WAIT_L(n) asm volatile("s_waitcnt lgkmcnt(" #n ")" ::: "memory")
; #define PG8_BAR do { if constexpr (VAR != 3) __builtin_amdgcn_s_barrier(); } while (0)
; #define PG8_SCHED __builtin_amdgcn_sched_barrier(0)
;     ...
;             const bool last = (t == nt - 2);
;             const char* a1 = cA + (size_t)(t + 1) * kstep;
;             const char* a2 = last ? nA : cA + (size_t)(t + 2) * kstep; const char* b2 = last ? nB : cB + (size_t)(t + 2) * kstep;
;             const char* a3 = a2 + kstep; const char* b3 = b2 + kstep;
;             PG8_LDB(B0, 0, 0); PG8_LDB(B1, 0, 1); PG8_SCHED; PG8_LDA(At, 0, 0); PG8_STAGE(PG8_SA(1, 1), a1 + hstepA, voffA);
;             PG8_WAIT_V(8); PG8_WAIT_L(0); PG8_BAR; PG8_MMA(0, 0, At, B0); PG8_MMA(0, 1, At, B1); PG8_BAR; PG8_SCHED;
;     ...
;             PG8_LDA(At, 1, 1); PG8_STAGE(PG8_SB(1, 0), b3, voffB); PG8_STAGE(PG8_SB(1, 1), b3 + hstepB, voffB); PG8_STAGE(PG8_SA(1, 0), a3, voffA);
;             PG8_WAIT_V(8); PG8_WAIT_L(0); PG8_BAR; PG8_MMA(1, 0, At, B0); PG8_MMA(1, 1, At, B1); PG8_BAR; PG8_SCHED;
;         }
	ds_read_b128 v[166:169], v185 offset:49152
	ds_read_b128 v[170:173], v185 offset:50176
	ds_read_b128 v[190:193], v185 offset:51200
	ds_read_b128 v[194:197], v185 offset:52224
	ds_read_b128 v[198:201], v185 offset:53248
	ds_read_b128 v[202:205], v185 offset:54272
	ds_read_b128 v[206:209], v185 offset:55296
	ds_read_b128 v[210:213], v185 offset:56320
	s_add_u32 s78, s76, 0x80
	s_addc_u32 s79, s77, 0
	s_mov_b32 m0, s33
	s_nop 0
	global_load_lds_dwordx4 v177, s[78:79]
	s_add_u32 s76, s76, 0x40080
	s_mov_b32 m0, s35
	s_nop 0
	global_load_lds_dwordx4 v179, s[78:79]
	s_addc_u32 s77, s77, 0
	s_mov_b32 m0, s80
	s_nop 0
	global_load_lds_dwordx4 v177, s[76:77]
	s_mov_b32 m0, s81
	s_nop 0
	global_load_lds_dwordx4 v179, s[76:77]
	s_mov_b32 m0, s71
	s_nop 0
	global_load_lds_dwordx4 v176, s[74:75]
	s_mov_b32 m0, s73
	s_nop 0
	global_load_lds_dwordx4 v178, s[74:75]
	s_waitcnt vmcnt(8)
	s_waitcnt lgkmcnt(0)
	s_barrier
	s_setprio 1
	v_mfma_f32_16x16x32_bf16 v[62:65], v[130:133], v[166:169], v[62:65]
	v_mfma_f32_16x16x32_bf16 v[58:61], v[138:141], v[166:169], v[58:61]
	v_mfma_f32_16x16x32_bf16 v[46:49], v[130:133], v[190:193], v[46:49]
	v_mfma_f32_16x16x32_bf16 v[42:45], v[138:141], v[190:193], v[42:45]
	v_mfma_f32_16x16x32_bf16 v[30:33], v[130:133], v[198:201], v[30:33]
	v_mfma_f32_16x16x32_bf16 v[26:29], v[138:141], v[198:201], v[26:29]
	v_mfma_f32_16x16x32_bf16 v[14:17], v[130:133], v[206:209], v[14:17]
	v_mfma_f32_16x16x32_bf16 v[10:13], v[138:141], v[206:209], v[10:13]
	v_mfma_f32_16x16x32_bf16 v[62:65], v[134:137], v[170:173], v[62:65]
	v_mfma_f32_16x16x32_bf16 v[58:61], v[142:145], v[170:173], v[58:61]
	v_mfma_f32_16x16x32_bf16 v[46:49], v[134:137], v[194:197], v[46:49]
	v_mfma_f32_16x16x32_bf16 v[42:45], v[142:145], v[194:197], v[42:45]
	v_mfma_f32_16x16x32_bf16 v[30:33], v[134:137], v[202:205], v[30:33]
	v_mfma_f32_16x16x32_bf16 v[26:29], v[142:145], v[202:205], v[26:29]
	v_mfma_f32_16x16x32_bf16 v[14:17], v[134:137], v[210:213], v[14:17]
	v_mfma_f32_16x16x32_bf16 v[10:13], v[142:145], v[210:213], v[10:13]
	v_mfma_f32_16x16x32_bf16 v[54:57], v[146:149], v[166:169], v[54:57]
	v_mfma_f32_16x16x32_bf16 v[50:53], v[154:157], v[166:169], v[50:53]
	v_mfma_f32_16x16x32_bf16 v[38:41], v[146:149], v[190:193], v[38:41]
	v_mfma_f32_16x16x32_bf16 v[34:37], v[154:157], v[190:193], v[34:37]
	v_mfma_f32_16x16x32_bf16 v[22:25], v[146:149], v[198:201], v[22:25]
	v_mfma_f32_16x16x32_bf16 v[18:21], v[154:157], v[198:201], v[18:21]
	v_mfma_f32_16x16x32_bf16 v[6:9], v[146:149], v[206:209], v[6:9]
	v_mfma_f32_16x16x32_bf16 v[2:5], v[154:157], v[206:209], v[2:5]
	v_mfma_f32_16x16x32_bf16 v[54:57], v[150:153], v[170:173], v[54:57]
	v_mfma_f32_16x16x32_bf16 v[50:53], v[162:165], v[170:173], v[50:53]
	v_mfma_f32_16x16x32_bf16 v[38:41], v[150:153], v[194:197], v[38:41]
	v_mfma_f32_16x16x32_bf16 v[34:37], v[162:165], v[194:197], v[34:37]
	v_mfma_f32_16x16x32_bf16 v[22:25], v[150:153], v[202:205], v[22:25]
	v_mfma_f32_16x16x32_bf16 v[18:21], v[162:165], v[202:205], v[18:21]
	v_mfma_f32_16x16x32_bf16 v[6:9], v[150:153], v[210:213], v[6:9]
	v_mfma_f32_16x16x32_bf16 v[2:5], v[162:165], v[210:213], v[2:5]
	s_setprio 0
	s_barrier
	s_add_i32 s86, s86, 2
	s_add_u32 s63, s63, 0x100
	s_addc_u32 s65, s65, 0
	s_add_u32 s84, s84, 0x100
	s_addc_u32 s85, s85, 0
	s_add_u32 s12, s12, 0x100
	s_addc_u32 s13, s13, 0
	s_cmp_gt_u32 s86, 13
	s_cbranch_scc0 .LBB0_1002
	s_branch .Lmy_kexit_7
.LBB0_1002:
	ds_read_b128 v[130:133], v183
	ds_read_b128 v[134:137], v183 offset:1024
	ds_read_b128 v[138:141], v183 offset:2048
	ds_read_b128 v[142:145], v183 offset:3072
	ds_read_b128 v[146:149], v184
	ds_read_b128 v[150:153], v184 offset:1024
	ds_read_b128 v[154:157], v184 offset:2048
	ds_read_b128 v[162:165], v184 offset:3072
	s_cmp_eq_u32 s86, 12
	s_cselect_b32 s78, s25, s63
	s_cselect_b32 s79, s24, s65
	s_cselect_b32 s76, s66, s84
	s_cselect_b32 s77, s67, s85
	s_add_u32 s74, s78, 0x80
	s_addc_u32 s75, s79, 0
	ds_read_b128 v[166:169], v185
	ds_read_b128 v[170:173], v185 offset:1024
	ds_read_b128 v[190:193], v185 offset:2048
	ds_read_b128 v[194:197], v185 offset:3072
	ds_read_b128 v[198:201], v185 offset:4096
	ds_read_b128 v[202:205], v185 offset:5120
	ds_read_b128 v[206:209], v185 offset:6144
	ds_read_b128 v[210:213], v185 offset:7168
	s_mov_b32 m0, s82
	s_nop 0
	global_load_lds_dwordx4 v176, s[12:13]
	s_mov_b32 m0, s83
	s_nop 0
	global_load_lds_dwordx4 v178, s[12:13]
	s_waitcnt vmcnt(8)
	s_waitcnt lgkmcnt(0)
	s_barrier
	s_setprio 1
	v_mfma_f32_16x16x32_bf16 v[126:129], v[130:133], v[166:169], v[126:129]
	v_mfma_f32_16x16x32_bf16 v[122:125], v[138:141], v[166:169], v[122:125]
	v_mfma_f32_16x16x32_bf16 v[110:113], v[130:133], v[190:193], v[110:113]
	v_mfma_f32_16x16x32_bf16 v[106:109], v[138:141], v[190:193], v[106:109]
	v_mfma_f32_16x16x32_bf16 v[94:97], v[130:133], v[198:201], v[94:97]
	v_mfma_f32_16x16x32_bf16 v[90:93], v[138:141], v[198:201], v[90:93]
	v_mfma_f32_16x16x32_bf16 v[78:81], v[130:133], v[206:209], v[78:81]
	v_mfma_f32_16x16x32_bf16 v[74:77], v[138:141], v[206:209], v[74:77]
	v_mfma_f32_16x16x32_bf16 v[126:129], v[134:137], v[170:173], v[126:129]
	v_mfma_f32_16x16x32_bf16 v[122:125], v[142:145], v[170:173], v[122:125]
	v_mfma_f32_16x16x32_bf16 v[110:113], v[134:137], v[194:197], v[110:113]
	v_mfma_f32_16x16x32_bf16 v[106:109], v[142:145], v[194:197], v[106:109]
	v_mfma_f32_16x16x32_bf16 v[94:97], v[134:137], v[202:205], v[94:97]
	v_mfma_f32_16x16x32_bf16 v[90:93], v[142:145], v[202:205], v[90:93]
	v_mfma_f32_16x16x32_bf16 v[78:81], v[134:137], v[210:213], v[78:81]
	v_mfma_f32_16x16x32_bf16 v[74:77], v[142:145], v[210:213], v[74:77]
	v_mfma_f32_16x16x32_bf16 v[118:121], v[146:149], v[166:169], v[118:121]
	v_mfma_f32_16x16x32_bf16 v[114:117], v[154:157], v[166:169], v[114:117]
	v_mfma_f32_16x16x32_bf16 v[102:105], v[146:149], v[190:193], v[102:105]
	v_mfma_f32_16x16x32_bf16 v[98:101], v[154:157], v[190:193], v[98:101]
	v_mfma_f32_16x16x32_bf16 v[86:89], v[146:149], v[198:201], v[86:89]
	v_mfma_f32_16x16x32_bf16 v[82:85], v[154:157], v[198:201], v[82:85]
	v_mfma_f32_16x16x32_bf16 v[70:73], v[146:149], v[206:209], v[70:73]
	v_mfma_f32_16x16x32_bf16 v[66:69], v[154:157], v[206:209], v[66:69]
	v_mfma_f32_16x16x32_bf16 v[118:121], v[150:153], v[170:173], v[118:121]
	v_mfma_f32_16x16x32_bf16 v[114:117], v[162:165], v[170:173], v[114:117]
	v_mfma_f32_16x16x32_bf16 v[102:105], v[150:153], v[194:197], v[102:105]
	v_mfma_f32_16x16x32_bf16 v[98:101], v[162:165], v[194:197], v[98:101]
	v_mfma_f32_16x16x32_bf16 v[86:89], v[150:153], v[202:205], v[86:89]
	v_mfma_f32_16x16x32_bf16 v[82:85], v[162:165], v[202:205], v[82:85]
	v_mfma_f32_16x16x32_bf16 v[70:73], v[150:153], v[210:213], v[70:73]
	v_mfma_f32_16x16x32_bf16 v[66:69], v[162:165], v[210:213], v[66:69]
	s_setprio 0
	s_barrier
; #define PG8_STAGE(bufoff, gbase, voff) do { if constexpr (VAR != 1 && VAR != 3) { _Pragma("unroll") for (int _i = 0; _i < 2; ++_i) \
;         asm volatile("s_mov_b32 m0, %2\n\ts_nop 0\n\tglobal_load_lds_dwordx4 %0, %1" :: "v"((voff)[_i]), "s"((const char*)(gbase)), "s"(ldsbase + (unsigned)((bufoff) + _i * 8192)) : "memory", "m0"); } } while (0)
; #define PG8_LDA(dst, b, h) do { if constexpr (VAR < 2) _Pragma("unroll") for (int m = 0; m < 4; ++m) _Pragma("unroll") for (int k = 0; k < 2; ++k) dst[m][k] = *(const LAS bf16x8*)(lds + PG8_SA(b, h) + aoff + m * 2048 + k * 1024); } while (0)
; #define PG8_LDB(dst, b, h) do { if constexpr (VAR < 2) _Pragma("unroll") for (int n = 0; n < 2; ++n) _Pragma("unroll") for (int k = 0; k < 2; ++k) dst[n][k] = *(const LAS bf16x8*)(lds + PG8_SB(b, h) + boff + n * 2048 + k * 1024); } while (0)
; #define PG8_WAIT_V(n) asm volatile("s_waitcnt vmcnt(" #n ")" ::: "memory")
; #define PG8_WAIT_L(n) asm volatile("s_waitcnt lgkmcnt(" #n ")" ::: "memory")
; #define PG8_BAR do { if constexpr (VAR != 3) __builtin_amdgcn_s_barrier(); } while (0)
; #define PG8_SCHED __builtin_amdgcn_sched_barrier(0)
;     ...
;             PG8_LDA(At, 0, 1); PG8_STAGE(PG8_SB(0, 0), b2, voffB); PG8_STAGE(PG8_SB(0, 1), b2 + hstepB, voffB); PG8_STAGE(PG8_SA(0, 0), a2, voffA);
;             PG8_WAIT_V(8); PG8_WAIT_L(0); PG8_BAR; PG8_MMA(1, 0, At, B0); PG8_MMA(1, 1, At, B1); PG8_BAR; PG8_SCHED;
;             PG8_LDB(B0, 1, 0); PG8_LDB(B1, 1, 1); PG8_SCHED; PG8_LDA(At, 1, 0); PG8_STAGE(PG8_SA(0, 1), a2 + hstepA, voffA);
;             PG8_WAIT_V(8); PG8_WAIT_L(0); PG8_BAR; PG8_MMA(0, 0, At, B0); PG8_MMA(0, 1, At, B1); PG8_BAR; PG8_SCHED;
	ds_read_b128 v[166:169], v185 offset:16384
	ds_read_b128 v[170:173], v185 offset:17408
	ds_read_b128 v[190:193], v185 offset:18432
	ds_read_b128 v[194:197], v185 offset:19456
	ds_read_b128 v[198:201], v185 offset:20480
	ds_read_b128 v[202:205], v185 offset:21504
	ds_read_b128 v[206:209], v185 offset:22528
	ds_read_b128 v[210:213], v185 offset:23552
	s_mov_b32 m0, s17
	s_nop 0
	global_load_lds_dwordx4 v177, s[76:77]
	s_add_u32 s88, s76, 0x40000
	s_mov_b32 m0, s19
	s_nop 0
	global_load_lds_dwordx4 v179, s[76:77]
	s_addc_u32 s89, s77, 0
	s_mov_b32 m0, s23
	s_nop 0
	global_load_lds_dwordx4 v177, s[88:89]
	s_mov_b32 m0, s26
	s_nop 0
	global_load_lds_dwordx4 v179, s[88:89]
	s_mov_b32 m0, s15
	s_nop 0
	global_load_lds_dwordx4 v176, s[78:79]
	s_mov_b32 m0, s27
	s_nop 0
	global_load_lds_dwordx4 v178, s[78:79]
	s_waitcnt vmcnt(8)
	s_waitcnt lgkmcnt(0)
	s_barrier
	s_setprio 1
	v_mfma_f32_16x16x32_bf16 v[62:65], v[130:133], v[166:169], v[62:65]
	v_mfma_f32_16x16x32_bf16 v[58:61], v[138:141], v[166:169], v[58:61]
	v_mfma_f32_16x16x32_bf16 v[46:49], v[130:133], v[190:193], v[46:49]
	v_mfma_f32_16x16x32_bf16 v[42:45], v[138:141], v[190:193], v[42:45]
	v_mfma_f32_16x16x32_bf16 v[30:33], v[130:133], v[198:201], v[30:33]
	v_mfma_f32_16x16x32_bf16 v[26:29], v[138:141], v[198:201], v[26:29]
	v_mfma_f32_16x16x32_bf16 v[14:17], v[130:133], v[206:209], v[14:17]
	v_mfma_f32_16x16x32_bf16 v[10:13], v[138:141], v[206:209], v[10:13]
	v_mfma_f32_16x16x32_bf16 v[62:65], v[134:137], v[170:173], v[62:65]
	v_mfma_f32_16x16x32_bf16 v[58:61], v[142:145], v[170:173], v[58:61]
	v_mfma_f32_16x16x32_bf16 v[46:49], v[134:137], v[194:197], v[46:49]
	v_mfma_f32_16x16x32_bf16 v[42:45], v[142:145], v[194:197], v[42:45]
	v_mfma_f32_16x16x32_bf16 v[30:33], v[134:137], v[202:205], v[30:33]
	v_mfma_f32_16x16x32_bf16 v[26:29], v[142:145], v[202:205], v[26:29]
	v_mfma_f32_16x16x32_bf16 v[14:17], v[134:137], v[210:213], v[14:17]
	v_mfma_f32_16x16x32_bf16 v[10:13], v[142:145], v[210:213], v[10:13]
	v_mfma_f32_16x16x32_bf16 v[54:57], v[146:149], v[166:169], v[54:57]
	v_mfma_f32_16x16x32_bf16 v[50:53], v[154:157], v[166:169], v[50:53]
	v_mfma_f32_16x16x32_bf16 v[38:41], v[146:149], v[190:193], v[38:41]
	v_mfma_f32_16x16x32_bf16 v[34:37], v[154:157], v[190:193], v[34:37]
	v_mfma_f32_16x16x32_bf16 v[22:25], v[146:149], v[198:201], v[22:25]
	v_mfma_f32_16x16x32_bf16 v[18:21], v[154:157], v[198:201], v[18:21]
	v_mfma_f32_16x16x32_bf16 v[6:9], v[146:149], v[206:209], v[6:9]
	v_mfma_f32_16x16x32_bf16 v[2:5], v[154:157], v[206:209], v[2:5]
	v_mfma_f32_16x16x32_bf16 v[54:57], v[150:153], v[170:173], v[54:57]
	v_mfma_f32_16x16x32_bf16 v[50:53], v[162:165], v[170:173], v[50:53]
	v_mfma_f32_16x16x32_bf16 v[38:41], v[150:153], v[194:197], v[38:41]
	v_mfma_f32_16x16x32_bf16 v[34:37], v[162:165], v[194:197], v[34:37]
	v_mfma_f32_16x16x32_bf16 v[22:25], v[150:153], v[202:205], v[22:25]
	v_mfma_f32_16x16x32_bf16 v[18:21], v[162:165], v[202:205], v[18:21]
	v_mfma_f32_16x16x32_bf16 v[6:9], v[150:153], v[210:213], v[6:9]
	v_mfma_f32_16x16x32_bf16 v[2:5], v[162:165], v[210:213], v[2:5]
	s_setprio 0
	s_barrier
	ds_read_b128 v[130:133], v186
	ds_read_b128 v[134:137], v186 offset:1024
	ds_read_b128 v[138:141], v186 offset:2048
	ds_read_b128 v[142:145], v186 offset:3072
	ds_read_b128 v[146:149], v187
	ds_read_b128 v[150:153], v187 offset:1024
	ds_read_b128 v[154:157], v187 offset:2048
	ds_read_b128 v[162:165], v187 offset:3072
	ds_read_b128 v[166:169], v185 offset:32768
	ds_read_b128 v[170:173], v185 offset:33792
	ds_read_b128 v[190:193], v185 offset:34816
	ds_read_b128 v[194:197], v185 offset:35840
	ds_read_b128 v[198:201], v185 offset:36864
	ds_read_b128 v[202:205], v185 offset:37888
	ds_read_b128 v[206:209], v185 offset:38912
	ds_read_b128 v[210:213], v185 offset:39936
	s_add_u32 s78, s78, 0x40000
	s_addc_u32 s79, s79, 0
	s_mov_b32 m0, s28
	s_nop 0
	global_load_lds_dwordx4 v176, s[78:79]
	s_mov_b32 m0, s29
	s_nop 0
	global_load_lds_dwordx4 v178, s[78:79]
	s_waitcnt vmcnt(8)
	s_waitcnt lgkmcnt(0)
	s_barrier
; #define PG8_STAGE(bufoff, gbase, voff) do { if constexpr (VAR != 1 && VAR != 3) { _Pragma("unroll") for (int _i = 0; _i < 2; ++_i) \
;         asm volatile("s_mov_b32 m0, %2\n\ts_nop 0\n\tglobal_load_lds_dwordx4 %0, %1" :: "v"((voff)[_i]), "s"((const char*)(gbase)), "s"(ldsbase + (unsigned)((bufoff) + _i * 8192)) : "memory", "m0"); } } while (0)
; #define PG8_LDA(dst, b, h) do { if constexpr (VAR < 2) _Pragma("unroll") for (int m = 0; m < 4; ++m) _Pragma("unroll") for (int k = 0; k < 2; ++k) dst[m][k] = *(const LAS bf16x8*)(lds + PG8_SA(b, h) + aoff + m * 2048 + k * 1024); } while (0)
; #define PG8_WAIT_V(n) asm volatile("s_waitcnt vmcnt(" #n ")" ::: "memory")
; #define PG8_WAIT_L(n) asm volatile("s_waitcnt lgkmcnt(" #n ")" ::: "memory")
; #define PG8_BAR do { if constexpr (VAR != 3) __builtin_amdgcn_s_barrier(); } while (0)
; #define PG8_SCHED __builtin_amdgcn_sched_barrier(0)
;     ...
;             PG8_WAIT_V(8); PG8_WAIT_L(0); PG8_BAR; PG8_MMA(0, 0, At, B0); PG8_MMA(0, 1, At, B1); PG8_BAR; PG8_SCHED;
;             PG8_LDA(At, 1, 1); PG8_STAGE(PG8_SB(1, 0), b3, voffB); PG8_STAGE(PG8_SB(1, 1), b3 + hstepB, voffB); PG8_STAGE(PG8_SA(1, 0), a3, voffA);
;             PG8_WAIT_V(8); PG8_WAIT_L(0); PG8_BAR; PG8_MMA(1, 0, At, B0); PG8_MMA(1, 1, At, B1); PG8_BAR; PG8_SCHED;
;         }
;         if (wr == 0) PG8_BAR;
	s_setprio 1
	v_mfma_f32_16x16x32_bf16 v[126:129], v[130:133], v[166:169], v[126:129]
	v_mfma_f32_16x16x32_bf16 v[122:125], v[138:141], v[166:169], v[122:125]
	v_mfma_f32_16x16x32_bf16 v[110:113], v[130:133], v[190:193], v[110:113]
	v_mfma_f32_16x16x32_bf16 v[106:109], v[138:141], v[190:193], v[106:109]
	v_mfma_f32_16x16x32_bf16 v[94:97], v[130:133], v[198:201], v[94:97]
	v_mfma_f32_16x16x32_bf16 v[90:93], v[138:141], v[198:201], v[90:93]
	v_mfma_f32_16x16x32_bf16 v[78:81], v[130:133], v[206:209], v[78:81]
	v_mfma_f32_16x16x32_bf16 v[74:77], v[138:141], v[206:209], v[74:77]
	v_mfma_f32_16x16x32_bf16 v[126:129], v[134:137], v[170:173], v[126:129]
	v_mfma_f32_16x16x32_bf16 v[122:125], v[142:145], v[170:173], v[122:125]
	v_mfma_f32_16x16x32_bf16 v[110:113], v[134:137], v[194:197], v[110:113]
	v_mfma_f32_16x16x32_bf16 v[106:109], v[142:145], v[194:197], v[106:109]
	v_mfma_f32_16x16x32_bf16 v[94:97], v[134:137], v[202:205], v[94:97]
	v_mfma_f32_16x16x32_bf16 v[90:93], v[142:145], v[202:205], v[90:93]
	v_mfma_f32_16x16x32_bf16 v[78:81], v[134:137], v[210:213], v[78:81]
	v_mfma_f32_16x16x32_bf16 v[74:77], v[142:145], v[210:213], v[74:77]
	v_mfma_f32_16x16x32_bf16 v[118:121], v[146:149], v[166:169], v[118:121]
	v_mfma_f32_16x16x32_bf16 v[114:117], v[154:157], v[166:169], v[114:117]
	v_mfma_f32_16x16x32_bf16 v[102:105], v[146:149], v[190:193], v[102:105]
	v_mfma_f32_16x16x32_bf16 v[98:101], v[154:157], v[190:193], v[98:101]
	v_mfma_f32_16x16x32_bf16 v[86:89], v[146:149], v[198:201], v[86:89]
	v_mfma_f32_16x16x32_bf16 v[82:85], v[154:157], v[198:201], v[82:85]
	v_mfma_f32_16x16x32_bf16 v[70:73], v[146:149], v[206:209], v[70:73]
	v_mfma_f32_16x16x32_bf16 v[66:69], v[154:157], v[206:209], v[66:69]
	v_mfma_f32_16x16x32_bf16 v[118:121], v[150:153], v[170:173], v[118:121]
	v_mfma_f32_16x16x32_bf16 v[114:117], v[162:165], v[170:173], v[114:117]
	v_mfma_f32_16x16x32_bf16 v[102:105], v[150:153], v[194:197], v[102:105]
	v_mfma_f32_16x16x32_bf16 v[98:101], v[162:165], v[194:197], v[98:101]
	v_mfma_f32_16x16x32_bf16 v[86:89], v[150:153], v[202:205], v[86:89]
	v_mfma_f32_16x16x32_bf16 v[82:85], v[162:165], v[202:205], v[82:85]
	v_mfma_f32_16x16x32_bf16 v[70:73], v[150:153], v[210:213], v[70:73]
	v_mfma_f32_16x16x32_bf16 v[66:69], v[162:165], v[210:213], v[66:69]
	s_setprio 0
	s_barrier
	ds_read_b128 v[166:169], v185 offset:49152
	ds_read_b128 v[170:173], v185 offset:50176
	ds_read_b128 v[190:193], v185 offset:51200
	ds_read_b128 v[194:197], v185 offset:52224
	ds_read_b128 v[198:201], v185 offset:53248
	ds_read_b128 v[202:205], v185 offset:54272
	ds_read_b128 v[206:209], v185 offset:55296
	ds_read_b128 v[210:213], v185 offset:56320
	s_add_u32 s78, s76, 0x80
	s_addc_u32 s79, s77, 0
	s_mov_b32 m0, s33
	s_nop 0
	global_load_lds_dwordx4 v177, s[78:79]
	s_add_u32 s76, s76, 0x40080
	s_mov_b32 m0, s35
	s_nop 0
	global_load_lds_dwordx4 v179, s[78:79]
	s_addc_u32 s77, s77, 0
	s_mov_b32 m0, s80
	s_nop 0
	global_load_lds_dwordx4 v177, s[76:77]
	s_mov_b32 m0, s81
	s_nop 0
	global_load_lds_dwordx4 v179, s[76:77]
	s_mov_b32 m0, s71
	s_nop 0
	global_load_lds_dwordx4 v176, s[74:75]
	s_mov_b32 m0, s73
	s_nop 0
	global_load_lds_dwordx4 v178, s[74:75]
	s_waitcnt vmcnt(8)
	s_waitcnt lgkmcnt(0)
	s_barrier
	s_setprio 1
	v_mfma_f32_16x16x32_bf16 v[62:65], v[130:133], v[166:169], v[62:65]
	v_mfma_f32_16x16x32_bf16 v[58:61], v[138:141], v[166:169], v[58:61]
	v_mfma_f32_16x16x32_bf16 v[46:49], v[130:133], v[190:193], v[46:49]
	v_mfma_f32_16x16x32_bf16 v[42:45], v[138:141], v[190:193], v[42:45]
	v_mfma_f32_16x16x32_bf16 v[30:33], v[130:133], v[198:201], v[30:33]
	v_mfma_f32_16x16x32_bf16 v[26:29], v[138:141], v[198:201], v[26:29]
	v_mfma_f32_16x16x32_bf16 v[14:17], v[130:133], v[206:209], v[14:17]
	v_mfma_f32_16x16x32_bf16 v[10:13], v[138:141], v[206:209], v[10:13]
	v_mfma_f32_16x16x32_bf16 v[62:65], v[134:137], v[170:173], v[62:65]
	v_mfma_f32_16x16x32_bf16 v[58:61], v[142:145], v[170:173], v[58:61]
	v_mfma_f32_16x16x32_bf16 v[46:49], v[134:137], v[194:197], v[46:49]
	v_mfma_f32_16x16x32_bf16 v[42:45], v[142:145], v[194:197], v[42:45]
	v_mfma_f32_16x16x32_bf16 v[30:33], v[134:137], v[202:205], v[30:33]
	v_mfma_f32_16x16x32_bf16 v[26:29], v[142:145], v[202:205], v[26:29]
	v_mfma_f32_16x16x32_bf16 v[14:17], v[134:137], v[210:213], v[14:17]
	v_mfma_f32_16x16x32_bf16 v[10:13], v[142:145], v[210:213], v[10:13]
	v_mfma_f32_16x16x32_bf16 v[54:57], v[146:149], v[166:169], v[54:57]
	v_mfma_f32_16x16x32_bf16 v[50:53], v[154:157], v[166:169], v[50:53]
	v_mfma_f32_16x16x32_bf16 v[38:41], v[146:149], v[190:193], v[38:41]
	v_mfma_f32_16x16x32_bf16 v[34:37], v[154:157], v[190:193], v[34:37]
	v_mfma_f32_16x16x32_bf16 v[22:25], v[146:149], v[198:201], v[22:25]
	v_mfma_f32_16x16x32_bf16 v[18:21], v[154:157], v[198:201], v[18:21]
	v_mfma_f32_16x16x32_bf16 v[6:9], v[146:149], v[206:209], v[6:9]
	v_mfma_f32_16x16x32_bf16 v[2:5], v[154:157], v[206:209], v[2:5]
	v_mfma_f32_16x16x32_bf16 v[54:57], v[150:153], v[170:173], v[54:57]
	v_mfma_f32_16x16x32_bf16 v[50:53], v[162:165], v[170:173], v[50:53]
	v_mfma_f32_16x16x32_bf16 v[38:41], v[150:153], v[194:197], v[38:41]
	v_mfma_f32_16x16x32_bf16 v[34:37], v[162:165], v[194:197], v[34:37]
	v_mfma_f32_16x16x32_bf16 v[22:25], v[150:153], v[202:205], v[22:25]
	v_mfma_f32_16x16x32_bf16 v[18:21], v[162:165], v[202:205], v[18:21]
	v_mfma_f32_16x16x32_bf16 v[6:9], v[150:153], v[210:213], v[6:9]
	v_mfma_f32_16x16x32_bf16 v[2:5], v[162:165], v[210:213], v[2:5]
	s_setprio 0
	s_barrier
	s_add_i32 s86, s86, 2
	s_add_u32 s63, s63, 0x100
	s_addc_u32 s65, s65, 0
	s_add_u32 s84, s84, 0x100
	s_addc_u32 s85, s85, 0
	s_add_u32 s12, s12, 0x100
	s_addc_u32 s13, s13, 0
	s_cmp_gt_u32 s86, 13
	s_cbranch_scc0 .LBB0_1002
.Lmy_kexit_7:
	s_and_b64 vcc, exec, s[60:61]
	s_cbranch_vccz .LBB0_1005
	s_barrier

; __device__ __forceinline__ const char* unitA(const Gemm& g, const Unit& u) { return (const char*)(g.A + (size_t)(u.z / g.zdiv) * g.sAhi + (size_t)(u.z % g.zdiv) * g.sAlo + (size_t)u.pm * BM * g.lda); }
; __device__ __forceinline__ const char* unitB(const Gemm& g, const Unit& u) { return (const char*)(g.Bt + (size_t)(u.z / g.zdiv) * g.sBhi + (size_t)(u.z % g.zdiv) * g.sBlo + (size_t)(u.pm / g.bdiv) * g.sBpm + (size_t)u.pn * BM * g.ldb); }
; #define PG8_STAGE(bufoff, gbase, voff) do { if constexpr (VAR != 1 && VAR != 3) { _Pragma("unroll") for (int _i = 0; _i < 2; ++_i) \
;         asm volatile("s_mov_b32 m0, %2\n\ts_nop 0\n\tglobal_load_lds_dwordx4 %0, %1" :: "v"((voff)[_i]), "s"((const char*)(gbase)), "s"(ldsbase + (unsigned)((bufoff) + _i * 8192)) : "memory", "m0"); } } while (0)
; #define PG8_LDA(dst, b, h) do { if constexpr (VAR < 2) _Pragma("unroll") for (int m = 0; m < 4; ++m) _Pragma("unroll") for (int k = 0; k < 2; ++k) dst[m][k] = *(const LAS bf16x8*)(lds + PG8_SA(b, h) + aoff + m * 2048 + k * 1024); } while (0)
; #define PG8_LDB(dst, b, h) do { if constexpr (VAR < 2) _Pragma("unroll") for (int n = 0; n < 2; ++n) _Pragma("unroll") for (int k = 0; k < 2; ++k) dst[n][k] = *(const LAS bf16x8*)(lds + PG8_SB(b, h) + boff + n * 2048 + k * 1024); } while (0)
; #define PG8_WAIT_V(n) asm volatile("s_waitcnt vmcnt(" #n ")" ::: "memory")
;     ...
;         const bool has_next = S.next(ui + 1, nxt);
;         const char* nA = has_next ? unitA(g, nxt) : cA; const char* nB = has_next ? unitB(g, nxt) : cB;
;         for (int t = 0; t < nt; t += 2) {
;             const bool last = (t == nt - 2);
;             const char* a1 = cA + (size_t)(t + 1) * kstep;
;             const char* a2 = last ? nA : cA + (size_t)(t + 2) * kstep; const char* b2 = last ? nB : cB + (size_t)(t + 2) * kstep;
;             const char* a3 = a2 + kstep; const char* b3 = b2 + kstep;
;             PG8_LDB(B0, 0, 0); PG8_LDB(B1, 0, 1); PG8_SCHED; PG8_LDA(At, 0, 0); PG8_STAGE(PG8_SA(1, 1), a1 + hstepA, voffA);
;             PG8_WAIT_V(8); PG8_WAIT_L(0); PG8_BAR; PG8_MMA(0, 0, At, B0); PG8_MMA(0, 1, At, B1); PG8_BAR; PG8_SCHED;
;             PG8_LDA(At, 0, 1); PG8_STAGE(PG8_SB(0, 0), b2, voffB); PG8_STAGE(PG8_SB(0, 1), b2 + hstepB, voffB); PG8_STAGE(PG8_SA(0, 0), a2, voffA);
;             PG8_WAIT_V(8); PG8_WAIT_L(0); PG8_BAR; PG8_MMA(1, 0, At, B0); PG8_MMA(1, 1, At, B1); PG8_BAR; PG8_SCHED;
.LBB0_1190:
	s_ashr_i32 s69, s68, 31
	s_lshl_b64 s[0:1], s[68:69], 20
	v_readlane_b32 s24, v244, 49
	v_readlane_b32 s25, v244, 50
	s_add_u32 s74, s24, s0
	s_addc_u32 s75, s25, s1
	s_and_b64 s[0:1], s[8:9], exec
	s_cselect_b32 s11, s75, s79
	s_cselect_b32 s24, s74, s78
	s_add_u32 s25, s80, 0x100
	s_addc_u32 s26, s81, 0
	s_add_u32 s27, s78, 0x100
	s_addc_u32 s69, s79, 0
	s_add_u32 s0, s80, 0x80080
	s_waitcnt vmcnt(38)
	s_addc_u32 s1, s81, 0
	s_mov_b32 s71, -2
	s_waitcnt vmcnt(36)
	s_waitcnt vmcnt(34)
	s_waitcnt vmcnt(33)
	s_waitcnt vmcnt(32)
	ds_read_b128 v[2:5], v231
	ds_read_b128 v[6:9], v231 offset:1024
	ds_read_b128 v[10:13], v231 offset:2048
	ds_read_b128 v[14:17], v231 offset:3072
	ds_read_b128 v[18:21], v232
	ds_read_b128 v[26:29], v232 offset:1024
	ds_read_b128 v[154:157], v232 offset:2048
	ds_read_b128 v[158:161], v232 offset:3072
	s_cmp_eq_u32 s71, 28
	s_cselect_b32 s82, s72, s25
	s_cselect_b32 s83, s73, s26
	s_cselect_b32 s80, s24, s27
	s_cselect_b32 s81, s11, s69
	s_add_u32 s78, s82, 0x80
	s_addc_u32 s79, s83, 0
	ds_read_b128 v[162:165], v233
	ds_read_b128 v[166:169], v233 offset:1024
	ds_read_b128 v[178:181], v233 offset:2048
	ds_read_b128 v[182:185], v233 offset:3072
	ds_read_b128 v[186:189], v233 offset:4096
	ds_read_b128 v[190:193], v233 offset:5120
	ds_read_b128 v[194:197], v233 offset:6144
	ds_read_b128 v[198:201], v233 offset:7168
	s_mov_b32 m0, s90
	s_nop 0
	global_load_lds_dwordx4 v208, s[0:1]
	s_mov_b32 m0, s91
	s_nop 0
	global_load_lds_dwordx4 v210, s[0:1]
	s_waitcnt vmcnt(8)
	s_waitcnt lgkmcnt(0)
	s_barrier
	s_setprio 1
	v_mfma_i32_16x16x64_i8 v[150:153], v[2:5], v[162:165], 0
	v_mfma_i32_16x16x64_i8 v[142:145], v[10:13], v[162:165], 0
	v_mfma_i32_16x16x64_i8 v[126:129], v[2:5], v[178:181], 0
	v_mfma_i32_16x16x64_i8 v[122:125], v[10:13], v[178:181], 0
	v_mfma_i32_16x16x64_i8 v[114:117], v[2:5], v[186:189], 0
	v_mfma_i32_16x16x64_i8 v[106:109], v[10:13], v[186:189], 0
	v_mfma_i32_16x16x64_i8 v[146:149], v[2:5], v[194:197], 0
	v_mfma_i32_16x16x64_i8 v[138:141], v[10:13], v[194:197], 0
	v_mfma_i32_16x16x64_i8 v[150:153], v[6:9], v[166:169], v[150:153]
	v_mfma_i32_16x16x64_i8 v[142:145], v[14:17], v[166:169], v[142:145]
	v_mfma_i32_16x16x64_i8 v[126:129], v[6:9], v[182:185], v[126:129]
	v_mfma_i32_16x16x64_i8 v[122:125], v[14:17], v[182:185], v[122:125]
	v_mfma_i32_16x16x64_i8 v[114:117], v[6:9], v[190:193], v[114:117]
	v_mfma_i32_16x16x64_i8 v[106:109], v[14:17], v[190:193], v[106:109]
	v_mfma_i32_16x16x64_i8 v[146:149], v[6:9], v[198:201], v[146:149]
	v_mfma_i32_16x16x64_i8 v[138:141], v[14:17], v[198:201], v[138:141]
	v_mfma_i32_16x16x64_i8 v[134:137], v[18:21], v[162:165], 0
	v_mfma_i32_16x16x64_i8 v[130:133], v[154:157], v[162:165], 0
	v_mfma_i32_16x16x64_i8 v[118:121], v[18:21], v[178:181], 0
	v_mfma_i32_16x16x64_i8 v[110:113], v[154:157], v[178:181], 0
	v_mfma_i32_16x16x64_i8 v[102:105], v[18:21], v[186:189], 0
	v_mfma_i32_16x16x64_i8 v[98:101], v[154:157], v[186:189], 0
	v_mfma_i32_16x16x64_i8 v[94:97], v[18:21], v[194:197], 0
	v_mfma_i32_16x16x64_i8 v[90:93], v[154:157], v[194:197], 0
	v_mfma_i32_16x16x64_i8 v[134:137], v[26:29], v[166:169], v[134:137]
	v_mfma_i32_16x16x64_i8 v[130:133], v[158:161], v[166:169], v[130:133]
	v_mfma_i32_16x16x64_i8 v[118:121], v[26:29], v[182:185], v[118:121]
	v_mfma_i32_16x16x64_i8 v[110:113], v[158:161], v[182:185], v[110:113]
	v_mfma_i32_16x16x64_i8 v[102:105], v[26:29], v[190:193], v[102:105]
	v_mfma_i32_16x16x64_i8 v[98:101], v[158:161], v[190:193], v[98:101]
	v_mfma_i32_16x16x64_i8 v[94:97], v[26:29], v[198:201], v[94:97]
	v_mfma_i32_16x16x64_i8 v[90:93], v[158:161], v[198:201], v[90:93]
	s_setprio 0
	s_barrier
	ds_read_b128 v[162:165], v233 offset:16384
	ds_read_b128 v[166:169], v233 offset:17408
	ds_read_b128 v[178:181], v233 offset:18432
	ds_read_b128 v[182:185], v233 offset:19456
	ds_read_b128 v[186:189], v233 offset:20480
	ds_read_b128 v[190:193], v233 offset:21504
	ds_read_b128 v[194:197], v233 offset:22528
	ds_read_b128 v[198:201], v233 offset:23552
	s_mov_b32 m0, s21
	s_nop 0
	global_load_lds_dwordx4 v209, s[80:81]
	s_add_u32 s96, s80, 0x80000
	s_mov_b32 m0, s23
	s_nop 0
	global_load_lds_dwordx4 v211, s[80:81]
	s_addc_u32 s97, s81, 0
	s_mov_b32 m0, s28
	s_nop 0
	global_load_lds_dwordx4 v209, s[96:97]
	s_mov_b32 m0, s29
	s_nop 0
	global_load_lds_dwordx4 v211, s[96:97]
	s_mov_b32 m0, s15
	s_nop 0
	global_load_lds_dwordx4 v208, s[82:83]
	s_mov_b32 m0, s30
	s_nop 0
	global_load_lds_dwordx4 v210, s[82:83]
	s_waitcnt vmcnt(8)
	s_waitcnt lgkmcnt(0)
	s_barrier
	s_setprio 1
	v_mfma_i32_16x16x64_i8 v[86:89], v[2:5], v[162:165], 0
	v_mfma_i32_16x16x64_i8 v[82:85], v[10:13], v[162:165], 0
	v_mfma_i32_16x16x64_i8 v[74:77], v[2:5], v[178:181], 0
	v_mfma_i32_16x16x64_i8 v[66:69], v[10:13], v[178:181], 0
	v_mfma_i32_16x16x64_i8 v[58:61], v[2:5], v[186:189], 0
	v_mfma_i32_16x16x64_i8 v[50:53], v[10:13], v[186:189], 0
	v_mfma_i32_16x16x64_i8 v[2:5], v[2:5], v[194:197], 0
	v_mfma_i32_16x16x64_i8 v[86:89], v[6:9], v[166:169], v[86:89]
	v_mfma_i32_16x16x64_i8 v[82:85], v[14:17], v[166:169], v[82:85]
	v_mfma_i32_16x16x64_i8 v[74:77], v[6:9], v[182:185], v[74:77]
	v_mfma_i32_16x16x64_i8 v[66:69], v[14:17], v[182:185], v[66:69]
	v_mfma_i32_16x16x64_i8 v[58:61], v[6:9], v[190:193], v[58:61]
	v_mfma_i32_16x16x64_i8 v[50:53], v[14:17], v[190:193], v[50:53]
	v_mfma_i32_16x16x64_i8 v[2:5], v[6:9], v[198:201], v[2:5]
	v_mfma_i32_16x16x64_i8 v[6:9], v[10:13], v[194:197], 0
	v_mfma_i32_16x16x64_i8 v[6:9], v[14:17], v[198:201], v[6:9]
	v_mfma_i32_16x16x64_i8 v[22:25], v[18:21], v[178:181], 0
	v_mfma_i32_16x16x64_i8 v[62:65], v[26:29], v[182:185], v[22:25]
	v_mfma_i32_16x16x64_i8 v[22:25], v[154:157], v[178:181], 0
	v_mfma_i32_16x16x64_i8 v[54:57], v[158:161], v[182:185], v[22:25]
	v_mfma_i32_16x16x64_i8 v[22:25], v[18:21], v[186:189], 0
	v_mfma_i32_16x16x64_i8 v[46:49], v[26:29], v[190:193], v[22:25]
	v_mfma_i32_16x16x64_i8 v[22:25], v[154:157], v[186:189], 0
	v_mfma_i32_16x16x64_i8 v[10:13], v[18:21], v[162:165], 0
	v_mfma_i32_16x16x64_i8 v[14:17], v[154:157], v[162:165], 0
	v_mfma_i32_16x16x64_i8 v[42:45], v[158:161], v[190:193], v[22:25]
	v_mfma_i32_16x16x64_i8 v[18:21], v[18:21], v[194:197], 0
	v_mfma_i32_16x16x64_i8 v[22:25], v[154:157], v[194:197], 0
	v_mfma_i32_16x16x64_i8 v[10:13], v[26:29], v[166:169], v[10:13]
	v_mfma_i32_16x16x64_i8 v[14:17], v[158:161], v[166:169], v[14:17]
	v_mfma_i32_16x16x64_i8 v[18:21], v[26:29], v[198:201], v[18:21]
	v_mfma_i32_16x16x64_i8 v[26:29], v[158:161], v[198:201], v[22:25]
	s_setprio 0
	s_barrier
; #define PG8_STAGE(bufoff, gbase, voff) do { if constexpr (VAR != 1 && VAR != 3) { _Pragma("unroll") for (int _i = 0; _i < 2; ++_i) \
;         asm volatile("s_mov_b32 m0, %2\n\ts_nop 0\n\tglobal_load_lds_dwordx4 %0, %1" :: "v"((voff)[_i]), "s"((const char*)(gbase)), "s"(ldsbase + (unsigned)((bufoff) + _i * 8192)) : "memory", "m0"); } } while (0)
; #define PG8_LDA(dst, b, h) do { if constexpr (VAR < 2) _Pragma("unroll") for (int m = 0; m < 4; ++m) _Pragma("unroll") for (int k = 0; k < 2; ++k) dst[m][k] = *(const LAS bf16x8*)(lds + PG8_SA(b, h) + aoff + m * 2048 + k * 1024); } while (0)
; #define PG8_LDB(dst, b, h) do { if constexpr (VAR < 2) _Pragma("unroll") for (int n = 0; n < 2; ++n) _Pragma("unroll") for (int k = 0; k < 2; ++k) dst[n][k] = *(const LAS bf16x8*)(lds + PG8_SB(b, h) + boff + n * 2048 + k * 1024); } while (0)
; #define PG8_WAIT_V(n) asm volatile("s_waitcnt vmcnt(" #n ")" ::: "memory")
; #define PG8_WAIT_L(n) asm volatile("s_waitcnt lgkmcnt(" #n ")" ::: "memory")
; #define PG8_BAR do { if constexpr (VAR != 3) __builtin_amdgcn_s_barrier(); } while (0)
; #define PG8_SCHED __builtin_amdgcn_sched_barrier(0)
;     ...
;             PG8_LDB(B0, 1, 0); PG8_LDB(B1, 1, 1); PG8_SCHED; PG8_LDA(At, 1, 0); PG8_STAGE(PG8_SA(0, 1), a2 + hstepA, voffA);
;             PG8_WAIT_V(8); PG8_WAIT_L(0); PG8_BAR; PG8_MMA(0, 0, At, B0); PG8_MMA(0, 1, At, B1); PG8_BAR; PG8_SCHED;
;             PG8_LDA(At, 1, 1); PG8_STAGE(PG8_SB(1, 0), b3, voffB); PG8_STAGE(PG8_SB(1, 1), b3 + hstepB, voffB); PG8_STAGE(PG8_SA(1, 0), a3, voffA);
;             PG8_WAIT_V(8); PG8_WAIT_L(0); PG8_BAR; PG8_MMA(1, 0, At, B0); PG8_MMA(1, 1, At, B1); PG8_BAR; PG8_SCHED;
;         }
	s_nop 1
	ds_read_b128 v[22:25], v234
	ds_read_b128 v[30:33], v234 offset:1024
	ds_read_b128 v[34:37], v234 offset:2048
	ds_read_b128 v[38:41], v234 offset:3072
	ds_read_b128 v[154:157], v235
	ds_read_b128 v[158:161], v235 offset:1024
	ds_read_b128 v[162:165], v235 offset:2048
	ds_read_b128 v[166:169], v235 offset:3072
	ds_read_b128 v[70:73], v233 offset:32768
	ds_read_b128 v[78:81], v233 offset:33792
	ds_read_b128 v[178:181], v233 offset:34816
	ds_read_b128 v[182:185], v233 offset:35840
	ds_read_b128 v[186:189], v233 offset:36864
	ds_read_b128 v[190:193], v233 offset:37888
	ds_read_b128 v[194:197], v233 offset:38912
	ds_read_b128 v[198:201], v233 offset:39936
	s_add_u32 s82, s82, 0x80000
	s_addc_u32 s83, s83, 0
	s_mov_b32 m0, s31
	s_nop 0
	global_load_lds_dwordx4 v208, s[82:83]
	s_mov_b32 m0, s33
	s_nop 0
	global_load_lds_dwordx4 v210, s[82:83]
	s_waitcnt vmcnt(8)
	s_waitcnt lgkmcnt(0)
	s_barrier
	s_setprio 1
	v_mfma_i32_16x16x64_i8 v[150:153], v[22:25], v[70:73], v[150:153]
	v_mfma_i32_16x16x64_i8 v[142:145], v[34:37], v[70:73], v[142:145]
	v_mfma_i32_16x16x64_i8 v[126:129], v[22:25], v[178:181], v[126:129]
	v_mfma_i32_16x16x64_i8 v[122:125], v[34:37], v[178:181], v[122:125]
	v_mfma_i32_16x16x64_i8 v[114:117], v[22:25], v[186:189], v[114:117]
	v_mfma_i32_16x16x64_i8 v[106:109], v[34:37], v[186:189], v[106:109]
	v_mfma_i32_16x16x64_i8 v[146:149], v[22:25], v[194:197], v[146:149]
	v_mfma_i32_16x16x64_i8 v[138:141], v[34:37], v[194:197], v[138:141]
	v_mfma_i32_16x16x64_i8 v[150:153], v[30:33], v[78:81], v[150:153]
	v_mfma_i32_16x16x64_i8 v[142:145], v[38:41], v[78:81], v[142:145]
	v_mfma_i32_16x16x64_i8 v[126:129], v[30:33], v[182:185], v[126:129]
	v_mfma_i32_16x16x64_i8 v[122:125], v[38:41], v[182:185], v[122:125]
	v_mfma_i32_16x16x64_i8 v[114:117], v[30:33], v[190:193], v[114:117]
	v_mfma_i32_16x16x64_i8 v[106:109], v[38:41], v[190:193], v[106:109]
	v_mfma_i32_16x16x64_i8 v[146:149], v[30:33], v[198:201], v[146:149]
	v_mfma_i32_16x16x64_i8 v[138:141], v[38:41], v[198:201], v[138:141]
	v_mfma_i32_16x16x64_i8 v[134:137], v[154:157], v[70:73], v[134:137]
	v_mfma_i32_16x16x64_i8 v[70:73], v[162:165], v[70:73], v[130:133]
	v_mfma_i32_16x16x64_i8 v[130:133], v[166:169], v[78:81], v[70:73]
	v_mfma_i32_16x16x64_i8 v[70:73], v[154:157], v[178:181], v[118:121]
	v_mfma_i32_16x16x64_i8 v[118:121], v[158:161], v[182:185], v[70:73]
	v_mfma_i32_16x16x64_i8 v[70:73], v[162:165], v[178:181], v[110:113]
	v_mfma_i32_16x16x64_i8 v[110:113], v[166:169], v[182:185], v[70:73]
	v_mfma_i32_16x16x64_i8 v[70:73], v[154:157], v[186:189], v[102:105]
	v_mfma_i32_16x16x64_i8 v[102:105], v[158:161], v[190:193], v[70:73]
	v_mfma_i32_16x16x64_i8 v[70:73], v[162:165], v[186:189], v[98:101]
	v_mfma_i32_16x16x64_i8 v[98:101], v[166:169], v[190:193], v[70:73]
	v_mfma_i32_16x16x64_i8 v[70:73], v[154:157], v[194:197], v[94:97]
	v_mfma_i32_16x16x64_i8 v[94:97], v[158:161], v[198:201], v[70:73]
	v_mfma_i32_16x16x64_i8 v[70:73], v[162:165], v[194:197], v[90:93]
	v_mfma_i32_16x16x64_i8 v[134:137], v[158:161], v[78:81], v[134:137]
	v_mfma_i32_16x16x64_i8 v[90:93], v[166:169], v[198:201], v[70:73]
	s_setprio 0
	s_barrier
	s_nop 3
	ds_read_b128 v[70:73], v233 offset:49152
	ds_read_b128 v[178:181], v233 offset:50176
	ds_read_b128 v[182:185], v233 offset:51200
	ds_read_b128 v[186:189], v233 offset:52224
	ds_read_b128 v[190:193], v233 offset:53248
	ds_read_b128 v[194:197], v233 offset:54272
	ds_read_b128 v[198:201], v233 offset:55296
	ds_read_b128 v[202:205], v233 offset:56320
	s_add_u32 s82, s80, 0x80
	s_addc_u32 s83, s81, 0
	s_mov_b32 m0, s84
	s_nop 0
	global_load_lds_dwordx4 v209, s[82:83]
	s_add_u32 s80, s80, 0x80080
	s_mov_b32 m0, s85
	s_nop 0
	global_load_lds_dwordx4 v211, s[82:83]
	s_addc_u32 s81, s81, 0
	s_mov_b32 m0, s88
	s_nop 0
	global_load_lds_dwordx4 v209, s[80:81]
	s_mov_b32 m0, s89
	s_nop 0
	global_load_lds_dwordx4 v211, s[80:81]
	s_mov_b32 m0, s86
	s_nop 0
	global_load_lds_dwordx4 v208, s[78:79]
	s_mov_b32 m0, s87
	s_nop 0
	global_load_lds_dwordx4 v210, s[78:79]
	s_waitcnt vmcnt(8)
	s_waitcnt lgkmcnt(0)
	s_barrier
	s_setprio 1
	v_mfma_i32_16x16x64_i8 v[78:81], v[22:25], v[70:73], v[86:89]
	v_mfma_i32_16x16x64_i8 v[74:77], v[22:25], v[182:185], v[74:77]
	v_mfma_i32_16x16x64_i8 v[58:61], v[22:25], v[190:193], v[58:61]
	v_mfma_i32_16x16x64_i8 v[2:5], v[22:25], v[198:201], v[2:5]
	v_mfma_i32_16x16x64_i8 v[86:89], v[30:33], v[178:181], v[78:81]
	v_mfma_i32_16x16x64_i8 v[78:81], v[34:37], v[70:73], v[82:85]
	v_mfma_i32_16x16x64_i8 v[74:77], v[30:33], v[186:189], v[74:77]
	v_mfma_i32_16x16x64_i8 v[66:69], v[34:37], v[182:185], v[66:69]
	v_mfma_i32_16x16x64_i8 v[58:61], v[30:33], v[194:197], v[58:61]
	v_mfma_i32_16x16x64_i8 v[50:53], v[34:37], v[190:193], v[50:53]
	v_mfma_i32_16x16x64_i8 v[30:33], v[30:33], v[202:205], v[2:5]
	v_mfma_i32_16x16x64_i8 v[2:5], v[34:37], v[198:201], v[6:9]
	v_mfma_i32_16x16x64_i8 v[82:85], v[38:41], v[178:181], v[78:81]
	v_mfma_i32_16x16x64_i8 v[66:69], v[38:41], v[186:189], v[66:69]
	v_mfma_i32_16x16x64_i8 v[50:53], v[38:41], v[194:197], v[50:53]
	v_mfma_i32_16x16x64_i8 v[22:25], v[38:41], v[202:205], v[2:5]
	v_mfma_i32_16x16x64_i8 v[2:5], v[154:157], v[70:73], v[10:13]
	v_mfma_i32_16x16x64_i8 v[78:81], v[158:161], v[178:181], v[2:5]
	v_mfma_i32_16x16x64_i8 v[2:5], v[162:165], v[70:73], v[14:17]
	v_mfma_i32_16x16x64_i8 v[70:73], v[166:169], v[178:181], v[2:5]
	v_mfma_i32_16x16x64_i8 v[2:5], v[154:157], v[182:185], v[62:65]
	v_mfma_i32_16x16x64_i8 v[62:65], v[158:161], v[186:189], v[2:5]
	v_mfma_i32_16x16x64_i8 v[2:5], v[162:165], v[182:185], v[54:57]
	v_mfma_i32_16x16x64_i8 v[54:57], v[166:169], v[186:189], v[2:5]
	v_mfma_i32_16x16x64_i8 v[2:5], v[154:157], v[190:193], v[46:49]
	v_mfma_i32_16x16x64_i8 v[46:49], v[158:161], v[194:197], v[2:5]
	v_mfma_i32_16x16x64_i8 v[2:5], v[162:165], v[190:193], v[42:45]
	v_mfma_i32_16x16x64_i8 v[42:45], v[166:169], v[194:197], v[2:5]
	v_mfma_i32_16x16x64_i8 v[2:5], v[154:157], v[198:201], v[18:21]
	v_mfma_i32_16x16x64_i8 v[38:41], v[158:161], v[202:205], v[2:5]
	v_mfma_i32_16x16x64_i8 v[2:5], v[162:165], v[198:201], v[26:29]
	v_mfma_i32_16x16x64_i8 v[34:37], v[166:169], v[202:205], v[2:5]
	s_setprio 0
	s_barrier
	s_add_i32 s71, s71, 2
	s_add_u32 s25, s25, 0x100
	s_addc_u32 s26, s26, 0
	s_add_u32 s27, s27, 0x100
	s_addc_u32 s69, s69, 0
	s_add_u32 s0, s0, 0x100
	s_addc_u32 s1, s1, 0
	s_cmp_gt_u32 s71, 29
	s_cbranch_scc0 .LBB0_1191
	s_branch .Lmy_kexit_8
; #define PG8_STAGE(bufoff, gbase, voff) do { if constexpr (VAR != 1 && VAR != 3) { _Pragma("unroll") for (int _i = 0; _i < 2; ++_i) \
;         asm volatile("s_mov_b32 m0, %2\n\ts_nop 0\n\tglobal_load_lds_dwordx4 %0, %1" :: "v"((voff)[_i]), "s"((const char*)(gbase)), "s"(ldsbase + (unsigned)((bufoff) + _i * 8192)) : "memory", "m0"); } } while (0)
; #define PG8_LDA(dst, b, h) do { if constexpr (VAR < 2) _Pragma("unroll") for (int m = 0; m < 4; ++m) _Pragma("unroll") for (int k = 0; k < 2; ++k) dst[m][k] = *(const LAS bf16x8*)(lds + PG8_SA(b, h) + aoff + m * 2048 + k * 1024); } while (0)
; #define PG8_LDB(dst, b, h) do { if constexpr (VAR < 2) _Pragma("unroll") for (int n = 0; n < 2; ++n) _Pragma("unroll") for (int k = 0; k < 2; ++k) dst[n][k] = *(const LAS bf16x8*)(lds + PG8_SB(b, h) + boff + n * 2048 + k * 1024); } while (0)
; #define PG8_WAIT_V(n) asm volatile("s_waitcnt vmcnt(" #n ")" ::: "memory")
; #define PG8_WAIT_L(n) asm volatile("s_waitcnt lgkmcnt(" #n ")" ::: "memory")
; #define PG8_BAR do { if constexpr (VAR != 3) __builtin_amdgcn_s_barrier(); } while (0)
; #define PG8_SCHED __builtin_amdgcn_sched_barrier(0)
;     ...
;             PG8_LDB(B0, 0, 0); PG8_LDB(B1, 0, 1); PG8_SCHED; PG8_LDA(At, 0, 0); PG8_STAGE(PG8_SA(1, 1), a1 + hstepA, voffA);
;             PG8_WAIT_V(8); PG8_WAIT_L(0); PG8_BAR; PG8_MMA(0, 0, At, B0); PG8_MMA(0, 1, At, B1); PG8_BAR; PG8_SCHED;
;             PG8_LDA(At, 0, 1); PG8_STAGE(PG8_SB(0, 0), b2, voffB); PG8_STAGE(PG8_SB(0, 1), b2 + hstepB, voffB); PG8_STAGE(PG8_SA(0, 0), a2, voffA);
;             PG8_WAIT_V(8); PG8_WAIT_L(0); PG8_BAR; PG8_MMA(1, 0, At, B0); PG8_MMA(1, 1, At, B1); PG8_BAR; PG8_SCHED;
;             PG8_LDB(B0, 1, 0); PG8_LDB(B1, 1, 1); PG8_SCHED; PG8_LDA(At, 1, 0); PG8_STAGE(PG8_SA(0, 1), a2 + hstepA, voffA);
;             PG8_WAIT_V(8); PG8_WAIT_L(0); PG8_BAR; PG8_MMA(0, 0, At, B0); PG8_MMA(0, 1, At, B1); PG8_BAR; PG8_SCHED;
.LBB0_1191:
	ds_read_b128 v[2:5], v231
	ds_read_b128 v[6:9], v231 offset:1024
	ds_read_b128 v[10:13], v231 offset:2048
	ds_read_b128 v[14:17], v231 offset:3072
	ds_read_b128 v[18:21], v232
	ds_read_b128 v[26:29], v232 offset:1024
	ds_read_b128 v[154:157], v232 offset:2048
	ds_read_b128 v[158:161], v232 offset:3072
	s_cmp_eq_u32 s71, 28
	s_cselect_b32 s82, s72, s25
	s_cselect_b32 s83, s73, s26
	s_cselect_b32 s80, s24, s27
	s_cselect_b32 s81, s11, s69
	s_add_u32 s78, s82, 0x80
	s_addc_u32 s79, s83, 0
	ds_read_b128 v[162:165], v233
	ds_read_b128 v[166:169], v233 offset:1024
	ds_read_b128 v[178:181], v233 offset:2048
	ds_read_b128 v[182:185], v233 offset:3072
	ds_read_b128 v[186:189], v233 offset:4096
	ds_read_b128 v[190:193], v233 offset:5120
	ds_read_b128 v[194:197], v233 offset:6144
	ds_read_b128 v[198:201], v233 offset:7168
	s_mov_b32 m0, s90
	s_nop 0
	global_load_lds_dwordx4 v208, s[0:1]
	s_mov_b32 m0, s91
	s_nop 0
	global_load_lds_dwordx4 v210, s[0:1]
	s_waitcnt vmcnt(8)
	s_waitcnt lgkmcnt(0)
	s_barrier
	s_setprio 1
	v_mfma_i32_16x16x64_i8 v[150:153], v[2:5], v[162:165], v[150:153]
	v_mfma_i32_16x16x64_i8 v[142:145], v[10:13], v[162:165], v[142:145]
	v_mfma_i32_16x16x64_i8 v[126:129], v[2:5], v[178:181], v[126:129]
	v_mfma_i32_16x16x64_i8 v[122:125], v[10:13], v[178:181], v[122:125]
	v_mfma_i32_16x16x64_i8 v[114:117], v[2:5], v[186:189], v[114:117]
	v_mfma_i32_16x16x64_i8 v[106:109], v[10:13], v[186:189], v[106:109]
	v_mfma_i32_16x16x64_i8 v[146:149], v[2:5], v[194:197], v[146:149]
	v_mfma_i32_16x16x64_i8 v[138:141], v[10:13], v[194:197], v[138:141]
	v_mfma_i32_16x16x64_i8 v[150:153], v[6:9], v[166:169], v[150:153]
	v_mfma_i32_16x16x64_i8 v[142:145], v[14:17], v[166:169], v[142:145]
	v_mfma_i32_16x16x64_i8 v[126:129], v[6:9], v[182:185], v[126:129]
	v_mfma_i32_16x16x64_i8 v[122:125], v[14:17], v[182:185], v[122:125]
	v_mfma_i32_16x16x64_i8 v[114:117], v[6:9], v[190:193], v[114:117]
	v_mfma_i32_16x16x64_i8 v[106:109], v[14:17], v[190:193], v[106:109]
	v_mfma_i32_16x16x64_i8 v[146:149], v[6:9], v[198:201], v[146:149]
	v_mfma_i32_16x16x64_i8 v[138:141], v[14:17], v[198:201], v[138:141]
	v_mfma_i32_16x16x64_i8 v[134:137], v[18:21], v[162:165], v[134:137]
	v_mfma_i32_16x16x64_i8 v[130:133], v[154:157], v[162:165], v[130:133]
	v_mfma_i32_16x16x64_i8 v[118:121], v[18:21], v[178:181], v[118:121]
	v_mfma_i32_16x16x64_i8 v[110:113], v[154:157], v[178:181], v[110:113]
	v_mfma_i32_16x16x64_i8 v[102:105], v[18:21], v[186:189], v[102:105]
	v_mfma_i32_16x16x64_i8 v[98:101], v[154:157], v[186:189], v[98:101]
	v_mfma_i32_16x16x64_i8 v[94:97], v[18:21], v[194:197], v[94:97]
	v_mfma_i32_16x16x64_i8 v[90:93], v[154:157], v[194:197], v[90:93]
	v_mfma_i32_16x16x64_i8 v[134:137], v[26:29], v[166:169], v[134:137]
	v_mfma_i32_16x16x64_i8 v[130:133], v[158:161], v[166:169], v[130:133]
	v_mfma_i32_16x16x64_i8 v[118:121], v[26:29], v[182:185], v[118:121]
	v_mfma_i32_16x16x64_i8 v[110:113], v[158:161], v[182:185], v[110:113]
	v_mfma_i32_16x16x64_i8 v[102:105], v[26:29], v[190:193], v[102:105]
	v_mfma_i32_16x16x64_i8 v[98:101], v[158:161], v[190:193], v[98:101]
	v_mfma_i32_16x16x64_i8 v[94:97], v[26:29], v[198:201], v[94:97]
	v_mfma_i32_16x16x64_i8 v[90:93], v[158:161], v[198:201], v[90:93]
	s_setprio 0
	s_barrier
	ds_read_b128 v[162:165], v233 offset:16384
	ds_read_b128 v[166:169], v233 offset:17408
	ds_read_b128 v[178:181], v233 offset:18432
	ds_read_b128 v[182:185], v233 offset:19456
	ds_read_b128 v[186:189], v233 offset:20480
	ds_read_b128 v[190:193], v233 offset:21504
	ds_read_b128 v[194:197], v233 offset:22528
	ds_read_b128 v[198:201], v233 offset:23552
	s_mov_b32 m0, s21
	s_nop 0
	global_load_lds_dwordx4 v209, s[80:81]
	s_add_u32 s96, s80, 0x80000
	s_mov_b32 m0, s23
	s_nop 0
	global_load_lds_dwordx4 v211, s[80:81]
	s_addc_u32 s97, s81, 0
	s_mov_b32 m0, s28
	s_nop 0
	global_load_lds_dwordx4 v209, s[96:97]
	s_mov_b32 m0, s29
	s_nop 0
	global_load_lds_dwordx4 v211, s[96:97]
	s_mov_b32 m0, s15
	s_nop 0
	global_load_lds_dwordx4 v208, s[82:83]
	s_mov_b32 m0, s30
	s_nop 0
	global_load_lds_dwordx4 v210, s[82:83]
	s_waitcnt vmcnt(8)
	s_waitcnt lgkmcnt(0)
	s_barrier
	s_setprio 1
	v_mfma_i32_16x16x64_i8 v[86:89], v[2:5], v[162:165], v[86:89]
	v_mfma_i32_16x16x64_i8 v[82:85], v[10:13], v[162:165], v[82:85]
	v_mfma_i32_16x16x64_i8 v[74:77], v[2:5], v[178:181], v[74:77]
	v_mfma_i32_16x16x64_i8 v[66:69], v[10:13], v[178:181], v[66:69]
	v_mfma_i32_16x16x64_i8 v[58:61], v[2:5], v[186:189], v[58:61]
	v_mfma_i32_16x16x64_i8 v[50:53], v[10:13], v[186:189], v[50:53]
	v_mfma_i32_16x16x64_i8 v[2:5], v[2:5], v[194:197], v[30:33]
	v_mfma_i32_16x16x64_i8 v[86:89], v[6:9], v[166:169], v[86:89]
	v_mfma_i32_16x16x64_i8 v[82:85], v[14:17], v[166:169], v[82:85]
	v_mfma_i32_16x16x64_i8 v[74:77], v[6:9], v[182:185], v[74:77]
	v_mfma_i32_16x16x64_i8 v[66:69], v[14:17], v[182:185], v[66:69]
	v_mfma_i32_16x16x64_i8 v[58:61], v[6:9], v[190:193], v[58:61]
	v_mfma_i32_16x16x64_i8 v[50:53], v[14:17], v[190:193], v[50:53]
	v_mfma_i32_16x16x64_i8 v[2:5], v[6:9], v[198:201], v[2:5]
	v_mfma_i32_16x16x64_i8 v[6:9], v[10:13], v[194:197], v[22:25]
	v_mfma_i32_16x16x64_i8 v[6:9], v[14:17], v[198:201], v[6:9]
	v_mfma_i32_16x16x64_i8 v[22:25], v[18:21], v[178:181], v[62:65]
	v_mfma_i32_16x16x64_i8 v[62:65], v[26:29], v[182:185], v[22:25]
	v_mfma_i32_16x16x64_i8 v[22:25], v[154:157], v[178:181], v[54:57]
	v_mfma_i32_16x16x64_i8 v[54:57], v[158:161], v[182:185], v[22:25]
	v_mfma_i32_16x16x64_i8 v[22:25], v[18:21], v[186:189], v[46:49]
	v_mfma_i32_16x16x64_i8 v[46:49], v[26:29], v[190:193], v[22:25]
	v_mfma_i32_16x16x64_i8 v[22:25], v[154:157], v[186:189], v[42:45]
	v_mfma_i32_16x16x64_i8 v[10:13], v[18:21], v[162:165], v[78:81]
	v_mfma_i32_16x16x64_i8 v[14:17], v[154:157], v[162:165], v[70:73]
	v_mfma_i32_16x16x64_i8 v[42:45], v[158:161], v[190:193], v[22:25]
	v_mfma_i32_16x16x64_i8 v[18:21], v[18:21], v[194:197], v[38:41]
	v_mfma_i32_16x16x64_i8 v[22:25], v[154:157], v[194:197], v[34:37]
	v_mfma_i32_16x16x64_i8 v[10:13], v[26:29], v[166:169], v[10:13]
	v_mfma_i32_16x16x64_i8 v[14:17], v[158:161], v[166:169], v[14:17]
	v_mfma_i32_16x16x64_i8 v[18:21], v[26:29], v[198:201], v[18:21]
	v_mfma_i32_16x16x64_i8 v[26:29], v[158:161], v[198:201], v[22:25]
	s_setprio 0
	s_barrier
; #define PG8_STAGE(bufoff, gbase, voff) do { if constexpr (VAR != 1 && VAR != 3) { _Pragma("unroll") for (int _i = 0; _i < 2; ++_i) \
;         asm volatile("s_mov_b32 m0, %2\n\ts_nop 0\n\tglobal_load_lds_dwordx4 %0, %1" :: "v"((voff)[_i]), "s"((const char*)(gbase)), "s"(ldsbase + (unsigned)((bufoff) + _i * 8192)) : "memory", "m0"); } } while (0)
; #define PG8_LDA(dst, b, h) do { if constexpr (VAR < 2) _Pragma("unroll") for (int m = 0; m < 4; ++m) _Pragma("unroll") for (int k = 0; k < 2; ++k) dst[m][k] = *(const LAS bf16x8*)(lds + PG8_SA(b, h) + aoff + m * 2048 + k * 1024); } while (0)
; #define PG8_LDB(dst, b, h) do { if constexpr (VAR < 2) _Pragma("unroll") for (int n = 0; n < 2; ++n) _Pragma("unroll") for (int k = 0; k < 2; ++k) dst[n][k] = *(const LAS bf16x8*)(lds + PG8_SB(b, h) + boff + n * 2048 + k * 1024); } while (0)
; #define PG8_WAIT_V(n) asm volatile("s_waitcnt vmcnt(" #n ")" ::: "memory")
; #define PG8_WAIT_L(n) asm volatile("s_waitcnt lgkmcnt(" #n ")" ::: "memory")
; #define PG8_BAR do { if constexpr (VAR != 3) __builtin_amdgcn_s_barrier(); } while (0)
; #define PG8_SCHED __builtin_amdgcn_sched_barrier(0)
;     ...
;             PG8_LDB(B0, 1, 0); PG8_LDB(B1, 1, 1); PG8_SCHED; PG8_LDA(At, 1, 0); PG8_STAGE(PG8_SA(0, 1), a2 + hstepA, voffA);
;             PG8_WAIT_V(8); PG8_WAIT_L(0); PG8_BAR; PG8_MMA(0, 0, At, B0); PG8_MMA(0, 1, At, B1); PG8_BAR; PG8_SCHED;
;             PG8_LDA(At, 1, 1); PG8_STAGE(PG8_SB(1, 0), b3, voffB); PG8_STAGE(PG8_SB(1, 1), b3 + hstepB, voffB); PG8_STAGE(PG8_SA(1, 0), a3, voffA);
;             PG8_WAIT_V(8); PG8_WAIT_L(0); PG8_BAR; PG8_MMA(1, 0, At, B0); PG8_MMA(1, 1, At, B1); PG8_BAR; PG8_SCHED;
;         }
;         if (wr == 0) PG8_BAR;
	s_nop 1
	ds_read_b128 v[22:25], v234
	ds_read_b128 v[30:33], v234 offset:1024
	ds_read_b128 v[34:37], v234 offset:2048
	ds_read_b128 v[38:41], v234 offset:3072
	ds_read_b128 v[154:157], v235
	ds_read_b128 v[158:161], v235 offset:1024
	ds_read_b128 v[162:165], v235 offset:2048
	ds_read_b128 v[166:169], v235 offset:3072
	ds_read_b128 v[70:73], v233 offset:32768
	ds_read_b128 v[78:81], v233 offset:33792
	ds_read_b128 v[178:181], v233 offset:34816
	ds_read_b128 v[182:185], v233 offset:35840
	ds_read_b128 v[186:189], v233 offset:36864
	ds_read_b128 v[190:193], v233 offset:37888
	ds_read_b128 v[194:197], v233 offset:38912
	ds_read_b128 v[198:201], v233 offset:39936
	s_add_u32 s82, s82, 0x80000
	s_addc_u32 s83, s83, 0
	s_mov_b32 m0, s31
	s_nop 0
	global_load_lds_dwordx4 v208, s[82:83]
	s_mov_b32 m0, s33
	s_nop 0
	global_load_lds_dwordx4 v210, s[82:83]
	s_waitcnt vmcnt(8)
	s_waitcnt lgkmcnt(0)
	s_barrier
	s_setprio 1
	v_mfma_i32_16x16x64_i8 v[150:153], v[22:25], v[70:73], v[150:153]
	v_mfma_i32_16x16x64_i8 v[142:145], v[34:37], v[70:73], v[142:145]
	v_mfma_i32_16x16x64_i8 v[126:129], v[22:25], v[178:181], v[126:129]
	v_mfma_i32_16x16x64_i8 v[122:125], v[34:37], v[178:181], v[122:125]
	v_mfma_i32_16x16x64_i8 v[114:117], v[22:25], v[186:189], v[114:117]
	v_mfma_i32_16x16x64_i8 v[106:109], v[34:37], v[186:189], v[106:109]
	v_mfma_i32_16x16x64_i8 v[146:149], v[22:25], v[194:197], v[146:149]
	v_mfma_i32_16x16x64_i8 v[138:141], v[34:37], v[194:197], v[138:141]
	v_mfma_i32_16x16x64_i8 v[150:153], v[30:33], v[78:81], v[150:153]
	v_mfma_i32_16x16x64_i8 v[142:145], v[38:41], v[78:81], v[142:145]
	v_mfma_i32_16x16x64_i8 v[126:129], v[30:33], v[182:185], v[126:129]
	v_mfma_i32_16x16x64_i8 v[122:125], v[38:41], v[182:185], v[122:125]
	v_mfma_i32_16x16x64_i8 v[114:117], v[30:33], v[190:193], v[114:117]
	v_mfma_i32_16x16x64_i8 v[106:109], v[38:41], v[190:193], v[106:109]
	v_mfma_i32_16x16x64_i8 v[146:149], v[30:33], v[198:201], v[146:149]
	v_mfma_i32_16x16x64_i8 v[138:141], v[38:41], v[198:201], v[138:141]
	v_mfma_i32_16x16x64_i8 v[134:137], v[154:157], v[70:73], v[134:137]
	v_mfma_i32_16x16x64_i8 v[70:73], v[162:165], v[70:73], v[130:133]
	v_mfma_i32_16x16x64_i8 v[130:133], v[166:169], v[78:81], v[70:73]
	v_mfma_i32_16x16x64_i8 v[70:73], v[154:157], v[178:181], v[118:121]
	v_mfma_i32_16x16x64_i8 v[118:121], v[158:161], v[182:185], v[70:73]
	v_mfma_i32_16x16x64_i8 v[70:73], v[162:165], v[178:181], v[110:113]
	v_mfma_i32_16x16x64_i8 v[110:113], v[166:169], v[182:185], v[70:73]
	v_mfma_i32_16x16x64_i8 v[70:73], v[154:157], v[186:189], v[102:105]
	v_mfma_i32_16x16x64_i8 v[102:105], v[158:161], v[190:193], v[70:73]
	v_mfma_i32_16x16x64_i8 v[70:73], v[162:165], v[186:189], v[98:101]
	v_mfma_i32_16x16x64_i8 v[98:101], v[166:169], v[190:193], v[70:73]
	v_mfma_i32_16x16x64_i8 v[70:73], v[154:157], v[194:197], v[94:97]
	v_mfma_i32_16x16x64_i8 v[94:97], v[158:161], v[198:201], v[70:73]
	v_mfma_i32_16x16x64_i8 v[70:73], v[162:165], v[194:197], v[90:93]
	v_mfma_i32_16x16x64_i8 v[134:137], v[158:161], v[78:81], v[134:137]
	v_mfma_i32_16x16x64_i8 v[90:93], v[166:169], v[198:201], v[70:73]
	s_setprio 0
	s_barrier
	s_nop 3
	ds_read_b128 v[70:73], v233 offset:49152
	ds_read_b128 v[178:181], v233 offset:50176
	ds_read_b128 v[182:185], v233 offset:51200
	ds_read_b128 v[186:189], v233 offset:52224
	ds_read_b128 v[190:193], v233 offset:53248
	ds_read_b128 v[194:197], v233 offset:54272
	ds_read_b128 v[198:201], v233 offset:55296
	ds_read_b128 v[202:205], v233 offset:56320
	s_add_u32 s82, s80, 0x80
	s_addc_u32 s83, s81, 0
	s_mov_b32 m0, s84
	s_nop 0
	global_load_lds_dwordx4 v209, s[82:83]
	s_add_u32 s80, s80, 0x80080
	s_mov_b32 m0, s85
	s_nop 0
	global_load_lds_dwordx4 v211, s[82:83]
	s_addc_u32 s81, s81, 0
	s_mov_b32 m0, s88
	s_nop 0
	global_load_lds_dwordx4 v209, s[80:81]
	s_mov_b32 m0, s89
	s_nop 0
	global_load_lds_dwordx4 v211, s[80:81]
	s_mov_b32 m0, s86
	s_nop 0
	global_load_lds_dwordx4 v208, s[78:79]
	s_mov_b32 m0, s87
	s_nop 0
	global_load_lds_dwordx4 v210, s[78:79]
	s_waitcnt vmcnt(8)
	s_waitcnt lgkmcnt(0)
	s_barrier
	s_setprio 1
	v_mfma_i32_16x16x64_i8 v[78:81], v[22:25], v[70:73], v[86:89]
	v_mfma_i32_16x16x64_i8 v[74:77], v[22:25], v[182:185], v[74:77]
	v_mfma_i32_16x16x64_i8 v[58:61], v[22:25], v[190:193], v[58:61]
	v_mfma_i32_16x16x64_i8 v[2:5], v[22:25], v[198:201], v[2:5]
	v_mfma_i32_16x16x64_i8 v[86:89], v[30:33], v[178:181], v[78:81]
	v_mfma_i32_16x16x64_i8 v[78:81], v[34:37], v[70:73], v[82:85]
	v_mfma_i32_16x16x64_i8 v[74:77], v[30:33], v[186:189], v[74:77]
	v_mfma_i32_16x16x64_i8 v[66:69], v[34:37], v[182:185], v[66:69]
	v_mfma_i32_16x16x64_i8 v[58:61], v[30:33], v[194:197], v[58:61]
	v_mfma_i32_16x16x64_i8 v[50:53], v[34:37], v[190:193], v[50:53]
	v_mfma_i32_16x16x64_i8 v[30:33], v[30:33], v[202:205], v[2:5]
	v_mfma_i32_16x16x64_i8 v[2:5], v[34:37], v[198:201], v[6:9]
	v_mfma_i32_16x16x64_i8 v[82:85], v[38:41], v[178:181], v[78:81]
	v_mfma_i32_16x16x64_i8 v[66:69], v[38:41], v[186:189], v[66:69]
	v_mfma_i32_16x16x64_i8 v[50:53], v[38:41], v[194:197], v[50:53]
	v_mfma_i32_16x16x64_i8 v[22:25], v[38:41], v[202:205], v[2:5]
	v_mfma_i32_16x16x64_i8 v[2:5], v[154:157], v[70:73], v[10:13]
	v_mfma_i32_16x16x64_i8 v[78:81], v[158:161], v[178:181], v[2:5]
	v_mfma_i32_16x16x64_i8 v[2:5], v[162:165], v[70:73], v[14:17]
	v_mfma_i32_16x16x64_i8 v[70:73], v[166:169], v[178:181], v[2:5]
	v_mfma_i32_16x16x64_i8 v[2:5], v[154:157], v[182:185], v[62:65]
	v_mfma_i32_16x16x64_i8 v[62:65], v[158:161], v[186:189], v[2:5]
	v_mfma_i32_16x16x64_i8 v[2:5], v[162:165], v[182:185], v[54:57]
	v_mfma_i32_16x16x64_i8 v[54:57], v[166:169], v[186:189], v[2:5]
	v_mfma_i32_16x16x64_i8 v[2:5], v[154:157], v[190:193], v[46:49]
	v_mfma_i32_16x16x64_i8 v[46:49], v[158:161], v[194:197], v[2:5]
	v_mfma_i32_16x16x64_i8 v[2:5], v[162:165], v[190:193], v[42:45]
	v_mfma_i32_16x16x64_i8 v[42:45], v[166:169], v[194:197], v[2:5]
	v_mfma_i32_16x16x64_i8 v[2:5], v[154:157], v[198:201], v[18:21]
	v_mfma_i32_16x16x64_i8 v[38:41], v[158:161], v[202:205], v[2:5]
	v_mfma_i32_16x16x64_i8 v[2:5], v[162:165], v[198:201], v[26:29]
	v_mfma_i32_16x16x64_i8 v[34:37], v[166:169], v[202:205], v[2:5]
	s_setprio 0
	s_barrier
	s_add_i32 s71, s71, 2
	s_add_u32 s25, s25, 0x100
	s_addc_u32 s26, s26, 0
	s_add_u32 s27, s27, 0x100
	s_addc_u32 s69, s69, 0
	s_add_u32 s0, s0, 0x100
	s_addc_u32 s1, s1, 0
	s_cmp_gt_u32 s71, 29
	s_cbranch_scc0 .LBB0_1191
.Lmy_kexit_8:
	s_and_b64 vcc, exec, s[64:65]
	s_cbranch_vccz .LBB0_1194
	s_barrier

; __device__ __forceinline__ const char* unitA(const Gemm& g, const Unit& u) { return (const char*)(g.A + (size_t)(u.z / g.zdiv) * g.sAhi + (size_t)(u.z % g.zdiv) * g.sAlo + (size_t)u.pm * BM * g.lda); }
; __device__ __forceinline__ const char* unitB(const Gemm& g, const Unit& u) { return (const char*)(g.Bt + (size_t)(u.z / g.zdiv) * g.sBhi + (size_t)(u.z % g.zdiv) * g.sBlo + (size_t)(u.pm / g.bdiv) * g.sBpm + (size_t)u.pn * BM * g.ldb); }
; #define PG8_STAGE(bufoff, gbase, voff) do { if constexpr (VAR != 1 && VAR != 3) { _Pragma("unroll") for (int _i = 0; _i < 2; ++_i) \
;         asm volatile("s_mov_b32 m0, %2\n\ts_nop 0\n\tglobal_load_lds_dwordx4 %0, %1" :: "v"((voff)[_i]), "s"((const char*)(gbase)), "s"(ldsbase + (unsigned)((bufoff) + _i * 8192)) : "memory", "m0"); } } while (0)
; #define PG8_LDA(dst, b, h) do { if constexpr (VAR < 2) _Pragma("unroll") for (int m = 0; m < 4; ++m) _Pragma("unroll") for (int k = 0; k < 2; ++k) dst[m][k] = *(const LAS bf16x8*)(lds + PG8_SA(b, h) + aoff + m * 2048 + k * 1024); } while (0)
; #define PG8_LDB(dst, b, h) do { if constexpr (VAR < 2) _Pragma("unroll") for (int n = 0; n < 2; ++n) _Pragma("unroll") for (int k = 0; k < 2; ++k) dst[n][k] = *(const LAS bf16x8*)(lds + PG8_SB(b, h) + boff + n * 2048 + k * 1024); } while (0)
; #define PG8_WAIT_V(n) asm volatile("s_waitcnt vmcnt(" #n ")" ::: "memory")
;     ...
;         const bool has_next = S.next(ui + 1, nxt);
;         const char* nA = has_next ? unitA(g, nxt) : cA; const char* nB = has_next ? unitB(g, nxt) : cB;
;         for (int t = 0; t < nt; t += 2) {
;             const bool last = (t == nt - 2);
;             const char* a1 = cA + (size_t)(t + 1) * kstep;
;             const char* a2 = last ? nA : cA + (size_t)(t + 2) * kstep; const char* b2 = last ? nB : cB + (size_t)(t + 2) * kstep;
;             const char* a3 = a2 + kstep; const char* b3 = b2 + kstep;
;             PG8_LDB(B0, 0, 0); PG8_LDB(B1, 0, 1); PG8_SCHED; PG8_LDA(At, 0, 0); PG8_STAGE(PG8_SA(1, 1), a1 + hstepA, voffA);
;             PG8_WAIT_V(8); PG8_WAIT_L(0); PG8_BAR; PG8_MMA(0, 0, At, B0); PG8_MMA(0, 1, At, B1); PG8_BAR; PG8_SCHED;
;             PG8_LDA(At, 0, 1); PG8_STAGE(PG8_SB(0, 0), b2, voffB); PG8_STAGE(PG8_SB(0, 1), b2 + hstepB, voffB); PG8_STAGE(PG8_SA(0, 0), a2, voffA);
;             PG8_WAIT_V(8); PG8_WAIT_L(0); PG8_BAR; PG8_MMA(1, 0, At, B0); PG8_MMA(1, 1, At, B1); PG8_BAR; PG8_SCHED;
.LBB0_1360:
	s_add_u32 s74, s60, 0x100
	s_addc_u32 s75, s61, 0
	s_add_u32 s76, s58, 0x100
	s_addc_u32 s77, s59, 0
	s_add_u32 s58, s60, 0x2b0080
	s_addc_u32 s59, s61, 0
	s_mov_b32 s78, -2
	s_waitcnt vmcnt(41)
	s_waitcnt vmcnt(40)
	s_waitcnt vmcnt(38)
	s_waitcnt vmcnt(35)
	s_waitcnt vmcnt(34)
	s_waitcnt vmcnt(32)
	ds_read_b128 v[130:133], v160
	ds_read_b128 v[134:137], v160 offset:1024
	ds_read_b128 v[142:145], v160 offset:2048
	ds_read_b128 v[146:149], v160 offset:3072
	ds_read_b128 v[150:153], v161
	ds_read_b128 v[166:169], v161 offset:1024
	ds_read_b128 v[170:173], v161 offset:2048
	ds_read_b128 v[174:177], v161 offset:3072
	s_cmpk_eq_i32 s78, 0xa8
	s_cselect_b32 s64, s12, s74
	s_cselect_b32 s65, s13, s75
	s_cselect_b32 s62, s56, s76
	s_cselect_b32 s63, s57, s77
	s_add_u32 s60, s64, 0x80
	s_addc_u32 s61, s65, 0
	ds_read_b128 v[178:181], v162
	ds_read_b128 v[182:185], v162 offset:1024
	ds_read_b128 v[186:189], v162 offset:2048
	ds_read_b128 v[190:193], v162 offset:3072
	ds_read_b128 v[194:197], v162 offset:4096
	ds_read_b128 v[198:201], v162 offset:5120
	ds_read_b128 v[202:205], v162 offset:6144
	ds_read_b128 v[206:209], v162 offset:7168
	s_mov_b32 m0, s69
	s_nop 0
	global_load_lds_dwordx4 v1, s[58:59]
	s_mov_b32 m0, s70
	s_nop 0
	global_load_lds_dwordx4 v155, s[58:59]
	s_waitcnt vmcnt(8)
	s_waitcnt lgkmcnt(0)
	s_barrier
	s_setprio 1
	v_mfma_f32_16x16x32_bf16 v[126:129], v[130:133], v[178:181], 0
	v_mfma_f32_16x16x32_bf16 v[122:125], v[142:145], v[178:181], 0
	v_mfma_f32_16x16x32_bf16 v[110:113], v[130:133], v[186:189], 0
	v_mfma_f32_16x16x32_bf16 v[106:109], v[142:145], v[186:189], 0
	v_mfma_f32_16x16x32_bf16 v[94:97], v[130:133], v[194:197], 0
	v_mfma_f32_16x16x32_bf16 v[90:93], v[142:145], v[194:197], 0
	v_mfma_f32_16x16x32_bf16 v[78:81], v[130:133], v[202:205], 0
	v_mfma_f32_16x16x32_bf16 v[74:77], v[142:145], v[202:205], 0
	v_mfma_f32_16x16x32_bf16 v[126:129], v[134:137], v[182:185], v[126:129]
	v_mfma_f32_16x16x32_bf16 v[122:125], v[146:149], v[182:185], v[122:125]
	v_mfma_f32_16x16x32_bf16 v[110:113], v[134:137], v[190:193], v[110:113]
	v_mfma_f32_16x16x32_bf16 v[106:109], v[146:149], v[190:193], v[106:109]
	v_mfma_f32_16x16x32_bf16 v[94:97], v[134:137], v[198:201], v[94:97]
	v_mfma_f32_16x16x32_bf16 v[90:93], v[146:149], v[198:201], v[90:93]
	v_mfma_f32_16x16x32_bf16 v[78:81], v[134:137], v[206:209], v[78:81]
	v_mfma_f32_16x16x32_bf16 v[74:77], v[146:149], v[206:209], v[74:77]
	v_mfma_f32_16x16x32_bf16 v[118:121], v[150:153], v[178:181], 0
	v_mfma_f32_16x16x32_bf16 v[114:117], v[170:173], v[178:181], 0
	v_mfma_f32_16x16x32_bf16 v[102:105], v[150:153], v[186:189], 0
	v_mfma_f32_16x16x32_bf16 v[98:101], v[170:173], v[186:189], 0
	v_mfma_f32_16x16x32_bf16 v[86:89], v[150:153], v[194:197], 0
	v_mfma_f32_16x16x32_bf16 v[82:85], v[170:173], v[194:197], 0
	v_mfma_f32_16x16x32_bf16 v[70:73], v[150:153], v[202:205], 0
	v_mfma_f32_16x16x32_bf16 v[66:69], v[170:173], v[202:205], 0
	v_mfma_f32_16x16x32_bf16 v[118:121], v[166:169], v[182:185], v[118:121]
	v_mfma_f32_16x16x32_bf16 v[114:117], v[174:177], v[182:185], v[114:117]
	v_mfma_f32_16x16x32_bf16 v[102:105], v[166:169], v[190:193], v[102:105]
	v_mfma_f32_16x16x32_bf16 v[98:101], v[174:177], v[190:193], v[98:101]
	v_mfma_f32_16x16x32_bf16 v[86:89], v[166:169], v[198:201], v[86:89]
	v_mfma_f32_16x16x32_bf16 v[82:85], v[174:177], v[198:201], v[82:85]
	v_mfma_f32_16x16x32_bf16 v[70:73], v[166:169], v[206:209], v[70:73]
	v_mfma_f32_16x16x32_bf16 v[66:69], v[174:177], v[206:209], v[66:69]
	s_setprio 0
	s_barrier
	ds_read_b128 v[178:181], v162 offset:16384
	ds_read_b128 v[182:185], v162 offset:17408
	ds_read_b128 v[186:189], v162 offset:18432
	ds_read_b128 v[190:193], v162 offset:19456
	ds_read_b128 v[194:197], v162 offset:20480
	ds_read_b128 v[198:201], v162 offset:21504
	ds_read_b128 v[202:205], v162 offset:22528
	ds_read_b128 v[206:209], v162 offset:23552
	s_mov_b32 m0, s19
	s_nop 0
	global_load_lds_dwordx4 v154, s[62:63]
	s_add_u32 s80, s62, 0x2b0000
	s_mov_b32 m0, s21
	s_nop 0
	global_load_lds_dwordx4 v156, s[62:63]
	s_addc_u32 s81, s63, 0
	s_mov_b32 m0, s23
	s_nop 0
	global_load_lds_dwordx4 v154, s[80:81]
	s_mov_b32 m0, s26
	s_nop 0
	global_load_lds_dwordx4 v156, s[80:81]
	s_mov_b32 m0, s17
	s_nop 0
	global_load_lds_dwordx4 v1, s[64:65]
	s_mov_b32 m0, s27
	s_nop 0
	global_load_lds_dwordx4 v155, s[64:65]
	s_waitcnt vmcnt(8)
	s_waitcnt lgkmcnt(0)
	s_barrier
	s_setprio 1
	v_mfma_f32_16x16x32_bf16 v[62:65], v[130:133], v[178:181], 0
	v_mfma_f32_16x16x32_bf16 v[58:61], v[142:145], v[178:181], 0
	v_mfma_f32_16x16x32_bf16 v[46:49], v[130:133], v[186:189], 0
	v_mfma_f32_16x16x32_bf16 v[42:45], v[142:145], v[186:189], 0
	v_mfma_f32_16x16x32_bf16 v[30:33], v[130:133], v[194:197], 0
	v_mfma_f32_16x16x32_bf16 v[26:29], v[142:145], v[194:197], 0
	v_mfma_f32_16x16x32_bf16 v[14:17], v[130:133], v[202:205], 0
	v_mfma_f32_16x16x32_bf16 v[10:13], v[142:145], v[202:205], 0
	v_mfma_f32_16x16x32_bf16 v[62:65], v[134:137], v[182:185], v[62:65]
	v_mfma_f32_16x16x32_bf16 v[58:61], v[146:149], v[182:185], v[58:61]
	v_mfma_f32_16x16x32_bf16 v[46:49], v[134:137], v[190:193], v[46:49]
	v_mfma_f32_16x16x32_bf16 v[42:45], v[146:149], v[190:193], v[42:45]
	v_mfma_f32_16x16x32_bf16 v[30:33], v[134:137], v[198:201], v[30:33]
	v_mfma_f32_16x16x32_bf16 v[26:29], v[146:149], v[198:201], v[26:29]
	v_mfma_f32_16x16x32_bf16 v[14:17], v[134:137], v[206:209], v[14:17]
	v_mfma_f32_16x16x32_bf16 v[10:13], v[146:149], v[206:209], v[10:13]
	v_mfma_f32_16x16x32_bf16 v[54:57], v[150:153], v[178:181], 0
	v_mfma_f32_16x16x32_bf16 v[50:53], v[170:173], v[178:181], 0
	v_mfma_f32_16x16x32_bf16 v[38:41], v[150:153], v[186:189], 0
	v_mfma_f32_16x16x32_bf16 v[34:37], v[170:173], v[186:189], 0
	v_mfma_f32_16x16x32_bf16 v[22:25], v[150:153], v[194:197], 0
	v_mfma_f32_16x16x32_bf16 v[18:21], v[170:173], v[194:197], 0
	v_mfma_f32_16x16x32_bf16 v[6:9], v[150:153], v[202:205], 0
	v_mfma_f32_16x16x32_bf16 v[2:5], v[170:173], v[202:205], 0
	v_mfma_f32_16x16x32_bf16 v[54:57], v[166:169], v[182:185], v[54:57]
	v_mfma_f32_16x16x32_bf16 v[50:53], v[174:177], v[182:185], v[50:53]
	v_mfma_f32_16x16x32_bf16 v[38:41], v[166:169], v[190:193], v[38:41]
	v_mfma_f32_16x16x32_bf16 v[34:37], v[174:177], v[190:193], v[34:37]
	v_mfma_f32_16x16x32_bf16 v[22:25], v[166:169], v[198:201], v[22:25]
	v_mfma_f32_16x16x32_bf16 v[18:21], v[174:177], v[198:201], v[18:21]
	v_mfma_f32_16x16x32_bf16 v[6:9], v[166:169], v[206:209], v[6:9]
	v_mfma_f32_16x16x32_bf16 v[2:5], v[174:177], v[206:209], v[2:5]
	s_setprio 0
	s_barrier
; #define PG8_STAGE(bufoff, gbase, voff) do { if constexpr (VAR != 1 && VAR != 3) { _Pragma("unroll") for (int _i = 0; _i < 2; ++_i) \
;         asm volatile("s_mov_b32 m0, %2\n\ts_nop 0\n\tglobal_load_lds_dwordx4 %0, %1" :: "v"((voff)[_i]), "s"((const char*)(gbase)), "s"(ldsbase + (unsigned)((bufoff) + _i * 8192)) : "memory", "m0"); } } while (0)
; #define PG8_LDA(dst, b, h) do { if constexpr (VAR < 2) _Pragma("unroll") for (int m = 0; m < 4; ++m) _Pragma("unroll") for (int k = 0; k < 2; ++k) dst[m][k] = *(const LAS bf16x8*)(lds + PG8_SA(b, h) + aoff + m * 2048 + k * 1024); } while (0)
; #define PG8_LDB(dst, b, h) do { if constexpr (VAR < 2) _Pragma("unroll") for (int n = 0; n < 2; ++n) _Pragma("unroll") for (int k = 0; k < 2; ++k) dst[n][k] = *(const LAS bf16x8*)(lds + PG8_SB(b, h) + boff + n * 2048 + k * 1024); } while (0)
; #define PG8_WAIT_V(n) asm volatile("s_waitcnt vmcnt(" #n ")" ::: "memory")
; #define PG8_WAIT_L(n) asm volatile("s_waitcnt lgkmcnt(" #n ")" ::: "memory")
; #define PG8_BAR do { if constexpr (VAR != 3) __builtin_amdgcn_s_barrier(); } while (0)
; #define PG8_SCHED __builtin_amdgcn_sched_barrier(0)
;     ...
;             PG8_LDB(B0, 1, 0); PG8_LDB(B1, 1, 1); PG8_SCHED; PG8_LDA(At, 1, 0); PG8_STAGE(PG8_SA(0, 1), a2 + hstepA, voffA);
;             PG8_WAIT_V(8); PG8_WAIT_L(0); PG8_BAR; PG8_MMA(0, 0, At, B0); PG8_MMA(0, 1, At, B1); PG8_BAR; PG8_SCHED;
;             PG8_LDA(At, 1, 1); PG8_STAGE(PG8_SB(1, 0), b3, voffB); PG8_STAGE(PG8_SB(1, 1), b3 + hstepB, voffB); PG8_STAGE(PG8_SA(1, 0), a3, voffA);
;             PG8_WAIT_V(8); PG8_WAIT_L(0); PG8_BAR; PG8_MMA(1, 0, At, B0); PG8_MMA(1, 1, At, B1); PG8_BAR; PG8_SCHED;
	ds_read_b128 v[130:133], v163
	ds_read_b128 v[134:137], v163 offset:1024
	ds_read_b128 v[142:145], v163 offset:2048
	ds_read_b128 v[146:149], v163 offset:3072
	ds_read_b128 v[150:153], v164
	ds_read_b128 v[166:169], v164 offset:1024
	ds_read_b128 v[170:173], v164 offset:2048
	ds_read_b128 v[174:177], v164 offset:3072
	ds_read_b128 v[178:181], v162 offset:32768
	ds_read_b128 v[182:185], v162 offset:33792
	ds_read_b128 v[186:189], v162 offset:34816
	ds_read_b128 v[190:193], v162 offset:35840
	ds_read_b128 v[194:197], v162 offset:36864
	ds_read_b128 v[198:201], v162 offset:37888
	ds_read_b128 v[202:205], v162 offset:38912
	ds_read_b128 v[206:209], v162 offset:39936
	s_add_u32 s64, s64, 0x2b0000
	s_addc_u32 s65, s65, 0
	s_mov_b32 m0, s28
	s_nop 0
	global_load_lds_dwordx4 v1, s[64:65]
	s_mov_b32 m0, s29
	s_nop 0
	global_load_lds_dwordx4 v155, s[64:65]
	s_waitcnt vmcnt(8)
	s_waitcnt lgkmcnt(0)
	s_barrier
	s_setprio 1
	v_mfma_f32_16x16x32_bf16 v[126:129], v[130:133], v[178:181], v[126:129]
	v_mfma_f32_16x16x32_bf16 v[122:125], v[142:145], v[178:181], v[122:125]
	v_mfma_f32_16x16x32_bf16 v[110:113], v[130:133], v[186:189], v[110:113]
	v_mfma_f32_16x16x32_bf16 v[106:109], v[142:145], v[186:189], v[106:109]
	v_mfma_f32_16x16x32_bf16 v[94:97], v[130:133], v[194:197], v[94:97]
	v_mfma_f32_16x16x32_bf16 v[90:93], v[142:145], v[194:197], v[90:93]
	v_mfma_f32_16x16x32_bf16 v[78:81], v[130:133], v[202:205], v[78:81]
	v_mfma_f32_16x16x32_bf16 v[74:77], v[142:145], v[202:205], v[74:77]
	v_mfma_f32_16x16x32_bf16 v[126:129], v[134:137], v[182:185], v[126:129]
	v_mfma_f32_16x16x32_bf16 v[122:125], v[146:149], v[182:185], v[122:125]
	v_mfma_f32_16x16x32_bf16 v[110:113], v[134:137], v[190:193], v[110:113]
	v_mfma_f32_16x16x32_bf16 v[106:109], v[146:149], v[190:193], v[106:109]
	v_mfma_f32_16x16x32_bf16 v[94:97], v[134:137], v[198:201], v[94:97]
	v_mfma_f32_16x16x32_bf16 v[90:93], v[146:149], v[198:201], v[90:93]
	v_mfma_f32_16x16x32_bf16 v[78:81], v[134:137], v[206:209], v[78:81]
	v_mfma_f32_16x16x32_bf16 v[74:77], v[146:149], v[206:209], v[74:77]
	v_mfma_f32_16x16x32_bf16 v[118:121], v[150:153], v[178:181], v[118:121]
	v_mfma_f32_16x16x32_bf16 v[114:117], v[170:173], v[178:181], v[114:117]
	v_mfma_f32_16x16x32_bf16 v[102:105], v[150:153], v[186:189], v[102:105]
	v_mfma_f32_16x16x32_bf16 v[98:101], v[170:173], v[186:189], v[98:101]
	v_mfma_f32_16x16x32_bf16 v[86:89], v[150:153], v[194:197], v[86:89]
	v_mfma_f32_16x16x32_bf16 v[82:85], v[170:173], v[194:197], v[82:85]
	v_mfma_f32_16x16x32_bf16 v[70:73], v[150:153], v[202:205], v[70:73]
	v_mfma_f32_16x16x32_bf16 v[66:69], v[170:173], v[202:205], v[66:69]
	v_mfma_f32_16x16x32_bf16 v[118:121], v[166:169], v[182:185], v[118:121]
	v_mfma_f32_16x16x32_bf16 v[114:117], v[174:177], v[182:185], v[114:117]
	v_mfma_f32_16x16x32_bf16 v[102:105], v[166:169], v[190:193], v[102:105]
	v_mfma_f32_16x16x32_bf16 v[98:101], v[174:177], v[190:193], v[98:101]
	v_mfma_f32_16x16x32_bf16 v[86:89], v[166:169], v[198:201], v[86:89]
	v_mfma_f32_16x16x32_bf16 v[82:85], v[174:177], v[198:201], v[82:85]
	v_mfma_f32_16x16x32_bf16 v[70:73], v[166:169], v[206:209], v[70:73]
	v_mfma_f32_16x16x32_bf16 v[66:69], v[174:177], v[206:209], v[66:69]
	s_setprio 0
	s_barrier
	ds_read_b128 v[178:181], v162 offset:49152
	ds_read_b128 v[182:185], v162 offset:50176
	ds_read_b128 v[186:189], v162 offset:51200
	ds_read_b128 v[190:193], v162 offset:52224
	ds_read_b128 v[194:197], v162 offset:53248
	ds_read_b128 v[198:201], v162 offset:54272
	ds_read_b128 v[202:205], v162 offset:55296
	ds_read_b128 v[206:209], v162 offset:56320
	s_add_u32 s64, s62, 0x80
	s_addc_u32 s65, s63, 0
	s_mov_b32 m0, s30
	s_nop 0
	global_load_lds_dwordx4 v154, s[64:65]
	s_add_u32 s62, s62, 0x2b0080
	s_mov_b32 m0, s31
	s_nop 0
	global_load_lds_dwordx4 v156, s[64:65]
	s_addc_u32 s63, s63, 0
	s_mov_b32 m0, s67
	s_nop 0
	global_load_lds_dwordx4 v154, s[62:63]
	s_mov_b32 m0, s68
	s_nop 0
	global_load_lds_dwordx4 v156, s[62:63]
	s_mov_b32 m0, s33
	s_nop 0
	global_load_lds_dwordx4 v1, s[60:61]
	s_mov_b32 m0, s66
	s_nop 0
	global_load_lds_dwordx4 v155, s[60:61]
	s_waitcnt vmcnt(8)
	s_waitcnt lgkmcnt(0)
	s_barrier
	s_setprio 1
	v_mfma_f32_16x16x32_bf16 v[62:65], v[130:133], v[178:181], v[62:65]
	v_mfma_f32_16x16x32_bf16 v[58:61], v[142:145], v[178:181], v[58:61]
	v_mfma_f32_16x16x32_bf16 v[46:49], v[130:133], v[186:189], v[46:49]
	v_mfma_f32_16x16x32_bf16 v[42:45], v[142:145], v[186:189], v[42:45]
	v_mfma_f32_16x16x32_bf16 v[30:33], v[130:133], v[194:197], v[30:33]
	v_mfma_f32_16x16x32_bf16 v[26:29], v[142:145], v[194:197], v[26:29]
	v_mfma_f32_16x16x32_bf16 v[14:17], v[130:133], v[202:205], v[14:17]
	v_mfma_f32_16x16x32_bf16 v[10:13], v[142:145], v[202:205], v[10:13]
	v_mfma_f32_16x16x32_bf16 v[62:65], v[134:137], v[182:185], v[62:65]
	v_mfma_f32_16x16x32_bf16 v[58:61], v[146:149], v[182:185], v[58:61]
	v_mfma_f32_16x16x32_bf16 v[46:49], v[134:137], v[190:193], v[46:49]
	v_mfma_f32_16x16x32_bf16 v[42:45], v[146:149], v[190:193], v[42:45]
	v_mfma_f32_16x16x32_bf16 v[30:33], v[134:137], v[198:201], v[30:33]
	v_mfma_f32_16x16x32_bf16 v[26:29], v[146:149], v[198:201], v[26:29]
	v_mfma_f32_16x16x32_bf16 v[14:17], v[134:137], v[206:209], v[14:17]
	v_mfma_f32_16x16x32_bf16 v[10:13], v[146:149], v[206:209], v[10:13]
	v_mfma_f32_16x16x32_bf16 v[54:57], v[150:153], v[178:181], v[54:57]
	v_mfma_f32_16x16x32_bf16 v[50:53], v[170:173], v[178:181], v[50:53]
	v_mfma_f32_16x16x32_bf16 v[38:41], v[150:153], v[186:189], v[38:41]
	v_mfma_f32_16x16x32_bf16 v[34:37], v[170:173], v[186:189], v[34:37]
	v_mfma_f32_16x16x32_bf16 v[22:25], v[150:153], v[194:197], v[22:25]
	v_mfma_f32_16x16x32_bf16 v[18:21], v[170:173], v[194:197], v[18:21]
	v_mfma_f32_16x16x32_bf16 v[6:9], v[150:153], v[202:205], v[6:9]
	v_mfma_f32_16x16x32_bf16 v[2:5], v[170:173], v[202:205], v[2:5]
	v_mfma_f32_16x16x32_bf16 v[54:57], v[166:169], v[182:185], v[54:57]
	v_mfma_f32_16x16x32_bf16 v[50:53], v[174:177], v[182:185], v[50:53]
	v_mfma_f32_16x16x32_bf16 v[38:41], v[166:169], v[190:193], v[38:41]
	v_mfma_f32_16x16x32_bf16 v[34:37], v[174:177], v[190:193], v[34:37]
	v_mfma_f32_16x16x32_bf16 v[22:25], v[166:169], v[198:201], v[22:25]
	v_mfma_f32_16x16x32_bf16 v[18:21], v[174:177], v[198:201], v[18:21]
	v_mfma_f32_16x16x32_bf16 v[6:9], v[166:169], v[206:209], v[6:9]
	v_mfma_f32_16x16x32_bf16 v[2:5], v[174:177], v[206:209], v[2:5]
	s_setprio 0
	s_barrier
	s_add_i32 s78, s78, 2
	s_add_u32 s74, s74, 0x100
	s_addc_u32 s75, s75, 0
	s_add_u32 s76, s76, 0x100
	s_addc_u32 s77, s77, 0
	s_add_u32 s58, s58, 0x100
	s_addc_u32 s59, s59, 0
	s_cmpk_gt_u32 s78, 0xa9
	s_cbranch_scc0 .LBB0_1361
	s_branch .Lmy_kexit_9
; #define PG8_STAGE(bufoff, gbase, voff) do { if constexpr (VAR != 1 && VAR != 3) { _Pragma("unroll") for (int _i = 0; _i < 2; ++_i) \
;         asm volatile("s_mov_b32 m0, %2\n\ts_nop 0\n\tglobal_load_lds_dwordx4 %0, %1" :: "v"((voff)[_i]), "s"((const char*)(gbase)), "s"(ldsbase + (unsigned)((bufoff) + _i * 8192)) : "memory", "m0"); } } while (0)
; #define PG8_LDA(dst, b, h) do { if constexpr (VAR < 2) _Pragma("unroll") for (int m = 0; m < 4; ++m) _Pragma("unroll") for (int k = 0; k < 2; ++k) dst[m][k] = *(const LAS bf16x8*)(lds + PG8_SA(b, h) + aoff + m * 2048 + k * 1024); } while (0)
; #define PG8_LDB(dst, b, h) do { if constexpr (VAR < 2) _Pragma("unroll") for (int n = 0; n < 2; ++n) _Pragma("unroll") for (int k = 0; k < 2; ++k) dst[n][k] = *(const LAS bf16x8*)(lds + PG8_SB(b, h) + boff + n * 2048 + k * 1024); } while (0)
; #define PG8_WAIT_V(n) asm volatile("s_waitcnt vmcnt(" #n ")" ::: "memory")
; #define PG8_WAIT_L(n) asm volatile("s_waitcnt lgkmcnt(" #n ")" ::: "memory")
; #define PG8_BAR do { if constexpr (VAR != 3) __builtin_amdgcn_s_barrier(); } while (0)
; #define PG8_SCHED __builtin_amdgcn_sched_barrier(0)
;     ...
;             PG8_LDB(B0, 0, 0); PG8_LDB(B1, 0, 1); PG8_SCHED; PG8_LDA(At, 0, 0); PG8_STAGE(PG8_SA(1, 1), a1 + hstepA, voffA);
;             PG8_WAIT_V(8); PG8_WAIT_L(0); PG8_BAR; PG8_MMA(0, 0, At, B0); PG8_MMA(0, 1, At, B1); PG8_BAR; PG8_SCHED;
;             PG8_LDA(At, 0, 1); PG8_STAGE(PG8_SB(0, 0), b2, voffB); PG8_STAGE(PG8_SB(0, 1), b2 + hstepB, voffB); PG8_STAGE(PG8_SA(0, 0), a2, voffA);
;             PG8_WAIT_V(8); PG8_WAIT_L(0); PG8_BAR; PG8_MMA(1, 0, At, B0); PG8_MMA(1, 1, At, B1); PG8_BAR; PG8_SCHED;
.LBB0_1361:
	ds_read_b128 v[130:133], v160
	ds_read_b128 v[134:137], v160 offset:1024
	ds_read_b128 v[142:145], v160 offset:2048
	ds_read_b128 v[146:149], v160 offset:3072
	ds_read_b128 v[150:153], v161
	ds_read_b128 v[166:169], v161 offset:1024
	ds_read_b128 v[170:173], v161 offset:2048
	ds_read_b128 v[174:177], v161 offset:3072
	s_cmpk_eq_i32 s78, 0xa8
	s_cselect_b32 s64, s12, s74
	s_cselect_b32 s65, s13, s75
	s_cselect_b32 s62, s56, s76
	s_cselect_b32 s63, s57, s77
	s_add_u32 s60, s64, 0x80
	s_addc_u32 s61, s65, 0
	ds_read_b128 v[178:181], v162
	ds_read_b128 v[182:185], v162 offset:1024
	ds_read_b128 v[186:189], v162 offset:2048
	ds_read_b128 v[190:193], v162 offset:3072
	ds_read_b128 v[194:197], v162 offset:4096
	ds_read_b128 v[198:201], v162 offset:5120
	ds_read_b128 v[202:205], v162 offset:6144
	ds_read_b128 v[206:209], v162 offset:7168
	s_mov_b32 m0, s69
	s_nop 0
	global_load_lds_dwordx4 v1, s[58:59]
	s_mov_b32 m0, s70
	s_nop 0
	global_load_lds_dwordx4 v155, s[58:59]
	s_waitcnt vmcnt(8)
	s_waitcnt lgkmcnt(0)
	s_barrier
	s_setprio 1
	v_mfma_f32_16x16x32_bf16 v[126:129], v[130:133], v[178:181], v[126:129]
	v_mfma_f32_16x16x32_bf16 v[122:125], v[142:145], v[178:181], v[122:125]
	v_mfma_f32_16x16x32_bf16 v[110:113], v[130:133], v[186:189], v[110:113]
	v_mfma_f32_16x16x32_bf16 v[106:109], v[142:145], v[186:189], v[106:109]
	v_mfma_f32_16x16x32_bf16 v[94:97], v[130:133], v[194:197], v[94:97]
	v_mfma_f32_16x16x32_bf16 v[90:93], v[142:145], v[194:197], v[90:93]
	v_mfma_f32_16x16x32_bf16 v[78:81], v[130:133], v[202:205], v[78:81]
	v_mfma_f32_16x16x32_bf16 v[74:77], v[142:145], v[202:205], v[74:77]
	v_mfma_f32_16x16x32_bf16 v[126:129], v[134:137], v[182:185], v[126:129]
	v_mfma_f32_16x16x32_bf16 v[122:125], v[146:149], v[182:185], v[122:125]
	v_mfma_f32_16x16x32_bf16 v[110:113], v[134:137], v[190:193], v[110:113]
	v_mfma_f32_16x16x32_bf16 v[106:109], v[146:149], v[190:193], v[106:109]
	v_mfma_f32_16x16x32_bf16 v[94:97], v[134:137], v[198:201], v[94:97]
	v_mfma_f32_16x16x32_bf16 v[90:93], v[146:149], v[198:201], v[90:93]
	v_mfma_f32_16x16x32_bf16 v[78:81], v[134:137], v[206:209], v[78:81]
	v_mfma_f32_16x16x32_bf16 v[74:77], v[146:149], v[206:209], v[74:77]
	v_mfma_f32_16x16x32_bf16 v[118:121], v[150:153], v[178:181], v[118:121]
	v_mfma_f32_16x16x32_bf16 v[114:117], v[170:173], v[178:181], v[114:117]
	v_mfma_f32_16x16x32_bf16 v[102:105], v[150:153], v[186:189], v[102:105]
	v_mfma_f32_16x16x32_bf16 v[98:101], v[170:173], v[186:189], v[98:101]
	v_mfma_f32_16x16x32_bf16 v[86:89], v[150:153], v[194:197], v[86:89]
	v_mfma_f32_16x16x32_bf16 v[82:85], v[170:173], v[194:197], v[82:85]
	v_mfma_f32_16x16x32_bf16 v[70:73], v[150:153], v[202:205], v[70:73]
	v_mfma_f32_16x16x32_bf16 v[66:69], v[170:173], v[202:205], v[66:69]
	v_mfma_f32_16x16x32_bf16 v[118:121], v[166:169], v[182:185], v[118:121]
	v_mfma_f32_16x16x32_bf16 v[114:117], v[174:177], v[182:185], v[114:117]
	v_mfma_f32_16x16x32_bf16 v[102:105], v[166:169], v[190:193], v[102:105]
	v_mfma_f32_16x16x32_bf16 v[98:101], v[174:177], v[190:193], v[98:101]
	v_mfma_f32_16x16x32_bf16 v[86:89], v[166:169], v[198:201], v[86:89]
	v_mfma_f32_16x16x32_bf16 v[82:85], v[174:177], v[198:201], v[82:85]
	v_mfma_f32_16x16x32_bf16 v[70:73], v[166:169], v[206:209], v[70:73]
	v_mfma_f32_16x16x32_bf16 v[66:69], v[174:177], v[206:209], v[66:69]
	s_setprio 0
	s_barrier
	ds_read_b128 v[178:181], v162 offset:16384
	ds_read_b128 v[182:185], v162 offset:17408
	ds_read_b128 v[186:189], v162 offset:18432
	ds_read_b128 v[190:193], v162 offset:19456
	ds_read_b128 v[194:197], v162 offset:20480
	ds_read_b128 v[198:201], v162 offset:21504
	ds_read_b128 v[202:205], v162 offset:22528
	ds_read_b128 v[206:209], v162 offset:23552
	s_mov_b32 m0, s19
	s_nop 0
	global_load_lds_dwordx4 v154, s[62:63]
	s_add_u32 s80, s62, 0x2b0000
	s_mov_b32 m0, s21
	s_nop 0
	global_load_lds_dwordx4 v156, s[62:63]
	s_addc_u32 s81, s63, 0
	s_mov_b32 m0, s23
	s_nop 0
	global_load_lds_dwordx4 v154, s[80:81]
	s_mov_b32 m0, s26
	s_nop 0
	global_load_lds_dwordx4 v156, s[80:81]
	s_mov_b32 m0, s17
	s_nop 0
	global_load_lds_dwordx4 v1, s[64:65]
	s_mov_b32 m0, s27
	s_nop 0
	global_load_lds_dwordx4 v155, s[64:65]
	s_waitcnt vmcnt(8)
	s_waitcnt lgkmcnt(0)
	s_barrier
	s_setprio 1
	v_mfma_f32_16x16x32_bf16 v[62:65], v[130:133], v[178:181], v[62:65]
	v_mfma_f32_16x16x32_bf16 v[58:61], v[142:145], v[178:181], v[58:61]
	v_mfma_f32_16x16x32_bf16 v[46:49], v[130:133], v[186:189], v[46:49]
	v_mfma_f32_16x16x32_bf16 v[42:45], v[142:145], v[186:189], v[42:45]
	v_mfma_f32_16x16x32_bf16 v[30:33], v[130:133], v[194:197], v[30:33]
	v_mfma_f32_16x16x32_bf16 v[26:29], v[142:145], v[194:197], v[26:29]
	v_mfma_f32_16x16x32_bf16 v[14:17], v[130:133], v[202:205], v[14:17]
	v_mfma_f32_16x16x32_bf16 v[10:13], v[142:145], v[202:205], v[10:13]
	v_mfma_f32_16x16x32_bf16 v[62:65], v[134:137], v[182:185], v[62:65]
	v_mfma_f32_16x16x32_bf16 v[58:61], v[146:149], v[182:185], v[58:61]
	v_mfma_f32_16x16x32_bf16 v[46:49], v[134:137], v[190:193], v[46:49]
	v_mfma_f32_16x16x32_bf16 v[42:45], v[146:149], v[190:193], v[42:45]
	v_mfma_f32_16x16x32_bf16 v[30:33], v[134:137], v[198:201], v[30:33]
	v_mfma_f32_16x16x32_bf16 v[26:29], v[146:149], v[198:201], v[26:29]
	v_mfma_f32_16x16x32_bf16 v[14:17], v[134:137], v[206:209], v[14:17]
	v_mfma_f32_16x16x32_bf16 v[10:13], v[146:149], v[206:209], v[10:13]
	v_mfma_f32_16x16x32_bf16 v[54:57], v[150:153], v[178:181], v[54:57]
	v_mfma_f32_16x16x32_bf16 v[50:53], v[170:173], v[178:181], v[50:53]
	v_mfma_f32_16x16x32_bf16 v[38:41], v[150:153], v[186:189], v[38:41]
	v_mfma_f32_16x16x32_bf16 v[34:37], v[170:173], v[186:189], v[34:37]
	v_mfma_f32_16x16x32_bf16 v[22:25], v[150:153], v[194:197], v[22:25]
	v_mfma_f32_16x16x32_bf16 v[18:21], v[170:173], v[194:197], v[18:21]
	v_mfma_f32_16x16x32_bf16 v[6:9], v[150:153], v[202:205], v[6:9]
	v_mfma_f32_16x16x32_bf16 v[2:5], v[170:173], v[202:205], v[2:5]
	v_mfma_f32_16x16x32_bf16 v[54:57], v[166:169], v[182:185], v[54:57]
	v_mfma_f32_16x16x32_bf16 v[50:53], v[174:177], v[182:185], v[50:53]
	v_mfma_f32_16x16x32_bf16 v[38:41], v[166:169], v[190:193], v[38:41]
	v_mfma_f32_16x16x32_bf16 v[34:37], v[174:177], v[190:193], v[34:37]
	v_mfma_f32_16x16x32_bf16 v[22:25], v[166:169], v[198:201], v[22:25]
	v_mfma_f32_16x16x32_bf16 v[18:21], v[174:177], v[198:201], v[18:21]
	v_mfma_f32_16x16x32_bf16 v[6:9], v[166:169], v[206:209], v[6:9]
	v_mfma_f32_16x16x32_bf16 v[2:5], v[174:177], v[206:209], v[2:5]
	s_setprio 0
	s_barrier
; #define PG8_STAGE(bufoff, gbase, voff) do { if constexpr (VAR != 1 && VAR != 3) { _Pragma("unroll") for (int _i = 0; _i < 2; ++_i) \
;         asm volatile("s_mov_b32 m0, %2\n\ts_nop 0\n\tglobal_load_lds_dwordx4 %0, %1" :: "v"((voff)[_i]), "s"((const char*)(gbase)), "s"(ldsbase + (unsigned)((bufoff) + _i * 8192)) : "memory", "m0"); } } while (0)
; #define PG8_LDA(dst, b, h) do { if constexpr (VAR < 2) _Pragma("unroll") for (int m = 0; m < 4; ++m) _Pragma("unroll") for (int k = 0; k < 2; ++k) dst[m][k] = *(const LAS bf16x8*)(lds + PG8_SA(b, h) + aoff + m * 2048 + k * 1024); } while (0)
; #define PG8_LDB(dst, b, h) do { if constexpr (VAR < 2) _Pragma("unroll") for (int n = 0; n < 2; ++n) _Pragma("unroll") for (int k = 0; k < 2; ++k) dst[n][k] = *(const LAS bf16x8*)(lds + PG8_SB(b, h) + boff + n * 2048 + k * 1024); } while (0)
; #define PG8_WAIT_V(n) asm volatile("s_waitcnt vmcnt(" #n ")" ::: "memory")
; #define PG8_WAIT_L(n) asm volatile("s_waitcnt lgkmcnt(" #n ")" ::: "memory")
; #define PG8_BAR do { if constexpr (VAR != 3) __builtin_amdgcn_s_barrier(); } while (0)
; #define PG8_SCHED __builtin_amdgcn_sched_barrier(0)
;     ...
;             PG8_LDB(B0, 1, 0); PG8_LDB(B1, 1, 1); PG8_SCHED; PG8_LDA(At, 1, 0); PG8_STAGE(PG8_SA(0, 1), a2 + hstepA, voffA);
;             PG8_WAIT_V(8); PG8_WAIT_L(0); PG8_BAR; PG8_MMA(0, 0, At, B0); PG8_MMA(0, 1, At, B1); PG8_BAR; PG8_SCHED;
;             PG8_LDA(At, 1, 1); PG8_STAGE(PG8_SB(1, 0), b3, voffB); PG8_STAGE(PG8_SB(1, 1), b3 + hstepB, voffB); PG8_STAGE(PG8_SA(1, 0), a3, voffA);
;             PG8_WAIT_V(8); PG8_WAIT_L(0); PG8_BAR; PG8_MMA(1, 0, At, B0); PG8_MMA(1, 1, At, B1); PG8_BAR; PG8_SCHED;
;         }
;         if (wr == 0) PG8_BAR;
	ds_read_b128 v[130:133], v163
	ds_read_b128 v[134:137], v163 offset:1024
	ds_read_b128 v[142:145], v163 offset:2048
	ds_read_b128 v[146:149], v163 offset:3072
	ds_read_b128 v[150:153], v164
	ds_read_b128 v[166:169], v164 offset:1024
	ds_read_b128 v[170:173], v164 offset:2048
	ds_read_b128 v[174:177], v164 offset:3072
	ds_read_b128 v[178:181], v162 offset:32768
	ds_read_b128 v[182:185], v162 offset:33792
	ds_read_b128 v[186:189], v162 offset:34816
	ds_read_b128 v[190:193], v162 offset:35840
	ds_read_b128 v[194:197], v162 offset:36864
	ds_read_b128 v[198:201], v162 offset:37888
	ds_read_b128 v[202:205], v162 offset:38912
	ds_read_b128 v[206:209], v162 offset:39936
	s_add_u32 s64, s64, 0x2b0000
	s_addc_u32 s65, s65, 0
	s_mov_b32 m0, s28
	s_nop 0
	global_load_lds_dwordx4 v1, s[64:65]
	s_mov_b32 m0, s29
	s_nop 0
	global_load_lds_dwordx4 v155, s[64:65]
	s_waitcnt vmcnt(8)
	s_waitcnt lgkmcnt(0)
	s_barrier
	s_setprio 1
	v_mfma_f32_16x16x32_bf16 v[126:129], v[130:133], v[178:181], v[126:129]
	v_mfma_f32_16x16x32_bf16 v[122:125], v[142:145], v[178:181], v[122:125]
	v_mfma_f32_16x16x32_bf16 v[110:113], v[130:133], v[186:189], v[110:113]
	v_mfma_f32_16x16x32_bf16 v[106:109], v[142:145], v[186:189], v[106:109]
	v_mfma_f32_16x16x32_bf16 v[94:97], v[130:133], v[194:197], v[94:97]
	v_mfma_f32_16x16x32_bf16 v[90:93], v[142:145], v[194:197], v[90:93]
	v_mfma_f32_16x16x32_bf16 v[78:81], v[130:133], v[202:205], v[78:81]
	v_mfma_f32_16x16x32_bf16 v[74:77], v[142:145], v[202:205], v[74:77]
	v_mfma_f32_16x16x32_bf16 v[126:129], v[134:137], v[182:185], v[126:129]
	v_mfma_f32_16x16x32_bf16 v[122:125], v[146:149], v[182:185], v[122:125]
	v_mfma_f32_16x16x32_bf16 v[110:113], v[134:137], v[190:193], v[110:113]
	v_mfma_f32_16x16x32_bf16 v[106:109], v[146:149], v[190:193], v[106:109]
	v_mfma_f32_16x16x32_bf16 v[94:97], v[134:137], v[198:201], v[94:97]
	v_mfma_f32_16x16x32_bf16 v[90:93], v[146:149], v[198:201], v[90:93]
	v_mfma_f32_16x16x32_bf16 v[78:81], v[134:137], v[206:209], v[78:81]
	v_mfma_f32_16x16x32_bf16 v[74:77], v[146:149], v[206:209], v[74:77]
	v_mfma_f32_16x16x32_bf16 v[118:121], v[150:153], v[178:181], v[118:121]
	v_mfma_f32_16x16x32_bf16 v[114:117], v[170:173], v[178:181], v[114:117]
	v_mfma_f32_16x16x32_bf16 v[102:105], v[150:153], v[186:189], v[102:105]
	v_mfma_f32_16x16x32_bf16 v[98:101], v[170:173], v[186:189], v[98:101]
	v_mfma_f32_16x16x32_bf16 v[86:89], v[150:153], v[194:197], v[86:89]
	v_mfma_f32_16x16x32_bf16 v[82:85], v[170:173], v[194:197], v[82:85]
	v_mfma_f32_16x16x32_bf16 v[70:73], v[150:153], v[202:205], v[70:73]
	v_mfma_f32_16x16x32_bf16 v[66:69], v[170:173], v[202:205], v[66:69]
	v_mfma_f32_16x16x32_bf16 v[118:121], v[166:169], v[182:185], v[118:121]
	v_mfma_f32_16x16x32_bf16 v[114:117], v[174:177], v[182:185], v[114:117]
	v_mfma_f32_16x16x32_bf16 v[102:105], v[166:169], v[190:193], v[102:105]
	v_mfma_f32_16x16x32_bf16 v[98:101], v[174:177], v[190:193], v[98:101]
	v_mfma_f32_16x16x32_bf16 v[86:89], v[166:169], v[198:201], v[86:89]
	v_mfma_f32_16x16x32_bf16 v[82:85], v[174:177], v[198:201], v[82:85]
	v_mfma_f32_16x16x32_bf16 v[70:73], v[166:169], v[206:209], v[70:73]
	v_mfma_f32_16x16x32_bf16 v[66:69], v[174:177], v[206:209], v[66:69]
	s_setprio 0
	s_barrier
	ds_read_b128 v[178:181], v162 offset:49152
	ds_read_b128 v[182:185], v162 offset:50176
	ds_read_b128 v[186:189], v162 offset:51200
	ds_read_b128 v[190:193], v162 offset:52224
	ds_read_b128 v[194:197], v162 offset:53248
	ds_read_b128 v[198:201], v162 offset:54272
	ds_read_b128 v[202:205], v162 offset:55296
	ds_read_b128 v[206:209], v162 offset:56320
	s_add_u32 s64, s62, 0x80
	s_addc_u32 s65, s63, 0
	s_mov_b32 m0, s30
	s_nop 0
	global_load_lds_dwordx4 v154, s[64:65]
	s_add_u32 s62, s62, 0x2b0080
	s_mov_b32 m0, s31
	s_nop 0
	global_load_lds_dwordx4 v156, s[64:65]
	s_addc_u32 s63, s63, 0
	s_mov_b32 m0, s67
	s_nop 0
	global_load_lds_dwordx4 v154, s[62:63]
	s_mov_b32 m0, s68
	s_nop 0
	global_load_lds_dwordx4 v156, s[62:63]
	s_mov_b32 m0, s33
	s_nop 0
	global_load_lds_dwordx4 v1, s[60:61]
	s_mov_b32 m0, s66
	s_nop 0
	global_load_lds_dwordx4 v155, s[60:61]
	s_waitcnt vmcnt(8)
	s_waitcnt lgkmcnt(0)
	s_barrier
	s_setprio 1
	v_mfma_f32_16x16x32_bf16 v[62:65], v[130:133], v[178:181], v[62:65]
	v_mfma_f32_16x16x32_bf16 v[58:61], v[142:145], v[178:181], v[58:61]
	v_mfma_f32_16x16x32_bf16 v[46:49], v[130:133], v[186:189], v[46:49]
	v_mfma_f32_16x16x32_bf16 v[42:45], v[142:145], v[186:189], v[42:45]
	v_mfma_f32_16x16x32_bf16 v[30:33], v[130:133], v[194:197], v[30:33]
	v_mfma_f32_16x16x32_bf16 v[26:29], v[142:145], v[194:197], v[26:29]
	v_mfma_f32_16x16x32_bf16 v[14:17], v[130:133], v[202:205], v[14:17]
	v_mfma_f32_16x16x32_bf16 v[10:13], v[142:145], v[202:205], v[10:13]
	v_mfma_f32_16x16x32_bf16 v[62:65], v[134:137], v[182:185], v[62:65]
	v_mfma_f32_16x16x32_bf16 v[58:61], v[146:149], v[182:185], v[58:61]
	v_mfma_f32_16x16x32_bf16 v[46:49], v[134:137], v[190:193], v[46:49]
	v_mfma_f32_16x16x32_bf16 v[42:45], v[146:149], v[190:193], v[42:45]
	v_mfma_f32_16x16x32_bf16 v[30:33], v[134:137], v[198:201], v[30:33]
	v_mfma_f32_16x16x32_bf16 v[26:29], v[146:149], v[198:201], v[26:29]
	v_mfma_f32_16x16x32_bf16 v[14:17], v[134:137], v[206:209], v[14:17]
	v_mfma_f32_16x16x32_bf16 v[10:13], v[146:149], v[206:209], v[10:13]
	v_mfma_f32_16x16x32_bf16 v[54:57], v[150:153], v[178:181], v[54:57]
	v_mfma_f32_16x16x32_bf16 v[50:53], v[170:173], v[178:181], v[50:53]
	v_mfma_f32_16x16x32_bf16 v[38:41], v[150:153], v[186:189], v[38:41]
	v_mfma_f32_16x16x32_bf16 v[34:37], v[170:173], v[186:189], v[34:37]
	v_mfma_f32_16x16x32_bf16 v[22:25], v[150:153], v[194:197], v[22:25]
	v_mfma_f32_16x16x32_bf16 v[18:21], v[170:173], v[194:197], v[18:21]
	v_mfma_f32_16x16x32_bf16 v[6:9], v[150:153], v[202:205], v[6:9]
	v_mfma_f32_16x16x32_bf16 v[2:5], v[170:173], v[202:205], v[2:5]
	v_mfma_f32_16x16x32_bf16 v[54:57], v[166:169], v[182:185], v[54:57]
	v_mfma_f32_16x16x32_bf16 v[50:53], v[174:177], v[182:185], v[50:53]
	v_mfma_f32_16x16x32_bf16 v[38:41], v[166:169], v[190:193], v[38:41]
	v_mfma_f32_16x16x32_bf16 v[34:37], v[174:177], v[190:193], v[34:37]
	v_mfma_f32_16x16x32_bf16 v[22:25], v[166:169], v[198:201], v[22:25]
	v_mfma_f32_16x16x32_bf16 v[18:21], v[174:177], v[198:201], v[18:21]
	v_mfma_f32_16x16x32_bf16 v[6:9], v[166:169], v[206:209], v[6:9]
	v_mfma_f32_16x16x32_bf16 v[2:5], v[174:177], v[206:209], v[2:5]
	s_setprio 0
	s_barrier
	s_add_i32 s78, s78, 2
	s_add_u32 s74, s74, 0x100
	s_addc_u32 s75, s75, 0
	s_add_u32 s76, s76, 0x100
	s_addc_u32 s77, s77, 0
	s_add_u32 s58, s58, 0x100
	s_addc_u32 s59, s59, 0
	s_cmpk_gt_u32 s78, 0xa9
	s_cbranch_scc0 .LBB0_1361
.Lmy_kexit_9:
	s_and_b64 vcc, exec, s[36:37]
	s_cbranch_vccz .LBB0_1364
	s_barrier
